# hand-off with priority staging, closing barrier 8 MFMAs early
# baseline (speedup 1.0000x reference)
.LBB0_183:
	s_ashr_i32 s13, s12, 31
	s_lshl_b64 s[24:25], s[12:13], 19
	s_add_u32 s24, s80, s24
	s_addc_u32 s25, s81, s25
	s_and_b64 s[30:31], s[4:5], exec
	s_cselect_b32 s13, s25, s45
	s_cselect_b32 s66, s24, s44
	s_ashr_i32 s11, s10, 31
	s_lshl_b64 s[30:31], s[10:11], 19
	s_add_u32 s30, s52, s30
	s_addc_u32 s31, s53, s31
	s_and_b64 s[48:49], s[4:5], exec
	s_cselect_b32 s11, s31, s47
	s_cselect_b32 s67, s30, s46
	s_add_u32 s44, s44, 0x40080
	s_addc_u32 s45, s45, 0
	s_add_u32 s68, s46, 0x100
	s_addc_u32 s69, s47, 0
	s_mov_b32 s70, -2
	ds_read_b128 v[140:143], v147
	ds_read_b128 v[150:153], v147 offset:1024
	ds_read_b128 v[154:157], v147 offset:2048
	ds_read_b128 v[158:161], v147 offset:3072
	ds_read_b128 v[162:165], v148
	ds_read_b128 v[166:169], v148 offset:1024
	ds_read_b128 v[170:173], v148 offset:2048
	ds_read_b128 v[174:177], v148 offset:3072
	s_add_u32 s18, s44, 0xfffc0080
	s_addc_u32 s19, s45, -1
	s_cmp_eq_u32 s70, 12
	s_cselect_b32 s49, s13, s19
	s_cselect_b32 s48, s66, s18
	s_cselect_b32 s47, s11, s69
	s_cselect_b32 s46, s67, s68
	v_lshl_add_u64 v[178:179], s[44:45], 0, v[132:133]
	s_add_i32 m0, s37, 0xc000
	ds_read_b128 v[184:187], v149
	ds_read_b128 v[188:191], v149 offset:1024
	ds_read_b128 v[192:195], v149 offset:2048
	ds_read_b128 v[196:199], v149 offset:3072
	ds_read_b128 v[200:203], v149 offset:4096
	ds_read_b128 v[204:207], v149 offset:5120
	ds_read_b128 v[208:211], v149 offset:6144
	ds_read_b128 v[212:215], v149 offset:7168
	global_load_lds_dwordx4 v[178:179], off
	v_lshl_add_u64 v[178:179], s[44:45], 0, v[134:135]
	s_add_i32 m0, s37, 0xe000
	s_nop 0
	global_load_lds_dwordx4 v[178:179], off
	s_waitcnt vmcnt(8)
	s_waitcnt lgkmcnt(0)
	s_barrier
	s_waitcnt lgkmcnt(0)
	v_mfma_f32_16x16x32_bf16 v[124:127], v[140:143], v[184:187], 0
	v_mfma_f32_16x16x32_bf16 v[124:127], v[150:153], v[188:191], v[124:127]
	v_mfma_f32_16x16x32_bf16 v[120:123], v[154:157], v[184:187], 0
	v_mfma_f32_16x16x32_bf16 v[120:123], v[158:161], v[188:191], v[120:123]
	v_mfma_f32_16x16x32_bf16 v[108:111], v[140:143], v[192:195], 0
	v_mfma_f32_16x16x32_bf16 v[108:111], v[150:153], v[196:199], v[108:111]
	v_mfma_f32_16x16x32_bf16 v[104:107], v[154:157], v[192:195], 0
	v_mfma_f32_16x16x32_bf16 v[104:107], v[158:161], v[196:199], v[104:107]
	s_setprio 1
	v_mfma_f32_16x16x32_bf16 v[92:95], v[140:143], v[200:203], 0
	v_mfma_f32_16x16x32_bf16 v[92:95], v[150:153], v[204:207], v[92:95]
	v_mfma_f32_16x16x32_bf16 v[88:91], v[154:157], v[200:203], 0
	v_mfma_f32_16x16x32_bf16 v[88:91], v[158:161], v[204:207], v[88:91]
	v_mfma_f32_16x16x32_bf16 v[76:79], v[140:143], v[208:211], 0
	v_mfma_f32_16x16x32_bf16 v[76:79], v[150:153], v[212:215], v[76:79]
	v_mfma_f32_16x16x32_bf16 v[72:75], v[154:157], v[208:211], 0
	v_mfma_f32_16x16x32_bf16 v[72:75], v[158:161], v[212:215], v[72:75]
	v_mfma_f32_16x16x32_bf16 v[116:119], v[162:165], v[184:187], 0
	v_mfma_f32_16x16x32_bf16 v[116:119], v[166:169], v[188:191], v[116:119]
	v_mfma_f32_16x16x32_bf16 v[112:115], v[170:173], v[184:187], 0
	v_mfma_f32_16x16x32_bf16 v[112:115], v[174:177], v[188:191], v[112:115]
	v_mfma_f32_16x16x32_bf16 v[100:103], v[162:165], v[192:195], 0
	v_mfma_f32_16x16x32_bf16 v[100:103], v[166:169], v[196:199], v[100:103]
	v_mfma_f32_16x16x32_bf16 v[96:99], v[170:173], v[192:195], 0
	v_mfma_f32_16x16x32_bf16 v[96:99], v[174:177], v[196:199], v[96:99]
	s_barrier
	v_mfma_f32_16x16x32_bf16 v[84:87], v[162:165], v[200:203], 0
	v_mfma_f32_16x16x32_bf16 v[84:87], v[166:169], v[204:207], v[84:87]
	v_mfma_f32_16x16x32_bf16 v[80:83], v[170:173], v[200:203], 0
	v_mfma_f32_16x16x32_bf16 v[80:83], v[174:177], v[204:207], v[80:83]
	v_mfma_f32_16x16x32_bf16 v[68:71], v[162:165], v[208:211], 0
	v_mfma_f32_16x16x32_bf16 v[68:71], v[166:169], v[212:215], v[68:71]
	v_mfma_f32_16x16x32_bf16 v[64:67], v[170:173], v[208:211], 0
	v_mfma_f32_16x16x32_bf16 v[64:67], v[174:177], v[212:215], v[64:67]
	s_setprio 0
	s_add_i32 s18, s62, s54
	v_lshl_add_u64 v[178:179], s[46:47], 0, v[130:131]
	s_mov_b32 m0, s18
	ds_read_b128 v[184:187], v149 offset:16384
	ds_read_b128 v[188:191], v149 offset:17408
	ds_read_b128 v[192:195], v149 offset:18432
	ds_read_b128 v[196:199], v149 offset:19456
	ds_read_b128 v[200:203], v149 offset:20480
	ds_read_b128 v[204:207], v149 offset:21504
	ds_read_b128 v[208:211], v149 offset:22528
	ds_read_b128 v[212:215], v149 offset:23552
	global_load_lds_dwordx4 v[178:179], off
	s_add_i32 m0, s18, 0x2000
	s_add_u32 s72, s46, 0x40000
	v_lshl_add_u64 v[216:217], s[46:47], 0, v[128:129]
	s_addc_u32 s73, s47, 0
	s_add_i32 s18, s63, s54
	global_load_lds_dwordx4 v[216:217], off
	v_lshl_add_u64 v[218:219], s[72:73], 0, v[130:131]
	s_mov_b32 m0, s18
	v_lshl_add_u64 v[220:221], s[48:49], 0, v[128:129]
	global_load_lds_dwordx4 v[218:219], off
	v_lshl_add_u64 v[218:219], s[72:73], 0, v[128:129]
	s_add_i32 m0, s18, 0x2000
	s_nop 0
	global_load_lds_dwordx4 v[218:219], off
	v_lshl_add_u64 v[218:219], s[48:49], 0, v[130:131]
	s_mov_b32 m0, s37
	s_nop 0
	global_load_lds_dwordx4 v[218:219], off
	s_mov_b32 m0, s56
	s_nop 0
	global_load_lds_dwordx4 v[220:221], off
	s_waitcnt vmcnt(8)
	s_waitcnt lgkmcnt(0)
	s_barrier
	s_waitcnt lgkmcnt(0)
	v_mfma_f32_16x16x32_bf16 v[60:63], v[140:143], v[184:187], 0
	v_mfma_f32_16x16x32_bf16 v[60:63], v[150:153], v[188:191], v[60:63]
	v_mfma_f32_16x16x32_bf16 v[56:59], v[154:157], v[184:187], 0
	v_mfma_f32_16x16x32_bf16 v[56:59], v[158:161], v[188:191], v[56:59]
	v_mfma_f32_16x16x32_bf16 v[44:47], v[140:143], v[192:195], 0
	v_mfma_f32_16x16x32_bf16 v[44:47], v[150:153], v[196:199], v[44:47]
	v_mfma_f32_16x16x32_bf16 v[40:43], v[154:157], v[192:195], 0
	v_mfma_f32_16x16x32_bf16 v[40:43], v[158:161], v[196:199], v[40:43]
	s_setprio 1
	v_mfma_f32_16x16x32_bf16 v[28:31], v[140:143], v[200:203], 0
	v_mfma_f32_16x16x32_bf16 v[28:31], v[150:153], v[204:207], v[28:31]
	v_mfma_f32_16x16x32_bf16 v[24:27], v[154:157], v[200:203], 0
	v_mfma_f32_16x16x32_bf16 v[24:27], v[158:161], v[204:207], v[24:27]
	v_mfma_f32_16x16x32_bf16 v[12:15], v[140:143], v[208:211], 0
	v_mfma_f32_16x16x32_bf16 v[12:15], v[150:153], v[212:215], v[12:15]
	v_mfma_f32_16x16x32_bf16 v[8:11], v[154:157], v[208:211], 0
	v_mfma_f32_16x16x32_bf16 v[8:11], v[158:161], v[212:215], v[8:11]
	v_mfma_f32_16x16x32_bf16 v[52:55], v[162:165], v[184:187], 0
	v_mfma_f32_16x16x32_bf16 v[52:55], v[166:169], v[188:191], v[52:55]
	v_mfma_f32_16x16x32_bf16 v[48:51], v[170:173], v[184:187], 0
	v_mfma_f32_16x16x32_bf16 v[48:51], v[174:177], v[188:191], v[48:51]
	v_mfma_f32_16x16x32_bf16 v[36:39], v[162:165], v[192:195], 0
	v_mfma_f32_16x16x32_bf16 v[36:39], v[166:169], v[196:199], v[36:39]
	v_mfma_f32_16x16x32_bf16 v[32:35], v[170:173], v[192:195], 0
	v_mfma_f32_16x16x32_bf16 v[32:35], v[174:177], v[196:199], v[32:35]
	s_barrier
	v_mfma_f32_16x16x32_bf16 v[20:23], v[162:165], v[200:203], 0
	v_mfma_f32_16x16x32_bf16 v[20:23], v[166:169], v[204:207], v[20:23]
	v_mfma_f32_16x16x32_bf16 v[16:19], v[170:173], v[200:203], 0
	v_mfma_f32_16x16x32_bf16 v[16:19], v[174:177], v[204:207], v[16:19]
	v_mfma_f32_16x16x32_bf16 v[4:7], v[162:165], v[208:211], 0
	v_mfma_f32_16x16x32_bf16 v[4:7], v[166:169], v[212:215], v[4:7]
	v_mfma_f32_16x16x32_bf16 v[0:3], v[170:173], v[208:211], 0
	v_mfma_f32_16x16x32_bf16 v[0:3], v[174:177], v[212:215], v[0:3]
	s_setprio 0
	s_branch .Lmid_gemm0
.LBB0_184:
	ds_read_b128 v[140:143], v147
	ds_read_b128 v[150:153], v147 offset:1024
	ds_read_b128 v[154:157], v147 offset:2048
	ds_read_b128 v[158:161], v147 offset:3072
	ds_read_b128 v[162:165], v148
	ds_read_b128 v[166:169], v148 offset:1024
	ds_read_b128 v[170:173], v148 offset:2048
	ds_read_b128 v[174:177], v148 offset:3072
	s_add_u32 s18, s44, 0xfffc0080
	s_addc_u32 s19, s45, -1
	s_cmp_eq_u32 s70, 12
	s_cselect_b32 s49, s13, s19
	s_cselect_b32 s48, s66, s18
	s_cselect_b32 s47, s11, s69
	s_cselect_b32 s46, s67, s68
	v_lshl_add_u64 v[178:179], s[44:45], 0, v[132:133]
	s_add_i32 m0, s37, 0xc000
	ds_read_b128 v[184:187], v149
	ds_read_b128 v[188:191], v149 offset:1024
	ds_read_b128 v[192:195], v149 offset:2048
	ds_read_b128 v[196:199], v149 offset:3072
	ds_read_b128 v[200:203], v149 offset:4096
	ds_read_b128 v[204:207], v149 offset:5120
	ds_read_b128 v[208:211], v149 offset:6144
	ds_read_b128 v[212:215], v149 offset:7168
	global_load_lds_dwordx4 v[178:179], off
	v_lshl_add_u64 v[178:179], s[44:45], 0, v[134:135]
	s_add_i32 m0, s37, 0xe000
	s_nop 0
	global_load_lds_dwordx4 v[178:179], off
	s_waitcnt vmcnt(8)
	s_waitcnt lgkmcnt(0)
	s_barrier
	s_waitcnt lgkmcnt(0)
	v_mfma_f32_16x16x32_bf16 v[124:127], v[140:143], v[184:187], v[124:127]
	v_mfma_f32_16x16x32_bf16 v[124:127], v[150:153], v[188:191], v[124:127]
	v_mfma_f32_16x16x32_bf16 v[120:123], v[154:157], v[184:187], v[120:123]
	v_mfma_f32_16x16x32_bf16 v[120:123], v[158:161], v[188:191], v[120:123]
	v_mfma_f32_16x16x32_bf16 v[108:111], v[140:143], v[192:195], v[108:111]
	v_mfma_f32_16x16x32_bf16 v[108:111], v[150:153], v[196:199], v[108:111]
	v_mfma_f32_16x16x32_bf16 v[104:107], v[154:157], v[192:195], v[104:107]
	v_mfma_f32_16x16x32_bf16 v[104:107], v[158:161], v[196:199], v[104:107]
	s_setprio 1
	v_mfma_f32_16x16x32_bf16 v[92:95], v[140:143], v[200:203], v[92:95]
	v_mfma_f32_16x16x32_bf16 v[92:95], v[150:153], v[204:207], v[92:95]
	v_mfma_f32_16x16x32_bf16 v[88:91], v[154:157], v[200:203], v[88:91]
	v_mfma_f32_16x16x32_bf16 v[88:91], v[158:161], v[204:207], v[88:91]
	v_mfma_f32_16x16x32_bf16 v[76:79], v[140:143], v[208:211], v[76:79]
	v_mfma_f32_16x16x32_bf16 v[76:79], v[150:153], v[212:215], v[76:79]
	v_mfma_f32_16x16x32_bf16 v[72:75], v[154:157], v[208:211], v[72:75]
	v_mfma_f32_16x16x32_bf16 v[72:75], v[158:161], v[212:215], v[72:75]
	v_mfma_f32_16x16x32_bf16 v[116:119], v[162:165], v[184:187], v[116:119]
	v_mfma_f32_16x16x32_bf16 v[116:119], v[166:169], v[188:191], v[116:119]
	v_mfma_f32_16x16x32_bf16 v[112:115], v[170:173], v[184:187], v[112:115]
	v_mfma_f32_16x16x32_bf16 v[112:115], v[174:177], v[188:191], v[112:115]
	v_mfma_f32_16x16x32_bf16 v[100:103], v[162:165], v[192:195], v[100:103]
	v_mfma_f32_16x16x32_bf16 v[100:103], v[166:169], v[196:199], v[100:103]
	v_mfma_f32_16x16x32_bf16 v[96:99], v[170:173], v[192:195], v[96:99]
	v_mfma_f32_16x16x32_bf16 v[96:99], v[174:177], v[196:199], v[96:99]
	s_barrier
	v_mfma_f32_16x16x32_bf16 v[84:87], v[162:165], v[200:203], v[84:87]
	v_mfma_f32_16x16x32_bf16 v[84:87], v[166:169], v[204:207], v[84:87]
	v_mfma_f32_16x16x32_bf16 v[80:83], v[170:173], v[200:203], v[80:83]
	v_mfma_f32_16x16x32_bf16 v[80:83], v[174:177], v[204:207], v[80:83]
	v_mfma_f32_16x16x32_bf16 v[68:71], v[162:165], v[208:211], v[68:71]
	v_mfma_f32_16x16x32_bf16 v[68:71], v[166:169], v[212:215], v[68:71]
	v_mfma_f32_16x16x32_bf16 v[64:67], v[170:173], v[208:211], v[64:67]
	v_mfma_f32_16x16x32_bf16 v[64:67], v[174:177], v[212:215], v[64:67]
	s_setprio 0
	s_add_i32 s18, s62, s54
	v_lshl_add_u64 v[178:179], s[46:47], 0, v[130:131]
	s_mov_b32 m0, s18
	ds_read_b128 v[184:187], v149 offset:16384
	ds_read_b128 v[188:191], v149 offset:17408
	ds_read_b128 v[192:195], v149 offset:18432
	ds_read_b128 v[196:199], v149 offset:19456
	ds_read_b128 v[200:203], v149 offset:20480
	ds_read_b128 v[204:207], v149 offset:21504
	ds_read_b128 v[208:211], v149 offset:22528
	ds_read_b128 v[212:215], v149 offset:23552
	global_load_lds_dwordx4 v[178:179], off
	s_add_i32 m0, s18, 0x2000
	s_add_u32 s72, s46, 0x40000
	v_lshl_add_u64 v[216:217], s[46:47], 0, v[128:129]
	s_addc_u32 s73, s47, 0
	s_add_i32 s18, s63, s54
	global_load_lds_dwordx4 v[216:217], off
	v_lshl_add_u64 v[218:219], s[72:73], 0, v[130:131]
	s_mov_b32 m0, s18
	v_lshl_add_u64 v[220:221], s[48:49], 0, v[128:129]
	global_load_lds_dwordx4 v[218:219], off
	v_lshl_add_u64 v[218:219], s[72:73], 0, v[128:129]
	s_add_i32 m0, s18, 0x2000
	s_nop 0
	global_load_lds_dwordx4 v[218:219], off
	v_lshl_add_u64 v[218:219], s[48:49], 0, v[130:131]
	s_mov_b32 m0, s37
	s_nop 0
	global_load_lds_dwordx4 v[218:219], off
	s_mov_b32 m0, s56
	s_nop 0
	global_load_lds_dwordx4 v[220:221], off
	s_waitcnt vmcnt(8)
	s_waitcnt lgkmcnt(0)
	s_barrier
	s_waitcnt lgkmcnt(0)
	v_mfma_f32_16x16x32_bf16 v[60:63], v[140:143], v[184:187], v[60:63]
	v_mfma_f32_16x16x32_bf16 v[60:63], v[150:153], v[188:191], v[60:63]
	v_mfma_f32_16x16x32_bf16 v[56:59], v[154:157], v[184:187], v[56:59]
	v_mfma_f32_16x16x32_bf16 v[56:59], v[158:161], v[188:191], v[56:59]
	v_mfma_f32_16x16x32_bf16 v[44:47], v[140:143], v[192:195], v[44:47]
	v_mfma_f32_16x16x32_bf16 v[44:47], v[150:153], v[196:199], v[44:47]
	v_mfma_f32_16x16x32_bf16 v[40:43], v[154:157], v[192:195], v[40:43]
	v_mfma_f32_16x16x32_bf16 v[40:43], v[158:161], v[196:199], v[40:43]
	s_setprio 1
	v_mfma_f32_16x16x32_bf16 v[28:31], v[140:143], v[200:203], v[28:31]
	v_mfma_f32_16x16x32_bf16 v[28:31], v[150:153], v[204:207], v[28:31]
	v_mfma_f32_16x16x32_bf16 v[24:27], v[154:157], v[200:203], v[24:27]
	v_mfma_f32_16x16x32_bf16 v[24:27], v[158:161], v[204:207], v[24:27]
	v_mfma_f32_16x16x32_bf16 v[12:15], v[140:143], v[208:211], v[12:15]
	v_mfma_f32_16x16x32_bf16 v[12:15], v[150:153], v[212:215], v[12:15]
	v_mfma_f32_16x16x32_bf16 v[8:11], v[154:157], v[208:211], v[8:11]
	v_mfma_f32_16x16x32_bf16 v[8:11], v[158:161], v[212:215], v[8:11]
	v_mfma_f32_16x16x32_bf16 v[52:55], v[162:165], v[184:187], v[52:55]
	v_mfma_f32_16x16x32_bf16 v[52:55], v[166:169], v[188:191], v[52:55]
	v_mfma_f32_16x16x32_bf16 v[48:51], v[170:173], v[184:187], v[48:51]
	v_mfma_f32_16x16x32_bf16 v[48:51], v[174:177], v[188:191], v[48:51]
	v_mfma_f32_16x16x32_bf16 v[36:39], v[162:165], v[192:195], v[36:39]
	v_mfma_f32_16x16x32_bf16 v[36:39], v[166:169], v[196:199], v[36:39]
	v_mfma_f32_16x16x32_bf16 v[32:35], v[170:173], v[192:195], v[32:35]
	v_mfma_f32_16x16x32_bf16 v[32:35], v[174:177], v[196:199], v[32:35]
	s_barrier
	v_mfma_f32_16x16x32_bf16 v[20:23], v[162:165], v[200:203], v[20:23]
	v_mfma_f32_16x16x32_bf16 v[20:23], v[166:169], v[204:207], v[20:23]
	v_mfma_f32_16x16x32_bf16 v[16:19], v[170:173], v[200:203], v[16:19]
	v_mfma_f32_16x16x32_bf16 v[16:19], v[174:177], v[204:207], v[16:19]
	v_mfma_f32_16x16x32_bf16 v[4:7], v[162:165], v[208:211], v[4:7]
	v_mfma_f32_16x16x32_bf16 v[4:7], v[166:169], v[212:215], v[4:7]
	v_mfma_f32_16x16x32_bf16 v[0:3], v[170:173], v[208:211], v[0:3]
	v_mfma_f32_16x16x32_bf16 v[0:3], v[174:177], v[212:215], v[0:3]
	s_setprio 0
.Lmid_gemm0:
	s_add_i32 s18, 0, 0x18000
	s_add_i32 s19, 0, 0x1c000
	v_add_u32_e32 v158, s18, v145
	v_add_u32_e32 v174, s19, v145
	ds_read_b128 v[140:143], v158
	ds_read_b128 v[150:153], v158 offset:1024
	ds_read_b128 v[154:157], v158 offset:2048
	ds_read_b128 v[158:161], v158 offset:3072
	ds_read_b128 v[162:165], v174
	ds_read_b128 v[166:169], v174 offset:1024
	ds_read_b128 v[170:173], v174 offset:2048
	ds_read_b128 v[174:177], v174 offset:3072
	s_add_u32 s48, s48, 0x40000
	s_addc_u32 s49, s49, 0
	s_mov_b32 m0, s57
	v_lshl_add_u64 v[222:223], s[48:49], 0, v[130:131]
	ds_read_b128 v[184:187], v149 offset:32768
	ds_read_b128 v[188:191], v149 offset:33792
	ds_read_b128 v[192:195], v149 offset:34816
	ds_read_b128 v[196:199], v149 offset:35840
	ds_read_b128 v[200:203], v149 offset:36864
	ds_read_b128 v[204:207], v149 offset:37888
	ds_read_b128 v[208:211], v149 offset:38912
	ds_read_b128 v[212:215], v149 offset:39936
	global_load_lds_dwordx4 v[222:223], off
	v_lshl_add_u64 v[222:223], s[48:49], 0, v[128:129]
	s_mov_b32 m0, s58
	s_nop 0
	global_load_lds_dwordx4 v[222:223], off
	s_waitcnt vmcnt(8)
	s_waitcnt lgkmcnt(0)
	s_barrier
	s_waitcnt lgkmcnt(0)
	v_mfma_f32_16x16x32_bf16 v[124:127], v[140:143], v[184:187], v[124:127]
	v_mfma_f32_16x16x32_bf16 v[124:127], v[150:153], v[188:191], v[124:127]
	v_mfma_f32_16x16x32_bf16 v[120:123], v[154:157], v[184:187], v[120:123]
	v_mfma_f32_16x16x32_bf16 v[120:123], v[158:161], v[188:191], v[120:123]
	v_mfma_f32_16x16x32_bf16 v[108:111], v[140:143], v[192:195], v[108:111]
	v_mfma_f32_16x16x32_bf16 v[108:111], v[150:153], v[196:199], v[108:111]
	v_mfma_f32_16x16x32_bf16 v[104:107], v[154:157], v[192:195], v[104:107]
	v_mfma_f32_16x16x32_bf16 v[104:107], v[158:161], v[196:199], v[104:107]
	s_setprio 1
	v_mfma_f32_16x16x32_bf16 v[92:95], v[140:143], v[200:203], v[92:95]
	v_mfma_f32_16x16x32_bf16 v[92:95], v[150:153], v[204:207], v[92:95]
	v_mfma_f32_16x16x32_bf16 v[88:91], v[154:157], v[200:203], v[88:91]
	v_mfma_f32_16x16x32_bf16 v[88:91], v[158:161], v[204:207], v[88:91]
	v_mfma_f32_16x16x32_bf16 v[76:79], v[140:143], v[208:211], v[76:79]
	v_mfma_f32_16x16x32_bf16 v[76:79], v[150:153], v[212:215], v[76:79]
	v_mfma_f32_16x16x32_bf16 v[72:75], v[154:157], v[208:211], v[72:75]
	v_mfma_f32_16x16x32_bf16 v[72:75], v[158:161], v[212:215], v[72:75]
	v_mfma_f32_16x16x32_bf16 v[116:119], v[162:165], v[184:187], v[116:119]
	v_mfma_f32_16x16x32_bf16 v[116:119], v[166:169], v[188:191], v[116:119]
	v_mfma_f32_16x16x32_bf16 v[112:115], v[170:173], v[184:187], v[112:115]
	v_mfma_f32_16x16x32_bf16 v[112:115], v[174:177], v[188:191], v[112:115]
	v_mfma_f32_16x16x32_bf16 v[100:103], v[162:165], v[192:195], v[100:103]
	v_mfma_f32_16x16x32_bf16 v[100:103], v[166:169], v[196:199], v[100:103]
	v_mfma_f32_16x16x32_bf16 v[96:99], v[170:173], v[192:195], v[96:99]
	v_mfma_f32_16x16x32_bf16 v[96:99], v[174:177], v[196:199], v[96:99]
	s_barrier
	v_mfma_f32_16x16x32_bf16 v[84:87], v[162:165], v[200:203], v[84:87]
	v_mfma_f32_16x16x32_bf16 v[84:87], v[166:169], v[204:207], v[84:87]
	v_mfma_f32_16x16x32_bf16 v[80:83], v[170:173], v[200:203], v[80:83]
	v_mfma_f32_16x16x32_bf16 v[80:83], v[174:177], v[204:207], v[80:83]
	v_mfma_f32_16x16x32_bf16 v[68:71], v[162:165], v[208:211], v[68:71]
	v_mfma_f32_16x16x32_bf16 v[68:71], v[166:169], v[212:215], v[68:71]
	v_mfma_f32_16x16x32_bf16 v[64:67], v[170:173], v[208:211], v[64:67]
	v_mfma_f32_16x16x32_bf16 v[64:67], v[174:177], v[212:215], v[64:67]
	s_setprio 0
	s_add_i32 s18, s18, s54
	v_lshl_add_u64 v[178:179], v[178:179], 0, s[6:7]
	s_mov_b32 m0, s18
	ds_read_b128 v[184:187], v149 offset:49152
	ds_read_b128 v[188:191], v149 offset:50176
	ds_read_b128 v[192:195], v149 offset:51200
	ds_read_b128 v[196:199], v149 offset:52224
	ds_read_b128 v[200:203], v149 offset:53248
	ds_read_b128 v[204:207], v149 offset:54272
	ds_read_b128 v[208:211], v149 offset:55296
	ds_read_b128 v[212:215], v149 offset:56320
	global_load_lds_dwordx4 v[178:179], off
	s_add_i32 m0, s18, 0x2000
	s_add_u32 s46, s46, 0x40080
	v_lshl_add_u64 v[178:179], v[216:217], 0, s[6:7]
	s_addc_u32 s47, s47, 0
	s_add_i32 s18, s19, s54
	global_load_lds_dwordx4 v[178:179], off
	v_lshl_add_u64 v[178:179], s[46:47], 0, v[130:131]
	s_mov_b32 m0, s18
	s_nop 0
	global_load_lds_dwordx4 v[178:179], off
	v_lshl_add_u64 v[178:179], s[46:47], 0, v[128:129]
	s_add_i32 m0, s18, 0x2000
	s_nop 0
	global_load_lds_dwordx4 v[178:179], off
	v_lshl_add_u64 v[178:179], v[218:219], 0, s[6:7]
	s_mov_b32 m0, s60
	s_nop 0
	global_load_lds_dwordx4 v[178:179], off
	v_lshl_add_u64 v[178:179], v[220:221], 0, s[6:7]
	s_mov_b32 m0, s61
	s_nop 0
	global_load_lds_dwordx4 v[178:179], off
	s_waitcnt vmcnt(8)
	s_waitcnt lgkmcnt(0)
	s_barrier
	s_waitcnt lgkmcnt(0)
	v_mfma_f32_16x16x32_bf16 v[60:63], v[140:143], v[184:187], v[60:63]
	v_mfma_f32_16x16x32_bf16 v[60:63], v[150:153], v[188:191], v[60:63]
	v_mfma_f32_16x16x32_bf16 v[56:59], v[154:157], v[184:187], v[56:59]
	v_mfma_f32_16x16x32_bf16 v[56:59], v[158:161], v[188:191], v[56:59]
	v_mfma_f32_16x16x32_bf16 v[44:47], v[140:143], v[192:195], v[44:47]
	v_mfma_f32_16x16x32_bf16 v[44:47], v[150:153], v[196:199], v[44:47]
	v_mfma_f32_16x16x32_bf16 v[40:43], v[154:157], v[192:195], v[40:43]
	v_mfma_f32_16x16x32_bf16 v[40:43], v[158:161], v[196:199], v[40:43]
	s_setprio 1
	v_mfma_f32_16x16x32_bf16 v[28:31], v[140:143], v[200:203], v[28:31]
	v_mfma_f32_16x16x32_bf16 v[28:31], v[150:153], v[204:207], v[28:31]
	v_mfma_f32_16x16x32_bf16 v[24:27], v[154:157], v[200:203], v[24:27]
	v_mfma_f32_16x16x32_bf16 v[24:27], v[158:161], v[204:207], v[24:27]
	v_mfma_f32_16x16x32_bf16 v[12:15], v[140:143], v[208:211], v[12:15]
	v_mfma_f32_16x16x32_bf16 v[12:15], v[150:153], v[212:215], v[12:15]
	v_mfma_f32_16x16x32_bf16 v[8:11], v[154:157], v[208:211], v[8:11]
	v_mfma_f32_16x16x32_bf16 v[8:11], v[158:161], v[212:215], v[8:11]
	v_mfma_f32_16x16x32_bf16 v[52:55], v[162:165], v[184:187], v[52:55]
	v_mfma_f32_16x16x32_bf16 v[52:55], v[166:169], v[188:191], v[52:55]
	v_mfma_f32_16x16x32_bf16 v[48:51], v[170:173], v[184:187], v[48:51]
	v_mfma_f32_16x16x32_bf16 v[48:51], v[174:177], v[188:191], v[48:51]
	v_mfma_f32_16x16x32_bf16 v[36:39], v[162:165], v[192:195], v[36:39]
	v_mfma_f32_16x16x32_bf16 v[36:39], v[166:169], v[196:199], v[36:39]
	v_mfma_f32_16x16x32_bf16 v[32:35], v[170:173], v[192:195], v[32:35]
	v_mfma_f32_16x16x32_bf16 v[32:35], v[174:177], v[196:199], v[32:35]
	s_barrier
	v_mfma_f32_16x16x32_bf16 v[20:23], v[162:165], v[200:203], v[20:23]
	v_mfma_f32_16x16x32_bf16 v[20:23], v[166:169], v[204:207], v[20:23]
	v_mfma_f32_16x16x32_bf16 v[16:19], v[170:173], v[200:203], v[16:19]
	v_mfma_f32_16x16x32_bf16 v[16:19], v[174:177], v[204:207], v[16:19]
	v_mfma_f32_16x16x32_bf16 v[4:7], v[162:165], v[208:211], v[4:7]
	v_mfma_f32_16x16x32_bf16 v[4:7], v[166:169], v[212:215], v[4:7]
	v_mfma_f32_16x16x32_bf16 v[0:3], v[170:173], v[208:211], v[0:3]
	v_mfma_f32_16x16x32_bf16 v[0:3], v[174:177], v[212:215], v[0:3]
	s_setprio 0
	s_add_i32 s70, s70, 2
	s_add_u32 s44, s44, 0x100
	s_addc_u32 s45, s45, 0
	s_add_u32 s68, s68, 0x100
	s_addc_u32 s69, s69, 0
	s_cmp_gt_u32 s70, 13
	s_cbranch_scc0 .LBB0_184
	s_and_b64 vcc, exec, s[8:9]
	s_cbranch_vccz .LBB0_187
	s_barrier

.LBB0_263:
	s_add_u32 s84, s54, 0x100
	s_addc_u32 s85, s55, 0
	s_mov_b32 s86, -2
	ds_read_b128 v[152:155], v149
	ds_read_b128 v[156:159], v149 offset:1024
	ds_read_b128 v[160:163], v149 offset:2048
	ds_read_b128 v[164:167], v149 offset:3072
	ds_read_b128 v[168:171], v150
	ds_read_b128 v[172:175], v150 offset:1024
	ds_read_b128 v[176:179], v150 offset:2048
	ds_read_b128 v[184:187], v150 offset:3072
	s_add_u32 s54, s52, 0x100
	s_addc_u32 s55, s53, 0
	s_cmp_eq_u32 s86, 40
	s_cselect_b32 s59, s7, s55
	s_cselect_b32 s58, s6, s54
	s_cselect_b32 s57, s49, s85
	s_cselect_b32 s56, s48, s84
	v_lshl_add_u64 v[144:145], s[52:53], 0, v[136:137]
	s_add_i32 m0, s63, 0xc000
	ds_read_b128 v[188:191], v151
	ds_read_b128 v[192:195], v151 offset:1024
	ds_read_b128 v[196:199], v151 offset:2048
	ds_read_b128 v[200:203], v151 offset:3072
	ds_read_b128 v[204:207], v151 offset:4096
	ds_read_b128 v[208:211], v151 offset:5120
	ds_read_b128 v[212:215], v151 offset:6144
	ds_read_b128 v[216:219], v151 offset:7168
	global_load_lds_dwordx4 v[144:145], off
	v_lshl_add_u64 v[144:145], s[52:53], 0, v[138:139]
	s_add_i32 m0, s63, 0xe000
	s_nop 0
	global_load_lds_dwordx4 v[144:145], off
	s_waitcnt vmcnt(8)
	s_waitcnt lgkmcnt(0)
	s_barrier
	s_waitcnt lgkmcnt(0)
	v_mfma_f32_16x16x32_bf16 v[124:127], v[152:155], v[188:191], 0
	v_mfma_f32_16x16x32_bf16 v[124:127], v[156:159], v[192:195], v[124:127]
	v_mfma_f32_16x16x32_bf16 v[120:123], v[160:163], v[188:191], 0
	v_mfma_f32_16x16x32_bf16 v[120:123], v[164:167], v[192:195], v[120:123]
	v_mfma_f32_16x16x32_bf16 v[116:119], v[152:155], v[196:199], 0
	v_mfma_f32_16x16x32_bf16 v[116:119], v[156:159], v[200:203], v[116:119]
	v_mfma_f32_16x16x32_bf16 v[108:111], v[160:163], v[196:199], 0
	v_mfma_f32_16x16x32_bf16 v[108:111], v[164:167], v[200:203], v[108:111]
	s_setprio 1
	v_mfma_f32_16x16x32_bf16 v[100:103], v[152:155], v[204:207], 0
	v_mfma_f32_16x16x32_bf16 v[100:103], v[156:159], v[208:211], v[100:103]
	v_mfma_f32_16x16x32_bf16 v[92:95], v[160:163], v[204:207], 0
	v_mfma_f32_16x16x32_bf16 v[92:95], v[164:167], v[208:211], v[92:95]
	v_mfma_f32_16x16x32_bf16 v[84:87], v[152:155], v[212:215], 0
	v_mfma_f32_16x16x32_bf16 v[84:87], v[156:159], v[216:219], v[84:87]
	v_mfma_f32_16x16x32_bf16 v[76:79], v[160:163], v[212:215], 0
	v_mfma_f32_16x16x32_bf16 v[76:79], v[164:167], v[216:219], v[76:79]
	v_mfma_f32_16x16x32_bf16 v[112:115], v[168:171], v[188:191], 0
	v_mfma_f32_16x16x32_bf16 v[112:115], v[172:175], v[192:195], v[112:115]
	v_mfma_f32_16x16x32_bf16 v[104:107], v[176:179], v[188:191], 0
	v_mfma_f32_16x16x32_bf16 v[104:107], v[184:187], v[192:195], v[104:107]
	v_mfma_f32_16x16x32_bf16 v[96:99], v[168:171], v[196:199], 0
	v_mfma_f32_16x16x32_bf16 v[96:99], v[172:175], v[200:203], v[96:99]
	v_mfma_f32_16x16x32_bf16 v[88:91], v[176:179], v[196:199], 0
	v_mfma_f32_16x16x32_bf16 v[88:91], v[184:187], v[200:203], v[88:91]
	s_barrier
	v_mfma_f32_16x16x32_bf16 v[80:83], v[168:171], v[204:207], 0
	v_mfma_f32_16x16x32_bf16 v[80:83], v[172:175], v[208:211], v[80:83]
	v_mfma_f32_16x16x32_bf16 v[72:75], v[176:179], v[204:207], 0
	v_mfma_f32_16x16x32_bf16 v[72:75], v[184:187], v[208:211], v[72:75]
	v_mfma_f32_16x16x32_bf16 v[68:71], v[168:171], v[212:215], 0
	v_mfma_f32_16x16x32_bf16 v[68:71], v[172:175], v[216:219], v[68:71]
	v_mfma_f32_16x16x32_bf16 v[64:67], v[176:179], v[212:215], 0
	v_mfma_f32_16x16x32_bf16 v[64:67], v[184:187], v[216:219], v[64:67]
	s_setprio 0
	s_add_i32 s18, s70, s62
	v_lshl_add_u64 v[144:145], s[56:57], 0, v[130:131]
	s_mov_b32 m0, s18
	ds_read_b128 v[188:191], v151 offset:16384
	ds_read_b128 v[192:195], v151 offset:17408
	ds_read_b128 v[196:199], v151 offset:18432
	ds_read_b128 v[200:203], v151 offset:19456
	ds_read_b128 v[204:207], v151 offset:20480
	ds_read_b128 v[208:211], v151 offset:21504
	ds_read_b128 v[212:215], v151 offset:22528
	ds_read_b128 v[216:219], v151 offset:23552
	global_load_lds_dwordx4 v[144:145], off
	s_add_i32 m0, s18, 0x2000
	s_add_u32 s52, s56, 0xb0000
	v_lshl_add_u64 v[220:221], s[56:57], 0, v[134:135]
	s_addc_u32 s53, s57, 0
	s_add_i32 s18, s71, s62
	global_load_lds_dwordx4 v[220:221], off
	v_lshl_add_u64 v[222:223], s[52:53], 0, v[130:131]
	s_mov_b32 m0, s18
	v_lshl_add_u64 v[224:225], s[58:59], 0, v[132:133]
	global_load_lds_dwordx4 v[222:223], off
	v_lshl_add_u64 v[222:223], s[52:53], 0, v[134:135]
	s_add_i32 m0, s18, 0x2000
	s_nop 0
	global_load_lds_dwordx4 v[222:223], off
	v_lshl_add_u64 v[222:223], s[58:59], 0, v[128:129]
	s_mov_b32 m0, s63
	s_nop 0
	global_load_lds_dwordx4 v[222:223], off
	s_mov_b32 m0, s64
	s_nop 0
	global_load_lds_dwordx4 v[224:225], off
	s_waitcnt vmcnt(8)
	s_waitcnt lgkmcnt(0)
	s_barrier
	s_waitcnt lgkmcnt(0)
	v_mfma_f32_16x16x32_bf16 v[60:63], v[152:155], v[188:191], 0
	v_mfma_f32_16x16x32_bf16 v[60:63], v[156:159], v[192:195], v[60:63]
	v_mfma_f32_16x16x32_bf16 v[56:59], v[160:163], v[188:191], 0
	v_mfma_f32_16x16x32_bf16 v[56:59], v[164:167], v[192:195], v[56:59]
	v_mfma_f32_16x16x32_bf16 v[52:55], v[152:155], v[196:199], 0
	v_mfma_f32_16x16x32_bf16 v[52:55], v[156:159], v[200:203], v[52:55]
	v_mfma_f32_16x16x32_bf16 v[44:47], v[160:163], v[196:199], 0
	v_mfma_f32_16x16x32_bf16 v[44:47], v[164:167], v[200:203], v[44:47]
	s_setprio 1
	v_mfma_f32_16x16x32_bf16 v[36:39], v[152:155], v[204:207], 0
	v_mfma_f32_16x16x32_bf16 v[36:39], v[156:159], v[208:211], v[36:39]
	v_mfma_f32_16x16x32_bf16 v[28:31], v[160:163], v[204:207], 0
	v_mfma_f32_16x16x32_bf16 v[28:31], v[164:167], v[208:211], v[28:31]
	v_mfma_f32_16x16x32_bf16 v[20:23], v[152:155], v[212:215], 0
	v_mfma_f32_16x16x32_bf16 v[20:23], v[156:159], v[216:219], v[20:23]
	v_mfma_f32_16x16x32_bf16 v[12:15], v[160:163], v[212:215], 0
	v_mfma_f32_16x16x32_bf16 v[12:15], v[164:167], v[216:219], v[12:15]
	v_mfma_f32_16x16x32_bf16 v[48:51], v[168:171], v[188:191], 0
	v_mfma_f32_16x16x32_bf16 v[48:51], v[172:175], v[192:195], v[48:51]
	v_mfma_f32_16x16x32_bf16 v[40:43], v[176:179], v[188:191], 0
	v_mfma_f32_16x16x32_bf16 v[40:43], v[184:187], v[192:195], v[40:43]
	v_mfma_f32_16x16x32_bf16 v[32:35], v[168:171], v[196:199], 0
	v_mfma_f32_16x16x32_bf16 v[32:35], v[172:175], v[200:203], v[32:35]
	v_mfma_f32_16x16x32_bf16 v[24:27], v[176:179], v[196:199], 0
	v_mfma_f32_16x16x32_bf16 v[24:27], v[184:187], v[200:203], v[24:27]
	s_barrier
	v_mfma_f32_16x16x32_bf16 v[16:19], v[168:171], v[204:207], 0
	v_mfma_f32_16x16x32_bf16 v[16:19], v[172:175], v[208:211], v[16:19]
	v_mfma_f32_16x16x32_bf16 v[8:11], v[176:179], v[204:207], 0
	v_mfma_f32_16x16x32_bf16 v[8:11], v[184:187], v[208:211], v[8:11]
	v_mfma_f32_16x16x32_bf16 v[4:7], v[168:171], v[212:215], 0
	v_mfma_f32_16x16x32_bf16 v[4:7], v[172:175], v[216:219], v[4:7]
	v_mfma_f32_16x16x32_bf16 v[0:3], v[176:179], v[212:215], 0
	v_mfma_f32_16x16x32_bf16 v[0:3], v[184:187], v[216:219], v[0:3]
	s_setprio 0
	s_branch .Lmid_gemm1
.LBB0_264:
	ds_read_b128 v[152:155], v149
	ds_read_b128 v[156:159], v149 offset:1024
	ds_read_b128 v[160:163], v149 offset:2048
	ds_read_b128 v[164:167], v149 offset:3072
	ds_read_b128 v[168:171], v150
	ds_read_b128 v[172:175], v150 offset:1024
	ds_read_b128 v[176:179], v150 offset:2048
	ds_read_b128 v[184:187], v150 offset:3072
	s_add_u32 s54, s52, 0x100
	s_addc_u32 s55, s53, 0
	s_cmp_eq_u32 s86, 40
	s_cselect_b32 s59, s7, s55
	s_cselect_b32 s58, s6, s54
	s_cselect_b32 s57, s49, s85
	s_cselect_b32 s56, s48, s84
	v_lshl_add_u64 v[144:145], s[52:53], 0, v[136:137]
	s_add_i32 m0, s63, 0xc000
	ds_read_b128 v[188:191], v151
	ds_read_b128 v[192:195], v151 offset:1024
	ds_read_b128 v[196:199], v151 offset:2048
	ds_read_b128 v[200:203], v151 offset:3072
	ds_read_b128 v[204:207], v151 offset:4096
	ds_read_b128 v[208:211], v151 offset:5120
	ds_read_b128 v[212:215], v151 offset:6144
	ds_read_b128 v[216:219], v151 offset:7168
	global_load_lds_dwordx4 v[144:145], off
	v_lshl_add_u64 v[144:145], s[52:53], 0, v[138:139]
	s_add_i32 m0, s63, 0xe000
	s_nop 0
	global_load_lds_dwordx4 v[144:145], off
	s_waitcnt vmcnt(8)
	s_waitcnt lgkmcnt(0)
	s_barrier
	s_waitcnt lgkmcnt(0)
	v_mfma_f32_16x16x32_bf16 v[124:127], v[152:155], v[188:191], v[124:127]
	v_mfma_f32_16x16x32_bf16 v[124:127], v[156:159], v[192:195], v[124:127]
	v_mfma_f32_16x16x32_bf16 v[120:123], v[160:163], v[188:191], v[120:123]
	v_mfma_f32_16x16x32_bf16 v[120:123], v[164:167], v[192:195], v[120:123]
	v_mfma_f32_16x16x32_bf16 v[116:119], v[152:155], v[196:199], v[116:119]
	v_mfma_f32_16x16x32_bf16 v[116:119], v[156:159], v[200:203], v[116:119]
	v_mfma_f32_16x16x32_bf16 v[108:111], v[160:163], v[196:199], v[108:111]
	v_mfma_f32_16x16x32_bf16 v[108:111], v[164:167], v[200:203], v[108:111]
	s_setprio 1
	v_mfma_f32_16x16x32_bf16 v[100:103], v[152:155], v[204:207], v[100:103]
	v_mfma_f32_16x16x32_bf16 v[100:103], v[156:159], v[208:211], v[100:103]
	v_mfma_f32_16x16x32_bf16 v[92:95], v[160:163], v[204:207], v[92:95]
	v_mfma_f32_16x16x32_bf16 v[92:95], v[164:167], v[208:211], v[92:95]
	v_mfma_f32_16x16x32_bf16 v[84:87], v[152:155], v[212:215], v[84:87]
	v_mfma_f32_16x16x32_bf16 v[84:87], v[156:159], v[216:219], v[84:87]
	v_mfma_f32_16x16x32_bf16 v[76:79], v[160:163], v[212:215], v[76:79]
	v_mfma_f32_16x16x32_bf16 v[76:79], v[164:167], v[216:219], v[76:79]
	v_mfma_f32_16x16x32_bf16 v[112:115], v[168:171], v[188:191], v[112:115]
	v_mfma_f32_16x16x32_bf16 v[112:115], v[172:175], v[192:195], v[112:115]
	v_mfma_f32_16x16x32_bf16 v[104:107], v[176:179], v[188:191], v[104:107]
	v_mfma_f32_16x16x32_bf16 v[104:107], v[184:187], v[192:195], v[104:107]
	v_mfma_f32_16x16x32_bf16 v[96:99], v[168:171], v[196:199], v[96:99]
	v_mfma_f32_16x16x32_bf16 v[96:99], v[172:175], v[200:203], v[96:99]
	v_mfma_f32_16x16x32_bf16 v[88:91], v[176:179], v[196:199], v[88:91]
	v_mfma_f32_16x16x32_bf16 v[88:91], v[184:187], v[200:203], v[88:91]
	s_barrier
	v_mfma_f32_16x16x32_bf16 v[80:83], v[168:171], v[204:207], v[80:83]
	v_mfma_f32_16x16x32_bf16 v[80:83], v[172:175], v[208:211], v[80:83]
	v_mfma_f32_16x16x32_bf16 v[72:75], v[176:179], v[204:207], v[72:75]
	v_mfma_f32_16x16x32_bf16 v[72:75], v[184:187], v[208:211], v[72:75]
	v_mfma_f32_16x16x32_bf16 v[68:71], v[168:171], v[212:215], v[68:71]
	v_mfma_f32_16x16x32_bf16 v[68:71], v[172:175], v[216:219], v[68:71]
	v_mfma_f32_16x16x32_bf16 v[64:67], v[176:179], v[212:215], v[64:67]
	v_mfma_f32_16x16x32_bf16 v[64:67], v[184:187], v[216:219], v[64:67]
	s_setprio 0
	s_add_i32 s18, s70, s62
	v_lshl_add_u64 v[144:145], s[56:57], 0, v[130:131]
	s_mov_b32 m0, s18
	ds_read_b128 v[188:191], v151 offset:16384
	ds_read_b128 v[192:195], v151 offset:17408
	ds_read_b128 v[196:199], v151 offset:18432
	ds_read_b128 v[200:203], v151 offset:19456
	ds_read_b128 v[204:207], v151 offset:20480
	ds_read_b128 v[208:211], v151 offset:21504
	ds_read_b128 v[212:215], v151 offset:22528
	ds_read_b128 v[216:219], v151 offset:23552
	global_load_lds_dwordx4 v[144:145], off
	s_add_i32 m0, s18, 0x2000
	s_add_u32 s52, s56, 0xb0000
	v_lshl_add_u64 v[220:221], s[56:57], 0, v[134:135]
	s_addc_u32 s53, s57, 0
	s_add_i32 s18, s71, s62
	global_load_lds_dwordx4 v[220:221], off
	v_lshl_add_u64 v[222:223], s[52:53], 0, v[130:131]
	s_mov_b32 m0, s18
	v_lshl_add_u64 v[224:225], s[58:59], 0, v[132:133]
	global_load_lds_dwordx4 v[222:223], off
	v_lshl_add_u64 v[222:223], s[52:53], 0, v[134:135]
	s_add_i32 m0, s18, 0x2000
	s_nop 0
	global_load_lds_dwordx4 v[222:223], off
	v_lshl_add_u64 v[222:223], s[58:59], 0, v[128:129]
	s_mov_b32 m0, s63
	s_nop 0
	global_load_lds_dwordx4 v[222:223], off
	s_mov_b32 m0, s64
	s_nop 0
	global_load_lds_dwordx4 v[224:225], off
	s_waitcnt vmcnt(8)
	s_waitcnt lgkmcnt(0)
	s_barrier
	s_waitcnt lgkmcnt(0)
	v_mfma_f32_16x16x32_bf16 v[60:63], v[152:155], v[188:191], v[60:63]
	v_mfma_f32_16x16x32_bf16 v[60:63], v[156:159], v[192:195], v[60:63]
	v_mfma_f32_16x16x32_bf16 v[56:59], v[160:163], v[188:191], v[56:59]
	v_mfma_f32_16x16x32_bf16 v[56:59], v[164:167], v[192:195], v[56:59]
	v_mfma_f32_16x16x32_bf16 v[52:55], v[152:155], v[196:199], v[52:55]
	v_mfma_f32_16x16x32_bf16 v[52:55], v[156:159], v[200:203], v[52:55]
	v_mfma_f32_16x16x32_bf16 v[44:47], v[160:163], v[196:199], v[44:47]
	v_mfma_f32_16x16x32_bf16 v[44:47], v[164:167], v[200:203], v[44:47]
	s_setprio 1
	v_mfma_f32_16x16x32_bf16 v[36:39], v[152:155], v[204:207], v[36:39]
	v_mfma_f32_16x16x32_bf16 v[36:39], v[156:159], v[208:211], v[36:39]
	v_mfma_f32_16x16x32_bf16 v[28:31], v[160:163], v[204:207], v[28:31]
	v_mfma_f32_16x16x32_bf16 v[28:31], v[164:167], v[208:211], v[28:31]
	v_mfma_f32_16x16x32_bf16 v[20:23], v[152:155], v[212:215], v[20:23]
	v_mfma_f32_16x16x32_bf16 v[20:23], v[156:159], v[216:219], v[20:23]
	v_mfma_f32_16x16x32_bf16 v[12:15], v[160:163], v[212:215], v[12:15]
	v_mfma_f32_16x16x32_bf16 v[12:15], v[164:167], v[216:219], v[12:15]
	v_mfma_f32_16x16x32_bf16 v[48:51], v[168:171], v[188:191], v[48:51]
	v_mfma_f32_16x16x32_bf16 v[48:51], v[172:175], v[192:195], v[48:51]
	v_mfma_f32_16x16x32_bf16 v[40:43], v[176:179], v[188:191], v[40:43]
	v_mfma_f32_16x16x32_bf16 v[40:43], v[184:187], v[192:195], v[40:43]
	v_mfma_f32_16x16x32_bf16 v[32:35], v[168:171], v[196:199], v[32:35]
	v_mfma_f32_16x16x32_bf16 v[32:35], v[172:175], v[200:203], v[32:35]
	v_mfma_f32_16x16x32_bf16 v[24:27], v[176:179], v[196:199], v[24:27]
	v_mfma_f32_16x16x32_bf16 v[24:27], v[184:187], v[200:203], v[24:27]
	s_barrier
	v_mfma_f32_16x16x32_bf16 v[16:19], v[168:171], v[204:207], v[16:19]
	v_mfma_f32_16x16x32_bf16 v[16:19], v[172:175], v[208:211], v[16:19]
	v_mfma_f32_16x16x32_bf16 v[8:11], v[176:179], v[204:207], v[8:11]
	v_mfma_f32_16x16x32_bf16 v[8:11], v[184:187], v[208:211], v[8:11]
	v_mfma_f32_16x16x32_bf16 v[4:7], v[168:171], v[212:215], v[4:7]
	v_mfma_f32_16x16x32_bf16 v[4:7], v[172:175], v[216:219], v[4:7]
	v_mfma_f32_16x16x32_bf16 v[0:3], v[176:179], v[212:215], v[0:3]
	v_mfma_f32_16x16x32_bf16 v[0:3], v[184:187], v[216:219], v[0:3]
	s_setprio 0
.Lmid_gemm1:
	s_add_i32 s18, 0, 0x18000
	s_add_i32 s19, 0, 0x1c000
	v_add_u32_e32 v164, s18, v147
	v_add_u32_e32 v181, s19, v147
	ds_read_b128 v[152:155], v164
	ds_read_b128 v[156:159], v164 offset:1024
	ds_read_b128 v[160:163], v164 offset:2048
	ds_read_b128 v[164:167], v164 offset:3072
	ds_read_b128 v[168:171], v181
	ds_read_b128 v[172:175], v181 offset:1024
	ds_read_b128 v[176:179], v181 offset:2048
	ds_read_b128 v[184:187], v181 offset:3072
	s_add_u32 s52, s58, 0xb0000
	s_addc_u32 s53, s59, 0
	s_mov_b32 m0, s65
	v_lshl_add_u64 v[226:227], s[52:53], 0, v[128:129]
	ds_read_b128 v[188:191], v151 offset:32768
	ds_read_b128 v[192:195], v151 offset:33792
	ds_read_b128 v[196:199], v151 offset:34816
	ds_read_b128 v[200:203], v151 offset:35840
	ds_read_b128 v[204:207], v151 offset:36864
	ds_read_b128 v[208:211], v151 offset:37888
	ds_read_b128 v[212:215], v151 offset:38912
	ds_read_b128 v[216:219], v151 offset:39936
	global_load_lds_dwordx4 v[226:227], off
	v_lshl_add_u64 v[226:227], s[52:53], 0, v[132:133]
	s_mov_b32 m0, s66
	s_nop 0
	global_load_lds_dwordx4 v[226:227], off
	s_waitcnt vmcnt(8)
	s_waitcnt lgkmcnt(0)
	s_barrier
	s_waitcnt lgkmcnt(0)
	v_mfma_f32_16x16x32_bf16 v[124:127], v[152:155], v[188:191], v[124:127]
	v_mfma_f32_16x16x32_bf16 v[124:127], v[156:159], v[192:195], v[124:127]
	v_mfma_f32_16x16x32_bf16 v[120:123], v[160:163], v[188:191], v[120:123]
	v_mfma_f32_16x16x32_bf16 v[120:123], v[164:167], v[192:195], v[120:123]
	v_mfma_f32_16x16x32_bf16 v[116:119], v[152:155], v[196:199], v[116:119]
	v_mfma_f32_16x16x32_bf16 v[116:119], v[156:159], v[200:203], v[116:119]
	v_mfma_f32_16x16x32_bf16 v[108:111], v[160:163], v[196:199], v[108:111]
	v_mfma_f32_16x16x32_bf16 v[108:111], v[164:167], v[200:203], v[108:111]
	s_setprio 1
	v_mfma_f32_16x16x32_bf16 v[100:103], v[152:155], v[204:207], v[100:103]
	v_mfma_f32_16x16x32_bf16 v[100:103], v[156:159], v[208:211], v[100:103]
	v_mfma_f32_16x16x32_bf16 v[92:95], v[160:163], v[204:207], v[92:95]
	v_mfma_f32_16x16x32_bf16 v[92:95], v[164:167], v[208:211], v[92:95]
	v_mfma_f32_16x16x32_bf16 v[84:87], v[152:155], v[212:215], v[84:87]
	v_mfma_f32_16x16x32_bf16 v[84:87], v[156:159], v[216:219], v[84:87]
	v_mfma_f32_16x16x32_bf16 v[76:79], v[160:163], v[212:215], v[76:79]
	v_mfma_f32_16x16x32_bf16 v[76:79], v[164:167], v[216:219], v[76:79]
	v_mfma_f32_16x16x32_bf16 v[112:115], v[168:171], v[188:191], v[112:115]
	v_mfma_f32_16x16x32_bf16 v[112:115], v[172:175], v[192:195], v[112:115]
	v_mfma_f32_16x16x32_bf16 v[104:107], v[176:179], v[188:191], v[104:107]
	v_mfma_f32_16x16x32_bf16 v[104:107], v[184:187], v[192:195], v[104:107]
	v_mfma_f32_16x16x32_bf16 v[96:99], v[168:171], v[196:199], v[96:99]
	v_mfma_f32_16x16x32_bf16 v[96:99], v[172:175], v[200:203], v[96:99]
	v_mfma_f32_16x16x32_bf16 v[88:91], v[176:179], v[196:199], v[88:91]
	v_mfma_f32_16x16x32_bf16 v[88:91], v[184:187], v[200:203], v[88:91]
	s_barrier
	v_mfma_f32_16x16x32_bf16 v[80:83], v[168:171], v[204:207], v[80:83]
	v_mfma_f32_16x16x32_bf16 v[80:83], v[172:175], v[208:211], v[80:83]
	v_mfma_f32_16x16x32_bf16 v[72:75], v[176:179], v[204:207], v[72:75]
	v_mfma_f32_16x16x32_bf16 v[72:75], v[184:187], v[208:211], v[72:75]
	v_mfma_f32_16x16x32_bf16 v[68:71], v[168:171], v[212:215], v[68:71]
	v_mfma_f32_16x16x32_bf16 v[68:71], v[172:175], v[216:219], v[68:71]
	v_mfma_f32_16x16x32_bf16 v[64:67], v[176:179], v[212:215], v[64:67]
	v_mfma_f32_16x16x32_bf16 v[64:67], v[184:187], v[216:219], v[64:67]
	s_setprio 0
	s_add_i32 s18, s18, s62
	v_lshl_add_u64 v[144:145], v[144:145], 0, s[8:9]
	s_mov_b32 m0, s18
	ds_read_b128 v[188:191], v151 offset:49152
	ds_read_b128 v[192:195], v151 offset:50176
	ds_read_b128 v[196:199], v151 offset:51200
	ds_read_b128 v[200:203], v151 offset:52224
	ds_read_b128 v[204:207], v151 offset:53248
	ds_read_b128 v[208:211], v151 offset:54272
	ds_read_b128 v[212:215], v151 offset:55296
	ds_read_b128 v[216:219], v151 offset:56320
	global_load_lds_dwordx4 v[144:145], off
	s_add_i32 m0, s18, 0x2000
	s_add_u32 s52, s56, 0xb0080
	v_lshl_add_u64 v[144:145], v[220:221], 0, s[8:9]
	s_addc_u32 s53, s57, 0
	s_add_i32 s18, s19, s62
	global_load_lds_dwordx4 v[144:145], off
	v_lshl_add_u64 v[144:145], s[52:53], 0, v[130:131]
	s_mov_b32 m0, s18
	s_nop 0
	global_load_lds_dwordx4 v[144:145], off
	v_lshl_add_u64 v[144:145], s[52:53], 0, v[134:135]
	s_add_i32 m0, s18, 0x2000
	s_nop 0
	global_load_lds_dwordx4 v[144:145], off
	v_lshl_add_u64 v[144:145], v[222:223], 0, s[8:9]
	s_mov_b32 m0, s68
	s_nop 0
	global_load_lds_dwordx4 v[144:145], off
	v_lshl_add_u64 v[144:145], v[224:225], 0, s[8:9]
	s_mov_b32 m0, s69
	s_nop 0
	global_load_lds_dwordx4 v[144:145], off
	s_waitcnt vmcnt(8)
	s_waitcnt lgkmcnt(0)
	s_barrier
	s_waitcnt lgkmcnt(0)
	v_mfma_f32_16x16x32_bf16 v[60:63], v[152:155], v[188:191], v[60:63]
	v_mfma_f32_16x16x32_bf16 v[60:63], v[156:159], v[192:195], v[60:63]
	v_mfma_f32_16x16x32_bf16 v[56:59], v[160:163], v[188:191], v[56:59]
	v_mfma_f32_16x16x32_bf16 v[56:59], v[164:167], v[192:195], v[56:59]
	v_mfma_f32_16x16x32_bf16 v[52:55], v[152:155], v[196:199], v[52:55]
	v_mfma_f32_16x16x32_bf16 v[52:55], v[156:159], v[200:203], v[52:55]
	v_mfma_f32_16x16x32_bf16 v[44:47], v[160:163], v[196:199], v[44:47]
	v_mfma_f32_16x16x32_bf16 v[44:47], v[164:167], v[200:203], v[44:47]
	s_setprio 1
	v_mfma_f32_16x16x32_bf16 v[36:39], v[152:155], v[204:207], v[36:39]
	v_mfma_f32_16x16x32_bf16 v[36:39], v[156:159], v[208:211], v[36:39]
	v_mfma_f32_16x16x32_bf16 v[28:31], v[160:163], v[204:207], v[28:31]
	v_mfma_f32_16x16x32_bf16 v[28:31], v[164:167], v[208:211], v[28:31]
	v_mfma_f32_16x16x32_bf16 v[20:23], v[152:155], v[212:215], v[20:23]
	v_mfma_f32_16x16x32_bf16 v[20:23], v[156:159], v[216:219], v[20:23]
	v_mfma_f32_16x16x32_bf16 v[12:15], v[160:163], v[212:215], v[12:15]
	v_mfma_f32_16x16x32_bf16 v[12:15], v[164:167], v[216:219], v[12:15]
	v_mfma_f32_16x16x32_bf16 v[48:51], v[168:171], v[188:191], v[48:51]
	v_mfma_f32_16x16x32_bf16 v[48:51], v[172:175], v[192:195], v[48:51]
	v_mfma_f32_16x16x32_bf16 v[40:43], v[176:179], v[188:191], v[40:43]
	v_mfma_f32_16x16x32_bf16 v[40:43], v[184:187], v[192:195], v[40:43]
	v_mfma_f32_16x16x32_bf16 v[32:35], v[168:171], v[196:199], v[32:35]
	v_mfma_f32_16x16x32_bf16 v[32:35], v[172:175], v[200:203], v[32:35]
	v_mfma_f32_16x16x32_bf16 v[24:27], v[176:179], v[196:199], v[24:27]
	v_mfma_f32_16x16x32_bf16 v[24:27], v[184:187], v[200:203], v[24:27]
	s_barrier
	v_mfma_f32_16x16x32_bf16 v[16:19], v[168:171], v[204:207], v[16:19]
	v_mfma_f32_16x16x32_bf16 v[16:19], v[172:175], v[208:211], v[16:19]
	v_mfma_f32_16x16x32_bf16 v[8:11], v[176:179], v[204:207], v[8:11]
	v_mfma_f32_16x16x32_bf16 v[8:11], v[184:187], v[208:211], v[8:11]
	v_mfma_f32_16x16x32_bf16 v[4:7], v[168:171], v[212:215], v[4:7]
	v_mfma_f32_16x16x32_bf16 v[4:7], v[172:175], v[216:219], v[4:7]
	v_mfma_f32_16x16x32_bf16 v[0:3], v[176:179], v[212:215], v[0:3]
	v_mfma_f32_16x16x32_bf16 v[0:3], v[184:187], v[216:219], v[0:3]
	s_setprio 0
	s_add_i32 s86, s86, 2
	s_add_u32 s84, s84, 0x100
	s_addc_u32 s85, s85, 0
	s_cmp_gt_u32 s86, 41
	s_mov_b64 s[52:53], s[54:55]
	s_cbranch_scc0 .LBB0_264
	s_and_b64 vcc, exec, s[10:11]
	s_cbranch_vccz .LBB0_267
	s_barrier

.LBB0_386:
	s_ashr_i32 s49, s48, 31
	s_lshl_b64 s[52:53], s[48:49], 19
	s_add_u32 s52, s80, s52
	s_addc_u32 s53, s81, s53
	s_and_b64 s[54:55], s[4:5], exec
	s_cselect_b32 s49, s53, s59
	s_cselect_b32 s82, s52, s58
	s_ashr_i32 s47, s46, 31
	s_lshl_b64 s[54:55], s[46:47], 19
	s_add_u32 s54, s64, s54
	s_addc_u32 s55, s65, s55
	s_and_b64 s[62:63], s[4:5], exec
	s_cselect_b32 s47, s55, s61
	s_cselect_b32 s83, s54, s60
	s_add_u32 s58, s58, 0x40080
	s_addc_u32 s59, s59, 0
	s_add_u32 s84, s60, 0x100
	s_addc_u32 s85, s61, 0
	s_mov_b32 s86, -2
	ds_read_b128 v[152:155], v148
	ds_read_b128 v[156:159], v148 offset:1024
	ds_read_b128 v[160:163], v148 offset:2048
	ds_read_b128 v[164:167], v148 offset:3072
	ds_read_b128 v[168:171], v149
	ds_read_b128 v[172:175], v149 offset:1024
	ds_read_b128 v[176:179], v149 offset:2048
	ds_read_b128 v[184:187], v149 offset:3072
	s_add_u32 s18, s58, 0xfffc0080
	s_addc_u32 s19, s59, -1
	s_cmp_eq_u32 s86, 12
	s_cselect_b32 s63, s49, s19
	s_cselect_b32 s62, s82, s18
	s_cselect_b32 s61, s47, s85
	s_cselect_b32 s60, s83, s84
	v_lshl_add_u64 v[220:221], s[58:59], 0, v[138:139]
	s_add_i32 m0, s68, 0xc000
	ds_read_b128 v[188:191], v150
	ds_read_b128 v[192:195], v150 offset:1024
	ds_read_b128 v[196:199], v150 offset:2048
	ds_read_b128 v[200:203], v150 offset:3072
	ds_read_b128 v[204:207], v150 offset:4096
	ds_read_b128 v[208:211], v150 offset:5120
	ds_read_b128 v[212:215], v150 offset:6144
	ds_read_b128 v[216:219], v150 offset:7168
	global_load_lds_dwordx4 v[220:221], off
	v_lshl_add_u64 v[220:221], s[58:59], 0, v[140:141]
	s_add_i32 m0, s68, 0xe000
	s_nop 0
	global_load_lds_dwordx4 v[220:221], off
	s_waitcnt vmcnt(8)
	s_waitcnt lgkmcnt(0)
	s_barrier
	s_waitcnt lgkmcnt(0)
	v_mfma_f32_16x16x32_bf16 v[124:127], v[152:155], v[188:191], 0
	v_mfma_f32_16x16x32_bf16 v[124:127], v[156:159], v[192:195], v[124:127]
	v_mfma_f32_16x16x32_bf16 v[120:123], v[160:163], v[188:191], 0
	v_mfma_f32_16x16x32_bf16 v[120:123], v[164:167], v[192:195], v[120:123]
	v_mfma_f32_16x16x32_bf16 v[116:119], v[152:155], v[196:199], 0
	v_mfma_f32_16x16x32_bf16 v[116:119], v[156:159], v[200:203], v[116:119]
	v_mfma_f32_16x16x32_bf16 v[112:115], v[160:163], v[196:199], 0
	v_mfma_f32_16x16x32_bf16 v[112:115], v[164:167], v[200:203], v[112:115]
	s_setprio 1
	v_mfma_f32_16x16x32_bf16 v[108:111], v[152:155], v[204:207], 0
	v_mfma_f32_16x16x32_bf16 v[108:111], v[156:159], v[208:211], v[108:111]
	v_mfma_f32_16x16x32_bf16 v[104:107], v[160:163], v[204:207], 0
	v_mfma_f32_16x16x32_bf16 v[104:107], v[164:167], v[208:211], v[104:107]
	v_mfma_f32_16x16x32_bf16 v[100:103], v[152:155], v[212:215], 0
	v_mfma_f32_16x16x32_bf16 v[100:103], v[156:159], v[216:219], v[100:103]
	v_mfma_f32_16x16x32_bf16 v[96:99], v[160:163], v[212:215], 0
	v_mfma_f32_16x16x32_bf16 v[96:99], v[164:167], v[216:219], v[96:99]
	v_mfma_f32_16x16x32_bf16 v[68:71], v[168:171], v[188:191], 0
	v_mfma_f32_16x16x32_bf16 v[68:71], v[172:175], v[192:195], v[68:71]
	v_mfma_f32_16x16x32_bf16 v[64:67], v[176:179], v[188:191], 0
	v_mfma_f32_16x16x32_bf16 v[64:67], v[184:187], v[192:195], v[64:67]
	v_mfma_f32_16x16x32_bf16 v[52:55], v[168:171], v[196:199], 0
	v_mfma_f32_16x16x32_bf16 v[52:55], v[172:175], v[200:203], v[52:55]
	v_mfma_f32_16x16x32_bf16 v[48:51], v[176:179], v[196:199], 0
	v_mfma_f32_16x16x32_bf16 v[48:51], v[184:187], v[200:203], v[48:51]
	s_barrier
	v_mfma_f32_16x16x32_bf16 v[44:47], v[168:171], v[204:207], 0
	v_mfma_f32_16x16x32_bf16 v[44:47], v[172:175], v[208:211], v[44:47]
	v_mfma_f32_16x16x32_bf16 v[40:43], v[176:179], v[204:207], 0
	v_mfma_f32_16x16x32_bf16 v[40:43], v[184:187], v[208:211], v[40:43]
	v_mfma_f32_16x16x32_bf16 v[36:39], v[168:171], v[212:215], 0
	v_mfma_f32_16x16x32_bf16 v[36:39], v[172:175], v[216:219], v[36:39]
	v_mfma_f32_16x16x32_bf16 v[32:35], v[176:179], v[212:215], 0
	v_mfma_f32_16x16x32_bf16 v[32:35], v[184:187], v[216:219], v[32:35]
	s_setprio 0
	s_add_i32 s18, s76, s66
	v_lshl_add_u64 v[220:221], s[60:61], 0, v[132:133]
	s_mov_b32 m0, s18
	ds_read_b128 v[188:191], v150 offset:16384
	ds_read_b128 v[192:195], v150 offset:17408
	ds_read_b128 v[196:199], v150 offset:18432
	ds_read_b128 v[200:203], v150 offset:19456
	ds_read_b128 v[204:207], v150 offset:20480
	ds_read_b128 v[208:211], v150 offset:21504
	ds_read_b128 v[212:215], v150 offset:22528
	ds_read_b128 v[216:219], v150 offset:23552
	global_load_lds_dwordx4 v[220:221], off
	s_add_i32 m0, s18, 0x2000
	s_add_u32 s88, s60, 0x40000
	v_lshl_add_u64 v[222:223], s[60:61], 0, v[128:129]
	s_addc_u32 s89, s61, 0
	s_add_i32 s18, s77, s66
	global_load_lds_dwordx4 v[222:223], off
	v_lshl_add_u64 v[224:225], s[88:89], 0, v[132:133]
	s_mov_b32 m0, s18
	v_lshl_add_u64 v[226:227], s[62:63], 0, v[130:131]
	global_load_lds_dwordx4 v[224:225], off
	v_lshl_add_u64 v[224:225], s[88:89], 0, v[128:129]
	s_add_i32 m0, s18, 0x2000
	s_nop 0
	global_load_lds_dwordx4 v[224:225], off
	v_lshl_add_u64 v[224:225], s[62:63], 0, v[134:135]
	s_mov_b32 m0, s68
	s_nop 0
	global_load_lds_dwordx4 v[224:225], off
	s_mov_b32 m0, s69
	s_nop 0
	global_load_lds_dwordx4 v[226:227], off
	s_waitcnt vmcnt(8)
	s_waitcnt lgkmcnt(0)
	s_barrier
	s_waitcnt lgkmcnt(0)
	v_mfma_f32_16x16x32_bf16 v[92:95], v[152:155], v[188:191], 0
	v_mfma_f32_16x16x32_bf16 v[92:95], v[156:159], v[192:195], v[92:95]
	v_mfma_f32_16x16x32_bf16 v[88:91], v[160:163], v[188:191], 0
	v_mfma_f32_16x16x32_bf16 v[88:91], v[164:167], v[192:195], v[88:91]
	v_mfma_f32_16x16x32_bf16 v[84:87], v[152:155], v[196:199], 0
	v_mfma_f32_16x16x32_bf16 v[84:87], v[156:159], v[200:203], v[84:87]
	v_mfma_f32_16x16x32_bf16 v[80:83], v[160:163], v[196:199], 0
	v_mfma_f32_16x16x32_bf16 v[80:83], v[164:167], v[200:203], v[80:83]
	s_setprio 1
	v_mfma_f32_16x16x32_bf16 v[76:79], v[152:155], v[204:207], 0
	v_mfma_f32_16x16x32_bf16 v[76:79], v[156:159], v[208:211], v[76:79]
	v_mfma_f32_16x16x32_bf16 v[72:75], v[160:163], v[204:207], 0
	v_mfma_f32_16x16x32_bf16 v[72:75], v[164:167], v[208:211], v[72:75]
	v_mfma_f32_16x16x32_bf16 v[60:63], v[152:155], v[212:215], 0
	v_mfma_f32_16x16x32_bf16 v[60:63], v[156:159], v[216:219], v[60:63]
	v_mfma_f32_16x16x32_bf16 v[56:59], v[160:163], v[212:215], 0
	v_mfma_f32_16x16x32_bf16 v[56:59], v[164:167], v[216:219], v[56:59]
	v_mfma_f32_16x16x32_bf16 v[28:31], v[168:171], v[188:191], 0
	v_mfma_f32_16x16x32_bf16 v[28:31], v[172:175], v[192:195], v[28:31]
	v_mfma_f32_16x16x32_bf16 v[24:27], v[176:179], v[188:191], 0
	v_mfma_f32_16x16x32_bf16 v[24:27], v[184:187], v[192:195], v[24:27]
	v_mfma_f32_16x16x32_bf16 v[20:23], v[168:171], v[196:199], 0
	v_mfma_f32_16x16x32_bf16 v[20:23], v[172:175], v[200:203], v[20:23]
	v_mfma_f32_16x16x32_bf16 v[16:19], v[176:179], v[196:199], 0
	v_mfma_f32_16x16x32_bf16 v[16:19], v[184:187], v[200:203], v[16:19]
	s_barrier
	v_mfma_f32_16x16x32_bf16 v[12:15], v[168:171], v[204:207], 0
	v_mfma_f32_16x16x32_bf16 v[12:15], v[172:175], v[208:211], v[12:15]
	v_mfma_f32_16x16x32_bf16 v[8:11], v[176:179], v[204:207], 0
	v_mfma_f32_16x16x32_bf16 v[8:11], v[184:187], v[208:211], v[8:11]
	v_mfma_f32_16x16x32_bf16 v[4:7], v[168:171], v[212:215], 0
	v_mfma_f32_16x16x32_bf16 v[4:7], v[172:175], v[216:219], v[4:7]
	v_mfma_f32_16x16x32_bf16 v[0:3], v[176:179], v[212:215], 0
	v_mfma_f32_16x16x32_bf16 v[0:3], v[184:187], v[216:219], v[0:3]
	s_setprio 0
	s_branch .Lmid_gemm2
.LBB0_387:
	ds_read_b128 v[152:155], v148
	ds_read_b128 v[156:159], v148 offset:1024
	ds_read_b128 v[160:163], v148 offset:2048
	ds_read_b128 v[164:167], v148 offset:3072
	ds_read_b128 v[168:171], v149
	ds_read_b128 v[172:175], v149 offset:1024
	ds_read_b128 v[176:179], v149 offset:2048
	ds_read_b128 v[184:187], v149 offset:3072
	s_add_u32 s18, s58, 0xfffc0080
	s_addc_u32 s19, s59, -1
	s_cmp_eq_u32 s86, 12
	s_cselect_b32 s63, s49, s19
	s_cselect_b32 s62, s82, s18
	s_cselect_b32 s61, s47, s85
	s_cselect_b32 s60, s83, s84
	v_lshl_add_u64 v[220:221], s[58:59], 0, v[138:139]
	s_add_i32 m0, s68, 0xc000
	ds_read_b128 v[188:191], v150
	ds_read_b128 v[192:195], v150 offset:1024
	ds_read_b128 v[196:199], v150 offset:2048
	ds_read_b128 v[200:203], v150 offset:3072
	ds_read_b128 v[204:207], v150 offset:4096
	ds_read_b128 v[208:211], v150 offset:5120
	ds_read_b128 v[212:215], v150 offset:6144
	ds_read_b128 v[216:219], v150 offset:7168
	global_load_lds_dwordx4 v[220:221], off
	v_lshl_add_u64 v[220:221], s[58:59], 0, v[140:141]
	s_add_i32 m0, s68, 0xe000
	s_nop 0
	global_load_lds_dwordx4 v[220:221], off
	s_waitcnt vmcnt(8)
	s_waitcnt lgkmcnt(0)
	s_barrier
	s_waitcnt lgkmcnt(0)
	v_mfma_f32_16x16x32_bf16 v[124:127], v[152:155], v[188:191], v[124:127]
	v_mfma_f32_16x16x32_bf16 v[124:127], v[156:159], v[192:195], v[124:127]
	v_mfma_f32_16x16x32_bf16 v[120:123], v[160:163], v[188:191], v[120:123]
	v_mfma_f32_16x16x32_bf16 v[120:123], v[164:167], v[192:195], v[120:123]
	v_mfma_f32_16x16x32_bf16 v[116:119], v[152:155], v[196:199], v[116:119]
	v_mfma_f32_16x16x32_bf16 v[116:119], v[156:159], v[200:203], v[116:119]
	v_mfma_f32_16x16x32_bf16 v[112:115], v[160:163], v[196:199], v[112:115]
	v_mfma_f32_16x16x32_bf16 v[112:115], v[164:167], v[200:203], v[112:115]
	s_setprio 1
	v_mfma_f32_16x16x32_bf16 v[108:111], v[152:155], v[204:207], v[108:111]
	v_mfma_f32_16x16x32_bf16 v[108:111], v[156:159], v[208:211], v[108:111]
	v_mfma_f32_16x16x32_bf16 v[104:107], v[160:163], v[204:207], v[104:107]
	v_mfma_f32_16x16x32_bf16 v[104:107], v[164:167], v[208:211], v[104:107]
	v_mfma_f32_16x16x32_bf16 v[100:103], v[152:155], v[212:215], v[100:103]
	v_mfma_f32_16x16x32_bf16 v[100:103], v[156:159], v[216:219], v[100:103]
	v_mfma_f32_16x16x32_bf16 v[96:99], v[160:163], v[212:215], v[96:99]
	v_mfma_f32_16x16x32_bf16 v[96:99], v[164:167], v[216:219], v[96:99]
	v_mfma_f32_16x16x32_bf16 v[68:71], v[168:171], v[188:191], v[68:71]
	v_mfma_f32_16x16x32_bf16 v[68:71], v[172:175], v[192:195], v[68:71]
	v_mfma_f32_16x16x32_bf16 v[64:67], v[176:179], v[188:191], v[64:67]
	v_mfma_f32_16x16x32_bf16 v[64:67], v[184:187], v[192:195], v[64:67]
	v_mfma_f32_16x16x32_bf16 v[52:55], v[168:171], v[196:199], v[52:55]
	v_mfma_f32_16x16x32_bf16 v[52:55], v[172:175], v[200:203], v[52:55]
	v_mfma_f32_16x16x32_bf16 v[48:51], v[176:179], v[196:199], v[48:51]
	v_mfma_f32_16x16x32_bf16 v[48:51], v[184:187], v[200:203], v[48:51]
	s_barrier
	v_mfma_f32_16x16x32_bf16 v[44:47], v[168:171], v[204:207], v[44:47]
	v_mfma_f32_16x16x32_bf16 v[44:47], v[172:175], v[208:211], v[44:47]
	v_mfma_f32_16x16x32_bf16 v[40:43], v[176:179], v[204:207], v[40:43]
	v_mfma_f32_16x16x32_bf16 v[40:43], v[184:187], v[208:211], v[40:43]
	v_mfma_f32_16x16x32_bf16 v[36:39], v[168:171], v[212:215], v[36:39]
	v_mfma_f32_16x16x32_bf16 v[36:39], v[172:175], v[216:219], v[36:39]
	v_mfma_f32_16x16x32_bf16 v[32:35], v[176:179], v[212:215], v[32:35]
	v_mfma_f32_16x16x32_bf16 v[32:35], v[184:187], v[216:219], v[32:35]
	s_setprio 0
	s_add_i32 s18, s76, s66
	v_lshl_add_u64 v[220:221], s[60:61], 0, v[132:133]
	s_mov_b32 m0, s18
	ds_read_b128 v[188:191], v150 offset:16384
	ds_read_b128 v[192:195], v150 offset:17408
	ds_read_b128 v[196:199], v150 offset:18432
	ds_read_b128 v[200:203], v150 offset:19456
	ds_read_b128 v[204:207], v150 offset:20480
	ds_read_b128 v[208:211], v150 offset:21504
	ds_read_b128 v[212:215], v150 offset:22528
	ds_read_b128 v[216:219], v150 offset:23552
	global_load_lds_dwordx4 v[220:221], off
	s_add_i32 m0, s18, 0x2000
	s_add_u32 s88, s60, 0x40000
	v_lshl_add_u64 v[222:223], s[60:61], 0, v[128:129]
	s_addc_u32 s89, s61, 0
	s_add_i32 s18, s77, s66
	global_load_lds_dwordx4 v[222:223], off
	v_lshl_add_u64 v[224:225], s[88:89], 0, v[132:133]
	s_mov_b32 m0, s18
	v_lshl_add_u64 v[226:227], s[62:63], 0, v[130:131]
	global_load_lds_dwordx4 v[224:225], off
	v_lshl_add_u64 v[224:225], s[88:89], 0, v[128:129]
	s_add_i32 m0, s18, 0x2000
	s_nop 0
	global_load_lds_dwordx4 v[224:225], off
	v_lshl_add_u64 v[224:225], s[62:63], 0, v[134:135]
	s_mov_b32 m0, s68
	s_nop 0
	global_load_lds_dwordx4 v[224:225], off
	s_mov_b32 m0, s69
	s_nop 0
	global_load_lds_dwordx4 v[226:227], off
	s_waitcnt vmcnt(8)
	s_waitcnt lgkmcnt(0)
	s_barrier
	s_waitcnt lgkmcnt(0)
	v_mfma_f32_16x16x32_bf16 v[92:95], v[152:155], v[188:191], v[92:95]
	v_mfma_f32_16x16x32_bf16 v[92:95], v[156:159], v[192:195], v[92:95]
	v_mfma_f32_16x16x32_bf16 v[88:91], v[160:163], v[188:191], v[88:91]
	v_mfma_f32_16x16x32_bf16 v[88:91], v[164:167], v[192:195], v[88:91]
	v_mfma_f32_16x16x32_bf16 v[84:87], v[152:155], v[196:199], v[84:87]
	v_mfma_f32_16x16x32_bf16 v[84:87], v[156:159], v[200:203], v[84:87]
	v_mfma_f32_16x16x32_bf16 v[80:83], v[160:163], v[196:199], v[80:83]
	v_mfma_f32_16x16x32_bf16 v[80:83], v[164:167], v[200:203], v[80:83]
	s_setprio 1
	v_mfma_f32_16x16x32_bf16 v[76:79], v[152:155], v[204:207], v[76:79]
	v_mfma_f32_16x16x32_bf16 v[76:79], v[156:159], v[208:211], v[76:79]
	v_mfma_f32_16x16x32_bf16 v[72:75], v[160:163], v[204:207], v[72:75]
	v_mfma_f32_16x16x32_bf16 v[72:75], v[164:167], v[208:211], v[72:75]
	v_mfma_f32_16x16x32_bf16 v[60:63], v[152:155], v[212:215], v[60:63]
	v_mfma_f32_16x16x32_bf16 v[60:63], v[156:159], v[216:219], v[60:63]
	v_mfma_f32_16x16x32_bf16 v[56:59], v[160:163], v[212:215], v[56:59]
	v_mfma_f32_16x16x32_bf16 v[56:59], v[164:167], v[216:219], v[56:59]
	v_mfma_f32_16x16x32_bf16 v[28:31], v[168:171], v[188:191], v[28:31]
	v_mfma_f32_16x16x32_bf16 v[28:31], v[172:175], v[192:195], v[28:31]
	v_mfma_f32_16x16x32_bf16 v[24:27], v[176:179], v[188:191], v[24:27]
	v_mfma_f32_16x16x32_bf16 v[24:27], v[184:187], v[192:195], v[24:27]
	v_mfma_f32_16x16x32_bf16 v[20:23], v[168:171], v[196:199], v[20:23]
	v_mfma_f32_16x16x32_bf16 v[20:23], v[172:175], v[200:203], v[20:23]
	v_mfma_f32_16x16x32_bf16 v[16:19], v[176:179], v[196:199], v[16:19]
	v_mfma_f32_16x16x32_bf16 v[16:19], v[184:187], v[200:203], v[16:19]
	s_barrier
	v_mfma_f32_16x16x32_bf16 v[12:15], v[168:171], v[204:207], v[12:15]
	v_mfma_f32_16x16x32_bf16 v[12:15], v[172:175], v[208:211], v[12:15]
	v_mfma_f32_16x16x32_bf16 v[8:11], v[176:179], v[204:207], v[8:11]
	v_mfma_f32_16x16x32_bf16 v[8:11], v[184:187], v[208:211], v[8:11]
	v_mfma_f32_16x16x32_bf16 v[4:7], v[168:171], v[212:215], v[4:7]
	v_mfma_f32_16x16x32_bf16 v[4:7], v[172:175], v[216:219], v[4:7]
	v_mfma_f32_16x16x32_bf16 v[0:3], v[176:179], v[212:215], v[0:3]
	v_mfma_f32_16x16x32_bf16 v[0:3], v[184:187], v[216:219], v[0:3]
	s_setprio 0
.Lmid_gemm2:
	s_add_i32 s18, 0, 0x18000
	s_add_i32 s19, 0, 0x1c000
	v_add_u32_e32 v164, s18, v147
	v_add_u32_e32 v181, s19, v147
	ds_read_b128 v[152:155], v164
	ds_read_b128 v[156:159], v164 offset:1024
	ds_read_b128 v[160:163], v164 offset:2048
	ds_read_b128 v[164:167], v164 offset:3072
	ds_read_b128 v[168:171], v181
	ds_read_b128 v[172:175], v181 offset:1024
	ds_read_b128 v[176:179], v181 offset:2048
	ds_read_b128 v[184:187], v181 offset:3072
	s_add_u32 s62, s62, 0x40000
	s_addc_u32 s63, s63, 0
	s_mov_b32 m0, s70
	v_lshl_add_u64 v[228:229], s[62:63], 0, v[134:135]
	ds_read_b128 v[188:191], v150 offset:32768
	ds_read_b128 v[192:195], v150 offset:33792
	ds_read_b128 v[196:199], v150 offset:34816
	ds_read_b128 v[200:203], v150 offset:35840
	ds_read_b128 v[204:207], v150 offset:36864
	ds_read_b128 v[208:211], v150 offset:37888
	ds_read_b128 v[212:215], v150 offset:38912
	ds_read_b128 v[216:219], v150 offset:39936
	global_load_lds_dwordx4 v[228:229], off
	v_lshl_add_u64 v[228:229], s[62:63], 0, v[130:131]
	s_mov_b32 m0, s71
	s_nop 0
	global_load_lds_dwordx4 v[228:229], off
	s_waitcnt vmcnt(8)
	s_waitcnt lgkmcnt(0)
	s_barrier
	s_waitcnt lgkmcnt(0)
	v_mfma_f32_16x16x32_bf16 v[124:127], v[152:155], v[188:191], v[124:127]
	v_mfma_f32_16x16x32_bf16 v[124:127], v[156:159], v[192:195], v[124:127]
	v_mfma_f32_16x16x32_bf16 v[120:123], v[160:163], v[188:191], v[120:123]
	v_mfma_f32_16x16x32_bf16 v[120:123], v[164:167], v[192:195], v[120:123]
	v_mfma_f32_16x16x32_bf16 v[116:119], v[152:155], v[196:199], v[116:119]
	v_mfma_f32_16x16x32_bf16 v[116:119], v[156:159], v[200:203], v[116:119]
	v_mfma_f32_16x16x32_bf16 v[112:115], v[160:163], v[196:199], v[112:115]
	v_mfma_f32_16x16x32_bf16 v[112:115], v[164:167], v[200:203], v[112:115]
	s_setprio 1
	v_mfma_f32_16x16x32_bf16 v[108:111], v[152:155], v[204:207], v[108:111]
	v_mfma_f32_16x16x32_bf16 v[108:111], v[156:159], v[208:211], v[108:111]
	v_mfma_f32_16x16x32_bf16 v[104:107], v[160:163], v[204:207], v[104:107]
	v_mfma_f32_16x16x32_bf16 v[104:107], v[164:167], v[208:211], v[104:107]
	v_mfma_f32_16x16x32_bf16 v[100:103], v[152:155], v[212:215], v[100:103]
	v_mfma_f32_16x16x32_bf16 v[100:103], v[156:159], v[216:219], v[100:103]
	v_mfma_f32_16x16x32_bf16 v[96:99], v[160:163], v[212:215], v[96:99]
	v_mfma_f32_16x16x32_bf16 v[96:99], v[164:167], v[216:219], v[96:99]
	v_mfma_f32_16x16x32_bf16 v[68:71], v[168:171], v[188:191], v[68:71]
	v_mfma_f32_16x16x32_bf16 v[68:71], v[172:175], v[192:195], v[68:71]
	v_mfma_f32_16x16x32_bf16 v[64:67], v[176:179], v[188:191], v[64:67]
	v_mfma_f32_16x16x32_bf16 v[64:67], v[184:187], v[192:195], v[64:67]
	v_mfma_f32_16x16x32_bf16 v[52:55], v[168:171], v[196:199], v[52:55]
	v_mfma_f32_16x16x32_bf16 v[52:55], v[172:175], v[200:203], v[52:55]
	v_mfma_f32_16x16x32_bf16 v[48:51], v[176:179], v[196:199], v[48:51]
	v_mfma_f32_16x16x32_bf16 v[48:51], v[184:187], v[200:203], v[48:51]
	s_barrier
	v_mfma_f32_16x16x32_bf16 v[44:47], v[168:171], v[204:207], v[44:47]
	v_mfma_f32_16x16x32_bf16 v[44:47], v[172:175], v[208:211], v[44:47]
	v_mfma_f32_16x16x32_bf16 v[40:43], v[176:179], v[204:207], v[40:43]
	v_mfma_f32_16x16x32_bf16 v[40:43], v[184:187], v[208:211], v[40:43]
	v_mfma_f32_16x16x32_bf16 v[36:39], v[168:171], v[212:215], v[36:39]
	v_mfma_f32_16x16x32_bf16 v[36:39], v[172:175], v[216:219], v[36:39]
	v_mfma_f32_16x16x32_bf16 v[32:35], v[176:179], v[212:215], v[32:35]
	v_mfma_f32_16x16x32_bf16 v[32:35], v[184:187], v[216:219], v[32:35]
	s_setprio 0
	s_add_i32 s18, s18, s66
	v_lshl_add_u64 v[220:221], v[220:221], 0, s[6:7]
	s_mov_b32 m0, s18
	ds_read_b128 v[188:191], v150 offset:49152
	ds_read_b128 v[192:195], v150 offset:50176
	ds_read_b128 v[196:199], v150 offset:51200
	ds_read_b128 v[200:203], v150 offset:52224
	ds_read_b128 v[204:207], v150 offset:53248
	ds_read_b128 v[208:211], v150 offset:54272
	ds_read_b128 v[212:215], v150 offset:55296
	ds_read_b128 v[216:219], v150 offset:56320
	global_load_lds_dwordx4 v[220:221], off
	s_add_i32 m0, s18, 0x2000
	s_add_u32 s60, s60, 0x40080
	v_lshl_add_u64 v[220:221], v[222:223], 0, s[6:7]
	s_addc_u32 s61, s61, 0
	s_add_i32 s18, s19, s66
	global_load_lds_dwordx4 v[220:221], off
	v_lshl_add_u64 v[220:221], s[60:61], 0, v[132:133]
	s_mov_b32 m0, s18
	s_nop 0
	global_load_lds_dwordx4 v[220:221], off
	v_lshl_add_u64 v[220:221], s[60:61], 0, v[128:129]
	s_add_i32 m0, s18, 0x2000
	s_nop 0
	global_load_lds_dwordx4 v[220:221], off
	v_lshl_add_u64 v[220:221], v[224:225], 0, s[6:7]
	s_mov_b32 m0, s74
	s_nop 0
	global_load_lds_dwordx4 v[220:221], off
	v_lshl_add_u64 v[220:221], v[226:227], 0, s[6:7]
	s_mov_b32 m0, s75
	s_nop 0
	global_load_lds_dwordx4 v[220:221], off
	s_waitcnt vmcnt(8)
	s_waitcnt lgkmcnt(0)
	s_barrier
	s_waitcnt lgkmcnt(0)
	v_mfma_f32_16x16x32_bf16 v[92:95], v[152:155], v[188:191], v[92:95]
	v_mfma_f32_16x16x32_bf16 v[92:95], v[156:159], v[192:195], v[92:95]
	v_mfma_f32_16x16x32_bf16 v[88:91], v[160:163], v[188:191], v[88:91]
	v_mfma_f32_16x16x32_bf16 v[88:91], v[164:167], v[192:195], v[88:91]
	v_mfma_f32_16x16x32_bf16 v[84:87], v[152:155], v[196:199], v[84:87]
	v_mfma_f32_16x16x32_bf16 v[84:87], v[156:159], v[200:203], v[84:87]
	v_mfma_f32_16x16x32_bf16 v[80:83], v[160:163], v[196:199], v[80:83]
	v_mfma_f32_16x16x32_bf16 v[80:83], v[164:167], v[200:203], v[80:83]
	s_setprio 1
	v_mfma_f32_16x16x32_bf16 v[76:79], v[152:155], v[204:207], v[76:79]
	v_mfma_f32_16x16x32_bf16 v[76:79], v[156:159], v[208:211], v[76:79]
	v_mfma_f32_16x16x32_bf16 v[72:75], v[160:163], v[204:207], v[72:75]
	v_mfma_f32_16x16x32_bf16 v[72:75], v[164:167], v[208:211], v[72:75]
	v_mfma_f32_16x16x32_bf16 v[60:63], v[152:155], v[212:215], v[60:63]
	v_mfma_f32_16x16x32_bf16 v[60:63], v[156:159], v[216:219], v[60:63]
	v_mfma_f32_16x16x32_bf16 v[56:59], v[160:163], v[212:215], v[56:59]
	v_mfma_f32_16x16x32_bf16 v[56:59], v[164:167], v[216:219], v[56:59]
	v_mfma_f32_16x16x32_bf16 v[28:31], v[168:171], v[188:191], v[28:31]
	v_mfma_f32_16x16x32_bf16 v[28:31], v[172:175], v[192:195], v[28:31]
	v_mfma_f32_16x16x32_bf16 v[24:27], v[176:179], v[188:191], v[24:27]
	v_mfma_f32_16x16x32_bf16 v[24:27], v[184:187], v[192:195], v[24:27]
	v_mfma_f32_16x16x32_bf16 v[20:23], v[168:171], v[196:199], v[20:23]
	v_mfma_f32_16x16x32_bf16 v[20:23], v[172:175], v[200:203], v[20:23]
	v_mfma_f32_16x16x32_bf16 v[16:19], v[176:179], v[196:199], v[16:19]
	v_mfma_f32_16x16x32_bf16 v[16:19], v[184:187], v[200:203], v[16:19]
	s_barrier
	v_mfma_f32_16x16x32_bf16 v[12:15], v[168:171], v[204:207], v[12:15]
	v_mfma_f32_16x16x32_bf16 v[12:15], v[172:175], v[208:211], v[12:15]
	v_mfma_f32_16x16x32_bf16 v[8:11], v[176:179], v[204:207], v[8:11]
	v_mfma_f32_16x16x32_bf16 v[8:11], v[184:187], v[208:211], v[8:11]
	v_mfma_f32_16x16x32_bf16 v[4:7], v[168:171], v[212:215], v[4:7]
	v_mfma_f32_16x16x32_bf16 v[4:7], v[172:175], v[216:219], v[4:7]
	v_mfma_f32_16x16x32_bf16 v[0:3], v[176:179], v[212:215], v[0:3]
	v_mfma_f32_16x16x32_bf16 v[0:3], v[184:187], v[216:219], v[0:3]
	s_setprio 0
	s_add_i32 s86, s86, 2
	s_add_u32 s58, s58, 0x100
	s_addc_u32 s59, s59, 0
	s_add_u32 s84, s84, 0x100
	s_addc_u32 s85, s85, 0
	s_cmp_gt_u32 s86, 13
	s_cbranch_scc0 .LBB0_387
	s_and_b64 vcc, exec, s[8:9]
	s_cbranch_vccz .LBB0_390
	s_barrier

.LBB0_600:
	s_ashr_i32 s49, s48, 31
	s_lshl_b64 s[18:19], s[48:49], 19
	s_add_u32 s52, s38, s18
	s_addc_u32 s53, s39, s19
	s_and_b64 s[18:19], s[4:5], exec
	s_cselect_b32 s49, s53, s59
	s_cselect_b32 s84, s52, s58
	s_ashr_i32 s47, s46, 31
	s_lshl_b64 s[18:19], s[46:47], 19
	s_add_u32 s54, s64, s18
	s_addc_u32 s55, s65, s19
	s_and_b64 s[18:19], s[4:5], exec
	s_cselect_b32 s47, s55, s61
	s_cselect_b32 s85, s54, s60
	s_add_u32 s58, s58, 0x40080
	s_addc_u32 s59, s59, 0
	s_add_u32 s86, s60, 0x100
	s_addc_u32 s87, s61, 0
	s_mov_b32 s88, -2
	ds_read_b128 v[152:155], v149
	ds_read_b128 v[156:159], v149 offset:1024
	ds_read_b128 v[160:163], v149 offset:2048
	ds_read_b128 v[164:167], v149 offset:3072
	ds_read_b128 v[168:171], v150
	ds_read_b128 v[172:175], v150 offset:1024
	ds_read_b128 v[176:179], v150 offset:2048
	ds_read_b128 v[184:187], v150 offset:3072
	s_add_u32 s18, s58, 0xfffc0080
	s_addc_u32 s19, s59, -1
	s_cmp_eq_u32 s88, 12
	s_cselect_b32 s63, s49, s19
	s_cselect_b32 s62, s84, s18
	s_cselect_b32 s61, s47, s87
	s_cselect_b32 s60, s85, s86
	v_lshl_add_u64 v[144:145], s[58:59], 0, v[136:137]
	s_add_i32 m0, s57, 0xc000
	ds_read_b128 v[188:191], v151
	ds_read_b128 v[192:195], v151 offset:1024
	ds_read_b128 v[196:199], v151 offset:2048
	ds_read_b128 v[200:203], v151 offset:3072
	ds_read_b128 v[204:207], v151 offset:4096
	ds_read_b128 v[208:211], v151 offset:5120
	ds_read_b128 v[212:215], v151 offset:6144
	ds_read_b128 v[216:219], v151 offset:7168
	global_load_lds_dwordx4 v[144:145], off
	v_lshl_add_u64 v[144:145], s[58:59], 0, v[138:139]
	s_add_i32 m0, s57, 0xe000
	s_nop 0
	global_load_lds_dwordx4 v[144:145], off
	s_waitcnt vmcnt(8)
	s_waitcnt lgkmcnt(0)
	s_barrier
	s_waitcnt lgkmcnt(0)
	v_mfma_f32_16x16x32_bf16 v[124:127], v[152:155], v[188:191], 0
	v_mfma_f32_16x16x32_bf16 v[124:127], v[156:159], v[192:195], v[124:127]
	v_mfma_f32_16x16x32_bf16 v[120:123], v[160:163], v[188:191], 0
	v_mfma_f32_16x16x32_bf16 v[120:123], v[164:167], v[192:195], v[120:123]
	v_mfma_f32_16x16x32_bf16 v[116:119], v[152:155], v[196:199], 0
	v_mfma_f32_16x16x32_bf16 v[116:119], v[156:159], v[200:203], v[116:119]
	v_mfma_f32_16x16x32_bf16 v[108:111], v[160:163], v[196:199], 0
	v_mfma_f32_16x16x32_bf16 v[108:111], v[164:167], v[200:203], v[108:111]
	s_setprio 1
	v_mfma_f32_16x16x32_bf16 v[100:103], v[152:155], v[204:207], 0
	v_mfma_f32_16x16x32_bf16 v[100:103], v[156:159], v[208:211], v[100:103]
	v_mfma_f32_16x16x32_bf16 v[92:95], v[160:163], v[204:207], 0
	v_mfma_f32_16x16x32_bf16 v[92:95], v[164:167], v[208:211], v[92:95]
	v_mfma_f32_16x16x32_bf16 v[84:87], v[152:155], v[212:215], 0
	v_mfma_f32_16x16x32_bf16 v[84:87], v[156:159], v[216:219], v[84:87]
	v_mfma_f32_16x16x32_bf16 v[76:79], v[160:163], v[212:215], 0
	v_mfma_f32_16x16x32_bf16 v[76:79], v[164:167], v[216:219], v[76:79]
	v_mfma_f32_16x16x32_bf16 v[112:115], v[168:171], v[188:191], 0
	v_mfma_f32_16x16x32_bf16 v[112:115], v[172:175], v[192:195], v[112:115]
	v_mfma_f32_16x16x32_bf16 v[104:107], v[176:179], v[188:191], 0
	v_mfma_f32_16x16x32_bf16 v[104:107], v[184:187], v[192:195], v[104:107]
	v_mfma_f32_16x16x32_bf16 v[96:99], v[168:171], v[196:199], 0
	v_mfma_f32_16x16x32_bf16 v[96:99], v[172:175], v[200:203], v[96:99]
	v_mfma_f32_16x16x32_bf16 v[88:91], v[176:179], v[196:199], 0
	v_mfma_f32_16x16x32_bf16 v[88:91], v[184:187], v[200:203], v[88:91]
	s_barrier
	v_mfma_f32_16x16x32_bf16 v[80:83], v[168:171], v[204:207], 0
	v_mfma_f32_16x16x32_bf16 v[80:83], v[172:175], v[208:211], v[80:83]
	v_mfma_f32_16x16x32_bf16 v[72:75], v[176:179], v[204:207], 0
	v_mfma_f32_16x16x32_bf16 v[72:75], v[184:187], v[208:211], v[72:75]
	v_mfma_f32_16x16x32_bf16 v[68:71], v[168:171], v[212:215], 0
	v_mfma_f32_16x16x32_bf16 v[68:71], v[172:175], v[216:219], v[68:71]
	v_mfma_f32_16x16x32_bf16 v[64:67], v[176:179], v[212:215], 0
	v_mfma_f32_16x16x32_bf16 v[64:67], v[184:187], v[216:219], v[64:67]
	s_setprio 0
	s_add_i32 s18, s73, s66
	v_lshl_add_u64 v[144:145], s[60:61], 0, v[130:131]
	s_mov_b32 m0, s18
	ds_read_b128 v[188:191], v151 offset:16384
	ds_read_b128 v[192:195], v151 offset:17408
	ds_read_b128 v[196:199], v151 offset:18432
	ds_read_b128 v[200:203], v151 offset:19456
	ds_read_b128 v[204:207], v151 offset:20480
	ds_read_b128 v[208:211], v151 offset:21504
	ds_read_b128 v[212:215], v151 offset:22528
	ds_read_b128 v[216:219], v151 offset:23552
	global_load_lds_dwordx4 v[144:145], off
	s_add_i32 m0, s18, 0x2000
	s_add_u32 s18, s60, 0x40000
	v_lshl_add_u64 v[220:221], s[60:61], 0, v[134:135]
	s_addc_u32 s19, s61, 0
	s_add_i32 s79, s74, s66
	global_load_lds_dwordx4 v[220:221], off
	v_lshl_add_u64 v[222:223], s[18:19], 0, v[130:131]
	s_mov_b32 m0, s79
	v_lshl_add_u64 v[224:225], s[62:63], 0, v[132:133]
	global_load_lds_dwordx4 v[222:223], off
	v_lshl_add_u64 v[222:223], s[18:19], 0, v[134:135]
	s_add_i32 m0, s79, 0x2000
	s_nop 0
	global_load_lds_dwordx4 v[222:223], off
	v_lshl_add_u64 v[222:223], s[62:63], 0, v[128:129]
	s_mov_b32 m0, s57
	s_nop 0
	global_load_lds_dwordx4 v[222:223], off
	s_mov_b32 m0, s67
	s_nop 0
	global_load_lds_dwordx4 v[224:225], off
	s_waitcnt vmcnt(8)
	s_waitcnt lgkmcnt(0)
	s_barrier
	s_waitcnt lgkmcnt(0)
	v_mfma_f32_16x16x32_bf16 v[60:63], v[152:155], v[188:191], 0
	v_mfma_f32_16x16x32_bf16 v[60:63], v[156:159], v[192:195], v[60:63]
	v_mfma_f32_16x16x32_bf16 v[56:59], v[160:163], v[188:191], 0
	v_mfma_f32_16x16x32_bf16 v[56:59], v[164:167], v[192:195], v[56:59]
	v_mfma_f32_16x16x32_bf16 v[52:55], v[152:155], v[196:199], 0
	v_mfma_f32_16x16x32_bf16 v[52:55], v[156:159], v[200:203], v[52:55]
	v_mfma_f32_16x16x32_bf16 v[44:47], v[160:163], v[196:199], 0
	v_mfma_f32_16x16x32_bf16 v[44:47], v[164:167], v[200:203], v[44:47]
	s_setprio 1
	v_mfma_f32_16x16x32_bf16 v[36:39], v[152:155], v[204:207], 0
	v_mfma_f32_16x16x32_bf16 v[36:39], v[156:159], v[208:211], v[36:39]
	v_mfma_f32_16x16x32_bf16 v[28:31], v[160:163], v[204:207], 0
	v_mfma_f32_16x16x32_bf16 v[28:31], v[164:167], v[208:211], v[28:31]
	v_mfma_f32_16x16x32_bf16 v[20:23], v[152:155], v[212:215], 0
	v_mfma_f32_16x16x32_bf16 v[20:23], v[156:159], v[216:219], v[20:23]
	v_mfma_f32_16x16x32_bf16 v[12:15], v[160:163], v[212:215], 0
	v_mfma_f32_16x16x32_bf16 v[12:15], v[164:167], v[216:219], v[12:15]
	v_mfma_f32_16x16x32_bf16 v[48:51], v[168:171], v[188:191], 0
	v_mfma_f32_16x16x32_bf16 v[48:51], v[172:175], v[192:195], v[48:51]
	v_mfma_f32_16x16x32_bf16 v[40:43], v[176:179], v[188:191], 0
	v_mfma_f32_16x16x32_bf16 v[40:43], v[184:187], v[192:195], v[40:43]
	v_mfma_f32_16x16x32_bf16 v[32:35], v[168:171], v[196:199], 0
	v_mfma_f32_16x16x32_bf16 v[32:35], v[172:175], v[200:203], v[32:35]
	v_mfma_f32_16x16x32_bf16 v[24:27], v[176:179], v[196:199], 0
	v_mfma_f32_16x16x32_bf16 v[24:27], v[184:187], v[200:203], v[24:27]
	s_barrier
	v_mfma_f32_16x16x32_bf16 v[16:19], v[168:171], v[204:207], 0
	v_mfma_f32_16x16x32_bf16 v[16:19], v[172:175], v[208:211], v[16:19]
	v_mfma_f32_16x16x32_bf16 v[8:11], v[176:179], v[204:207], 0
	v_mfma_f32_16x16x32_bf16 v[8:11], v[184:187], v[208:211], v[8:11]
	v_mfma_f32_16x16x32_bf16 v[4:7], v[168:171], v[212:215], 0
	v_mfma_f32_16x16x32_bf16 v[4:7], v[172:175], v[216:219], v[4:7]
	v_mfma_f32_16x16x32_bf16 v[0:3], v[176:179], v[212:215], 0
	v_mfma_f32_16x16x32_bf16 v[0:3], v[184:187], v[216:219], v[0:3]
	s_setprio 0
	s_branch .Lmid_gemm3
.LBB0_601:
	ds_read_b128 v[152:155], v149
	ds_read_b128 v[156:159], v149 offset:1024
	ds_read_b128 v[160:163], v149 offset:2048
	ds_read_b128 v[164:167], v149 offset:3072
	ds_read_b128 v[168:171], v150
	ds_read_b128 v[172:175], v150 offset:1024
	ds_read_b128 v[176:179], v150 offset:2048
	ds_read_b128 v[184:187], v150 offset:3072
	s_add_u32 s18, s58, 0xfffc0080
	s_addc_u32 s19, s59, -1
	s_cmp_eq_u32 s88, 12
	s_cselect_b32 s63, s49, s19
	s_cselect_b32 s62, s84, s18
	s_cselect_b32 s61, s47, s87
	s_cselect_b32 s60, s85, s86
	v_lshl_add_u64 v[144:145], s[58:59], 0, v[136:137]
	s_add_i32 m0, s57, 0xc000
	ds_read_b128 v[188:191], v151
	ds_read_b128 v[192:195], v151 offset:1024
	ds_read_b128 v[196:199], v151 offset:2048
	ds_read_b128 v[200:203], v151 offset:3072
	ds_read_b128 v[204:207], v151 offset:4096
	ds_read_b128 v[208:211], v151 offset:5120
	ds_read_b128 v[212:215], v151 offset:6144
	ds_read_b128 v[216:219], v151 offset:7168
	global_load_lds_dwordx4 v[144:145], off
	v_lshl_add_u64 v[144:145], s[58:59], 0, v[138:139]
	s_add_i32 m0, s57, 0xe000
	s_nop 0
	global_load_lds_dwordx4 v[144:145], off
	s_waitcnt vmcnt(8)
	s_waitcnt lgkmcnt(0)
	s_barrier
	s_waitcnt lgkmcnt(0)
	v_mfma_f32_16x16x32_bf16 v[124:127], v[152:155], v[188:191], v[124:127]
	v_mfma_f32_16x16x32_bf16 v[124:127], v[156:159], v[192:195], v[124:127]
	v_mfma_f32_16x16x32_bf16 v[120:123], v[160:163], v[188:191], v[120:123]
	v_mfma_f32_16x16x32_bf16 v[120:123], v[164:167], v[192:195], v[120:123]
	v_mfma_f32_16x16x32_bf16 v[116:119], v[152:155], v[196:199], v[116:119]
	v_mfma_f32_16x16x32_bf16 v[116:119], v[156:159], v[200:203], v[116:119]
	v_mfma_f32_16x16x32_bf16 v[108:111], v[160:163], v[196:199], v[108:111]
	v_mfma_f32_16x16x32_bf16 v[108:111], v[164:167], v[200:203], v[108:111]
	s_setprio 1
	v_mfma_f32_16x16x32_bf16 v[100:103], v[152:155], v[204:207], v[100:103]
	v_mfma_f32_16x16x32_bf16 v[100:103], v[156:159], v[208:211], v[100:103]
	v_mfma_f32_16x16x32_bf16 v[92:95], v[160:163], v[204:207], v[92:95]
	v_mfma_f32_16x16x32_bf16 v[92:95], v[164:167], v[208:211], v[92:95]
	v_mfma_f32_16x16x32_bf16 v[84:87], v[152:155], v[212:215], v[84:87]
	v_mfma_f32_16x16x32_bf16 v[84:87], v[156:159], v[216:219], v[84:87]
	v_mfma_f32_16x16x32_bf16 v[76:79], v[160:163], v[212:215], v[76:79]
	v_mfma_f32_16x16x32_bf16 v[76:79], v[164:167], v[216:219], v[76:79]
	v_mfma_f32_16x16x32_bf16 v[112:115], v[168:171], v[188:191], v[112:115]
	v_mfma_f32_16x16x32_bf16 v[112:115], v[172:175], v[192:195], v[112:115]
	v_mfma_f32_16x16x32_bf16 v[104:107], v[176:179], v[188:191], v[104:107]
	v_mfma_f32_16x16x32_bf16 v[104:107], v[184:187], v[192:195], v[104:107]
	v_mfma_f32_16x16x32_bf16 v[96:99], v[168:171], v[196:199], v[96:99]
	v_mfma_f32_16x16x32_bf16 v[96:99], v[172:175], v[200:203], v[96:99]
	v_mfma_f32_16x16x32_bf16 v[88:91], v[176:179], v[196:199], v[88:91]
	v_mfma_f32_16x16x32_bf16 v[88:91], v[184:187], v[200:203], v[88:91]
	s_barrier
	v_mfma_f32_16x16x32_bf16 v[80:83], v[168:171], v[204:207], v[80:83]
	v_mfma_f32_16x16x32_bf16 v[80:83], v[172:175], v[208:211], v[80:83]
	v_mfma_f32_16x16x32_bf16 v[72:75], v[176:179], v[204:207], v[72:75]
	v_mfma_f32_16x16x32_bf16 v[72:75], v[184:187], v[208:211], v[72:75]
	v_mfma_f32_16x16x32_bf16 v[68:71], v[168:171], v[212:215], v[68:71]
	v_mfma_f32_16x16x32_bf16 v[68:71], v[172:175], v[216:219], v[68:71]
	v_mfma_f32_16x16x32_bf16 v[64:67], v[176:179], v[212:215], v[64:67]
	v_mfma_f32_16x16x32_bf16 v[64:67], v[184:187], v[216:219], v[64:67]
	s_setprio 0
	s_add_i32 s18, s73, s66
	v_lshl_add_u64 v[144:145], s[60:61], 0, v[130:131]
	s_mov_b32 m0, s18
	ds_read_b128 v[188:191], v151 offset:16384
	ds_read_b128 v[192:195], v151 offset:17408
	ds_read_b128 v[196:199], v151 offset:18432
	ds_read_b128 v[200:203], v151 offset:19456
	ds_read_b128 v[204:207], v151 offset:20480
	ds_read_b128 v[208:211], v151 offset:21504
	ds_read_b128 v[212:215], v151 offset:22528
	ds_read_b128 v[216:219], v151 offset:23552
	global_load_lds_dwordx4 v[144:145], off
	s_add_i32 m0, s18, 0x2000
	s_add_u32 s18, s60, 0x40000
	v_lshl_add_u64 v[220:221], s[60:61], 0, v[134:135]
	s_addc_u32 s19, s61, 0
	s_add_i32 s79, s74, s66
	global_load_lds_dwordx4 v[220:221], off
	v_lshl_add_u64 v[222:223], s[18:19], 0, v[130:131]
	s_mov_b32 m0, s79
	v_lshl_add_u64 v[224:225], s[62:63], 0, v[132:133]
	global_load_lds_dwordx4 v[222:223], off
	v_lshl_add_u64 v[222:223], s[18:19], 0, v[134:135]
	s_add_i32 m0, s79, 0x2000
	s_nop 0
	global_load_lds_dwordx4 v[222:223], off
	v_lshl_add_u64 v[222:223], s[62:63], 0, v[128:129]
	s_mov_b32 m0, s57
	s_nop 0
	global_load_lds_dwordx4 v[222:223], off
	s_mov_b32 m0, s67
	s_nop 0
	global_load_lds_dwordx4 v[224:225], off
	s_waitcnt vmcnt(8)
	s_waitcnt lgkmcnt(0)
	s_barrier
	s_waitcnt lgkmcnt(0)
	v_mfma_f32_16x16x32_bf16 v[60:63], v[152:155], v[188:191], v[60:63]
	v_mfma_f32_16x16x32_bf16 v[60:63], v[156:159], v[192:195], v[60:63]
	v_mfma_f32_16x16x32_bf16 v[56:59], v[160:163], v[188:191], v[56:59]
	v_mfma_f32_16x16x32_bf16 v[56:59], v[164:167], v[192:195], v[56:59]
	v_mfma_f32_16x16x32_bf16 v[52:55], v[152:155], v[196:199], v[52:55]
	v_mfma_f32_16x16x32_bf16 v[52:55], v[156:159], v[200:203], v[52:55]
	v_mfma_f32_16x16x32_bf16 v[44:47], v[160:163], v[196:199], v[44:47]
	v_mfma_f32_16x16x32_bf16 v[44:47], v[164:167], v[200:203], v[44:47]
	s_setprio 1
	v_mfma_f32_16x16x32_bf16 v[36:39], v[152:155], v[204:207], v[36:39]
	v_mfma_f32_16x16x32_bf16 v[36:39], v[156:159], v[208:211], v[36:39]
	v_mfma_f32_16x16x32_bf16 v[28:31], v[160:163], v[204:207], v[28:31]
	v_mfma_f32_16x16x32_bf16 v[28:31], v[164:167], v[208:211], v[28:31]
	v_mfma_f32_16x16x32_bf16 v[20:23], v[152:155], v[212:215], v[20:23]
	v_mfma_f32_16x16x32_bf16 v[20:23], v[156:159], v[216:219], v[20:23]
	v_mfma_f32_16x16x32_bf16 v[12:15], v[160:163], v[212:215], v[12:15]
	v_mfma_f32_16x16x32_bf16 v[12:15], v[164:167], v[216:219], v[12:15]
	v_mfma_f32_16x16x32_bf16 v[48:51], v[168:171], v[188:191], v[48:51]
	v_mfma_f32_16x16x32_bf16 v[48:51], v[172:175], v[192:195], v[48:51]
	v_mfma_f32_16x16x32_bf16 v[40:43], v[176:179], v[188:191], v[40:43]
	v_mfma_f32_16x16x32_bf16 v[40:43], v[184:187], v[192:195], v[40:43]
	v_mfma_f32_16x16x32_bf16 v[32:35], v[168:171], v[196:199], v[32:35]
	v_mfma_f32_16x16x32_bf16 v[32:35], v[172:175], v[200:203], v[32:35]
	v_mfma_f32_16x16x32_bf16 v[24:27], v[176:179], v[196:199], v[24:27]
	v_mfma_f32_16x16x32_bf16 v[24:27], v[184:187], v[200:203], v[24:27]
	s_barrier
	v_mfma_f32_16x16x32_bf16 v[16:19], v[168:171], v[204:207], v[16:19]
	v_mfma_f32_16x16x32_bf16 v[16:19], v[172:175], v[208:211], v[16:19]
	v_mfma_f32_16x16x32_bf16 v[8:11], v[176:179], v[204:207], v[8:11]
	v_mfma_f32_16x16x32_bf16 v[8:11], v[184:187], v[208:211], v[8:11]
	v_mfma_f32_16x16x32_bf16 v[4:7], v[168:171], v[212:215], v[4:7]
	v_mfma_f32_16x16x32_bf16 v[4:7], v[172:175], v[216:219], v[4:7]
	v_mfma_f32_16x16x32_bf16 v[0:3], v[176:179], v[212:215], v[0:3]
	v_mfma_f32_16x16x32_bf16 v[0:3], v[184:187], v[216:219], v[0:3]
	s_setprio 0
.Lmid_gemm3:
	s_add_i32 s79, 0, 0x18000
	s_add_i32 s89, 0, 0x1c000
	v_add_u32_e32 v164, s79, v147
	v_add_u32_e32 v181, s89, v147
	ds_read_b128 v[152:155], v164
	ds_read_b128 v[156:159], v164 offset:1024
	ds_read_b128 v[160:163], v164 offset:2048
	ds_read_b128 v[164:167], v164 offset:3072
	ds_read_b128 v[168:171], v181
	ds_read_b128 v[172:175], v181 offset:1024
	ds_read_b128 v[176:179], v181 offset:2048
	ds_read_b128 v[184:187], v181 offset:3072
	s_add_u32 s18, s62, 0x40000
	s_addc_u32 s19, s63, 0
	s_mov_b32 m0, s68
	v_lshl_add_u64 v[226:227], s[18:19], 0, v[128:129]
	ds_read_b128 v[188:191], v151 offset:32768
	ds_read_b128 v[192:195], v151 offset:33792
	ds_read_b128 v[196:199], v151 offset:34816
	ds_read_b128 v[200:203], v151 offset:35840
	ds_read_b128 v[204:207], v151 offset:36864
	ds_read_b128 v[208:211], v151 offset:37888
	ds_read_b128 v[212:215], v151 offset:38912
	ds_read_b128 v[216:219], v151 offset:39936
	global_load_lds_dwordx4 v[226:227], off
	v_lshl_add_u64 v[226:227], s[18:19], 0, v[132:133]
	s_mov_b32 m0, s69
	s_nop 0
	global_load_lds_dwordx4 v[226:227], off
	s_waitcnt vmcnt(8)
	s_waitcnt lgkmcnt(0)
	s_barrier
	s_waitcnt lgkmcnt(0)
	v_mfma_f32_16x16x32_bf16 v[124:127], v[152:155], v[188:191], v[124:127]
	v_mfma_f32_16x16x32_bf16 v[124:127], v[156:159], v[192:195], v[124:127]
	v_mfma_f32_16x16x32_bf16 v[120:123], v[160:163], v[188:191], v[120:123]
	v_mfma_f32_16x16x32_bf16 v[120:123], v[164:167], v[192:195], v[120:123]
	v_mfma_f32_16x16x32_bf16 v[116:119], v[152:155], v[196:199], v[116:119]
	v_mfma_f32_16x16x32_bf16 v[116:119], v[156:159], v[200:203], v[116:119]
	v_mfma_f32_16x16x32_bf16 v[108:111], v[160:163], v[196:199], v[108:111]
	v_mfma_f32_16x16x32_bf16 v[108:111], v[164:167], v[200:203], v[108:111]
	s_setprio 1
	v_mfma_f32_16x16x32_bf16 v[100:103], v[152:155], v[204:207], v[100:103]
	v_mfma_f32_16x16x32_bf16 v[100:103], v[156:159], v[208:211], v[100:103]
	v_mfma_f32_16x16x32_bf16 v[92:95], v[160:163], v[204:207], v[92:95]
	v_mfma_f32_16x16x32_bf16 v[92:95], v[164:167], v[208:211], v[92:95]
	v_mfma_f32_16x16x32_bf16 v[84:87], v[152:155], v[212:215], v[84:87]
	v_mfma_f32_16x16x32_bf16 v[84:87], v[156:159], v[216:219], v[84:87]
	v_mfma_f32_16x16x32_bf16 v[76:79], v[160:163], v[212:215], v[76:79]
	v_mfma_f32_16x16x32_bf16 v[76:79], v[164:167], v[216:219], v[76:79]
	v_mfma_f32_16x16x32_bf16 v[112:115], v[168:171], v[188:191], v[112:115]
	v_mfma_f32_16x16x32_bf16 v[112:115], v[172:175], v[192:195], v[112:115]
	v_mfma_f32_16x16x32_bf16 v[104:107], v[176:179], v[188:191], v[104:107]
	v_mfma_f32_16x16x32_bf16 v[104:107], v[184:187], v[192:195], v[104:107]
	v_mfma_f32_16x16x32_bf16 v[96:99], v[168:171], v[196:199], v[96:99]
	v_mfma_f32_16x16x32_bf16 v[96:99], v[172:175], v[200:203], v[96:99]
	v_mfma_f32_16x16x32_bf16 v[88:91], v[176:179], v[196:199], v[88:91]
	v_mfma_f32_16x16x32_bf16 v[88:91], v[184:187], v[200:203], v[88:91]
	s_barrier
	v_mfma_f32_16x16x32_bf16 v[80:83], v[168:171], v[204:207], v[80:83]
	v_mfma_f32_16x16x32_bf16 v[80:83], v[172:175], v[208:211], v[80:83]
	v_mfma_f32_16x16x32_bf16 v[72:75], v[176:179], v[204:207], v[72:75]
	v_mfma_f32_16x16x32_bf16 v[72:75], v[184:187], v[208:211], v[72:75]
	v_mfma_f32_16x16x32_bf16 v[68:71], v[168:171], v[212:215], v[68:71]
	v_mfma_f32_16x16x32_bf16 v[68:71], v[172:175], v[216:219], v[68:71]
	v_mfma_f32_16x16x32_bf16 v[64:67], v[176:179], v[212:215], v[64:67]
	v_mfma_f32_16x16x32_bf16 v[64:67], v[184:187], v[216:219], v[64:67]
	s_setprio 0
	s_add_i32 s18, s79, s66
	v_lshl_add_u64 v[144:145], v[144:145], 0, s[10:11]
	s_mov_b32 m0, s18
	ds_read_b128 v[188:191], v151 offset:49152
	ds_read_b128 v[192:195], v151 offset:50176
	ds_read_b128 v[196:199], v151 offset:51200
	ds_read_b128 v[200:203], v151 offset:52224
	ds_read_b128 v[204:207], v151 offset:53248
	ds_read_b128 v[208:211], v151 offset:54272
	ds_read_b128 v[212:215], v151 offset:55296
	ds_read_b128 v[216:219], v151 offset:56320
	global_load_lds_dwordx4 v[144:145], off
	s_add_i32 m0, s18, 0x2000
	s_add_u32 s18, s60, 0x40080
	v_lshl_add_u64 v[144:145], v[220:221], 0, s[10:11]
	s_addc_u32 s19, s61, 0
	s_add_i32 s60, s89, s66
	global_load_lds_dwordx4 v[144:145], off
	v_lshl_add_u64 v[144:145], s[18:19], 0, v[130:131]
	s_mov_b32 m0, s60
	s_nop 0
	global_load_lds_dwordx4 v[144:145], off
	v_lshl_add_u64 v[144:145], s[18:19], 0, v[134:135]
	s_add_i32 m0, s60, 0x2000
	s_nop 0
	global_load_lds_dwordx4 v[144:145], off
	v_lshl_add_u64 v[144:145], v[222:223], 0, s[10:11]
	s_mov_b32 m0, s71
	s_nop 0
	global_load_lds_dwordx4 v[144:145], off
	v_lshl_add_u64 v[144:145], v[224:225], 0, s[10:11]
	s_mov_b32 m0, s72
	s_nop 0
	global_load_lds_dwordx4 v[144:145], off
	s_waitcnt vmcnt(8)
	s_waitcnt lgkmcnt(0)
	s_barrier
	s_waitcnt lgkmcnt(0)
	v_mfma_f32_16x16x32_bf16 v[60:63], v[152:155], v[188:191], v[60:63]
	v_mfma_f32_16x16x32_bf16 v[60:63], v[156:159], v[192:195], v[60:63]
	v_mfma_f32_16x16x32_bf16 v[56:59], v[160:163], v[188:191], v[56:59]
	v_mfma_f32_16x16x32_bf16 v[56:59], v[164:167], v[192:195], v[56:59]
	v_mfma_f32_16x16x32_bf16 v[52:55], v[152:155], v[196:199], v[52:55]
	v_mfma_f32_16x16x32_bf16 v[52:55], v[156:159], v[200:203], v[52:55]
	v_mfma_f32_16x16x32_bf16 v[44:47], v[160:163], v[196:199], v[44:47]
	v_mfma_f32_16x16x32_bf16 v[44:47], v[164:167], v[200:203], v[44:47]
	s_setprio 1
	v_mfma_f32_16x16x32_bf16 v[36:39], v[152:155], v[204:207], v[36:39]
	v_mfma_f32_16x16x32_bf16 v[36:39], v[156:159], v[208:211], v[36:39]
	v_mfma_f32_16x16x32_bf16 v[28:31], v[160:163], v[204:207], v[28:31]
	v_mfma_f32_16x16x32_bf16 v[28:31], v[164:167], v[208:211], v[28:31]
	v_mfma_f32_16x16x32_bf16 v[20:23], v[152:155], v[212:215], v[20:23]
	v_mfma_f32_16x16x32_bf16 v[20:23], v[156:159], v[216:219], v[20:23]
	v_mfma_f32_16x16x32_bf16 v[12:15], v[160:163], v[212:215], v[12:15]
	v_mfma_f32_16x16x32_bf16 v[12:15], v[164:167], v[216:219], v[12:15]
	v_mfma_f32_16x16x32_bf16 v[48:51], v[168:171], v[188:191], v[48:51]
	v_mfma_f32_16x16x32_bf16 v[48:51], v[172:175], v[192:195], v[48:51]
	v_mfma_f32_16x16x32_bf16 v[40:43], v[176:179], v[188:191], v[40:43]
	v_mfma_f32_16x16x32_bf16 v[40:43], v[184:187], v[192:195], v[40:43]
	v_mfma_f32_16x16x32_bf16 v[32:35], v[168:171], v[196:199], v[32:35]
	v_mfma_f32_16x16x32_bf16 v[32:35], v[172:175], v[200:203], v[32:35]
	v_mfma_f32_16x16x32_bf16 v[24:27], v[176:179], v[196:199], v[24:27]
	v_mfma_f32_16x16x32_bf16 v[24:27], v[184:187], v[200:203], v[24:27]
	s_barrier
	v_mfma_f32_16x16x32_bf16 v[16:19], v[168:171], v[204:207], v[16:19]
	v_mfma_f32_16x16x32_bf16 v[16:19], v[172:175], v[208:211], v[16:19]
	v_mfma_f32_16x16x32_bf16 v[8:11], v[176:179], v[204:207], v[8:11]
	v_mfma_f32_16x16x32_bf16 v[8:11], v[184:187], v[208:211], v[8:11]
	v_mfma_f32_16x16x32_bf16 v[4:7], v[168:171], v[212:215], v[4:7]
	v_mfma_f32_16x16x32_bf16 v[4:7], v[172:175], v[216:219], v[4:7]
	v_mfma_f32_16x16x32_bf16 v[0:3], v[176:179], v[212:215], v[0:3]
	v_mfma_f32_16x16x32_bf16 v[0:3], v[184:187], v[216:219], v[0:3]
	s_setprio 0
	s_add_i32 s88, s88, 2
	s_add_u32 s58, s58, 0x100
	s_addc_u32 s59, s59, 0
	s_add_u32 s86, s86, 0x100
	s_addc_u32 s87, s87, 0
	s_cmp_gt_u32 s88, 13
	s_cbranch_scc0 .LBB0_601
	s_and_b64 vcc, exec, s[12:13]
	s_cbranch_vccz .LBB0_604
	s_barrier

.LBB0_723:
	s_ashr_i32 s31, s30, 31
	s_lshl_b64 s[36:37], s[30:31], 19
	s_add_u32 s36, s80, s36
	s_addc_u32 s37, s81, s37
	s_and_b64 s[44:45], s[10:11], exec
	s_cselect_b32 s31, s37, s49
	s_cselect_b32 s70, s36, s48
	s_ashr_i32 s19, s18, 31
	s_lshl_b64 s[44:45], s[18:19], 19
	s_add_u32 s44, s56, s44
	s_addc_u32 s45, s57, s45
	s_and_b64 s[54:55], s[10:11], exec
	s_cselect_b32 s19, s45, s53
	s_cselect_b32 s71, s44, s52
	s_add_u32 s48, s48, 0x40080
	s_addc_u32 s49, s49, 0
	s_add_u32 s72, s52, 0x100
	s_addc_u32 s73, s53, 0
	s_mov_b32 s74, -2
	ds_read_b128 v[140:143], v147
	ds_read_b128 v[150:153], v147 offset:1024
	ds_read_b128 v[154:157], v147 offset:2048
	ds_read_b128 v[158:161], v147 offset:3072
	ds_read_b128 v[162:165], v148
	ds_read_b128 v[166:169], v148 offset:1024
	ds_read_b128 v[170:173], v148 offset:2048
	ds_read_b128 v[174:177], v148 offset:3072
	s_add_u32 s52, s48, 0xfffc0080
	s_addc_u32 s53, s49, -1
	s_cmp_eq_u32 s74, 12
	s_cselect_b32 s55, s31, s53
	s_cselect_b32 s54, s70, s52
	s_cselect_b32 s53, s19, s73
	s_cselect_b32 s52, s71, s72
	v_lshl_add_u64 v[178:179], s[48:49], 0, v[132:133]
	s_add_i32 m0, s47, 0xc000
	ds_read_b128 v[184:187], v149
	ds_read_b128 v[188:191], v149 offset:1024
	ds_read_b128 v[192:195], v149 offset:2048
	ds_read_b128 v[196:199], v149 offset:3072
	ds_read_b128 v[200:203], v149 offset:4096
	ds_read_b128 v[204:207], v149 offset:5120
	ds_read_b128 v[208:211], v149 offset:6144
	ds_read_b128 v[212:215], v149 offset:7168
	global_load_lds_dwordx4 v[178:179], off
	v_lshl_add_u64 v[178:179], s[48:49], 0, v[134:135]
	s_add_i32 m0, s47, 0xe000
	s_nop 0
	global_load_lds_dwordx4 v[178:179], off
	s_waitcnt vmcnt(8)
	s_waitcnt lgkmcnt(0)
	s_barrier
	s_waitcnt lgkmcnt(0)
	v_mfma_f32_16x16x32_bf16 v[124:127], v[140:143], v[184:187], 0
	v_mfma_f32_16x16x32_bf16 v[124:127], v[150:153], v[188:191], v[124:127]
	v_mfma_f32_16x16x32_bf16 v[120:123], v[154:157], v[184:187], 0
	v_mfma_f32_16x16x32_bf16 v[120:123], v[158:161], v[188:191], v[120:123]
	v_mfma_f32_16x16x32_bf16 v[108:111], v[140:143], v[192:195], 0
	v_mfma_f32_16x16x32_bf16 v[108:111], v[150:153], v[196:199], v[108:111]
	v_mfma_f32_16x16x32_bf16 v[104:107], v[154:157], v[192:195], 0
	v_mfma_f32_16x16x32_bf16 v[104:107], v[158:161], v[196:199], v[104:107]
	s_setprio 1
	v_mfma_f32_16x16x32_bf16 v[92:95], v[140:143], v[200:203], 0
	v_mfma_f32_16x16x32_bf16 v[92:95], v[150:153], v[204:207], v[92:95]
	v_mfma_f32_16x16x32_bf16 v[88:91], v[154:157], v[200:203], 0
	v_mfma_f32_16x16x32_bf16 v[88:91], v[158:161], v[204:207], v[88:91]
	v_mfma_f32_16x16x32_bf16 v[76:79], v[140:143], v[208:211], 0
	v_mfma_f32_16x16x32_bf16 v[76:79], v[150:153], v[212:215], v[76:79]
	v_mfma_f32_16x16x32_bf16 v[72:75], v[154:157], v[208:211], 0
	v_mfma_f32_16x16x32_bf16 v[72:75], v[158:161], v[212:215], v[72:75]
	v_mfma_f32_16x16x32_bf16 v[116:119], v[162:165], v[184:187], 0
	v_mfma_f32_16x16x32_bf16 v[116:119], v[166:169], v[188:191], v[116:119]
	v_mfma_f32_16x16x32_bf16 v[112:115], v[170:173], v[184:187], 0
	v_mfma_f32_16x16x32_bf16 v[112:115], v[174:177], v[188:191], v[112:115]
	v_mfma_f32_16x16x32_bf16 v[100:103], v[162:165], v[192:195], 0
	v_mfma_f32_16x16x32_bf16 v[100:103], v[166:169], v[196:199], v[100:103]
	v_mfma_f32_16x16x32_bf16 v[96:99], v[170:173], v[192:195], 0
	v_mfma_f32_16x16x32_bf16 v[96:99], v[174:177], v[196:199], v[96:99]
	s_barrier
	v_mfma_f32_16x16x32_bf16 v[84:87], v[162:165], v[200:203], 0
	v_mfma_f32_16x16x32_bf16 v[84:87], v[166:169], v[204:207], v[84:87]
	v_mfma_f32_16x16x32_bf16 v[80:83], v[170:173], v[200:203], 0
	v_mfma_f32_16x16x32_bf16 v[80:83], v[174:177], v[204:207], v[80:83]
	v_mfma_f32_16x16x32_bf16 v[68:71], v[162:165], v[208:211], 0
	v_mfma_f32_16x16x32_bf16 v[68:71], v[166:169], v[212:215], v[68:71]
	v_mfma_f32_16x16x32_bf16 v[64:67], v[170:173], v[208:211], 0
	v_mfma_f32_16x16x32_bf16 v[64:67], v[174:177], v[212:215], v[64:67]
	s_setprio 0
	s_add_i32 s75, s66, s58
	v_lshl_add_u64 v[178:179], s[52:53], 0, v[130:131]
	s_mov_b32 m0, s75
	ds_read_b128 v[184:187], v149 offset:16384
	ds_read_b128 v[188:191], v149 offset:17408
	ds_read_b128 v[192:195], v149 offset:18432
	ds_read_b128 v[196:199], v149 offset:19456
	ds_read_b128 v[200:203], v149 offset:20480
	ds_read_b128 v[204:207], v149 offset:21504
	ds_read_b128 v[208:211], v149 offset:22528
	ds_read_b128 v[212:215], v149 offset:23552
	global_load_lds_dwordx4 v[178:179], off
	s_add_i32 m0, s75, 0x2000
	s_add_u32 s76, s52, 0x40000
	v_lshl_add_u64 v[216:217], s[52:53], 0, v[128:129]
	s_addc_u32 s77, s53, 0
	s_add_i32 s75, s67, s58
	global_load_lds_dwordx4 v[216:217], off
	v_lshl_add_u64 v[218:219], s[76:77], 0, v[130:131]
	s_mov_b32 m0, s75
	v_lshl_add_u64 v[220:221], s[54:55], 0, v[128:129]
	global_load_lds_dwordx4 v[218:219], off
	v_lshl_add_u64 v[218:219], s[76:77], 0, v[128:129]
	s_add_i32 m0, s75, 0x2000
	s_nop 0
	global_load_lds_dwordx4 v[218:219], off
	v_lshl_add_u64 v[218:219], s[54:55], 0, v[130:131]
	s_mov_b32 m0, s47
	s_nop 0
	global_load_lds_dwordx4 v[218:219], off
	s_mov_b32 m0, s60
	s_nop 0
	global_load_lds_dwordx4 v[220:221], off
	s_waitcnt vmcnt(8)
	s_waitcnt lgkmcnt(0)
	s_barrier
	s_waitcnt lgkmcnt(0)
	v_mfma_f32_16x16x32_bf16 v[60:63], v[140:143], v[184:187], 0
	v_mfma_f32_16x16x32_bf16 v[60:63], v[150:153], v[188:191], v[60:63]
	v_mfma_f32_16x16x32_bf16 v[56:59], v[154:157], v[184:187], 0
	v_mfma_f32_16x16x32_bf16 v[56:59], v[158:161], v[188:191], v[56:59]
	v_mfma_f32_16x16x32_bf16 v[44:47], v[140:143], v[192:195], 0
	v_mfma_f32_16x16x32_bf16 v[44:47], v[150:153], v[196:199], v[44:47]
	v_mfma_f32_16x16x32_bf16 v[40:43], v[154:157], v[192:195], 0
	v_mfma_f32_16x16x32_bf16 v[40:43], v[158:161], v[196:199], v[40:43]
	s_setprio 1
	v_mfma_f32_16x16x32_bf16 v[28:31], v[140:143], v[200:203], 0
	v_mfma_f32_16x16x32_bf16 v[28:31], v[150:153], v[204:207], v[28:31]
	v_mfma_f32_16x16x32_bf16 v[24:27], v[154:157], v[200:203], 0
	v_mfma_f32_16x16x32_bf16 v[24:27], v[158:161], v[204:207], v[24:27]
	v_mfma_f32_16x16x32_bf16 v[12:15], v[140:143], v[208:211], 0
	v_mfma_f32_16x16x32_bf16 v[12:15], v[150:153], v[212:215], v[12:15]
	v_mfma_f32_16x16x32_bf16 v[8:11], v[154:157], v[208:211], 0
	v_mfma_f32_16x16x32_bf16 v[8:11], v[158:161], v[212:215], v[8:11]
	v_mfma_f32_16x16x32_bf16 v[52:55], v[162:165], v[184:187], 0
	v_mfma_f32_16x16x32_bf16 v[52:55], v[166:169], v[188:191], v[52:55]
	v_mfma_f32_16x16x32_bf16 v[48:51], v[170:173], v[184:187], 0
	v_mfma_f32_16x16x32_bf16 v[48:51], v[174:177], v[188:191], v[48:51]
	v_mfma_f32_16x16x32_bf16 v[36:39], v[162:165], v[192:195], 0
	v_mfma_f32_16x16x32_bf16 v[36:39], v[166:169], v[196:199], v[36:39]
	v_mfma_f32_16x16x32_bf16 v[32:35], v[170:173], v[192:195], 0
	v_mfma_f32_16x16x32_bf16 v[32:35], v[174:177], v[196:199], v[32:35]
	s_barrier
	v_mfma_f32_16x16x32_bf16 v[20:23], v[162:165], v[200:203], 0
	v_mfma_f32_16x16x32_bf16 v[20:23], v[166:169], v[204:207], v[20:23]
	v_mfma_f32_16x16x32_bf16 v[16:19], v[170:173], v[200:203], 0
	v_mfma_f32_16x16x32_bf16 v[16:19], v[174:177], v[204:207], v[16:19]
	v_mfma_f32_16x16x32_bf16 v[4:7], v[162:165], v[208:211], 0
	v_mfma_f32_16x16x32_bf16 v[4:7], v[166:169], v[212:215], v[4:7]
	v_mfma_f32_16x16x32_bf16 v[0:3], v[170:173], v[208:211], 0
	v_mfma_f32_16x16x32_bf16 v[0:3], v[174:177], v[212:215], v[0:3]
	s_setprio 0
	s_branch .Lmid_gemm4
.LBB0_724:
	ds_read_b128 v[140:143], v147
	ds_read_b128 v[150:153], v147 offset:1024
	ds_read_b128 v[154:157], v147 offset:2048
	ds_read_b128 v[158:161], v147 offset:3072
	ds_read_b128 v[162:165], v148
	ds_read_b128 v[166:169], v148 offset:1024
	ds_read_b128 v[170:173], v148 offset:2048
	ds_read_b128 v[174:177], v148 offset:3072
	s_add_u32 s52, s48, 0xfffc0080
	s_addc_u32 s53, s49, -1
	s_cmp_eq_u32 s74, 12
	s_cselect_b32 s55, s31, s53
	s_cselect_b32 s54, s70, s52
	s_cselect_b32 s53, s19, s73
	s_cselect_b32 s52, s71, s72
	v_lshl_add_u64 v[178:179], s[48:49], 0, v[132:133]
	s_add_i32 m0, s47, 0xc000
	ds_read_b128 v[184:187], v149
	ds_read_b128 v[188:191], v149 offset:1024
	ds_read_b128 v[192:195], v149 offset:2048
	ds_read_b128 v[196:199], v149 offset:3072
	ds_read_b128 v[200:203], v149 offset:4096
	ds_read_b128 v[204:207], v149 offset:5120
	ds_read_b128 v[208:211], v149 offset:6144
	ds_read_b128 v[212:215], v149 offset:7168
	global_load_lds_dwordx4 v[178:179], off
	v_lshl_add_u64 v[178:179], s[48:49], 0, v[134:135]
	s_add_i32 m0, s47, 0xe000
	s_nop 0
	global_load_lds_dwordx4 v[178:179], off
	s_waitcnt vmcnt(8)
	s_waitcnt lgkmcnt(0)
	s_barrier
	s_waitcnt lgkmcnt(0)
	v_mfma_f32_16x16x32_bf16 v[124:127], v[140:143], v[184:187], v[124:127]
	v_mfma_f32_16x16x32_bf16 v[124:127], v[150:153], v[188:191], v[124:127]
	v_mfma_f32_16x16x32_bf16 v[120:123], v[154:157], v[184:187], v[120:123]
	v_mfma_f32_16x16x32_bf16 v[120:123], v[158:161], v[188:191], v[120:123]
	v_mfma_f32_16x16x32_bf16 v[108:111], v[140:143], v[192:195], v[108:111]
	v_mfma_f32_16x16x32_bf16 v[108:111], v[150:153], v[196:199], v[108:111]
	v_mfma_f32_16x16x32_bf16 v[104:107], v[154:157], v[192:195], v[104:107]
	v_mfma_f32_16x16x32_bf16 v[104:107], v[158:161], v[196:199], v[104:107]
	s_setprio 1
	v_mfma_f32_16x16x32_bf16 v[92:95], v[140:143], v[200:203], v[92:95]
	v_mfma_f32_16x16x32_bf16 v[92:95], v[150:153], v[204:207], v[92:95]
	v_mfma_f32_16x16x32_bf16 v[88:91], v[154:157], v[200:203], v[88:91]
	v_mfma_f32_16x16x32_bf16 v[88:91], v[158:161], v[204:207], v[88:91]
	v_mfma_f32_16x16x32_bf16 v[76:79], v[140:143], v[208:211], v[76:79]
	v_mfma_f32_16x16x32_bf16 v[76:79], v[150:153], v[212:215], v[76:79]
	v_mfma_f32_16x16x32_bf16 v[72:75], v[154:157], v[208:211], v[72:75]
	v_mfma_f32_16x16x32_bf16 v[72:75], v[158:161], v[212:215], v[72:75]
	v_mfma_f32_16x16x32_bf16 v[116:119], v[162:165], v[184:187], v[116:119]
	v_mfma_f32_16x16x32_bf16 v[116:119], v[166:169], v[188:191], v[116:119]
	v_mfma_f32_16x16x32_bf16 v[112:115], v[170:173], v[184:187], v[112:115]
	v_mfma_f32_16x16x32_bf16 v[112:115], v[174:177], v[188:191], v[112:115]
	v_mfma_f32_16x16x32_bf16 v[100:103], v[162:165], v[192:195], v[100:103]
	v_mfma_f32_16x16x32_bf16 v[100:103], v[166:169], v[196:199], v[100:103]
	v_mfma_f32_16x16x32_bf16 v[96:99], v[170:173], v[192:195], v[96:99]
	v_mfma_f32_16x16x32_bf16 v[96:99], v[174:177], v[196:199], v[96:99]
	s_barrier
	v_mfma_f32_16x16x32_bf16 v[84:87], v[162:165], v[200:203], v[84:87]
	v_mfma_f32_16x16x32_bf16 v[84:87], v[166:169], v[204:207], v[84:87]
	v_mfma_f32_16x16x32_bf16 v[80:83], v[170:173], v[200:203], v[80:83]
	v_mfma_f32_16x16x32_bf16 v[80:83], v[174:177], v[204:207], v[80:83]
	v_mfma_f32_16x16x32_bf16 v[68:71], v[162:165], v[208:211], v[68:71]
	v_mfma_f32_16x16x32_bf16 v[68:71], v[166:169], v[212:215], v[68:71]
	v_mfma_f32_16x16x32_bf16 v[64:67], v[170:173], v[208:211], v[64:67]
	v_mfma_f32_16x16x32_bf16 v[64:67], v[174:177], v[212:215], v[64:67]
	s_setprio 0
	s_add_i32 s75, s66, s58
	v_lshl_add_u64 v[178:179], s[52:53], 0, v[130:131]
	s_mov_b32 m0, s75
	ds_read_b128 v[184:187], v149 offset:16384
	ds_read_b128 v[188:191], v149 offset:17408
	ds_read_b128 v[192:195], v149 offset:18432
	ds_read_b128 v[196:199], v149 offset:19456
	ds_read_b128 v[200:203], v149 offset:20480
	ds_read_b128 v[204:207], v149 offset:21504
	ds_read_b128 v[208:211], v149 offset:22528
	ds_read_b128 v[212:215], v149 offset:23552
	global_load_lds_dwordx4 v[178:179], off
	s_add_i32 m0, s75, 0x2000
	s_add_u32 s76, s52, 0x40000
	v_lshl_add_u64 v[216:217], s[52:53], 0, v[128:129]
	s_addc_u32 s77, s53, 0
	s_add_i32 s75, s67, s58
	global_load_lds_dwordx4 v[216:217], off
	v_lshl_add_u64 v[218:219], s[76:77], 0, v[130:131]
	s_mov_b32 m0, s75
	v_lshl_add_u64 v[220:221], s[54:55], 0, v[128:129]
	global_load_lds_dwordx4 v[218:219], off
	v_lshl_add_u64 v[218:219], s[76:77], 0, v[128:129]
	s_add_i32 m0, s75, 0x2000
	s_nop 0
	global_load_lds_dwordx4 v[218:219], off
	v_lshl_add_u64 v[218:219], s[54:55], 0, v[130:131]
	s_mov_b32 m0, s47
	s_nop 0
	global_load_lds_dwordx4 v[218:219], off
	s_mov_b32 m0, s60
	s_nop 0
	global_load_lds_dwordx4 v[220:221], off
	s_waitcnt vmcnt(8)
	s_waitcnt lgkmcnt(0)
	s_barrier
	s_waitcnt lgkmcnt(0)
	v_mfma_f32_16x16x32_bf16 v[60:63], v[140:143], v[184:187], v[60:63]
	v_mfma_f32_16x16x32_bf16 v[60:63], v[150:153], v[188:191], v[60:63]
	v_mfma_f32_16x16x32_bf16 v[56:59], v[154:157], v[184:187], v[56:59]
	v_mfma_f32_16x16x32_bf16 v[56:59], v[158:161], v[188:191], v[56:59]
	v_mfma_f32_16x16x32_bf16 v[44:47], v[140:143], v[192:195], v[44:47]
	v_mfma_f32_16x16x32_bf16 v[44:47], v[150:153], v[196:199], v[44:47]
	v_mfma_f32_16x16x32_bf16 v[40:43], v[154:157], v[192:195], v[40:43]
	v_mfma_f32_16x16x32_bf16 v[40:43], v[158:161], v[196:199], v[40:43]
	s_setprio 1
	v_mfma_f32_16x16x32_bf16 v[28:31], v[140:143], v[200:203], v[28:31]
	v_mfma_f32_16x16x32_bf16 v[28:31], v[150:153], v[204:207], v[28:31]
	v_mfma_f32_16x16x32_bf16 v[24:27], v[154:157], v[200:203], v[24:27]
	v_mfma_f32_16x16x32_bf16 v[24:27], v[158:161], v[204:207], v[24:27]
	v_mfma_f32_16x16x32_bf16 v[12:15], v[140:143], v[208:211], v[12:15]
	v_mfma_f32_16x16x32_bf16 v[12:15], v[150:153], v[212:215], v[12:15]
	v_mfma_f32_16x16x32_bf16 v[8:11], v[154:157], v[208:211], v[8:11]
	v_mfma_f32_16x16x32_bf16 v[8:11], v[158:161], v[212:215], v[8:11]
	v_mfma_f32_16x16x32_bf16 v[52:55], v[162:165], v[184:187], v[52:55]
	v_mfma_f32_16x16x32_bf16 v[52:55], v[166:169], v[188:191], v[52:55]
	v_mfma_f32_16x16x32_bf16 v[48:51], v[170:173], v[184:187], v[48:51]
	v_mfma_f32_16x16x32_bf16 v[48:51], v[174:177], v[188:191], v[48:51]
	v_mfma_f32_16x16x32_bf16 v[36:39], v[162:165], v[192:195], v[36:39]
	v_mfma_f32_16x16x32_bf16 v[36:39], v[166:169], v[196:199], v[36:39]
	v_mfma_f32_16x16x32_bf16 v[32:35], v[170:173], v[192:195], v[32:35]
	v_mfma_f32_16x16x32_bf16 v[32:35], v[174:177], v[196:199], v[32:35]
	s_barrier
	v_mfma_f32_16x16x32_bf16 v[20:23], v[162:165], v[200:203], v[20:23]
	v_mfma_f32_16x16x32_bf16 v[20:23], v[166:169], v[204:207], v[20:23]
	v_mfma_f32_16x16x32_bf16 v[16:19], v[170:173], v[200:203], v[16:19]
	v_mfma_f32_16x16x32_bf16 v[16:19], v[174:177], v[204:207], v[16:19]
	v_mfma_f32_16x16x32_bf16 v[4:7], v[162:165], v[208:211], v[4:7]
	v_mfma_f32_16x16x32_bf16 v[4:7], v[166:169], v[212:215], v[4:7]
	v_mfma_f32_16x16x32_bf16 v[0:3], v[170:173], v[208:211], v[0:3]
	v_mfma_f32_16x16x32_bf16 v[0:3], v[174:177], v[212:215], v[0:3]
	s_setprio 0
.Lmid_gemm4:
	s_add_i32 s75, 0, 0x18000
	s_add_i32 s76, 0, 0x1c000
	v_add_u32_e32 v158, s75, v145
	v_add_u32_e32 v174, s76, v145
	ds_read_b128 v[140:143], v158
	ds_read_b128 v[150:153], v158 offset:1024
	ds_read_b128 v[154:157], v158 offset:2048
	ds_read_b128 v[158:161], v158 offset:3072
	ds_read_b128 v[162:165], v174
	ds_read_b128 v[166:169], v174 offset:1024
	ds_read_b128 v[170:173], v174 offset:2048
	ds_read_b128 v[174:177], v174 offset:3072
	s_add_u32 s54, s54, 0x40000
	s_addc_u32 s55, s55, 0
	s_mov_b32 m0, s61
	v_lshl_add_u64 v[222:223], s[54:55], 0, v[130:131]
	ds_read_b128 v[184:187], v149 offset:32768
	ds_read_b128 v[188:191], v149 offset:33792
	ds_read_b128 v[192:195], v149 offset:34816
	ds_read_b128 v[196:199], v149 offset:35840
	ds_read_b128 v[200:203], v149 offset:36864
	ds_read_b128 v[204:207], v149 offset:37888
	ds_read_b128 v[208:211], v149 offset:38912
	ds_read_b128 v[212:215], v149 offset:39936
	global_load_lds_dwordx4 v[222:223], off
	v_lshl_add_u64 v[222:223], s[54:55], 0, v[128:129]
	s_mov_b32 m0, s62
	s_nop 0
	global_load_lds_dwordx4 v[222:223], off
	s_waitcnt vmcnt(8)
	s_waitcnt lgkmcnt(0)
	s_barrier
	s_waitcnt lgkmcnt(0)
	v_mfma_f32_16x16x32_bf16 v[124:127], v[140:143], v[184:187], v[124:127]
	v_mfma_f32_16x16x32_bf16 v[124:127], v[150:153], v[188:191], v[124:127]
	v_mfma_f32_16x16x32_bf16 v[120:123], v[154:157], v[184:187], v[120:123]
	v_mfma_f32_16x16x32_bf16 v[120:123], v[158:161], v[188:191], v[120:123]
	v_mfma_f32_16x16x32_bf16 v[108:111], v[140:143], v[192:195], v[108:111]
	v_mfma_f32_16x16x32_bf16 v[108:111], v[150:153], v[196:199], v[108:111]
	v_mfma_f32_16x16x32_bf16 v[104:107], v[154:157], v[192:195], v[104:107]
	v_mfma_f32_16x16x32_bf16 v[104:107], v[158:161], v[196:199], v[104:107]
	s_setprio 1
	v_mfma_f32_16x16x32_bf16 v[92:95], v[140:143], v[200:203], v[92:95]
	v_mfma_f32_16x16x32_bf16 v[92:95], v[150:153], v[204:207], v[92:95]
	v_mfma_f32_16x16x32_bf16 v[88:91], v[154:157], v[200:203], v[88:91]
	v_mfma_f32_16x16x32_bf16 v[88:91], v[158:161], v[204:207], v[88:91]
	v_mfma_f32_16x16x32_bf16 v[76:79], v[140:143], v[208:211], v[76:79]
	v_mfma_f32_16x16x32_bf16 v[76:79], v[150:153], v[212:215], v[76:79]
	v_mfma_f32_16x16x32_bf16 v[72:75], v[154:157], v[208:211], v[72:75]
	v_mfma_f32_16x16x32_bf16 v[72:75], v[158:161], v[212:215], v[72:75]
	v_mfma_f32_16x16x32_bf16 v[116:119], v[162:165], v[184:187], v[116:119]
	v_mfma_f32_16x16x32_bf16 v[116:119], v[166:169], v[188:191], v[116:119]
	v_mfma_f32_16x16x32_bf16 v[112:115], v[170:173], v[184:187], v[112:115]
	v_mfma_f32_16x16x32_bf16 v[112:115], v[174:177], v[188:191], v[112:115]
	v_mfma_f32_16x16x32_bf16 v[100:103], v[162:165], v[192:195], v[100:103]
	v_mfma_f32_16x16x32_bf16 v[100:103], v[166:169], v[196:199], v[100:103]
	v_mfma_f32_16x16x32_bf16 v[96:99], v[170:173], v[192:195], v[96:99]
	v_mfma_f32_16x16x32_bf16 v[96:99], v[174:177], v[196:199], v[96:99]
	s_barrier
	v_mfma_f32_16x16x32_bf16 v[84:87], v[162:165], v[200:203], v[84:87]
	v_mfma_f32_16x16x32_bf16 v[84:87], v[166:169], v[204:207], v[84:87]
	v_mfma_f32_16x16x32_bf16 v[80:83], v[170:173], v[200:203], v[80:83]
	v_mfma_f32_16x16x32_bf16 v[80:83], v[174:177], v[204:207], v[80:83]
	v_mfma_f32_16x16x32_bf16 v[68:71], v[162:165], v[208:211], v[68:71]
	v_mfma_f32_16x16x32_bf16 v[68:71], v[166:169], v[212:215], v[68:71]
	v_mfma_f32_16x16x32_bf16 v[64:67], v[170:173], v[208:211], v[64:67]
	v_mfma_f32_16x16x32_bf16 v[64:67], v[174:177], v[212:215], v[64:67]
	s_setprio 0
	s_add_i32 s54, s75, s58
	v_lshl_add_u64 v[178:179], v[178:179], 0, s[12:13]
	s_mov_b32 m0, s54
	ds_read_b128 v[184:187], v149 offset:49152
	ds_read_b128 v[188:191], v149 offset:50176
	ds_read_b128 v[192:195], v149 offset:51200
	ds_read_b128 v[196:199], v149 offset:52224
	ds_read_b128 v[200:203], v149 offset:53248
	ds_read_b128 v[204:207], v149 offset:54272
	ds_read_b128 v[208:211], v149 offset:55296
	ds_read_b128 v[212:215], v149 offset:56320
	global_load_lds_dwordx4 v[178:179], off
	s_add_i32 m0, s54, 0x2000
	s_add_u32 s52, s52, 0x40080
	v_lshl_add_u64 v[178:179], v[216:217], 0, s[12:13]
	s_addc_u32 s53, s53, 0
	s_add_i32 s54, s76, s58
	global_load_lds_dwordx4 v[178:179], off
	v_lshl_add_u64 v[178:179], s[52:53], 0, v[130:131]
	s_mov_b32 m0, s54
	s_nop 0
	global_load_lds_dwordx4 v[178:179], off
	v_lshl_add_u64 v[178:179], s[52:53], 0, v[128:129]
	s_add_i32 m0, s54, 0x2000
	s_nop 0
	global_load_lds_dwordx4 v[178:179], off
	v_lshl_add_u64 v[178:179], v[218:219], 0, s[12:13]
	s_mov_b32 m0, s64
	s_nop 0
	global_load_lds_dwordx4 v[178:179], off
	v_lshl_add_u64 v[178:179], v[220:221], 0, s[12:13]
	s_mov_b32 m0, s65
	s_nop 0
	global_load_lds_dwordx4 v[178:179], off
	s_waitcnt vmcnt(8)
	s_waitcnt lgkmcnt(0)
	s_barrier
	s_waitcnt lgkmcnt(0)
	v_mfma_f32_16x16x32_bf16 v[60:63], v[140:143], v[184:187], v[60:63]
	v_mfma_f32_16x16x32_bf16 v[60:63], v[150:153], v[188:191], v[60:63]
	v_mfma_f32_16x16x32_bf16 v[56:59], v[154:157], v[184:187], v[56:59]
	v_mfma_f32_16x16x32_bf16 v[56:59], v[158:161], v[188:191], v[56:59]
	v_mfma_f32_16x16x32_bf16 v[44:47], v[140:143], v[192:195], v[44:47]
	v_mfma_f32_16x16x32_bf16 v[44:47], v[150:153], v[196:199], v[44:47]
	v_mfma_f32_16x16x32_bf16 v[40:43], v[154:157], v[192:195], v[40:43]
	v_mfma_f32_16x16x32_bf16 v[40:43], v[158:161], v[196:199], v[40:43]
	s_setprio 1
	v_mfma_f32_16x16x32_bf16 v[28:31], v[140:143], v[200:203], v[28:31]
	v_mfma_f32_16x16x32_bf16 v[28:31], v[150:153], v[204:207], v[28:31]
	v_mfma_f32_16x16x32_bf16 v[24:27], v[154:157], v[200:203], v[24:27]
	v_mfma_f32_16x16x32_bf16 v[24:27], v[158:161], v[204:207], v[24:27]
	v_mfma_f32_16x16x32_bf16 v[12:15], v[140:143], v[208:211], v[12:15]
	v_mfma_f32_16x16x32_bf16 v[12:15], v[150:153], v[212:215], v[12:15]
	v_mfma_f32_16x16x32_bf16 v[8:11], v[154:157], v[208:211], v[8:11]
	v_mfma_f32_16x16x32_bf16 v[8:11], v[158:161], v[212:215], v[8:11]
	v_mfma_f32_16x16x32_bf16 v[52:55], v[162:165], v[184:187], v[52:55]
	v_mfma_f32_16x16x32_bf16 v[52:55], v[166:169], v[188:191], v[52:55]
	v_mfma_f32_16x16x32_bf16 v[48:51], v[170:173], v[184:187], v[48:51]
	v_mfma_f32_16x16x32_bf16 v[48:51], v[174:177], v[188:191], v[48:51]
	v_mfma_f32_16x16x32_bf16 v[36:39], v[162:165], v[192:195], v[36:39]
	v_mfma_f32_16x16x32_bf16 v[36:39], v[166:169], v[196:199], v[36:39]
	v_mfma_f32_16x16x32_bf16 v[32:35], v[170:173], v[192:195], v[32:35]
	v_mfma_f32_16x16x32_bf16 v[32:35], v[174:177], v[196:199], v[32:35]
	s_barrier
	v_mfma_f32_16x16x32_bf16 v[20:23], v[162:165], v[200:203], v[20:23]
	v_mfma_f32_16x16x32_bf16 v[20:23], v[166:169], v[204:207], v[20:23]
	v_mfma_f32_16x16x32_bf16 v[16:19], v[170:173], v[200:203], v[16:19]
	v_mfma_f32_16x16x32_bf16 v[16:19], v[174:177], v[204:207], v[16:19]
	v_mfma_f32_16x16x32_bf16 v[4:7], v[162:165], v[208:211], v[4:7]
	v_mfma_f32_16x16x32_bf16 v[4:7], v[166:169], v[212:215], v[4:7]
	v_mfma_f32_16x16x32_bf16 v[0:3], v[170:173], v[208:211], v[0:3]
	v_mfma_f32_16x16x32_bf16 v[0:3], v[174:177], v[212:215], v[0:3]
	s_setprio 0
	s_add_i32 s74, s74, 2
	s_add_u32 s48, s48, 0x100
	s_addc_u32 s49, s49, 0
	s_add_u32 s72, s72, 0x100
	s_addc_u32 s73, s73, 0
	s_cmp_gt_u32 s74, 13
	s_cbranch_scc0 .LBB0_724
	s_and_b64 vcc, exec, s[16:17]
	s_cbranch_vccz .LBB0_727
	s_barrier

.LBB0_803:
	s_add_u32 s84, s54, 0x100
	s_addc_u32 s85, s55, 0
	s_mov_b32 s86, -2
	ds_read_b128 v[152:155], v149
	ds_read_b128 v[156:159], v149 offset:1024
	ds_read_b128 v[160:163], v149 offset:2048
	ds_read_b128 v[164:167], v149 offset:3072
	ds_read_b128 v[168:171], v150
	ds_read_b128 v[172:175], v150 offset:1024
	ds_read_b128 v[176:179], v150 offset:2048
	ds_read_b128 v[184:187], v150 offset:3072
	s_add_u32 s54, s52, 0x100
	s_addc_u32 s55, s53, 0
	s_cmp_eq_u32 s86, 40
	s_cselect_b32 s59, s13, s55
	s_cselect_b32 s58, s12, s54
	s_cselect_b32 s57, s49, s85
	s_cselect_b32 s56, s48, s84
	v_lshl_add_u64 v[144:145], s[52:53], 0, v[136:137]
	s_add_i32 m0, s63, 0xc000
	ds_read_b128 v[188:191], v151
	ds_read_b128 v[192:195], v151 offset:1024
	ds_read_b128 v[196:199], v151 offset:2048
	ds_read_b128 v[200:203], v151 offset:3072
	ds_read_b128 v[204:207], v151 offset:4096
	ds_read_b128 v[208:211], v151 offset:5120
	ds_read_b128 v[212:215], v151 offset:6144
	ds_read_b128 v[216:219], v151 offset:7168
	global_load_lds_dwordx4 v[144:145], off
	v_lshl_add_u64 v[144:145], s[52:53], 0, v[138:139]
	s_add_i32 m0, s63, 0xe000
	s_nop 0
	global_load_lds_dwordx4 v[144:145], off
	s_waitcnt vmcnt(8)
	s_waitcnt lgkmcnt(0)
	s_barrier
	s_waitcnt lgkmcnt(0)
	v_mfma_f32_16x16x32_bf16 v[124:127], v[152:155], v[188:191], 0
	v_mfma_f32_16x16x32_bf16 v[124:127], v[156:159], v[192:195], v[124:127]
	v_mfma_f32_16x16x32_bf16 v[120:123], v[160:163], v[188:191], 0
	v_mfma_f32_16x16x32_bf16 v[120:123], v[164:167], v[192:195], v[120:123]
	v_mfma_f32_16x16x32_bf16 v[116:119], v[152:155], v[196:199], 0
	v_mfma_f32_16x16x32_bf16 v[116:119], v[156:159], v[200:203], v[116:119]
	v_mfma_f32_16x16x32_bf16 v[108:111], v[160:163], v[196:199], 0
	v_mfma_f32_16x16x32_bf16 v[108:111], v[164:167], v[200:203], v[108:111]
	s_setprio 1
	v_mfma_f32_16x16x32_bf16 v[100:103], v[152:155], v[204:207], 0
	v_mfma_f32_16x16x32_bf16 v[100:103], v[156:159], v[208:211], v[100:103]
	v_mfma_f32_16x16x32_bf16 v[92:95], v[160:163], v[204:207], 0
	v_mfma_f32_16x16x32_bf16 v[92:95], v[164:167], v[208:211], v[92:95]
	v_mfma_f32_16x16x32_bf16 v[84:87], v[152:155], v[212:215], 0
	v_mfma_f32_16x16x32_bf16 v[84:87], v[156:159], v[216:219], v[84:87]
	v_mfma_f32_16x16x32_bf16 v[76:79], v[160:163], v[212:215], 0
	v_mfma_f32_16x16x32_bf16 v[76:79], v[164:167], v[216:219], v[76:79]
	v_mfma_f32_16x16x32_bf16 v[112:115], v[168:171], v[188:191], 0
	v_mfma_f32_16x16x32_bf16 v[112:115], v[172:175], v[192:195], v[112:115]
	v_mfma_f32_16x16x32_bf16 v[104:107], v[176:179], v[188:191], 0
	v_mfma_f32_16x16x32_bf16 v[104:107], v[184:187], v[192:195], v[104:107]
	v_mfma_f32_16x16x32_bf16 v[96:99], v[168:171], v[196:199], 0
	v_mfma_f32_16x16x32_bf16 v[96:99], v[172:175], v[200:203], v[96:99]
	v_mfma_f32_16x16x32_bf16 v[88:91], v[176:179], v[196:199], 0
	v_mfma_f32_16x16x32_bf16 v[88:91], v[184:187], v[200:203], v[88:91]
	s_barrier
	v_mfma_f32_16x16x32_bf16 v[80:83], v[168:171], v[204:207], 0
	v_mfma_f32_16x16x32_bf16 v[80:83], v[172:175], v[208:211], v[80:83]
	v_mfma_f32_16x16x32_bf16 v[72:75], v[176:179], v[204:207], 0
	v_mfma_f32_16x16x32_bf16 v[72:75], v[184:187], v[208:211], v[72:75]
	v_mfma_f32_16x16x32_bf16 v[68:71], v[168:171], v[212:215], 0
	v_mfma_f32_16x16x32_bf16 v[68:71], v[172:175], v[216:219], v[68:71]
	v_mfma_f32_16x16x32_bf16 v[64:67], v[176:179], v[212:215], 0
	v_mfma_f32_16x16x32_bf16 v[64:67], v[184:187], v[216:219], v[64:67]
	s_setprio 0
	s_add_i32 s52, s70, s62
	v_lshl_add_u64 v[144:145], s[56:57], 0, v[130:131]
	s_mov_b32 m0, s52
	ds_read_b128 v[188:191], v151 offset:16384
	ds_read_b128 v[192:195], v151 offset:17408
	ds_read_b128 v[196:199], v151 offset:18432
	ds_read_b128 v[200:203], v151 offset:19456
	ds_read_b128 v[204:207], v151 offset:20480
	ds_read_b128 v[208:211], v151 offset:21504
	ds_read_b128 v[212:215], v151 offset:22528
	ds_read_b128 v[216:219], v151 offset:23552
	global_load_lds_dwordx4 v[144:145], off
	s_add_i32 m0, s52, 0x2000
	s_add_u32 s52, s56, 0xb0000
	v_lshl_add_u64 v[220:221], s[56:57], 0, v[134:135]
	s_addc_u32 s53, s57, 0
	s_add_i32 s79, s71, s62
	global_load_lds_dwordx4 v[220:221], off
	v_lshl_add_u64 v[222:223], s[52:53], 0, v[130:131]
	s_mov_b32 m0, s79
	v_lshl_add_u64 v[224:225], s[58:59], 0, v[132:133]
	global_load_lds_dwordx4 v[222:223], off
	v_lshl_add_u64 v[222:223], s[52:53], 0, v[134:135]
	s_add_i32 m0, s79, 0x2000
	s_nop 0
	global_load_lds_dwordx4 v[222:223], off
	v_lshl_add_u64 v[222:223], s[58:59], 0, v[128:129]
	s_mov_b32 m0, s63
	s_nop 0
	global_load_lds_dwordx4 v[222:223], off
	s_mov_b32 m0, s64
	s_nop 0
	global_load_lds_dwordx4 v[224:225], off
	s_waitcnt vmcnt(8)
	s_waitcnt lgkmcnt(0)
	s_barrier
	s_waitcnt lgkmcnt(0)
	v_mfma_f32_16x16x32_bf16 v[60:63], v[152:155], v[188:191], 0
	v_mfma_f32_16x16x32_bf16 v[60:63], v[156:159], v[192:195], v[60:63]
	v_mfma_f32_16x16x32_bf16 v[56:59], v[160:163], v[188:191], 0
	v_mfma_f32_16x16x32_bf16 v[56:59], v[164:167], v[192:195], v[56:59]
	v_mfma_f32_16x16x32_bf16 v[52:55], v[152:155], v[196:199], 0
	v_mfma_f32_16x16x32_bf16 v[52:55], v[156:159], v[200:203], v[52:55]
	v_mfma_f32_16x16x32_bf16 v[44:47], v[160:163], v[196:199], 0
	v_mfma_f32_16x16x32_bf16 v[44:47], v[164:167], v[200:203], v[44:47]
	s_setprio 1
	v_mfma_f32_16x16x32_bf16 v[36:39], v[152:155], v[204:207], 0
	v_mfma_f32_16x16x32_bf16 v[36:39], v[156:159], v[208:211], v[36:39]
	v_mfma_f32_16x16x32_bf16 v[28:31], v[160:163], v[204:207], 0
	v_mfma_f32_16x16x32_bf16 v[28:31], v[164:167], v[208:211], v[28:31]
	v_mfma_f32_16x16x32_bf16 v[20:23], v[152:155], v[212:215], 0
	v_mfma_f32_16x16x32_bf16 v[20:23], v[156:159], v[216:219], v[20:23]
	v_mfma_f32_16x16x32_bf16 v[12:15], v[160:163], v[212:215], 0
	v_mfma_f32_16x16x32_bf16 v[12:15], v[164:167], v[216:219], v[12:15]
	v_mfma_f32_16x16x32_bf16 v[48:51], v[168:171], v[188:191], 0
	v_mfma_f32_16x16x32_bf16 v[48:51], v[172:175], v[192:195], v[48:51]
	v_mfma_f32_16x16x32_bf16 v[40:43], v[176:179], v[188:191], 0
	v_mfma_f32_16x16x32_bf16 v[40:43], v[184:187], v[192:195], v[40:43]
	v_mfma_f32_16x16x32_bf16 v[32:35], v[168:171], v[196:199], 0
	v_mfma_f32_16x16x32_bf16 v[32:35], v[172:175], v[200:203], v[32:35]
	v_mfma_f32_16x16x32_bf16 v[24:27], v[176:179], v[196:199], 0
	v_mfma_f32_16x16x32_bf16 v[24:27], v[184:187], v[200:203], v[24:27]
	s_barrier
	v_mfma_f32_16x16x32_bf16 v[16:19], v[168:171], v[204:207], 0
	v_mfma_f32_16x16x32_bf16 v[16:19], v[172:175], v[208:211], v[16:19]
	v_mfma_f32_16x16x32_bf16 v[8:11], v[176:179], v[204:207], 0
	v_mfma_f32_16x16x32_bf16 v[8:11], v[184:187], v[208:211], v[8:11]
	v_mfma_f32_16x16x32_bf16 v[4:7], v[168:171], v[212:215], 0
	v_mfma_f32_16x16x32_bf16 v[4:7], v[172:175], v[216:219], v[4:7]
	v_mfma_f32_16x16x32_bf16 v[0:3], v[176:179], v[212:215], 0
	v_mfma_f32_16x16x32_bf16 v[0:3], v[184:187], v[216:219], v[0:3]
	s_setprio 0
	s_branch .Lmid_gemm5
.LBB0_804:
	ds_read_b128 v[152:155], v149
	ds_read_b128 v[156:159], v149 offset:1024
	ds_read_b128 v[160:163], v149 offset:2048
	ds_read_b128 v[164:167], v149 offset:3072
	ds_read_b128 v[168:171], v150
	ds_read_b128 v[172:175], v150 offset:1024
	ds_read_b128 v[176:179], v150 offset:2048
	ds_read_b128 v[184:187], v150 offset:3072
	s_add_u32 s54, s52, 0x100
	s_addc_u32 s55, s53, 0
	s_cmp_eq_u32 s86, 40
	s_cselect_b32 s59, s13, s55
	s_cselect_b32 s58, s12, s54
	s_cselect_b32 s57, s49, s85
	s_cselect_b32 s56, s48, s84
	v_lshl_add_u64 v[144:145], s[52:53], 0, v[136:137]
	s_add_i32 m0, s63, 0xc000
	ds_read_b128 v[188:191], v151
	ds_read_b128 v[192:195], v151 offset:1024
	ds_read_b128 v[196:199], v151 offset:2048
	ds_read_b128 v[200:203], v151 offset:3072
	ds_read_b128 v[204:207], v151 offset:4096
	ds_read_b128 v[208:211], v151 offset:5120
	ds_read_b128 v[212:215], v151 offset:6144
	ds_read_b128 v[216:219], v151 offset:7168
	global_load_lds_dwordx4 v[144:145], off
	v_lshl_add_u64 v[144:145], s[52:53], 0, v[138:139]
	s_add_i32 m0, s63, 0xe000
	s_nop 0
	global_load_lds_dwordx4 v[144:145], off
	s_waitcnt vmcnt(8)
	s_waitcnt lgkmcnt(0)
	s_barrier
	s_waitcnt lgkmcnt(0)
	v_mfma_f32_16x16x32_bf16 v[124:127], v[152:155], v[188:191], v[124:127]
	v_mfma_f32_16x16x32_bf16 v[124:127], v[156:159], v[192:195], v[124:127]
	v_mfma_f32_16x16x32_bf16 v[120:123], v[160:163], v[188:191], v[120:123]
	v_mfma_f32_16x16x32_bf16 v[120:123], v[164:167], v[192:195], v[120:123]
	v_mfma_f32_16x16x32_bf16 v[116:119], v[152:155], v[196:199], v[116:119]
	v_mfma_f32_16x16x32_bf16 v[116:119], v[156:159], v[200:203], v[116:119]
	v_mfma_f32_16x16x32_bf16 v[108:111], v[160:163], v[196:199], v[108:111]
	v_mfma_f32_16x16x32_bf16 v[108:111], v[164:167], v[200:203], v[108:111]
	s_setprio 1
	v_mfma_f32_16x16x32_bf16 v[100:103], v[152:155], v[204:207], v[100:103]
	v_mfma_f32_16x16x32_bf16 v[100:103], v[156:159], v[208:211], v[100:103]
	v_mfma_f32_16x16x32_bf16 v[92:95], v[160:163], v[204:207], v[92:95]
	v_mfma_f32_16x16x32_bf16 v[92:95], v[164:167], v[208:211], v[92:95]
	v_mfma_f32_16x16x32_bf16 v[84:87], v[152:155], v[212:215], v[84:87]
	v_mfma_f32_16x16x32_bf16 v[84:87], v[156:159], v[216:219], v[84:87]
	v_mfma_f32_16x16x32_bf16 v[76:79], v[160:163], v[212:215], v[76:79]
	v_mfma_f32_16x16x32_bf16 v[76:79], v[164:167], v[216:219], v[76:79]
	v_mfma_f32_16x16x32_bf16 v[112:115], v[168:171], v[188:191], v[112:115]
	v_mfma_f32_16x16x32_bf16 v[112:115], v[172:175], v[192:195], v[112:115]
	v_mfma_f32_16x16x32_bf16 v[104:107], v[176:179], v[188:191], v[104:107]
	v_mfma_f32_16x16x32_bf16 v[104:107], v[184:187], v[192:195], v[104:107]
	v_mfma_f32_16x16x32_bf16 v[96:99], v[168:171], v[196:199], v[96:99]
	v_mfma_f32_16x16x32_bf16 v[96:99], v[172:175], v[200:203], v[96:99]
	v_mfma_f32_16x16x32_bf16 v[88:91], v[176:179], v[196:199], v[88:91]
	v_mfma_f32_16x16x32_bf16 v[88:91], v[184:187], v[200:203], v[88:91]
	s_barrier
	v_mfma_f32_16x16x32_bf16 v[80:83], v[168:171], v[204:207], v[80:83]
	v_mfma_f32_16x16x32_bf16 v[80:83], v[172:175], v[208:211], v[80:83]
	v_mfma_f32_16x16x32_bf16 v[72:75], v[176:179], v[204:207], v[72:75]
	v_mfma_f32_16x16x32_bf16 v[72:75], v[184:187], v[208:211], v[72:75]
	v_mfma_f32_16x16x32_bf16 v[68:71], v[168:171], v[212:215], v[68:71]
	v_mfma_f32_16x16x32_bf16 v[68:71], v[172:175], v[216:219], v[68:71]
	v_mfma_f32_16x16x32_bf16 v[64:67], v[176:179], v[212:215], v[64:67]
	v_mfma_f32_16x16x32_bf16 v[64:67], v[184:187], v[216:219], v[64:67]
	s_setprio 0
	s_add_i32 s52, s70, s62
	v_lshl_add_u64 v[144:145], s[56:57], 0, v[130:131]
	s_mov_b32 m0, s52
	ds_read_b128 v[188:191], v151 offset:16384
	ds_read_b128 v[192:195], v151 offset:17408
	ds_read_b128 v[196:199], v151 offset:18432
	ds_read_b128 v[200:203], v151 offset:19456
	ds_read_b128 v[204:207], v151 offset:20480
	ds_read_b128 v[208:211], v151 offset:21504
	ds_read_b128 v[212:215], v151 offset:22528
	ds_read_b128 v[216:219], v151 offset:23552
	global_load_lds_dwordx4 v[144:145], off
	s_add_i32 m0, s52, 0x2000
	s_add_u32 s52, s56, 0xb0000
	v_lshl_add_u64 v[220:221], s[56:57], 0, v[134:135]
	s_addc_u32 s53, s57, 0
	s_add_i32 s79, s71, s62
	global_load_lds_dwordx4 v[220:221], off
	v_lshl_add_u64 v[222:223], s[52:53], 0, v[130:131]
	s_mov_b32 m0, s79
	v_lshl_add_u64 v[224:225], s[58:59], 0, v[132:133]
	global_load_lds_dwordx4 v[222:223], off
	v_lshl_add_u64 v[222:223], s[52:53], 0, v[134:135]
	s_add_i32 m0, s79, 0x2000
	s_nop 0
	global_load_lds_dwordx4 v[222:223], off
	v_lshl_add_u64 v[222:223], s[58:59], 0, v[128:129]
	s_mov_b32 m0, s63
	s_nop 0
	global_load_lds_dwordx4 v[222:223], off
	s_mov_b32 m0, s64
	s_nop 0
	global_load_lds_dwordx4 v[224:225], off
	s_waitcnt vmcnt(8)
	s_waitcnt lgkmcnt(0)
	s_barrier
	s_waitcnt lgkmcnt(0)
	v_mfma_f32_16x16x32_bf16 v[60:63], v[152:155], v[188:191], v[60:63]
	v_mfma_f32_16x16x32_bf16 v[60:63], v[156:159], v[192:195], v[60:63]
	v_mfma_f32_16x16x32_bf16 v[56:59], v[160:163], v[188:191], v[56:59]
	v_mfma_f32_16x16x32_bf16 v[56:59], v[164:167], v[192:195], v[56:59]
	v_mfma_f32_16x16x32_bf16 v[52:55], v[152:155], v[196:199], v[52:55]
	v_mfma_f32_16x16x32_bf16 v[52:55], v[156:159], v[200:203], v[52:55]
	v_mfma_f32_16x16x32_bf16 v[44:47], v[160:163], v[196:199], v[44:47]
	v_mfma_f32_16x16x32_bf16 v[44:47], v[164:167], v[200:203], v[44:47]
	s_setprio 1
	v_mfma_f32_16x16x32_bf16 v[36:39], v[152:155], v[204:207], v[36:39]
	v_mfma_f32_16x16x32_bf16 v[36:39], v[156:159], v[208:211], v[36:39]
	v_mfma_f32_16x16x32_bf16 v[28:31], v[160:163], v[204:207], v[28:31]
	v_mfma_f32_16x16x32_bf16 v[28:31], v[164:167], v[208:211], v[28:31]
	v_mfma_f32_16x16x32_bf16 v[20:23], v[152:155], v[212:215], v[20:23]
	v_mfma_f32_16x16x32_bf16 v[20:23], v[156:159], v[216:219], v[20:23]
	v_mfma_f32_16x16x32_bf16 v[12:15], v[160:163], v[212:215], v[12:15]
	v_mfma_f32_16x16x32_bf16 v[12:15], v[164:167], v[216:219], v[12:15]
	v_mfma_f32_16x16x32_bf16 v[48:51], v[168:171], v[188:191], v[48:51]
	v_mfma_f32_16x16x32_bf16 v[48:51], v[172:175], v[192:195], v[48:51]
	v_mfma_f32_16x16x32_bf16 v[40:43], v[176:179], v[188:191], v[40:43]
	v_mfma_f32_16x16x32_bf16 v[40:43], v[184:187], v[192:195], v[40:43]
	v_mfma_f32_16x16x32_bf16 v[32:35], v[168:171], v[196:199], v[32:35]
	v_mfma_f32_16x16x32_bf16 v[32:35], v[172:175], v[200:203], v[32:35]
	v_mfma_f32_16x16x32_bf16 v[24:27], v[176:179], v[196:199], v[24:27]
	v_mfma_f32_16x16x32_bf16 v[24:27], v[184:187], v[200:203], v[24:27]
	s_barrier
	v_mfma_f32_16x16x32_bf16 v[16:19], v[168:171], v[204:207], v[16:19]
	v_mfma_f32_16x16x32_bf16 v[16:19], v[172:175], v[208:211], v[16:19]
	v_mfma_f32_16x16x32_bf16 v[8:11], v[176:179], v[204:207], v[8:11]
	v_mfma_f32_16x16x32_bf16 v[8:11], v[184:187], v[208:211], v[8:11]
	v_mfma_f32_16x16x32_bf16 v[4:7], v[168:171], v[212:215], v[4:7]
	v_mfma_f32_16x16x32_bf16 v[4:7], v[172:175], v[216:219], v[4:7]
	v_mfma_f32_16x16x32_bf16 v[0:3], v[176:179], v[212:215], v[0:3]
	v_mfma_f32_16x16x32_bf16 v[0:3], v[184:187], v[216:219], v[0:3]
	s_setprio 0
.Lmid_gemm5:
	s_add_i32 s79, 0, 0x18000
	s_add_i32 s87, 0, 0x1c000
	v_add_u32_e32 v164, s79, v147
	v_add_u32_e32 v181, s87, v147
	ds_read_b128 v[152:155], v164
	ds_read_b128 v[156:159], v164 offset:1024
	ds_read_b128 v[160:163], v164 offset:2048
	ds_read_b128 v[164:167], v164 offset:3072
	ds_read_b128 v[168:171], v181
	ds_read_b128 v[172:175], v181 offset:1024
	ds_read_b128 v[176:179], v181 offset:2048
	ds_read_b128 v[184:187], v181 offset:3072
	s_add_u32 s52, s58, 0xb0000
	s_addc_u32 s53, s59, 0
	s_mov_b32 m0, s65
	v_lshl_add_u64 v[226:227], s[52:53], 0, v[128:129]
	ds_read_b128 v[188:191], v151 offset:32768
	ds_read_b128 v[192:195], v151 offset:33792
	ds_read_b128 v[196:199], v151 offset:34816
	ds_read_b128 v[200:203], v151 offset:35840
	ds_read_b128 v[204:207], v151 offset:36864
	ds_read_b128 v[208:211], v151 offset:37888
	ds_read_b128 v[212:215], v151 offset:38912
	ds_read_b128 v[216:219], v151 offset:39936
	global_load_lds_dwordx4 v[226:227], off
	v_lshl_add_u64 v[226:227], s[52:53], 0, v[132:133]
	s_mov_b32 m0, s66
	s_nop 0
	global_load_lds_dwordx4 v[226:227], off
	s_waitcnt vmcnt(8)
	s_waitcnt lgkmcnt(0)
	s_barrier
	s_waitcnt lgkmcnt(0)
	v_mfma_f32_16x16x32_bf16 v[124:127], v[152:155], v[188:191], v[124:127]
	v_mfma_f32_16x16x32_bf16 v[124:127], v[156:159], v[192:195], v[124:127]
	v_mfma_f32_16x16x32_bf16 v[120:123], v[160:163], v[188:191], v[120:123]
	v_mfma_f32_16x16x32_bf16 v[120:123], v[164:167], v[192:195], v[120:123]
	v_mfma_f32_16x16x32_bf16 v[116:119], v[152:155], v[196:199], v[116:119]
	v_mfma_f32_16x16x32_bf16 v[116:119], v[156:159], v[200:203], v[116:119]
	v_mfma_f32_16x16x32_bf16 v[108:111], v[160:163], v[196:199], v[108:111]
	v_mfma_f32_16x16x32_bf16 v[108:111], v[164:167], v[200:203], v[108:111]
	s_setprio 1
	v_mfma_f32_16x16x32_bf16 v[100:103], v[152:155], v[204:207], v[100:103]
	v_mfma_f32_16x16x32_bf16 v[100:103], v[156:159], v[208:211], v[100:103]
	v_mfma_f32_16x16x32_bf16 v[92:95], v[160:163], v[204:207], v[92:95]
	v_mfma_f32_16x16x32_bf16 v[92:95], v[164:167], v[208:211], v[92:95]
	v_mfma_f32_16x16x32_bf16 v[84:87], v[152:155], v[212:215], v[84:87]
	v_mfma_f32_16x16x32_bf16 v[84:87], v[156:159], v[216:219], v[84:87]
	v_mfma_f32_16x16x32_bf16 v[76:79], v[160:163], v[212:215], v[76:79]
	v_mfma_f32_16x16x32_bf16 v[76:79], v[164:167], v[216:219], v[76:79]
	v_mfma_f32_16x16x32_bf16 v[112:115], v[168:171], v[188:191], v[112:115]
	v_mfma_f32_16x16x32_bf16 v[112:115], v[172:175], v[192:195], v[112:115]
	v_mfma_f32_16x16x32_bf16 v[104:107], v[176:179], v[188:191], v[104:107]
	v_mfma_f32_16x16x32_bf16 v[104:107], v[184:187], v[192:195], v[104:107]
	v_mfma_f32_16x16x32_bf16 v[96:99], v[168:171], v[196:199], v[96:99]
	v_mfma_f32_16x16x32_bf16 v[96:99], v[172:175], v[200:203], v[96:99]
	v_mfma_f32_16x16x32_bf16 v[88:91], v[176:179], v[196:199], v[88:91]
	v_mfma_f32_16x16x32_bf16 v[88:91], v[184:187], v[200:203], v[88:91]
	s_barrier
	v_mfma_f32_16x16x32_bf16 v[80:83], v[168:171], v[204:207], v[80:83]
	v_mfma_f32_16x16x32_bf16 v[80:83], v[172:175], v[208:211], v[80:83]
	v_mfma_f32_16x16x32_bf16 v[72:75], v[176:179], v[204:207], v[72:75]
	v_mfma_f32_16x16x32_bf16 v[72:75], v[184:187], v[208:211], v[72:75]
	v_mfma_f32_16x16x32_bf16 v[68:71], v[168:171], v[212:215], v[68:71]
	v_mfma_f32_16x16x32_bf16 v[68:71], v[172:175], v[216:219], v[68:71]
	v_mfma_f32_16x16x32_bf16 v[64:67], v[176:179], v[212:215], v[64:67]
	v_mfma_f32_16x16x32_bf16 v[64:67], v[184:187], v[216:219], v[64:67]
	s_setprio 0
	s_add_i32 s52, s79, s62
	v_lshl_add_u64 v[144:145], v[144:145], 0, s[16:17]
	s_mov_b32 m0, s52
	ds_read_b128 v[188:191], v151 offset:49152
	ds_read_b128 v[192:195], v151 offset:50176
	ds_read_b128 v[196:199], v151 offset:51200
	ds_read_b128 v[200:203], v151 offset:52224
	ds_read_b128 v[204:207], v151 offset:53248
	ds_read_b128 v[208:211], v151 offset:54272
	ds_read_b128 v[212:215], v151 offset:55296
	ds_read_b128 v[216:219], v151 offset:56320
	global_load_lds_dwordx4 v[144:145], off
	s_add_i32 m0, s52, 0x2000
	s_add_u32 s52, s56, 0xb0080
	v_lshl_add_u64 v[144:145], v[220:221], 0, s[16:17]
	s_addc_u32 s53, s57, 0
	s_add_i32 s56, s87, s62
	global_load_lds_dwordx4 v[144:145], off
	v_lshl_add_u64 v[144:145], s[52:53], 0, v[130:131]
	s_mov_b32 m0, s56
	s_nop 0
	global_load_lds_dwordx4 v[144:145], off
	v_lshl_add_u64 v[144:145], s[52:53], 0, v[134:135]
	s_add_i32 m0, s56, 0x2000
	s_nop 0
	global_load_lds_dwordx4 v[144:145], off
	v_lshl_add_u64 v[144:145], v[222:223], 0, s[16:17]
	s_mov_b32 m0, s68
	s_nop 0
	global_load_lds_dwordx4 v[144:145], off
	v_lshl_add_u64 v[144:145], v[224:225], 0, s[16:17]
	s_mov_b32 m0, s69
	s_nop 0
	global_load_lds_dwordx4 v[144:145], off
	s_waitcnt vmcnt(8)
	s_waitcnt lgkmcnt(0)
	s_barrier
	s_waitcnt lgkmcnt(0)
	v_mfma_f32_16x16x32_bf16 v[60:63], v[152:155], v[188:191], v[60:63]
	v_mfma_f32_16x16x32_bf16 v[60:63], v[156:159], v[192:195], v[60:63]
	v_mfma_f32_16x16x32_bf16 v[56:59], v[160:163], v[188:191], v[56:59]
	v_mfma_f32_16x16x32_bf16 v[56:59], v[164:167], v[192:195], v[56:59]
	v_mfma_f32_16x16x32_bf16 v[52:55], v[152:155], v[196:199], v[52:55]
	v_mfma_f32_16x16x32_bf16 v[52:55], v[156:159], v[200:203], v[52:55]
	v_mfma_f32_16x16x32_bf16 v[44:47], v[160:163], v[196:199], v[44:47]
	v_mfma_f32_16x16x32_bf16 v[44:47], v[164:167], v[200:203], v[44:47]
	s_setprio 1
	v_mfma_f32_16x16x32_bf16 v[36:39], v[152:155], v[204:207], v[36:39]
	v_mfma_f32_16x16x32_bf16 v[36:39], v[156:159], v[208:211], v[36:39]
	v_mfma_f32_16x16x32_bf16 v[28:31], v[160:163], v[204:207], v[28:31]
	v_mfma_f32_16x16x32_bf16 v[28:31], v[164:167], v[208:211], v[28:31]
	v_mfma_f32_16x16x32_bf16 v[20:23], v[152:155], v[212:215], v[20:23]
	v_mfma_f32_16x16x32_bf16 v[20:23], v[156:159], v[216:219], v[20:23]
	v_mfma_f32_16x16x32_bf16 v[12:15], v[160:163], v[212:215], v[12:15]
	v_mfma_f32_16x16x32_bf16 v[12:15], v[164:167], v[216:219], v[12:15]
	v_mfma_f32_16x16x32_bf16 v[48:51], v[168:171], v[188:191], v[48:51]
	v_mfma_f32_16x16x32_bf16 v[48:51], v[172:175], v[192:195], v[48:51]
	v_mfma_f32_16x16x32_bf16 v[40:43], v[176:179], v[188:191], v[40:43]
	v_mfma_f32_16x16x32_bf16 v[40:43], v[184:187], v[192:195], v[40:43]
	v_mfma_f32_16x16x32_bf16 v[32:35], v[168:171], v[196:199], v[32:35]
	v_mfma_f32_16x16x32_bf16 v[32:35], v[172:175], v[200:203], v[32:35]
	v_mfma_f32_16x16x32_bf16 v[24:27], v[176:179], v[196:199], v[24:27]
	v_mfma_f32_16x16x32_bf16 v[24:27], v[184:187], v[200:203], v[24:27]
	s_barrier
	v_mfma_f32_16x16x32_bf16 v[16:19], v[168:171], v[204:207], v[16:19]
	v_mfma_f32_16x16x32_bf16 v[16:19], v[172:175], v[208:211], v[16:19]
	v_mfma_f32_16x16x32_bf16 v[8:11], v[176:179], v[204:207], v[8:11]
	v_mfma_f32_16x16x32_bf16 v[8:11], v[184:187], v[208:211], v[8:11]
	v_mfma_f32_16x16x32_bf16 v[4:7], v[168:171], v[212:215], v[4:7]
	v_mfma_f32_16x16x32_bf16 v[4:7], v[172:175], v[216:219], v[4:7]
	v_mfma_f32_16x16x32_bf16 v[0:3], v[176:179], v[212:215], v[0:3]
	v_mfma_f32_16x16x32_bf16 v[0:3], v[184:187], v[216:219], v[0:3]
	s_setprio 0
	s_add_i32 s86, s86, 2
	s_add_u32 s84, s84, 0x100
	s_addc_u32 s85, s85, 0
	s_cmp_gt_u32 s86, 41
	s_mov_b64 s[52:53], s[54:55]
	s_cbranch_scc0 .LBB0_804
	s_and_b64 vcc, exec, s[18:19]
	s_cbranch_vccz .LBB0_807
	s_barrier

.LBB0_934:
	s_ashr_i32 s53, s52, 31
	s_lshl_b64 s[54:55], s[52:53], 19
	s_add_u32 s54, s80, s54
	s_addc_u32 s55, s81, s55
	s_and_b64 s[56:57], s[10:11], exec
	s_cselect_b32 s53, s55, s61
	s_cselect_b32 s83, s54, s60
	s_ashr_i32 s49, s48, 31
	s_lshl_b64 s[56:57], s[48:49], 19
	s_add_u32 s56, s66, s56
	s_addc_u32 s57, s67, s57
	s_and_b64 s[64:65], s[10:11], exec
	s_cselect_b32 s49, s57, s63
	s_cselect_b32 s84, s56, s62
	s_add_u32 s60, s60, 0x40080
	s_addc_u32 s61, s61, 0
	s_add_u32 s85, s62, 0x100
	s_addc_u32 s86, s63, 0
	s_mov_b32 s87, -2
	ds_read_b128 v[152:155], v148
	ds_read_b128 v[156:159], v148 offset:1024
	ds_read_b128 v[160:163], v148 offset:2048
	ds_read_b128 v[164:167], v148 offset:3072
	ds_read_b128 v[168:171], v149
	ds_read_b128 v[172:175], v149 offset:1024
	ds_read_b128 v[176:179], v149 offset:2048
	ds_read_b128 v[184:187], v149 offset:3072
	s_add_u32 s62, s60, 0xfffc0080
	s_addc_u32 s63, s61, -1
	s_cmp_eq_u32 s87, 12
	s_cselect_b32 s65, s53, s63
	s_cselect_b32 s64, s83, s62
	s_cselect_b32 s63, s49, s86
	s_cselect_b32 s62, s84, s85
	v_lshl_add_u64 v[220:221], s[60:61], 0, v[138:139]
	s_add_i32 m0, s69, 0xc000
	ds_read_b128 v[188:191], v150
	ds_read_b128 v[192:195], v150 offset:1024
	ds_read_b128 v[196:199], v150 offset:2048
	ds_read_b128 v[200:203], v150 offset:3072
	ds_read_b128 v[204:207], v150 offset:4096
	ds_read_b128 v[208:211], v150 offset:5120
	ds_read_b128 v[212:215], v150 offset:6144
	ds_read_b128 v[216:219], v150 offset:7168
	global_load_lds_dwordx4 v[220:221], off
	v_lshl_add_u64 v[220:221], s[60:61], 0, v[140:141]
	s_add_i32 m0, s69, 0xe000
	s_nop 0
	global_load_lds_dwordx4 v[220:221], off
	s_waitcnt vmcnt(8)
	s_waitcnt lgkmcnt(0)
	s_barrier
	s_waitcnt lgkmcnt(0)
	v_mfma_f32_16x16x32_bf16 v[124:127], v[152:155], v[188:191], 0
	v_mfma_f32_16x16x32_bf16 v[124:127], v[156:159], v[192:195], v[124:127]
	v_mfma_f32_16x16x32_bf16 v[120:123], v[160:163], v[188:191], 0
	v_mfma_f32_16x16x32_bf16 v[120:123], v[164:167], v[192:195], v[120:123]
	v_mfma_f32_16x16x32_bf16 v[116:119], v[152:155], v[196:199], 0
	v_mfma_f32_16x16x32_bf16 v[116:119], v[156:159], v[200:203], v[116:119]
	v_mfma_f32_16x16x32_bf16 v[112:115], v[160:163], v[196:199], 0
	v_mfma_f32_16x16x32_bf16 v[112:115], v[164:167], v[200:203], v[112:115]
	s_setprio 1
	v_mfma_f32_16x16x32_bf16 v[108:111], v[152:155], v[204:207], 0
	v_mfma_f32_16x16x32_bf16 v[108:111], v[156:159], v[208:211], v[108:111]
	v_mfma_f32_16x16x32_bf16 v[104:107], v[160:163], v[204:207], 0
	v_mfma_f32_16x16x32_bf16 v[104:107], v[164:167], v[208:211], v[104:107]
	v_mfma_f32_16x16x32_bf16 v[100:103], v[152:155], v[212:215], 0
	v_mfma_f32_16x16x32_bf16 v[100:103], v[156:159], v[216:219], v[100:103]
	v_mfma_f32_16x16x32_bf16 v[96:99], v[160:163], v[212:215], 0
	v_mfma_f32_16x16x32_bf16 v[96:99], v[164:167], v[216:219], v[96:99]
	v_mfma_f32_16x16x32_bf16 v[76:79], v[168:171], v[188:191], 0
	v_mfma_f32_16x16x32_bf16 v[76:79], v[172:175], v[192:195], v[76:79]
	v_mfma_f32_16x16x32_bf16 v[68:71], v[176:179], v[188:191], 0
	v_mfma_f32_16x16x32_bf16 v[68:71], v[184:187], v[192:195], v[68:71]
	v_mfma_f32_16x16x32_bf16 v[60:63], v[168:171], v[196:199], 0
	v_mfma_f32_16x16x32_bf16 v[60:63], v[172:175], v[200:203], v[60:63]
	v_mfma_f32_16x16x32_bf16 v[52:55], v[176:179], v[196:199], 0
	v_mfma_f32_16x16x32_bf16 v[52:55], v[184:187], v[200:203], v[52:55]
	s_barrier
	v_mfma_f32_16x16x32_bf16 v[44:47], v[168:171], v[204:207], 0
	v_mfma_f32_16x16x32_bf16 v[44:47], v[172:175], v[208:211], v[44:47]
	v_mfma_f32_16x16x32_bf16 v[40:43], v[176:179], v[204:207], 0
	v_mfma_f32_16x16x32_bf16 v[40:43], v[184:187], v[208:211], v[40:43]
	v_mfma_f32_16x16x32_bf16 v[36:39], v[168:171], v[212:215], 0
	v_mfma_f32_16x16x32_bf16 v[36:39], v[172:175], v[216:219], v[36:39]
	v_mfma_f32_16x16x32_bf16 v[32:35], v[176:179], v[212:215], 0
	v_mfma_f32_16x16x32_bf16 v[32:35], v[184:187], v[216:219], v[32:35]
	s_setprio 0
	s_add_i32 s79, s77, s68
	v_lshl_add_u64 v[220:221], s[62:63], 0, v[130:131]
	s_mov_b32 m0, s79
	ds_read_b128 v[188:191], v150 offset:16384
	ds_read_b128 v[192:195], v150 offset:17408
	ds_read_b128 v[196:199], v150 offset:18432
	ds_read_b128 v[200:203], v150 offset:19456
	ds_read_b128 v[204:207], v150 offset:20480
	ds_read_b128 v[208:211], v150 offset:21504
	ds_read_b128 v[212:215], v150 offset:22528
	ds_read_b128 v[216:219], v150 offset:23552
	global_load_lds_dwordx4 v[220:221], off
	s_add_i32 m0, s79, 0x2000
	s_add_u32 s88, s62, 0x40000
	v_lshl_add_u64 v[222:223], s[62:63], 0, v[134:135]
	s_addc_u32 s89, s63, 0
	s_add_i32 s79, s82, s68
	global_load_lds_dwordx4 v[222:223], off
	v_lshl_add_u64 v[224:225], s[88:89], 0, v[130:131]
	s_mov_b32 m0, s79
	v_lshl_add_u64 v[226:227], s[64:65], 0, v[132:133]
	global_load_lds_dwordx4 v[224:225], off
	v_lshl_add_u64 v[224:225], s[88:89], 0, v[134:135]
	s_add_i32 m0, s79, 0x2000
	s_nop 0
	global_load_lds_dwordx4 v[224:225], off
	v_lshl_add_u64 v[224:225], s[64:65], 0, v[128:129]
	s_mov_b32 m0, s69
	s_nop 0
	global_load_lds_dwordx4 v[224:225], off
	s_mov_b32 m0, s70
	s_nop 0
	global_load_lds_dwordx4 v[226:227], off
	s_waitcnt vmcnt(8)
	s_waitcnt lgkmcnt(0)
	s_barrier
	s_waitcnt lgkmcnt(0)
	v_mfma_f32_16x16x32_bf16 v[92:95], v[152:155], v[188:191], 0
	v_mfma_f32_16x16x32_bf16 v[92:95], v[156:159], v[192:195], v[92:95]
	v_mfma_f32_16x16x32_bf16 v[88:91], v[160:163], v[188:191], 0
	v_mfma_f32_16x16x32_bf16 v[88:91], v[164:167], v[192:195], v[88:91]
	v_mfma_f32_16x16x32_bf16 v[84:87], v[152:155], v[196:199], 0
	v_mfma_f32_16x16x32_bf16 v[84:87], v[156:159], v[200:203], v[84:87]
	v_mfma_f32_16x16x32_bf16 v[80:83], v[160:163], v[196:199], 0
	v_mfma_f32_16x16x32_bf16 v[80:83], v[164:167], v[200:203], v[80:83]
	s_setprio 1
	v_mfma_f32_16x16x32_bf16 v[72:75], v[152:155], v[204:207], 0
	v_mfma_f32_16x16x32_bf16 v[72:75], v[156:159], v[208:211], v[72:75]
	v_mfma_f32_16x16x32_bf16 v[64:67], v[160:163], v[204:207], 0
	v_mfma_f32_16x16x32_bf16 v[64:67], v[164:167], v[208:211], v[64:67]
	v_mfma_f32_16x16x32_bf16 v[56:59], v[152:155], v[212:215], 0
	v_mfma_f32_16x16x32_bf16 v[56:59], v[156:159], v[216:219], v[56:59]
	v_mfma_f32_16x16x32_bf16 v[48:51], v[160:163], v[212:215], 0
	v_mfma_f32_16x16x32_bf16 v[48:51], v[164:167], v[216:219], v[48:51]
	v_mfma_f32_16x16x32_bf16 v[28:31], v[168:171], v[188:191], 0
	v_mfma_f32_16x16x32_bf16 v[28:31], v[172:175], v[192:195], v[28:31]
	v_mfma_f32_16x16x32_bf16 v[24:27], v[176:179], v[188:191], 0
	v_mfma_f32_16x16x32_bf16 v[24:27], v[184:187], v[192:195], v[24:27]
	v_mfma_f32_16x16x32_bf16 v[20:23], v[168:171], v[196:199], 0
	v_mfma_f32_16x16x32_bf16 v[20:23], v[172:175], v[200:203], v[20:23]
	v_mfma_f32_16x16x32_bf16 v[16:19], v[176:179], v[196:199], 0
	v_mfma_f32_16x16x32_bf16 v[16:19], v[184:187], v[200:203], v[16:19]
	s_barrier
	v_mfma_f32_16x16x32_bf16 v[12:15], v[168:171], v[204:207], 0
	v_mfma_f32_16x16x32_bf16 v[12:15], v[172:175], v[208:211], v[12:15]
	v_mfma_f32_16x16x32_bf16 v[8:11], v[176:179], v[204:207], 0
	v_mfma_f32_16x16x32_bf16 v[8:11], v[184:187], v[208:211], v[8:11]
	v_mfma_f32_16x16x32_bf16 v[4:7], v[168:171], v[212:215], 0
	v_mfma_f32_16x16x32_bf16 v[4:7], v[172:175], v[216:219], v[4:7]
	v_mfma_f32_16x16x32_bf16 v[0:3], v[176:179], v[212:215], 0
	v_mfma_f32_16x16x32_bf16 v[0:3], v[184:187], v[216:219], v[0:3]
	s_setprio 0
	s_branch .Lmid_gemm6
.LBB0_935:
	ds_read_b128 v[152:155], v148
	ds_read_b128 v[156:159], v148 offset:1024
	ds_read_b128 v[160:163], v148 offset:2048
	ds_read_b128 v[164:167], v148 offset:3072
	ds_read_b128 v[168:171], v149
	ds_read_b128 v[172:175], v149 offset:1024
	ds_read_b128 v[176:179], v149 offset:2048
	ds_read_b128 v[184:187], v149 offset:3072
	s_add_u32 s62, s60, 0xfffc0080
	s_addc_u32 s63, s61, -1
	s_cmp_eq_u32 s87, 12
	s_cselect_b32 s65, s53, s63
	s_cselect_b32 s64, s83, s62
	s_cselect_b32 s63, s49, s86
	s_cselect_b32 s62, s84, s85
	v_lshl_add_u64 v[220:221], s[60:61], 0, v[138:139]
	s_add_i32 m0, s69, 0xc000
	ds_read_b128 v[188:191], v150
	ds_read_b128 v[192:195], v150 offset:1024
	ds_read_b128 v[196:199], v150 offset:2048
	ds_read_b128 v[200:203], v150 offset:3072
	ds_read_b128 v[204:207], v150 offset:4096
	ds_read_b128 v[208:211], v150 offset:5120
	ds_read_b128 v[212:215], v150 offset:6144
	ds_read_b128 v[216:219], v150 offset:7168
	global_load_lds_dwordx4 v[220:221], off
	v_lshl_add_u64 v[220:221], s[60:61], 0, v[140:141]
	s_add_i32 m0, s69, 0xe000
	s_nop 0
	global_load_lds_dwordx4 v[220:221], off
	s_waitcnt vmcnt(8)
	s_waitcnt lgkmcnt(0)
	s_barrier
	s_waitcnt lgkmcnt(0)
	v_mfma_f32_16x16x32_bf16 v[124:127], v[152:155], v[188:191], v[124:127]
	v_mfma_f32_16x16x32_bf16 v[124:127], v[156:159], v[192:195], v[124:127]
	v_mfma_f32_16x16x32_bf16 v[120:123], v[160:163], v[188:191], v[120:123]
	v_mfma_f32_16x16x32_bf16 v[120:123], v[164:167], v[192:195], v[120:123]
	v_mfma_f32_16x16x32_bf16 v[116:119], v[152:155], v[196:199], v[116:119]
	v_mfma_f32_16x16x32_bf16 v[116:119], v[156:159], v[200:203], v[116:119]
	v_mfma_f32_16x16x32_bf16 v[112:115], v[160:163], v[196:199], v[112:115]
	v_mfma_f32_16x16x32_bf16 v[112:115], v[164:167], v[200:203], v[112:115]
	s_setprio 1
	v_mfma_f32_16x16x32_bf16 v[108:111], v[152:155], v[204:207], v[108:111]
	v_mfma_f32_16x16x32_bf16 v[108:111], v[156:159], v[208:211], v[108:111]
	v_mfma_f32_16x16x32_bf16 v[104:107], v[160:163], v[204:207], v[104:107]
	v_mfma_f32_16x16x32_bf16 v[104:107], v[164:167], v[208:211], v[104:107]
	v_mfma_f32_16x16x32_bf16 v[100:103], v[152:155], v[212:215], v[100:103]
	v_mfma_f32_16x16x32_bf16 v[100:103], v[156:159], v[216:219], v[100:103]
	v_mfma_f32_16x16x32_bf16 v[96:99], v[160:163], v[212:215], v[96:99]
	v_mfma_f32_16x16x32_bf16 v[96:99], v[164:167], v[216:219], v[96:99]
	v_mfma_f32_16x16x32_bf16 v[76:79], v[168:171], v[188:191], v[76:79]
	v_mfma_f32_16x16x32_bf16 v[76:79], v[172:175], v[192:195], v[76:79]
	v_mfma_f32_16x16x32_bf16 v[68:71], v[176:179], v[188:191], v[68:71]
	v_mfma_f32_16x16x32_bf16 v[68:71], v[184:187], v[192:195], v[68:71]
	v_mfma_f32_16x16x32_bf16 v[60:63], v[168:171], v[196:199], v[60:63]
	v_mfma_f32_16x16x32_bf16 v[60:63], v[172:175], v[200:203], v[60:63]
	v_mfma_f32_16x16x32_bf16 v[52:55], v[176:179], v[196:199], v[52:55]
	v_mfma_f32_16x16x32_bf16 v[52:55], v[184:187], v[200:203], v[52:55]
	s_barrier
	v_mfma_f32_16x16x32_bf16 v[44:47], v[168:171], v[204:207], v[44:47]
	v_mfma_f32_16x16x32_bf16 v[44:47], v[172:175], v[208:211], v[44:47]
	v_mfma_f32_16x16x32_bf16 v[40:43], v[176:179], v[204:207], v[40:43]
	v_mfma_f32_16x16x32_bf16 v[40:43], v[184:187], v[208:211], v[40:43]
	v_mfma_f32_16x16x32_bf16 v[36:39], v[168:171], v[212:215], v[36:39]
	v_mfma_f32_16x16x32_bf16 v[36:39], v[172:175], v[216:219], v[36:39]
	v_mfma_f32_16x16x32_bf16 v[32:35], v[176:179], v[212:215], v[32:35]
	v_mfma_f32_16x16x32_bf16 v[32:35], v[184:187], v[216:219], v[32:35]
	s_setprio 0
	s_add_i32 s79, s77, s68
	v_lshl_add_u64 v[220:221], s[62:63], 0, v[130:131]
	s_mov_b32 m0, s79
	ds_read_b128 v[188:191], v150 offset:16384
	ds_read_b128 v[192:195], v150 offset:17408
	ds_read_b128 v[196:199], v150 offset:18432
	ds_read_b128 v[200:203], v150 offset:19456
	ds_read_b128 v[204:207], v150 offset:20480
	ds_read_b128 v[208:211], v150 offset:21504
	ds_read_b128 v[212:215], v150 offset:22528
	ds_read_b128 v[216:219], v150 offset:23552
	global_load_lds_dwordx4 v[220:221], off
	s_add_i32 m0, s79, 0x2000
	s_add_u32 s88, s62, 0x40000
	v_lshl_add_u64 v[222:223], s[62:63], 0, v[134:135]
	s_addc_u32 s89, s63, 0
	s_add_i32 s79, s82, s68
	global_load_lds_dwordx4 v[222:223], off
	v_lshl_add_u64 v[224:225], s[88:89], 0, v[130:131]
	s_mov_b32 m0, s79
	v_lshl_add_u64 v[226:227], s[64:65], 0, v[132:133]
	global_load_lds_dwordx4 v[224:225], off
	v_lshl_add_u64 v[224:225], s[88:89], 0, v[134:135]
	s_add_i32 m0, s79, 0x2000
	s_nop 0
	global_load_lds_dwordx4 v[224:225], off
	v_lshl_add_u64 v[224:225], s[64:65], 0, v[128:129]
	s_mov_b32 m0, s69
	s_nop 0
	global_load_lds_dwordx4 v[224:225], off
	s_mov_b32 m0, s70
	s_nop 0
	global_load_lds_dwordx4 v[226:227], off
	s_waitcnt vmcnt(8)
	s_waitcnt lgkmcnt(0)
	s_barrier
	s_waitcnt lgkmcnt(0)
	v_mfma_f32_16x16x32_bf16 v[92:95], v[152:155], v[188:191], v[92:95]
	v_mfma_f32_16x16x32_bf16 v[92:95], v[156:159], v[192:195], v[92:95]
	v_mfma_f32_16x16x32_bf16 v[88:91], v[160:163], v[188:191], v[88:91]
	v_mfma_f32_16x16x32_bf16 v[88:91], v[164:167], v[192:195], v[88:91]
	v_mfma_f32_16x16x32_bf16 v[84:87], v[152:155], v[196:199], v[84:87]
	v_mfma_f32_16x16x32_bf16 v[84:87], v[156:159], v[200:203], v[84:87]
	v_mfma_f32_16x16x32_bf16 v[80:83], v[160:163], v[196:199], v[80:83]
	v_mfma_f32_16x16x32_bf16 v[80:83], v[164:167], v[200:203], v[80:83]
	s_setprio 1
	v_mfma_f32_16x16x32_bf16 v[72:75], v[152:155], v[204:207], v[72:75]
	v_mfma_f32_16x16x32_bf16 v[72:75], v[156:159], v[208:211], v[72:75]
	v_mfma_f32_16x16x32_bf16 v[64:67], v[160:163], v[204:207], v[64:67]
	v_mfma_f32_16x16x32_bf16 v[64:67], v[164:167], v[208:211], v[64:67]
	v_mfma_f32_16x16x32_bf16 v[56:59], v[152:155], v[212:215], v[56:59]
	v_mfma_f32_16x16x32_bf16 v[56:59], v[156:159], v[216:219], v[56:59]
	v_mfma_f32_16x16x32_bf16 v[48:51], v[160:163], v[212:215], v[48:51]
	v_mfma_f32_16x16x32_bf16 v[48:51], v[164:167], v[216:219], v[48:51]
	v_mfma_f32_16x16x32_bf16 v[28:31], v[168:171], v[188:191], v[28:31]
	v_mfma_f32_16x16x32_bf16 v[28:31], v[172:175], v[192:195], v[28:31]
	v_mfma_f32_16x16x32_bf16 v[24:27], v[176:179], v[188:191], v[24:27]
	v_mfma_f32_16x16x32_bf16 v[24:27], v[184:187], v[192:195], v[24:27]
	v_mfma_f32_16x16x32_bf16 v[20:23], v[168:171], v[196:199], v[20:23]
	v_mfma_f32_16x16x32_bf16 v[20:23], v[172:175], v[200:203], v[20:23]
	v_mfma_f32_16x16x32_bf16 v[16:19], v[176:179], v[196:199], v[16:19]
	v_mfma_f32_16x16x32_bf16 v[16:19], v[184:187], v[200:203], v[16:19]
	s_barrier
	v_mfma_f32_16x16x32_bf16 v[12:15], v[168:171], v[204:207], v[12:15]
	v_mfma_f32_16x16x32_bf16 v[12:15], v[172:175], v[208:211], v[12:15]
	v_mfma_f32_16x16x32_bf16 v[8:11], v[176:179], v[204:207], v[8:11]
	v_mfma_f32_16x16x32_bf16 v[8:11], v[184:187], v[208:211], v[8:11]
	v_mfma_f32_16x16x32_bf16 v[4:7], v[168:171], v[212:215], v[4:7]
	v_mfma_f32_16x16x32_bf16 v[4:7], v[172:175], v[216:219], v[4:7]
	v_mfma_f32_16x16x32_bf16 v[0:3], v[176:179], v[212:215], v[0:3]
	v_mfma_f32_16x16x32_bf16 v[0:3], v[184:187], v[216:219], v[0:3]
	s_setprio 0
.Lmid_gemm6:
	s_add_i32 s79, 0, 0x18000
	v_add_u32_e32 v151, s79, v147
	s_add_i32 s88, 0, 0x1c000
	ds_read_b128 v[152:155], v151
	ds_read_b128 v[156:159], v151 offset:1024
	ds_read_b128 v[160:163], v151 offset:2048
	ds_read_b128 v[164:167], v151 offset:3072
	v_add_u32_e32 v151, s88, v147
	ds_read_b128 v[168:171], v151
	ds_read_b128 v[172:175], v151 offset:1024
	ds_read_b128 v[176:179], v151 offset:2048
	ds_read_b128 v[184:187], v151 offset:3072
	s_add_u32 s64, s64, 0x40000
	s_addc_u32 s65, s65, 0
	s_mov_b32 m0, s71
	v_lshl_add_u64 v[228:229], s[64:65], 0, v[128:129]
	ds_read_b128 v[188:191], v150 offset:32768
	ds_read_b128 v[192:195], v150 offset:33792
	ds_read_b128 v[196:199], v150 offset:34816
	ds_read_b128 v[200:203], v150 offset:35840
	ds_read_b128 v[204:207], v150 offset:36864
	ds_read_b128 v[208:211], v150 offset:37888
	ds_read_b128 v[212:215], v150 offset:38912
	ds_read_b128 v[216:219], v150 offset:39936
	global_load_lds_dwordx4 v[228:229], off
	v_lshl_add_u64 v[228:229], s[64:65], 0, v[132:133]
	s_mov_b32 m0, s72
	s_nop 0
	global_load_lds_dwordx4 v[228:229], off
	s_waitcnt vmcnt(8)
	s_waitcnt lgkmcnt(0)
	s_barrier
	s_waitcnt lgkmcnt(0)
	v_mfma_f32_16x16x32_bf16 v[124:127], v[152:155], v[188:191], v[124:127]
	v_mfma_f32_16x16x32_bf16 v[124:127], v[156:159], v[192:195], v[124:127]
	v_mfma_f32_16x16x32_bf16 v[120:123], v[160:163], v[188:191], v[120:123]
	v_mfma_f32_16x16x32_bf16 v[120:123], v[164:167], v[192:195], v[120:123]
	v_mfma_f32_16x16x32_bf16 v[116:119], v[152:155], v[196:199], v[116:119]
	v_mfma_f32_16x16x32_bf16 v[116:119], v[156:159], v[200:203], v[116:119]
	v_mfma_f32_16x16x32_bf16 v[112:115], v[160:163], v[196:199], v[112:115]
	v_mfma_f32_16x16x32_bf16 v[112:115], v[164:167], v[200:203], v[112:115]
	s_setprio 1
	v_mfma_f32_16x16x32_bf16 v[108:111], v[152:155], v[204:207], v[108:111]
	v_mfma_f32_16x16x32_bf16 v[108:111], v[156:159], v[208:211], v[108:111]
	v_mfma_f32_16x16x32_bf16 v[104:107], v[160:163], v[204:207], v[104:107]
	v_mfma_f32_16x16x32_bf16 v[104:107], v[164:167], v[208:211], v[104:107]
	v_mfma_f32_16x16x32_bf16 v[100:103], v[152:155], v[212:215], v[100:103]
	v_mfma_f32_16x16x32_bf16 v[100:103], v[156:159], v[216:219], v[100:103]
	v_mfma_f32_16x16x32_bf16 v[96:99], v[160:163], v[212:215], v[96:99]
	v_mfma_f32_16x16x32_bf16 v[96:99], v[164:167], v[216:219], v[96:99]
	v_mfma_f32_16x16x32_bf16 v[76:79], v[168:171], v[188:191], v[76:79]
	v_mfma_f32_16x16x32_bf16 v[76:79], v[172:175], v[192:195], v[76:79]
	v_mfma_f32_16x16x32_bf16 v[68:71], v[176:179], v[188:191], v[68:71]
	v_mfma_f32_16x16x32_bf16 v[68:71], v[184:187], v[192:195], v[68:71]
	v_mfma_f32_16x16x32_bf16 v[60:63], v[168:171], v[196:199], v[60:63]
	v_mfma_f32_16x16x32_bf16 v[60:63], v[172:175], v[200:203], v[60:63]
	v_mfma_f32_16x16x32_bf16 v[52:55], v[176:179], v[196:199], v[52:55]
	v_mfma_f32_16x16x32_bf16 v[52:55], v[184:187], v[200:203], v[52:55]
	s_barrier
	v_mfma_f32_16x16x32_bf16 v[44:47], v[168:171], v[204:207], v[44:47]
	v_mfma_f32_16x16x32_bf16 v[44:47], v[172:175], v[208:211], v[44:47]
	v_mfma_f32_16x16x32_bf16 v[40:43], v[176:179], v[204:207], v[40:43]
	v_mfma_f32_16x16x32_bf16 v[40:43], v[184:187], v[208:211], v[40:43]
	v_mfma_f32_16x16x32_bf16 v[36:39], v[168:171], v[212:215], v[36:39]
	v_mfma_f32_16x16x32_bf16 v[36:39], v[172:175], v[216:219], v[36:39]
	v_mfma_f32_16x16x32_bf16 v[32:35], v[176:179], v[212:215], v[32:35]
	v_mfma_f32_16x16x32_bf16 v[32:35], v[184:187], v[216:219], v[32:35]
	s_setprio 0
	s_add_i32 s64, s79, s68
	v_lshl_add_u64 v[220:221], v[220:221], 0, s[12:13]
	s_mov_b32 m0, s64
	ds_read_b128 v[188:191], v150 offset:49152
	ds_read_b128 v[192:195], v150 offset:50176
	ds_read_b128 v[196:199], v150 offset:51200
	ds_read_b128 v[200:203], v150 offset:52224
	ds_read_b128 v[204:207], v150 offset:53248
	ds_read_b128 v[208:211], v150 offset:54272
	ds_read_b128 v[212:215], v150 offset:55296
	ds_read_b128 v[216:219], v150 offset:56320
	global_load_lds_dwordx4 v[220:221], off
	s_add_i32 m0, s64, 0x2000
	s_add_u32 s62, s62, 0x40080
	v_lshl_add_u64 v[220:221], v[222:223], 0, s[12:13]
	s_addc_u32 s63, s63, 0
	s_add_i32 s64, s88, s68
	global_load_lds_dwordx4 v[220:221], off
	v_lshl_add_u64 v[220:221], s[62:63], 0, v[130:131]
	s_mov_b32 m0, s64
	s_nop 0
	global_load_lds_dwordx4 v[220:221], off
	v_lshl_add_u64 v[220:221], s[62:63], 0, v[134:135]
	s_add_i32 m0, s64, 0x2000
	s_nop 0
	global_load_lds_dwordx4 v[220:221], off
	v_lshl_add_u64 v[220:221], v[224:225], 0, s[12:13]
	s_mov_b32 m0, s75
	s_nop 0
	global_load_lds_dwordx4 v[220:221], off
	v_lshl_add_u64 v[220:221], v[226:227], 0, s[12:13]
	s_mov_b32 m0, s76
	s_nop 0
	global_load_lds_dwordx4 v[220:221], off
	s_waitcnt vmcnt(8)
	s_waitcnt lgkmcnt(0)
	s_barrier
	s_waitcnt lgkmcnt(0)
	v_mfma_f32_16x16x32_bf16 v[92:95], v[152:155], v[188:191], v[92:95]
	v_mfma_f32_16x16x32_bf16 v[92:95], v[156:159], v[192:195], v[92:95]
	v_mfma_f32_16x16x32_bf16 v[88:91], v[160:163], v[188:191], v[88:91]
	v_mfma_f32_16x16x32_bf16 v[88:91], v[164:167], v[192:195], v[88:91]
	v_mfma_f32_16x16x32_bf16 v[84:87], v[152:155], v[196:199], v[84:87]
	v_mfma_f32_16x16x32_bf16 v[84:87], v[156:159], v[200:203], v[84:87]
	v_mfma_f32_16x16x32_bf16 v[80:83], v[160:163], v[196:199], v[80:83]
	v_mfma_f32_16x16x32_bf16 v[80:83], v[164:167], v[200:203], v[80:83]
	s_setprio 1
	v_mfma_f32_16x16x32_bf16 v[72:75], v[152:155], v[204:207], v[72:75]
	v_mfma_f32_16x16x32_bf16 v[72:75], v[156:159], v[208:211], v[72:75]
	v_mfma_f32_16x16x32_bf16 v[64:67], v[160:163], v[204:207], v[64:67]
	v_mfma_f32_16x16x32_bf16 v[64:67], v[164:167], v[208:211], v[64:67]
	v_mfma_f32_16x16x32_bf16 v[56:59], v[152:155], v[212:215], v[56:59]
	v_mfma_f32_16x16x32_bf16 v[56:59], v[156:159], v[216:219], v[56:59]
	v_mfma_f32_16x16x32_bf16 v[48:51], v[160:163], v[212:215], v[48:51]
	v_mfma_f32_16x16x32_bf16 v[48:51], v[164:167], v[216:219], v[48:51]
	v_mfma_f32_16x16x32_bf16 v[28:31], v[168:171], v[188:191], v[28:31]
	v_mfma_f32_16x16x32_bf16 v[28:31], v[172:175], v[192:195], v[28:31]
	v_mfma_f32_16x16x32_bf16 v[24:27], v[176:179], v[188:191], v[24:27]
	v_mfma_f32_16x16x32_bf16 v[24:27], v[184:187], v[192:195], v[24:27]
	v_mfma_f32_16x16x32_bf16 v[20:23], v[168:171], v[196:199], v[20:23]
	v_mfma_f32_16x16x32_bf16 v[20:23], v[172:175], v[200:203], v[20:23]
	v_mfma_f32_16x16x32_bf16 v[16:19], v[176:179], v[196:199], v[16:19]
	v_mfma_f32_16x16x32_bf16 v[16:19], v[184:187], v[200:203], v[16:19]
	s_barrier
	v_mfma_f32_16x16x32_bf16 v[12:15], v[168:171], v[204:207], v[12:15]
	v_mfma_f32_16x16x32_bf16 v[12:15], v[172:175], v[208:211], v[12:15]
	v_mfma_f32_16x16x32_bf16 v[8:11], v[176:179], v[204:207], v[8:11]
	v_mfma_f32_16x16x32_bf16 v[8:11], v[184:187], v[208:211], v[8:11]
	v_mfma_f32_16x16x32_bf16 v[4:7], v[168:171], v[212:215], v[4:7]
	v_mfma_f32_16x16x32_bf16 v[4:7], v[172:175], v[216:219], v[4:7]
	v_mfma_f32_16x16x32_bf16 v[0:3], v[176:179], v[212:215], v[0:3]
	v_mfma_f32_16x16x32_bf16 v[0:3], v[184:187], v[216:219], v[0:3]
	s_setprio 0
	s_add_i32 s87, s87, 2
	s_add_u32 s60, s60, 0x100
	s_addc_u32 s61, s61, 0
	s_add_u32 s85, s85, 0x100
	s_addc_u32 s86, s86, 0
	s_cmp_gt_u32 s87, 13
	s_cbranch_scc0 .LBB0_935
	s_and_b64 vcc, exec, s[16:17]
	s_cbranch_vccz .LBB0_938
	s_barrier

.LBB0_950:
	s_ashr_i32 s37, s36, 31
	s_lshl_b64 s[44:45], s[36:37], 19
	s_add_u32 s44, s80, s44
	s_addc_u32 s45, s81, s45
	s_and_b64 s[46:47], s[10:11], exec
	s_cselect_b32 s37, s45, s53
	s_cselect_b32 s72, s44, s52
	s_ashr_i32 s19, s18, 31
	s_lshl_b64 s[46:47], s[18:19], 19
	s_add_u32 s46, s58, s46
	s_addc_u32 s47, s59, s47
	s_and_b64 s[56:57], s[10:11], exec
	s_cselect_b32 s19, s47, s55
	s_cselect_b32 s73, s46, s54
	s_add_u32 s52, s52, 0x40080
	s_addc_u32 s53, s53, 0
	s_add_u32 s74, s54, 0x100
	s_addc_u32 s75, s55, 0
	s_mov_b32 s76, -2
	ds_read_b128 v[140:143], v147
	ds_read_b128 v[150:153], v147 offset:1024
	ds_read_b128 v[154:157], v147 offset:2048
	ds_read_b128 v[158:161], v147 offset:3072
	ds_read_b128 v[162:165], v148
	ds_read_b128 v[166:169], v148 offset:1024
	ds_read_b128 v[170:173], v148 offset:2048
	ds_read_b128 v[174:177], v148 offset:3072
	s_add_u32 s54, s52, 0xfffc0080
	s_addc_u32 s55, s53, -1
	s_cmp_eq_u32 s76, 12
	s_cselect_b32 s57, s37, s55
	s_cselect_b32 s56, s72, s54
	s_cselect_b32 s55, s19, s75
	s_cselect_b32 s54, s73, s74
	v_lshl_add_u64 v[178:179], s[52:53], 0, v[132:133]
	s_add_i32 m0, s49, 0xc000
	ds_read_b128 v[184:187], v149
	ds_read_b128 v[188:191], v149 offset:1024
	ds_read_b128 v[192:195], v149 offset:2048
	ds_read_b128 v[196:199], v149 offset:3072
	ds_read_b128 v[200:203], v149 offset:4096
	ds_read_b128 v[204:207], v149 offset:5120
	ds_read_b128 v[208:211], v149 offset:6144
	ds_read_b128 v[212:215], v149 offset:7168
	global_load_lds_dwordx4 v[178:179], off
	v_lshl_add_u64 v[178:179], s[52:53], 0, v[134:135]
	s_add_i32 m0, s49, 0xe000
	s_nop 0
	global_load_lds_dwordx4 v[178:179], off
	s_waitcnt vmcnt(8)
	s_waitcnt lgkmcnt(0)
	s_barrier
	s_waitcnt lgkmcnt(0)
	v_mfma_f32_16x16x32_bf16 v[124:127], v[140:143], v[184:187], 0
	v_mfma_f32_16x16x32_bf16 v[124:127], v[150:153], v[188:191], v[124:127]
	v_mfma_f32_16x16x32_bf16 v[120:123], v[154:157], v[184:187], 0
	v_mfma_f32_16x16x32_bf16 v[120:123], v[158:161], v[188:191], v[120:123]
	v_mfma_f32_16x16x32_bf16 v[108:111], v[140:143], v[192:195], 0
	v_mfma_f32_16x16x32_bf16 v[108:111], v[150:153], v[196:199], v[108:111]
	v_mfma_f32_16x16x32_bf16 v[104:107], v[154:157], v[192:195], 0
	v_mfma_f32_16x16x32_bf16 v[104:107], v[158:161], v[196:199], v[104:107]
	s_setprio 1
	v_mfma_f32_16x16x32_bf16 v[92:95], v[140:143], v[200:203], 0
	v_mfma_f32_16x16x32_bf16 v[92:95], v[150:153], v[204:207], v[92:95]
	v_mfma_f32_16x16x32_bf16 v[88:91], v[154:157], v[200:203], 0
	v_mfma_f32_16x16x32_bf16 v[88:91], v[158:161], v[204:207], v[88:91]
	v_mfma_f32_16x16x32_bf16 v[76:79], v[140:143], v[208:211], 0
	v_mfma_f32_16x16x32_bf16 v[76:79], v[150:153], v[212:215], v[76:79]
	v_mfma_f32_16x16x32_bf16 v[72:75], v[154:157], v[208:211], 0
	v_mfma_f32_16x16x32_bf16 v[72:75], v[158:161], v[212:215], v[72:75]
	v_mfma_f32_16x16x32_bf16 v[116:119], v[162:165], v[184:187], 0
	v_mfma_f32_16x16x32_bf16 v[116:119], v[166:169], v[188:191], v[116:119]
	v_mfma_f32_16x16x32_bf16 v[112:115], v[170:173], v[184:187], 0
	v_mfma_f32_16x16x32_bf16 v[112:115], v[174:177], v[188:191], v[112:115]
	v_mfma_f32_16x16x32_bf16 v[100:103], v[162:165], v[192:195], 0
	v_mfma_f32_16x16x32_bf16 v[100:103], v[166:169], v[196:199], v[100:103]
	v_mfma_f32_16x16x32_bf16 v[96:99], v[170:173], v[192:195], 0
	v_mfma_f32_16x16x32_bf16 v[96:99], v[174:177], v[196:199], v[96:99]
	s_barrier
	v_mfma_f32_16x16x32_bf16 v[84:87], v[162:165], v[200:203], 0
	v_mfma_f32_16x16x32_bf16 v[84:87], v[166:169], v[204:207], v[84:87]
	v_mfma_f32_16x16x32_bf16 v[80:83], v[170:173], v[200:203], 0
	v_mfma_f32_16x16x32_bf16 v[80:83], v[174:177], v[204:207], v[80:83]
	v_mfma_f32_16x16x32_bf16 v[68:71], v[162:165], v[208:211], 0
	v_mfma_f32_16x16x32_bf16 v[68:71], v[166:169], v[212:215], v[68:71]
	v_mfma_f32_16x16x32_bf16 v[64:67], v[170:173], v[208:211], 0
	v_mfma_f32_16x16x32_bf16 v[64:67], v[174:177], v[212:215], v[64:67]
	s_setprio 0
	s_add_i32 s77, s68, s60
	v_lshl_add_u64 v[178:179], s[54:55], 0, v[130:131]
	s_mov_b32 m0, s77
	ds_read_b128 v[184:187], v149 offset:16384
	ds_read_b128 v[188:191], v149 offset:17408
	ds_read_b128 v[192:195], v149 offset:18432
	ds_read_b128 v[196:199], v149 offset:19456
	ds_read_b128 v[200:203], v149 offset:20480
	ds_read_b128 v[204:207], v149 offset:21504
	ds_read_b128 v[208:211], v149 offset:22528
	ds_read_b128 v[212:215], v149 offset:23552
	global_load_lds_dwordx4 v[178:179], off
	s_add_i32 m0, s77, 0x2000
	s_add_u32 s82, s54, 0x40000
	v_lshl_add_u64 v[216:217], s[54:55], 0, v[128:129]
	s_addc_u32 s83, s55, 0
	s_add_i32 s77, s69, s60
	global_load_lds_dwordx4 v[216:217], off
	v_lshl_add_u64 v[218:219], s[82:83], 0, v[130:131]
	s_mov_b32 m0, s77
	v_lshl_add_u64 v[220:221], s[56:57], 0, v[128:129]
	global_load_lds_dwordx4 v[218:219], off
	v_lshl_add_u64 v[218:219], s[82:83], 0, v[128:129]
	s_add_i32 m0, s77, 0x2000
	s_nop 0
	global_load_lds_dwordx4 v[218:219], off
	v_lshl_add_u64 v[218:219], s[56:57], 0, v[130:131]
	s_mov_b32 m0, s49
	s_nop 0
	global_load_lds_dwordx4 v[218:219], off
	s_mov_b32 m0, s62
	s_nop 0
	global_load_lds_dwordx4 v[220:221], off
	s_waitcnt vmcnt(8)
	s_waitcnt lgkmcnt(0)
	s_barrier
	s_waitcnt lgkmcnt(0)
	v_mfma_f32_16x16x32_bf16 v[60:63], v[140:143], v[184:187], 0
	v_mfma_f32_16x16x32_bf16 v[60:63], v[150:153], v[188:191], v[60:63]
	v_mfma_f32_16x16x32_bf16 v[56:59], v[154:157], v[184:187], 0
	v_mfma_f32_16x16x32_bf16 v[56:59], v[158:161], v[188:191], v[56:59]
	v_mfma_f32_16x16x32_bf16 v[44:47], v[140:143], v[192:195], 0
	v_mfma_f32_16x16x32_bf16 v[44:47], v[150:153], v[196:199], v[44:47]
	v_mfma_f32_16x16x32_bf16 v[40:43], v[154:157], v[192:195], 0
	v_mfma_f32_16x16x32_bf16 v[40:43], v[158:161], v[196:199], v[40:43]
	s_setprio 1
	v_mfma_f32_16x16x32_bf16 v[28:31], v[140:143], v[200:203], 0
	v_mfma_f32_16x16x32_bf16 v[28:31], v[150:153], v[204:207], v[28:31]
	v_mfma_f32_16x16x32_bf16 v[24:27], v[154:157], v[200:203], 0
	v_mfma_f32_16x16x32_bf16 v[24:27], v[158:161], v[204:207], v[24:27]
	v_mfma_f32_16x16x32_bf16 v[12:15], v[140:143], v[208:211], 0
	v_mfma_f32_16x16x32_bf16 v[12:15], v[150:153], v[212:215], v[12:15]
	v_mfma_f32_16x16x32_bf16 v[8:11], v[154:157], v[208:211], 0
	v_mfma_f32_16x16x32_bf16 v[8:11], v[158:161], v[212:215], v[8:11]
	v_mfma_f32_16x16x32_bf16 v[52:55], v[162:165], v[184:187], 0
	v_mfma_f32_16x16x32_bf16 v[52:55], v[166:169], v[188:191], v[52:55]
	v_mfma_f32_16x16x32_bf16 v[48:51], v[170:173], v[184:187], 0
	v_mfma_f32_16x16x32_bf16 v[48:51], v[174:177], v[188:191], v[48:51]
	v_mfma_f32_16x16x32_bf16 v[36:39], v[162:165], v[192:195], 0
	v_mfma_f32_16x16x32_bf16 v[36:39], v[166:169], v[196:199], v[36:39]
	v_mfma_f32_16x16x32_bf16 v[32:35], v[170:173], v[192:195], 0
	v_mfma_f32_16x16x32_bf16 v[32:35], v[174:177], v[196:199], v[32:35]
	s_barrier
	v_mfma_f32_16x16x32_bf16 v[20:23], v[162:165], v[200:203], 0
	v_mfma_f32_16x16x32_bf16 v[20:23], v[166:169], v[204:207], v[20:23]
	v_mfma_f32_16x16x32_bf16 v[16:19], v[170:173], v[200:203], 0
	v_mfma_f32_16x16x32_bf16 v[16:19], v[174:177], v[204:207], v[16:19]
	v_mfma_f32_16x16x32_bf16 v[4:7], v[162:165], v[208:211], 0
	v_mfma_f32_16x16x32_bf16 v[4:7], v[166:169], v[212:215], v[4:7]
	v_mfma_f32_16x16x32_bf16 v[0:3], v[170:173], v[208:211], 0
	v_mfma_f32_16x16x32_bf16 v[0:3], v[174:177], v[212:215], v[0:3]
	s_setprio 0
	s_branch .Lmid_gemm7
.LBB0_951:
	ds_read_b128 v[140:143], v147
	ds_read_b128 v[150:153], v147 offset:1024
	ds_read_b128 v[154:157], v147 offset:2048
	ds_read_b128 v[158:161], v147 offset:3072
	ds_read_b128 v[162:165], v148
	ds_read_b128 v[166:169], v148 offset:1024
	ds_read_b128 v[170:173], v148 offset:2048
	ds_read_b128 v[174:177], v148 offset:3072
	s_add_u32 s54, s52, 0xfffc0080
	s_addc_u32 s55, s53, -1
	s_cmp_eq_u32 s76, 12
	s_cselect_b32 s57, s37, s55
	s_cselect_b32 s56, s72, s54
	s_cselect_b32 s55, s19, s75
	s_cselect_b32 s54, s73, s74
	v_lshl_add_u64 v[178:179], s[52:53], 0, v[132:133]
	s_add_i32 m0, s49, 0xc000
	ds_read_b128 v[184:187], v149
	ds_read_b128 v[188:191], v149 offset:1024
	ds_read_b128 v[192:195], v149 offset:2048
	ds_read_b128 v[196:199], v149 offset:3072
	ds_read_b128 v[200:203], v149 offset:4096
	ds_read_b128 v[204:207], v149 offset:5120
	ds_read_b128 v[208:211], v149 offset:6144
	ds_read_b128 v[212:215], v149 offset:7168
	global_load_lds_dwordx4 v[178:179], off
	v_lshl_add_u64 v[178:179], s[52:53], 0, v[134:135]
	s_add_i32 m0, s49, 0xe000
	s_nop 0
	global_load_lds_dwordx4 v[178:179], off
	s_waitcnt vmcnt(8)
	s_waitcnt lgkmcnt(0)
	s_barrier
	s_waitcnt lgkmcnt(0)
	v_mfma_f32_16x16x32_bf16 v[124:127], v[140:143], v[184:187], v[124:127]
	v_mfma_f32_16x16x32_bf16 v[124:127], v[150:153], v[188:191], v[124:127]
	v_mfma_f32_16x16x32_bf16 v[120:123], v[154:157], v[184:187], v[120:123]
	v_mfma_f32_16x16x32_bf16 v[120:123], v[158:161], v[188:191], v[120:123]
	v_mfma_f32_16x16x32_bf16 v[108:111], v[140:143], v[192:195], v[108:111]
	v_mfma_f32_16x16x32_bf16 v[108:111], v[150:153], v[196:199], v[108:111]
	v_mfma_f32_16x16x32_bf16 v[104:107], v[154:157], v[192:195], v[104:107]
	v_mfma_f32_16x16x32_bf16 v[104:107], v[158:161], v[196:199], v[104:107]
	s_setprio 1
	v_mfma_f32_16x16x32_bf16 v[92:95], v[140:143], v[200:203], v[92:95]
	v_mfma_f32_16x16x32_bf16 v[92:95], v[150:153], v[204:207], v[92:95]
	v_mfma_f32_16x16x32_bf16 v[88:91], v[154:157], v[200:203], v[88:91]
	v_mfma_f32_16x16x32_bf16 v[88:91], v[158:161], v[204:207], v[88:91]
	v_mfma_f32_16x16x32_bf16 v[76:79], v[140:143], v[208:211], v[76:79]
	v_mfma_f32_16x16x32_bf16 v[76:79], v[150:153], v[212:215], v[76:79]
	v_mfma_f32_16x16x32_bf16 v[72:75], v[154:157], v[208:211], v[72:75]
	v_mfma_f32_16x16x32_bf16 v[72:75], v[158:161], v[212:215], v[72:75]
	v_mfma_f32_16x16x32_bf16 v[116:119], v[162:165], v[184:187], v[116:119]
	v_mfma_f32_16x16x32_bf16 v[116:119], v[166:169], v[188:191], v[116:119]
	v_mfma_f32_16x16x32_bf16 v[112:115], v[170:173], v[184:187], v[112:115]
	v_mfma_f32_16x16x32_bf16 v[112:115], v[174:177], v[188:191], v[112:115]
	v_mfma_f32_16x16x32_bf16 v[100:103], v[162:165], v[192:195], v[100:103]
	v_mfma_f32_16x16x32_bf16 v[100:103], v[166:169], v[196:199], v[100:103]
	v_mfma_f32_16x16x32_bf16 v[96:99], v[170:173], v[192:195], v[96:99]
	v_mfma_f32_16x16x32_bf16 v[96:99], v[174:177], v[196:199], v[96:99]
	s_barrier
	v_mfma_f32_16x16x32_bf16 v[84:87], v[162:165], v[200:203], v[84:87]
	v_mfma_f32_16x16x32_bf16 v[84:87], v[166:169], v[204:207], v[84:87]
	v_mfma_f32_16x16x32_bf16 v[80:83], v[170:173], v[200:203], v[80:83]
	v_mfma_f32_16x16x32_bf16 v[80:83], v[174:177], v[204:207], v[80:83]
	v_mfma_f32_16x16x32_bf16 v[68:71], v[162:165], v[208:211], v[68:71]
	v_mfma_f32_16x16x32_bf16 v[68:71], v[166:169], v[212:215], v[68:71]
	v_mfma_f32_16x16x32_bf16 v[64:67], v[170:173], v[208:211], v[64:67]
	v_mfma_f32_16x16x32_bf16 v[64:67], v[174:177], v[212:215], v[64:67]
	s_setprio 0
	s_add_i32 s77, s68, s60
	v_lshl_add_u64 v[178:179], s[54:55], 0, v[130:131]
	s_mov_b32 m0, s77
	ds_read_b128 v[184:187], v149 offset:16384
	ds_read_b128 v[188:191], v149 offset:17408
	ds_read_b128 v[192:195], v149 offset:18432
	ds_read_b128 v[196:199], v149 offset:19456
	ds_read_b128 v[200:203], v149 offset:20480
	ds_read_b128 v[204:207], v149 offset:21504
	ds_read_b128 v[208:211], v149 offset:22528
	ds_read_b128 v[212:215], v149 offset:23552
	global_load_lds_dwordx4 v[178:179], off
	s_add_i32 m0, s77, 0x2000
	s_add_u32 s82, s54, 0x40000
	v_lshl_add_u64 v[216:217], s[54:55], 0, v[128:129]
	s_addc_u32 s83, s55, 0
	s_add_i32 s77, s69, s60
	global_load_lds_dwordx4 v[216:217], off
	v_lshl_add_u64 v[218:219], s[82:83], 0, v[130:131]
	s_mov_b32 m0, s77
	v_lshl_add_u64 v[220:221], s[56:57], 0, v[128:129]
	global_load_lds_dwordx4 v[218:219], off
	v_lshl_add_u64 v[218:219], s[82:83], 0, v[128:129]
	s_add_i32 m0, s77, 0x2000
	s_nop 0
	global_load_lds_dwordx4 v[218:219], off
	v_lshl_add_u64 v[218:219], s[56:57], 0, v[130:131]
	s_mov_b32 m0, s49
	s_nop 0
	global_load_lds_dwordx4 v[218:219], off
	s_mov_b32 m0, s62
	s_nop 0
	global_load_lds_dwordx4 v[220:221], off
	s_waitcnt vmcnt(8)
	s_waitcnt lgkmcnt(0)
	s_barrier
	s_waitcnt lgkmcnt(0)
	v_mfma_f32_16x16x32_bf16 v[60:63], v[140:143], v[184:187], v[60:63]
	v_mfma_f32_16x16x32_bf16 v[60:63], v[150:153], v[188:191], v[60:63]
	v_mfma_f32_16x16x32_bf16 v[56:59], v[154:157], v[184:187], v[56:59]
	v_mfma_f32_16x16x32_bf16 v[56:59], v[158:161], v[188:191], v[56:59]
	v_mfma_f32_16x16x32_bf16 v[44:47], v[140:143], v[192:195], v[44:47]
	v_mfma_f32_16x16x32_bf16 v[44:47], v[150:153], v[196:199], v[44:47]
	v_mfma_f32_16x16x32_bf16 v[40:43], v[154:157], v[192:195], v[40:43]
	v_mfma_f32_16x16x32_bf16 v[40:43], v[158:161], v[196:199], v[40:43]
	s_setprio 1
	v_mfma_f32_16x16x32_bf16 v[28:31], v[140:143], v[200:203], v[28:31]
	v_mfma_f32_16x16x32_bf16 v[28:31], v[150:153], v[204:207], v[28:31]
	v_mfma_f32_16x16x32_bf16 v[24:27], v[154:157], v[200:203], v[24:27]
	v_mfma_f32_16x16x32_bf16 v[24:27], v[158:161], v[204:207], v[24:27]
	v_mfma_f32_16x16x32_bf16 v[12:15], v[140:143], v[208:211], v[12:15]
	v_mfma_f32_16x16x32_bf16 v[12:15], v[150:153], v[212:215], v[12:15]
	v_mfma_f32_16x16x32_bf16 v[8:11], v[154:157], v[208:211], v[8:11]
	v_mfma_f32_16x16x32_bf16 v[8:11], v[158:161], v[212:215], v[8:11]
	v_mfma_f32_16x16x32_bf16 v[52:55], v[162:165], v[184:187], v[52:55]
	v_mfma_f32_16x16x32_bf16 v[52:55], v[166:169], v[188:191], v[52:55]
	v_mfma_f32_16x16x32_bf16 v[48:51], v[170:173], v[184:187], v[48:51]
	v_mfma_f32_16x16x32_bf16 v[48:51], v[174:177], v[188:191], v[48:51]
	v_mfma_f32_16x16x32_bf16 v[36:39], v[162:165], v[192:195], v[36:39]
	v_mfma_f32_16x16x32_bf16 v[36:39], v[166:169], v[196:199], v[36:39]
	v_mfma_f32_16x16x32_bf16 v[32:35], v[170:173], v[192:195], v[32:35]
	v_mfma_f32_16x16x32_bf16 v[32:35], v[174:177], v[196:199], v[32:35]
	s_barrier
	v_mfma_f32_16x16x32_bf16 v[20:23], v[162:165], v[200:203], v[20:23]
	v_mfma_f32_16x16x32_bf16 v[20:23], v[166:169], v[204:207], v[20:23]
	v_mfma_f32_16x16x32_bf16 v[16:19], v[170:173], v[200:203], v[16:19]
	v_mfma_f32_16x16x32_bf16 v[16:19], v[174:177], v[204:207], v[16:19]
	v_mfma_f32_16x16x32_bf16 v[4:7], v[162:165], v[208:211], v[4:7]
	v_mfma_f32_16x16x32_bf16 v[4:7], v[166:169], v[212:215], v[4:7]
	v_mfma_f32_16x16x32_bf16 v[0:3], v[170:173], v[208:211], v[0:3]
	v_mfma_f32_16x16x32_bf16 v[0:3], v[174:177], v[212:215], v[0:3]
	s_setprio 0
.Lmid_gemm7:
	s_add_i32 s77, 0, 0x18000
	s_add_i32 s79, 0, 0x1c000
	v_add_u32_e32 v158, s77, v145
	v_add_u32_e32 v174, s79, v145
	ds_read_b128 v[140:143], v158
	ds_read_b128 v[150:153], v158 offset:1024
	ds_read_b128 v[154:157], v158 offset:2048
	ds_read_b128 v[158:161], v158 offset:3072
	ds_read_b128 v[162:165], v174
	ds_read_b128 v[166:169], v174 offset:1024
	ds_read_b128 v[170:173], v174 offset:2048
	ds_read_b128 v[174:177], v174 offset:3072
	s_add_u32 s56, s56, 0x40000
	s_addc_u32 s57, s57, 0
	s_mov_b32 m0, s63
	v_lshl_add_u64 v[222:223], s[56:57], 0, v[130:131]
	ds_read_b128 v[184:187], v149 offset:32768
	ds_read_b128 v[188:191], v149 offset:33792
	ds_read_b128 v[192:195], v149 offset:34816
	ds_read_b128 v[196:199], v149 offset:35840
	ds_read_b128 v[200:203], v149 offset:36864
	ds_read_b128 v[204:207], v149 offset:37888
	ds_read_b128 v[208:211], v149 offset:38912
	ds_read_b128 v[212:215], v149 offset:39936
	global_load_lds_dwordx4 v[222:223], off
	v_lshl_add_u64 v[222:223], s[56:57], 0, v[128:129]
	s_mov_b32 m0, s64
	s_nop 0
	global_load_lds_dwordx4 v[222:223], off
	s_waitcnt vmcnt(8)
	s_waitcnt lgkmcnt(0)
	s_barrier
	s_waitcnt lgkmcnt(0)
	v_mfma_f32_16x16x32_bf16 v[124:127], v[140:143], v[184:187], v[124:127]
	v_mfma_f32_16x16x32_bf16 v[124:127], v[150:153], v[188:191], v[124:127]
	v_mfma_f32_16x16x32_bf16 v[120:123], v[154:157], v[184:187], v[120:123]
	v_mfma_f32_16x16x32_bf16 v[120:123], v[158:161], v[188:191], v[120:123]
	v_mfma_f32_16x16x32_bf16 v[108:111], v[140:143], v[192:195], v[108:111]
	v_mfma_f32_16x16x32_bf16 v[108:111], v[150:153], v[196:199], v[108:111]
	v_mfma_f32_16x16x32_bf16 v[104:107], v[154:157], v[192:195], v[104:107]
	v_mfma_f32_16x16x32_bf16 v[104:107], v[158:161], v[196:199], v[104:107]
	s_setprio 1
	v_mfma_f32_16x16x32_bf16 v[92:95], v[140:143], v[200:203], v[92:95]
	v_mfma_f32_16x16x32_bf16 v[92:95], v[150:153], v[204:207], v[92:95]
	v_mfma_f32_16x16x32_bf16 v[88:91], v[154:157], v[200:203], v[88:91]
	v_mfma_f32_16x16x32_bf16 v[88:91], v[158:161], v[204:207], v[88:91]
	v_mfma_f32_16x16x32_bf16 v[76:79], v[140:143], v[208:211], v[76:79]
	v_mfma_f32_16x16x32_bf16 v[76:79], v[150:153], v[212:215], v[76:79]
	v_mfma_f32_16x16x32_bf16 v[72:75], v[154:157], v[208:211], v[72:75]
	v_mfma_f32_16x16x32_bf16 v[72:75], v[158:161], v[212:215], v[72:75]
	v_mfma_f32_16x16x32_bf16 v[116:119], v[162:165], v[184:187], v[116:119]
	v_mfma_f32_16x16x32_bf16 v[116:119], v[166:169], v[188:191], v[116:119]
	v_mfma_f32_16x16x32_bf16 v[112:115], v[170:173], v[184:187], v[112:115]
	v_mfma_f32_16x16x32_bf16 v[112:115], v[174:177], v[188:191], v[112:115]
	v_mfma_f32_16x16x32_bf16 v[100:103], v[162:165], v[192:195], v[100:103]
	v_mfma_f32_16x16x32_bf16 v[100:103], v[166:169], v[196:199], v[100:103]
	v_mfma_f32_16x16x32_bf16 v[96:99], v[170:173], v[192:195], v[96:99]
	v_mfma_f32_16x16x32_bf16 v[96:99], v[174:177], v[196:199], v[96:99]
	s_barrier
	v_mfma_f32_16x16x32_bf16 v[84:87], v[162:165], v[200:203], v[84:87]
	v_mfma_f32_16x16x32_bf16 v[84:87], v[166:169], v[204:207], v[84:87]
	v_mfma_f32_16x16x32_bf16 v[80:83], v[170:173], v[200:203], v[80:83]
	v_mfma_f32_16x16x32_bf16 v[80:83], v[174:177], v[204:207], v[80:83]
	v_mfma_f32_16x16x32_bf16 v[68:71], v[162:165], v[208:211], v[68:71]
	v_mfma_f32_16x16x32_bf16 v[68:71], v[166:169], v[212:215], v[68:71]
	v_mfma_f32_16x16x32_bf16 v[64:67], v[170:173], v[208:211], v[64:67]
	v_mfma_f32_16x16x32_bf16 v[64:67], v[174:177], v[212:215], v[64:67]
	s_setprio 0
	s_add_i32 s56, s77, s60
	v_lshl_add_u64 v[178:179], v[178:179], 0, s[12:13]
	s_mov_b32 m0, s56
	ds_read_b128 v[184:187], v149 offset:49152
	ds_read_b128 v[188:191], v149 offset:50176
	ds_read_b128 v[192:195], v149 offset:51200
	ds_read_b128 v[196:199], v149 offset:52224
	ds_read_b128 v[200:203], v149 offset:53248
	ds_read_b128 v[204:207], v149 offset:54272
	ds_read_b128 v[208:211], v149 offset:55296
	ds_read_b128 v[212:215], v149 offset:56320
	global_load_lds_dwordx4 v[178:179], off
	s_add_i32 m0, s56, 0x2000
	s_add_u32 s54, s54, 0x40080
	v_lshl_add_u64 v[178:179], v[216:217], 0, s[12:13]
	s_addc_u32 s55, s55, 0
	s_add_i32 s56, s79, s60
	global_load_lds_dwordx4 v[178:179], off
	v_lshl_add_u64 v[178:179], s[54:55], 0, v[130:131]
	s_mov_b32 m0, s56
	s_nop 0
	global_load_lds_dwordx4 v[178:179], off
	v_lshl_add_u64 v[178:179], s[54:55], 0, v[128:129]
	s_add_i32 m0, s56, 0x2000
	s_nop 0
	global_load_lds_dwordx4 v[178:179], off
	v_lshl_add_u64 v[178:179], v[218:219], 0, s[12:13]
	s_mov_b32 m0, s66
	s_nop 0
	global_load_lds_dwordx4 v[178:179], off
	v_lshl_add_u64 v[178:179], v[220:221], 0, s[12:13]
	s_mov_b32 m0, s67
	s_nop 0
	global_load_lds_dwordx4 v[178:179], off
	s_waitcnt vmcnt(8)
	s_waitcnt lgkmcnt(0)
	s_barrier
	s_waitcnt lgkmcnt(0)
	v_mfma_f32_16x16x32_bf16 v[60:63], v[140:143], v[184:187], v[60:63]
	v_mfma_f32_16x16x32_bf16 v[60:63], v[150:153], v[188:191], v[60:63]
	v_mfma_f32_16x16x32_bf16 v[56:59], v[154:157], v[184:187], v[56:59]
	v_mfma_f32_16x16x32_bf16 v[56:59], v[158:161], v[188:191], v[56:59]
	v_mfma_f32_16x16x32_bf16 v[44:47], v[140:143], v[192:195], v[44:47]
	v_mfma_f32_16x16x32_bf16 v[44:47], v[150:153], v[196:199], v[44:47]
	v_mfma_f32_16x16x32_bf16 v[40:43], v[154:157], v[192:195], v[40:43]
	v_mfma_f32_16x16x32_bf16 v[40:43], v[158:161], v[196:199], v[40:43]
	s_setprio 1
	v_mfma_f32_16x16x32_bf16 v[28:31], v[140:143], v[200:203], v[28:31]
	v_mfma_f32_16x16x32_bf16 v[28:31], v[150:153], v[204:207], v[28:31]
	v_mfma_f32_16x16x32_bf16 v[24:27], v[154:157], v[200:203], v[24:27]
	v_mfma_f32_16x16x32_bf16 v[24:27], v[158:161], v[204:207], v[24:27]
	v_mfma_f32_16x16x32_bf16 v[12:15], v[140:143], v[208:211], v[12:15]
	v_mfma_f32_16x16x32_bf16 v[12:15], v[150:153], v[212:215], v[12:15]
	v_mfma_f32_16x16x32_bf16 v[8:11], v[154:157], v[208:211], v[8:11]
	v_mfma_f32_16x16x32_bf16 v[8:11], v[158:161], v[212:215], v[8:11]
	v_mfma_f32_16x16x32_bf16 v[52:55], v[162:165], v[184:187], v[52:55]
	v_mfma_f32_16x16x32_bf16 v[52:55], v[166:169], v[188:191], v[52:55]
	v_mfma_f32_16x16x32_bf16 v[48:51], v[170:173], v[184:187], v[48:51]
	v_mfma_f32_16x16x32_bf16 v[48:51], v[174:177], v[188:191], v[48:51]
	v_mfma_f32_16x16x32_bf16 v[36:39], v[162:165], v[192:195], v[36:39]
	v_mfma_f32_16x16x32_bf16 v[36:39], v[166:169], v[196:199], v[36:39]
	v_mfma_f32_16x16x32_bf16 v[32:35], v[170:173], v[192:195], v[32:35]
	v_mfma_f32_16x16x32_bf16 v[32:35], v[174:177], v[196:199], v[32:35]
	s_barrier
	v_mfma_f32_16x16x32_bf16 v[20:23], v[162:165], v[200:203], v[20:23]
	v_mfma_f32_16x16x32_bf16 v[20:23], v[166:169], v[204:207], v[20:23]
	v_mfma_f32_16x16x32_bf16 v[16:19], v[170:173], v[200:203], v[16:19]
	v_mfma_f32_16x16x32_bf16 v[16:19], v[174:177], v[204:207], v[16:19]
	v_mfma_f32_16x16x32_bf16 v[4:7], v[162:165], v[208:211], v[4:7]
	v_mfma_f32_16x16x32_bf16 v[4:7], v[166:169], v[212:215], v[4:7]
	v_mfma_f32_16x16x32_bf16 v[0:3], v[170:173], v[208:211], v[0:3]
	v_mfma_f32_16x16x32_bf16 v[0:3], v[174:177], v[212:215], v[0:3]
	s_setprio 0
	s_add_i32 s76, s76, 2
	s_add_u32 s52, s52, 0x100
	s_addc_u32 s53, s53, 0
	s_add_u32 s74, s74, 0x100
	s_addc_u32 s75, s75, 0
	s_cmp_gt_u32 s76, 13
	s_cbranch_scc0 .LBB0_951
	s_and_b64 vcc, exec, s[16:17]
	s_cbranch_vccz .LBB0_954
	s_barrier

.LBB0_1030:
	s_add_u32 s86, s56, 0x100
	s_addc_u32 s87, s57, 0
	s_mov_b32 s88, -2
	ds_read_b128 v[152:155], v149
	ds_read_b128 v[156:159], v149 offset:1024
	ds_read_b128 v[160:163], v149 offset:2048
	ds_read_b128 v[164:167], v149 offset:3072
	ds_read_b128 v[168:171], v150
	ds_read_b128 v[172:175], v150 offset:1024
	ds_read_b128 v[176:179], v150 offset:2048
	ds_read_b128 v[184:187], v150 offset:3072
	s_add_u32 s56, s54, 0x100
	s_addc_u32 s57, s55, 0
	s_cmp_eq_u32 s88, 40
	s_cselect_b32 s61, s13, s57
	s_cselect_b32 s60, s12, s56
	s_cselect_b32 s59, s53, s87
	s_cselect_b32 s58, s52, s86
	v_lshl_add_u64 v[144:145], s[54:55], 0, v[136:137]
	s_add_i32 m0, s65, 0xc000
	ds_read_b128 v[188:191], v151
	ds_read_b128 v[192:195], v151 offset:1024
	ds_read_b128 v[196:199], v151 offset:2048
	ds_read_b128 v[200:203], v151 offset:3072
	ds_read_b128 v[204:207], v151 offset:4096
	ds_read_b128 v[208:211], v151 offset:5120
	ds_read_b128 v[212:215], v151 offset:6144
	ds_read_b128 v[216:219], v151 offset:7168
	global_load_lds_dwordx4 v[144:145], off
	v_lshl_add_u64 v[144:145], s[54:55], 0, v[138:139]
	s_add_i32 m0, s65, 0xe000
	s_nop 0
	global_load_lds_dwordx4 v[144:145], off
	s_waitcnt vmcnt(8)
	s_waitcnt lgkmcnt(0)
	s_barrier
	s_waitcnt lgkmcnt(0)
	v_mfma_f32_16x16x32_bf16 v[124:127], v[152:155], v[188:191], 0
	v_mfma_f32_16x16x32_bf16 v[124:127], v[156:159], v[192:195], v[124:127]
	v_mfma_f32_16x16x32_bf16 v[120:123], v[160:163], v[188:191], 0
	v_mfma_f32_16x16x32_bf16 v[120:123], v[164:167], v[192:195], v[120:123]
	v_mfma_f32_16x16x32_bf16 v[116:119], v[152:155], v[196:199], 0
	v_mfma_f32_16x16x32_bf16 v[116:119], v[156:159], v[200:203], v[116:119]
	v_mfma_f32_16x16x32_bf16 v[108:111], v[160:163], v[196:199], 0
	v_mfma_f32_16x16x32_bf16 v[108:111], v[164:167], v[200:203], v[108:111]
	s_setprio 1
	v_mfma_f32_16x16x32_bf16 v[100:103], v[152:155], v[204:207], 0
	v_mfma_f32_16x16x32_bf16 v[100:103], v[156:159], v[208:211], v[100:103]
	v_mfma_f32_16x16x32_bf16 v[92:95], v[160:163], v[204:207], 0
	v_mfma_f32_16x16x32_bf16 v[92:95], v[164:167], v[208:211], v[92:95]
	v_mfma_f32_16x16x32_bf16 v[84:87], v[152:155], v[212:215], 0
	v_mfma_f32_16x16x32_bf16 v[84:87], v[156:159], v[216:219], v[84:87]
	v_mfma_f32_16x16x32_bf16 v[76:79], v[160:163], v[212:215], 0
	v_mfma_f32_16x16x32_bf16 v[76:79], v[164:167], v[216:219], v[76:79]
	v_mfma_f32_16x16x32_bf16 v[112:115], v[168:171], v[188:191], 0
	v_mfma_f32_16x16x32_bf16 v[112:115], v[172:175], v[192:195], v[112:115]
	v_mfma_f32_16x16x32_bf16 v[104:107], v[176:179], v[188:191], 0
	v_mfma_f32_16x16x32_bf16 v[104:107], v[184:187], v[192:195], v[104:107]
	v_mfma_f32_16x16x32_bf16 v[96:99], v[168:171], v[196:199], 0
	v_mfma_f32_16x16x32_bf16 v[96:99], v[172:175], v[200:203], v[96:99]
	v_mfma_f32_16x16x32_bf16 v[88:91], v[176:179], v[196:199], 0
	v_mfma_f32_16x16x32_bf16 v[88:91], v[184:187], v[200:203], v[88:91]
	s_barrier
	v_mfma_f32_16x16x32_bf16 v[80:83], v[168:171], v[204:207], 0
	v_mfma_f32_16x16x32_bf16 v[80:83], v[172:175], v[208:211], v[80:83]
	v_mfma_f32_16x16x32_bf16 v[72:75], v[176:179], v[204:207], 0
	v_mfma_f32_16x16x32_bf16 v[72:75], v[184:187], v[208:211], v[72:75]
	v_mfma_f32_16x16x32_bf16 v[68:71], v[168:171], v[212:215], 0
	v_mfma_f32_16x16x32_bf16 v[68:71], v[172:175], v[216:219], v[68:71]
	v_mfma_f32_16x16x32_bf16 v[64:67], v[176:179], v[212:215], 0
	v_mfma_f32_16x16x32_bf16 v[64:67], v[184:187], v[216:219], v[64:67]
	s_setprio 0
	s_add_i32 s54, s72, s64
	v_lshl_add_u64 v[144:145], s[58:59], 0, v[130:131]
	s_mov_b32 m0, s54
	ds_read_b128 v[188:191], v151 offset:16384
	ds_read_b128 v[192:195], v151 offset:17408
	ds_read_b128 v[196:199], v151 offset:18432
	ds_read_b128 v[200:203], v151 offset:19456
	ds_read_b128 v[204:207], v151 offset:20480
	ds_read_b128 v[208:211], v151 offset:21504
	ds_read_b128 v[212:215], v151 offset:22528
	ds_read_b128 v[216:219], v151 offset:23552
	global_load_lds_dwordx4 v[144:145], off
	s_add_i32 m0, s54, 0x2000
	s_add_u32 s54, s58, 0xb0000
	v_lshl_add_u64 v[220:221], s[58:59], 0, v[134:135]
	s_addc_u32 s55, s59, 0
	s_add_i32 s79, s73, s64
	global_load_lds_dwordx4 v[220:221], off
	v_lshl_add_u64 v[222:223], s[54:55], 0, v[130:131]
	s_mov_b32 m0, s79
	v_lshl_add_u64 v[224:225], s[60:61], 0, v[132:133]
	global_load_lds_dwordx4 v[222:223], off
	v_lshl_add_u64 v[222:223], s[54:55], 0, v[134:135]
	s_add_i32 m0, s79, 0x2000
	s_nop 0
	global_load_lds_dwordx4 v[222:223], off
	v_lshl_add_u64 v[222:223], s[60:61], 0, v[128:129]
	s_mov_b32 m0, s65
	s_nop 0
	global_load_lds_dwordx4 v[222:223], off
	s_mov_b32 m0, s66
	s_nop 0
	global_load_lds_dwordx4 v[224:225], off
	s_waitcnt vmcnt(8)
	s_waitcnt lgkmcnt(0)
	s_barrier
	s_waitcnt lgkmcnt(0)
	v_mfma_f32_16x16x32_bf16 v[60:63], v[152:155], v[188:191], 0
	v_mfma_f32_16x16x32_bf16 v[60:63], v[156:159], v[192:195], v[60:63]
	v_mfma_f32_16x16x32_bf16 v[56:59], v[160:163], v[188:191], 0
	v_mfma_f32_16x16x32_bf16 v[56:59], v[164:167], v[192:195], v[56:59]
	v_mfma_f32_16x16x32_bf16 v[52:55], v[152:155], v[196:199], 0
	v_mfma_f32_16x16x32_bf16 v[52:55], v[156:159], v[200:203], v[52:55]
	v_mfma_f32_16x16x32_bf16 v[44:47], v[160:163], v[196:199], 0
	v_mfma_f32_16x16x32_bf16 v[44:47], v[164:167], v[200:203], v[44:47]
	s_setprio 1
	v_mfma_f32_16x16x32_bf16 v[36:39], v[152:155], v[204:207], 0
	v_mfma_f32_16x16x32_bf16 v[36:39], v[156:159], v[208:211], v[36:39]
	v_mfma_f32_16x16x32_bf16 v[28:31], v[160:163], v[204:207], 0
	v_mfma_f32_16x16x32_bf16 v[28:31], v[164:167], v[208:211], v[28:31]
	v_mfma_f32_16x16x32_bf16 v[20:23], v[152:155], v[212:215], 0
	v_mfma_f32_16x16x32_bf16 v[20:23], v[156:159], v[216:219], v[20:23]
	v_mfma_f32_16x16x32_bf16 v[12:15], v[160:163], v[212:215], 0
	v_mfma_f32_16x16x32_bf16 v[12:15], v[164:167], v[216:219], v[12:15]
	v_mfma_f32_16x16x32_bf16 v[48:51], v[168:171], v[188:191], 0
	v_mfma_f32_16x16x32_bf16 v[48:51], v[172:175], v[192:195], v[48:51]
	v_mfma_f32_16x16x32_bf16 v[40:43], v[176:179], v[188:191], 0
	v_mfma_f32_16x16x32_bf16 v[40:43], v[184:187], v[192:195], v[40:43]
	v_mfma_f32_16x16x32_bf16 v[32:35], v[168:171], v[196:199], 0
	v_mfma_f32_16x16x32_bf16 v[32:35], v[172:175], v[200:203], v[32:35]
	v_mfma_f32_16x16x32_bf16 v[24:27], v[176:179], v[196:199], 0
	v_mfma_f32_16x16x32_bf16 v[24:27], v[184:187], v[200:203], v[24:27]
	s_barrier
	v_mfma_f32_16x16x32_bf16 v[16:19], v[168:171], v[204:207], 0
	v_mfma_f32_16x16x32_bf16 v[16:19], v[172:175], v[208:211], v[16:19]
	v_mfma_f32_16x16x32_bf16 v[8:11], v[176:179], v[204:207], 0
	v_mfma_f32_16x16x32_bf16 v[8:11], v[184:187], v[208:211], v[8:11]
	v_mfma_f32_16x16x32_bf16 v[4:7], v[168:171], v[212:215], 0
	v_mfma_f32_16x16x32_bf16 v[4:7], v[172:175], v[216:219], v[4:7]
	v_mfma_f32_16x16x32_bf16 v[0:3], v[176:179], v[212:215], 0
	v_mfma_f32_16x16x32_bf16 v[0:3], v[184:187], v[216:219], v[0:3]
	s_setprio 0
	s_branch .Lmid_gemm8
.LBB0_1031:
	ds_read_b128 v[152:155], v149
	ds_read_b128 v[156:159], v149 offset:1024
	ds_read_b128 v[160:163], v149 offset:2048
	ds_read_b128 v[164:167], v149 offset:3072
	ds_read_b128 v[168:171], v150
	ds_read_b128 v[172:175], v150 offset:1024
	ds_read_b128 v[176:179], v150 offset:2048
	ds_read_b128 v[184:187], v150 offset:3072
	s_add_u32 s56, s54, 0x100
	s_addc_u32 s57, s55, 0
	s_cmp_eq_u32 s88, 40
	s_cselect_b32 s61, s13, s57
	s_cselect_b32 s60, s12, s56
	s_cselect_b32 s59, s53, s87
	s_cselect_b32 s58, s52, s86
	v_lshl_add_u64 v[144:145], s[54:55], 0, v[136:137]
	s_add_i32 m0, s65, 0xc000
	ds_read_b128 v[188:191], v151
	ds_read_b128 v[192:195], v151 offset:1024
	ds_read_b128 v[196:199], v151 offset:2048
	ds_read_b128 v[200:203], v151 offset:3072
	ds_read_b128 v[204:207], v151 offset:4096
	ds_read_b128 v[208:211], v151 offset:5120
	ds_read_b128 v[212:215], v151 offset:6144
	ds_read_b128 v[216:219], v151 offset:7168
	global_load_lds_dwordx4 v[144:145], off
	v_lshl_add_u64 v[144:145], s[54:55], 0, v[138:139]
	s_add_i32 m0, s65, 0xe000
	s_nop 0
	global_load_lds_dwordx4 v[144:145], off
	s_waitcnt vmcnt(8)
	s_waitcnt lgkmcnt(0)
	s_barrier
	s_waitcnt lgkmcnt(0)
	v_mfma_f32_16x16x32_bf16 v[124:127], v[152:155], v[188:191], v[124:127]
	v_mfma_f32_16x16x32_bf16 v[124:127], v[156:159], v[192:195], v[124:127]
	v_mfma_f32_16x16x32_bf16 v[120:123], v[160:163], v[188:191], v[120:123]
	v_mfma_f32_16x16x32_bf16 v[120:123], v[164:167], v[192:195], v[120:123]
	v_mfma_f32_16x16x32_bf16 v[116:119], v[152:155], v[196:199], v[116:119]
	v_mfma_f32_16x16x32_bf16 v[116:119], v[156:159], v[200:203], v[116:119]
	v_mfma_f32_16x16x32_bf16 v[108:111], v[160:163], v[196:199], v[108:111]
	v_mfma_f32_16x16x32_bf16 v[108:111], v[164:167], v[200:203], v[108:111]
	s_setprio 1
	v_mfma_f32_16x16x32_bf16 v[100:103], v[152:155], v[204:207], v[100:103]
	v_mfma_f32_16x16x32_bf16 v[100:103], v[156:159], v[208:211], v[100:103]
	v_mfma_f32_16x16x32_bf16 v[92:95], v[160:163], v[204:207], v[92:95]
	v_mfma_f32_16x16x32_bf16 v[92:95], v[164:167], v[208:211], v[92:95]
	v_mfma_f32_16x16x32_bf16 v[84:87], v[152:155], v[212:215], v[84:87]
	v_mfma_f32_16x16x32_bf16 v[84:87], v[156:159], v[216:219], v[84:87]
	v_mfma_f32_16x16x32_bf16 v[76:79], v[160:163], v[212:215], v[76:79]
	v_mfma_f32_16x16x32_bf16 v[76:79], v[164:167], v[216:219], v[76:79]
	v_mfma_f32_16x16x32_bf16 v[112:115], v[168:171], v[188:191], v[112:115]
	v_mfma_f32_16x16x32_bf16 v[112:115], v[172:175], v[192:195], v[112:115]
	v_mfma_f32_16x16x32_bf16 v[104:107], v[176:179], v[188:191], v[104:107]
	v_mfma_f32_16x16x32_bf16 v[104:107], v[184:187], v[192:195], v[104:107]
	v_mfma_f32_16x16x32_bf16 v[96:99], v[168:171], v[196:199], v[96:99]
	v_mfma_f32_16x16x32_bf16 v[96:99], v[172:175], v[200:203], v[96:99]
	v_mfma_f32_16x16x32_bf16 v[88:91], v[176:179], v[196:199], v[88:91]
	v_mfma_f32_16x16x32_bf16 v[88:91], v[184:187], v[200:203], v[88:91]
	s_barrier
	v_mfma_f32_16x16x32_bf16 v[80:83], v[168:171], v[204:207], v[80:83]
	v_mfma_f32_16x16x32_bf16 v[80:83], v[172:175], v[208:211], v[80:83]
	v_mfma_f32_16x16x32_bf16 v[72:75], v[176:179], v[204:207], v[72:75]
	v_mfma_f32_16x16x32_bf16 v[72:75], v[184:187], v[208:211], v[72:75]
	v_mfma_f32_16x16x32_bf16 v[68:71], v[168:171], v[212:215], v[68:71]
	v_mfma_f32_16x16x32_bf16 v[68:71], v[172:175], v[216:219], v[68:71]
	v_mfma_f32_16x16x32_bf16 v[64:67], v[176:179], v[212:215], v[64:67]
	v_mfma_f32_16x16x32_bf16 v[64:67], v[184:187], v[216:219], v[64:67]
	s_setprio 0
	s_add_i32 s54, s72, s64
	v_lshl_add_u64 v[144:145], s[58:59], 0, v[130:131]
	s_mov_b32 m0, s54
	ds_read_b128 v[188:191], v151 offset:16384
	ds_read_b128 v[192:195], v151 offset:17408
	ds_read_b128 v[196:199], v151 offset:18432
	ds_read_b128 v[200:203], v151 offset:19456
	ds_read_b128 v[204:207], v151 offset:20480
	ds_read_b128 v[208:211], v151 offset:21504
	ds_read_b128 v[212:215], v151 offset:22528
	ds_read_b128 v[216:219], v151 offset:23552
	global_load_lds_dwordx4 v[144:145], off
	s_add_i32 m0, s54, 0x2000
	s_add_u32 s54, s58, 0xb0000
	v_lshl_add_u64 v[220:221], s[58:59], 0, v[134:135]
	s_addc_u32 s55, s59, 0
	s_add_i32 s79, s73, s64
	global_load_lds_dwordx4 v[220:221], off
	v_lshl_add_u64 v[222:223], s[54:55], 0, v[130:131]
	s_mov_b32 m0, s79
	v_lshl_add_u64 v[224:225], s[60:61], 0, v[132:133]
	global_load_lds_dwordx4 v[222:223], off
	v_lshl_add_u64 v[222:223], s[54:55], 0, v[134:135]
	s_add_i32 m0, s79, 0x2000
	s_nop 0
	global_load_lds_dwordx4 v[222:223], off
	v_lshl_add_u64 v[222:223], s[60:61], 0, v[128:129]
	s_mov_b32 m0, s65
	s_nop 0
	global_load_lds_dwordx4 v[222:223], off
	s_mov_b32 m0, s66
	s_nop 0
	global_load_lds_dwordx4 v[224:225], off
	s_waitcnt vmcnt(8)
	s_waitcnt lgkmcnt(0)
	s_barrier
	s_waitcnt lgkmcnt(0)
	v_mfma_f32_16x16x32_bf16 v[60:63], v[152:155], v[188:191], v[60:63]
	v_mfma_f32_16x16x32_bf16 v[60:63], v[156:159], v[192:195], v[60:63]
	v_mfma_f32_16x16x32_bf16 v[56:59], v[160:163], v[188:191], v[56:59]
	v_mfma_f32_16x16x32_bf16 v[56:59], v[164:167], v[192:195], v[56:59]
	v_mfma_f32_16x16x32_bf16 v[52:55], v[152:155], v[196:199], v[52:55]
	v_mfma_f32_16x16x32_bf16 v[52:55], v[156:159], v[200:203], v[52:55]
	v_mfma_f32_16x16x32_bf16 v[44:47], v[160:163], v[196:199], v[44:47]
	v_mfma_f32_16x16x32_bf16 v[44:47], v[164:167], v[200:203], v[44:47]
	s_setprio 1
	v_mfma_f32_16x16x32_bf16 v[36:39], v[152:155], v[204:207], v[36:39]
	v_mfma_f32_16x16x32_bf16 v[36:39], v[156:159], v[208:211], v[36:39]
	v_mfma_f32_16x16x32_bf16 v[28:31], v[160:163], v[204:207], v[28:31]
	v_mfma_f32_16x16x32_bf16 v[28:31], v[164:167], v[208:211], v[28:31]
	v_mfma_f32_16x16x32_bf16 v[20:23], v[152:155], v[212:215], v[20:23]
	v_mfma_f32_16x16x32_bf16 v[20:23], v[156:159], v[216:219], v[20:23]
	v_mfma_f32_16x16x32_bf16 v[12:15], v[160:163], v[212:215], v[12:15]
	v_mfma_f32_16x16x32_bf16 v[12:15], v[164:167], v[216:219], v[12:15]
	v_mfma_f32_16x16x32_bf16 v[48:51], v[168:171], v[188:191], v[48:51]
	v_mfma_f32_16x16x32_bf16 v[48:51], v[172:175], v[192:195], v[48:51]
	v_mfma_f32_16x16x32_bf16 v[40:43], v[176:179], v[188:191], v[40:43]
	v_mfma_f32_16x16x32_bf16 v[40:43], v[184:187], v[192:195], v[40:43]
	v_mfma_f32_16x16x32_bf16 v[32:35], v[168:171], v[196:199], v[32:35]
	v_mfma_f32_16x16x32_bf16 v[32:35], v[172:175], v[200:203], v[32:35]
	v_mfma_f32_16x16x32_bf16 v[24:27], v[176:179], v[196:199], v[24:27]
	v_mfma_f32_16x16x32_bf16 v[24:27], v[184:187], v[200:203], v[24:27]
	s_barrier
	v_mfma_f32_16x16x32_bf16 v[16:19], v[168:171], v[204:207], v[16:19]
	v_mfma_f32_16x16x32_bf16 v[16:19], v[172:175], v[208:211], v[16:19]
	v_mfma_f32_16x16x32_bf16 v[8:11], v[176:179], v[204:207], v[8:11]
	v_mfma_f32_16x16x32_bf16 v[8:11], v[184:187], v[208:211], v[8:11]
	v_mfma_f32_16x16x32_bf16 v[4:7], v[168:171], v[212:215], v[4:7]
	v_mfma_f32_16x16x32_bf16 v[4:7], v[172:175], v[216:219], v[4:7]
	v_mfma_f32_16x16x32_bf16 v[0:3], v[176:179], v[212:215], v[0:3]
	v_mfma_f32_16x16x32_bf16 v[0:3], v[184:187], v[216:219], v[0:3]
	s_setprio 0
.Lmid_gemm8:
	s_add_i32 s79, 0, 0x18000
	s_add_i32 s89, 0, 0x1c000
	v_add_u32_e32 v164, s79, v147
	v_add_u32_e32 v181, s89, v147
	ds_read_b128 v[152:155], v164
	ds_read_b128 v[156:159], v164 offset:1024
	ds_read_b128 v[160:163], v164 offset:2048
	ds_read_b128 v[164:167], v164 offset:3072
	ds_read_b128 v[168:171], v181
	ds_read_b128 v[172:175], v181 offset:1024
	ds_read_b128 v[176:179], v181 offset:2048
	ds_read_b128 v[184:187], v181 offset:3072
	s_add_u32 s54, s60, 0xb0000
	s_addc_u32 s55, s61, 0
	s_mov_b32 m0, s67
	v_lshl_add_u64 v[226:227], s[54:55], 0, v[128:129]
	ds_read_b128 v[188:191], v151 offset:32768
	ds_read_b128 v[192:195], v151 offset:33792
	ds_read_b128 v[196:199], v151 offset:34816
	ds_read_b128 v[200:203], v151 offset:35840
	ds_read_b128 v[204:207], v151 offset:36864
	ds_read_b128 v[208:211], v151 offset:37888
	ds_read_b128 v[212:215], v151 offset:38912
	ds_read_b128 v[216:219], v151 offset:39936
	global_load_lds_dwordx4 v[226:227], off
	v_lshl_add_u64 v[226:227], s[54:55], 0, v[132:133]
	s_mov_b32 m0, s68
	s_nop 0
	global_load_lds_dwordx4 v[226:227], off
	s_waitcnt vmcnt(8)
	s_waitcnt lgkmcnt(0)
	s_barrier
	s_waitcnt lgkmcnt(0)
	v_mfma_f32_16x16x32_bf16 v[124:127], v[152:155], v[188:191], v[124:127]
	v_mfma_f32_16x16x32_bf16 v[124:127], v[156:159], v[192:195], v[124:127]
	v_mfma_f32_16x16x32_bf16 v[120:123], v[160:163], v[188:191], v[120:123]
	v_mfma_f32_16x16x32_bf16 v[120:123], v[164:167], v[192:195], v[120:123]
	v_mfma_f32_16x16x32_bf16 v[116:119], v[152:155], v[196:199], v[116:119]
	v_mfma_f32_16x16x32_bf16 v[116:119], v[156:159], v[200:203], v[116:119]
	v_mfma_f32_16x16x32_bf16 v[108:111], v[160:163], v[196:199], v[108:111]
	v_mfma_f32_16x16x32_bf16 v[108:111], v[164:167], v[200:203], v[108:111]
	s_setprio 1
	v_mfma_f32_16x16x32_bf16 v[100:103], v[152:155], v[204:207], v[100:103]
	v_mfma_f32_16x16x32_bf16 v[100:103], v[156:159], v[208:211], v[100:103]
	v_mfma_f32_16x16x32_bf16 v[92:95], v[160:163], v[204:207], v[92:95]
	v_mfma_f32_16x16x32_bf16 v[92:95], v[164:167], v[208:211], v[92:95]
	v_mfma_f32_16x16x32_bf16 v[84:87], v[152:155], v[212:215], v[84:87]
	v_mfma_f32_16x16x32_bf16 v[84:87], v[156:159], v[216:219], v[84:87]
	v_mfma_f32_16x16x32_bf16 v[76:79], v[160:163], v[212:215], v[76:79]
	v_mfma_f32_16x16x32_bf16 v[76:79], v[164:167], v[216:219], v[76:79]
	v_mfma_f32_16x16x32_bf16 v[112:115], v[168:171], v[188:191], v[112:115]
	v_mfma_f32_16x16x32_bf16 v[112:115], v[172:175], v[192:195], v[112:115]
	v_mfma_f32_16x16x32_bf16 v[104:107], v[176:179], v[188:191], v[104:107]
	v_mfma_f32_16x16x32_bf16 v[104:107], v[184:187], v[192:195], v[104:107]
	v_mfma_f32_16x16x32_bf16 v[96:99], v[168:171], v[196:199], v[96:99]
	v_mfma_f32_16x16x32_bf16 v[96:99], v[172:175], v[200:203], v[96:99]
	v_mfma_f32_16x16x32_bf16 v[88:91], v[176:179], v[196:199], v[88:91]
	v_mfma_f32_16x16x32_bf16 v[88:91], v[184:187], v[200:203], v[88:91]
	s_barrier
	v_mfma_f32_16x16x32_bf16 v[80:83], v[168:171], v[204:207], v[80:83]
	v_mfma_f32_16x16x32_bf16 v[80:83], v[172:175], v[208:211], v[80:83]
	v_mfma_f32_16x16x32_bf16 v[72:75], v[176:179], v[204:207], v[72:75]
	v_mfma_f32_16x16x32_bf16 v[72:75], v[184:187], v[208:211], v[72:75]
	v_mfma_f32_16x16x32_bf16 v[68:71], v[168:171], v[212:215], v[68:71]
	v_mfma_f32_16x16x32_bf16 v[68:71], v[172:175], v[216:219], v[68:71]
	v_mfma_f32_16x16x32_bf16 v[64:67], v[176:179], v[212:215], v[64:67]
	v_mfma_f32_16x16x32_bf16 v[64:67], v[184:187], v[216:219], v[64:67]
	s_setprio 0
	s_add_i32 s54, s79, s64
	v_lshl_add_u64 v[144:145], v[144:145], 0, s[16:17]
	s_mov_b32 m0, s54
	ds_read_b128 v[188:191], v151 offset:49152
	ds_read_b128 v[192:195], v151 offset:50176
	ds_read_b128 v[196:199], v151 offset:51200
	ds_read_b128 v[200:203], v151 offset:52224
	ds_read_b128 v[204:207], v151 offset:53248
	ds_read_b128 v[208:211], v151 offset:54272
	ds_read_b128 v[212:215], v151 offset:55296
	ds_read_b128 v[216:219], v151 offset:56320
	global_load_lds_dwordx4 v[144:145], off
	s_add_i32 m0, s54, 0x2000
	s_add_u32 s54, s58, 0xb0080
	v_lshl_add_u64 v[144:145], v[220:221], 0, s[16:17]
	s_addc_u32 s55, s59, 0
	s_add_i32 s58, s89, s64
	global_load_lds_dwordx4 v[144:145], off
	v_lshl_add_u64 v[144:145], s[54:55], 0, v[130:131]
	s_mov_b32 m0, s58
	s_nop 0
	global_load_lds_dwordx4 v[144:145], off
	v_lshl_add_u64 v[144:145], s[54:55], 0, v[134:135]
	s_add_i32 m0, s58, 0x2000
	s_nop 0
	global_load_lds_dwordx4 v[144:145], off
	v_lshl_add_u64 v[144:145], v[222:223], 0, s[16:17]
	s_mov_b32 m0, s70
	s_nop 0
	global_load_lds_dwordx4 v[144:145], off
	v_lshl_add_u64 v[144:145], v[224:225], 0, s[16:17]
	s_mov_b32 m0, s71
	s_nop 0
	global_load_lds_dwordx4 v[144:145], off
	s_waitcnt vmcnt(8)
	s_waitcnt lgkmcnt(0)
	s_barrier
	s_waitcnt lgkmcnt(0)
	v_mfma_f32_16x16x32_bf16 v[60:63], v[152:155], v[188:191], v[60:63]
	v_mfma_f32_16x16x32_bf16 v[60:63], v[156:159], v[192:195], v[60:63]
	v_mfma_f32_16x16x32_bf16 v[56:59], v[160:163], v[188:191], v[56:59]
	v_mfma_f32_16x16x32_bf16 v[56:59], v[164:167], v[192:195], v[56:59]
	v_mfma_f32_16x16x32_bf16 v[52:55], v[152:155], v[196:199], v[52:55]
	v_mfma_f32_16x16x32_bf16 v[52:55], v[156:159], v[200:203], v[52:55]
	v_mfma_f32_16x16x32_bf16 v[44:47], v[160:163], v[196:199], v[44:47]
	v_mfma_f32_16x16x32_bf16 v[44:47], v[164:167], v[200:203], v[44:47]
	s_setprio 1
	v_mfma_f32_16x16x32_bf16 v[36:39], v[152:155], v[204:207], v[36:39]
	v_mfma_f32_16x16x32_bf16 v[36:39], v[156:159], v[208:211], v[36:39]
	v_mfma_f32_16x16x32_bf16 v[28:31], v[160:163], v[204:207], v[28:31]
	v_mfma_f32_16x16x32_bf16 v[28:31], v[164:167], v[208:211], v[28:31]
	v_mfma_f32_16x16x32_bf16 v[20:23], v[152:155], v[212:215], v[20:23]
	v_mfma_f32_16x16x32_bf16 v[20:23], v[156:159], v[216:219], v[20:23]
	v_mfma_f32_16x16x32_bf16 v[12:15], v[160:163], v[212:215], v[12:15]
	v_mfma_f32_16x16x32_bf16 v[12:15], v[164:167], v[216:219], v[12:15]
	v_mfma_f32_16x16x32_bf16 v[48:51], v[168:171], v[188:191], v[48:51]
	v_mfma_f32_16x16x32_bf16 v[48:51], v[172:175], v[192:195], v[48:51]
	v_mfma_f32_16x16x32_bf16 v[40:43], v[176:179], v[188:191], v[40:43]
	v_mfma_f32_16x16x32_bf16 v[40:43], v[184:187], v[192:195], v[40:43]
	v_mfma_f32_16x16x32_bf16 v[32:35], v[168:171], v[196:199], v[32:35]
	v_mfma_f32_16x16x32_bf16 v[32:35], v[172:175], v[200:203], v[32:35]
	v_mfma_f32_16x16x32_bf16 v[24:27], v[176:179], v[196:199], v[24:27]
	v_mfma_f32_16x16x32_bf16 v[24:27], v[184:187], v[200:203], v[24:27]
	s_barrier
	v_mfma_f32_16x16x32_bf16 v[16:19], v[168:171], v[204:207], v[16:19]
	v_mfma_f32_16x16x32_bf16 v[16:19], v[172:175], v[208:211], v[16:19]
	v_mfma_f32_16x16x32_bf16 v[8:11], v[176:179], v[204:207], v[8:11]
	v_mfma_f32_16x16x32_bf16 v[8:11], v[184:187], v[208:211], v[8:11]
	v_mfma_f32_16x16x32_bf16 v[4:7], v[168:171], v[212:215], v[4:7]
	v_mfma_f32_16x16x32_bf16 v[4:7], v[172:175], v[216:219], v[4:7]
	v_mfma_f32_16x16x32_bf16 v[0:3], v[176:179], v[212:215], v[0:3]
	v_mfma_f32_16x16x32_bf16 v[0:3], v[184:187], v[216:219], v[0:3]
	s_setprio 0
	s_add_i32 s88, s88, 2
	s_add_u32 s86, s86, 0x100
	s_addc_u32 s87, s87, 0
	s_cmp_gt_u32 s88, 41
	s_mov_b64 s[54:55], s[56:57]
	s_cbranch_scc0 .LBB0_1031
	s_and_b64 vcc, exec, s[18:19]
	s_cbranch_vccz .LBB0_1034
	s_barrier

.LBB0_1161:
	s_ashr_i32 s53, s52, 31
	s_lshl_b64 s[54:55], s[52:53], 19
	s_add_u32 s54, s80, s54
	s_addc_u32 s55, s81, s55
	s_and_b64 s[56:57], s[10:11], exec
	s_cselect_b32 s53, s55, s61
	s_cselect_b32 s83, s54, s60
	s_ashr_i32 s49, s48, 31
	s_lshl_b64 s[56:57], s[48:49], 19
	s_add_u32 s56, s66, s56
	s_addc_u32 s57, s67, s57
	s_and_b64 s[64:65], s[10:11], exec
	s_cselect_b32 s49, s57, s63
	s_cselect_b32 s84, s56, s62
	s_add_u32 s60, s60, 0x40080
	s_addc_u32 s61, s61, 0
	s_add_u32 s85, s62, 0x100
	s_addc_u32 s86, s63, 0
	s_mov_b32 s87, -2
	ds_read_b128 v[152:155], v148
	ds_read_b128 v[156:159], v148 offset:1024
	ds_read_b128 v[160:163], v148 offset:2048
	ds_read_b128 v[164:167], v148 offset:3072
	ds_read_b128 v[168:171], v149
	ds_read_b128 v[172:175], v149 offset:1024
	ds_read_b128 v[176:179], v149 offset:2048
	ds_read_b128 v[184:187], v149 offset:3072
	s_add_u32 s62, s60, 0xfffc0080
	s_addc_u32 s63, s61, -1
	s_cmp_eq_u32 s87, 12
	s_cselect_b32 s65, s53, s63
	s_cselect_b32 s64, s83, s62
	s_cselect_b32 s63, s49, s86
	s_cselect_b32 s62, s84, s85
	v_lshl_add_u64 v[220:221], s[60:61], 0, v[138:139]
	s_add_i32 m0, s69, 0xc000
	ds_read_b128 v[188:191], v150
	ds_read_b128 v[192:195], v150 offset:1024
	ds_read_b128 v[196:199], v150 offset:2048
	ds_read_b128 v[200:203], v150 offset:3072
	ds_read_b128 v[204:207], v150 offset:4096
	ds_read_b128 v[208:211], v150 offset:5120
	ds_read_b128 v[212:215], v150 offset:6144
	ds_read_b128 v[216:219], v150 offset:7168
	global_load_lds_dwordx4 v[220:221], off
	v_lshl_add_u64 v[220:221], s[60:61], 0, v[140:141]
	s_add_i32 m0, s69, 0xe000
	s_nop 0
	global_load_lds_dwordx4 v[220:221], off
	s_waitcnt vmcnt(8)
	s_waitcnt lgkmcnt(0)
	s_barrier
	s_waitcnt lgkmcnt(0)
	v_mfma_f32_16x16x32_bf16 v[124:127], v[152:155], v[188:191], 0
	v_mfma_f32_16x16x32_bf16 v[124:127], v[156:159], v[192:195], v[124:127]
	v_mfma_f32_16x16x32_bf16 v[120:123], v[160:163], v[188:191], 0
	v_mfma_f32_16x16x32_bf16 v[120:123], v[164:167], v[192:195], v[120:123]
	v_mfma_f32_16x16x32_bf16 v[116:119], v[152:155], v[196:199], 0
	v_mfma_f32_16x16x32_bf16 v[116:119], v[156:159], v[200:203], v[116:119]
	v_mfma_f32_16x16x32_bf16 v[112:115], v[160:163], v[196:199], 0
	v_mfma_f32_16x16x32_bf16 v[112:115], v[164:167], v[200:203], v[112:115]
	s_setprio 1
	v_mfma_f32_16x16x32_bf16 v[108:111], v[152:155], v[204:207], 0
	v_mfma_f32_16x16x32_bf16 v[108:111], v[156:159], v[208:211], v[108:111]
	v_mfma_f32_16x16x32_bf16 v[104:107], v[160:163], v[204:207], 0
	v_mfma_f32_16x16x32_bf16 v[104:107], v[164:167], v[208:211], v[104:107]
	v_mfma_f32_16x16x32_bf16 v[100:103], v[152:155], v[212:215], 0
	v_mfma_f32_16x16x32_bf16 v[100:103], v[156:159], v[216:219], v[100:103]
	v_mfma_f32_16x16x32_bf16 v[96:99], v[160:163], v[212:215], 0
	v_mfma_f32_16x16x32_bf16 v[96:99], v[164:167], v[216:219], v[96:99]
	v_mfma_f32_16x16x32_bf16 v[68:71], v[168:171], v[188:191], 0
	v_mfma_f32_16x16x32_bf16 v[68:71], v[172:175], v[192:195], v[68:71]
	v_mfma_f32_16x16x32_bf16 v[64:67], v[176:179], v[188:191], 0
	v_mfma_f32_16x16x32_bf16 v[64:67], v[184:187], v[192:195], v[64:67]
	v_mfma_f32_16x16x32_bf16 v[52:55], v[168:171], v[196:199], 0
	v_mfma_f32_16x16x32_bf16 v[52:55], v[172:175], v[200:203], v[52:55]
	v_mfma_f32_16x16x32_bf16 v[48:51], v[176:179], v[196:199], 0
	v_mfma_f32_16x16x32_bf16 v[48:51], v[184:187], v[200:203], v[48:51]
	s_barrier
	v_mfma_f32_16x16x32_bf16 v[44:47], v[168:171], v[204:207], 0
	v_mfma_f32_16x16x32_bf16 v[44:47], v[172:175], v[208:211], v[44:47]
	v_mfma_f32_16x16x32_bf16 v[40:43], v[176:179], v[204:207], 0
	v_mfma_f32_16x16x32_bf16 v[40:43], v[184:187], v[208:211], v[40:43]
	v_mfma_f32_16x16x32_bf16 v[36:39], v[168:171], v[212:215], 0
	v_mfma_f32_16x16x32_bf16 v[36:39], v[172:175], v[216:219], v[36:39]
	v_mfma_f32_16x16x32_bf16 v[32:35], v[176:179], v[212:215], 0
	v_mfma_f32_16x16x32_bf16 v[32:35], v[184:187], v[216:219], v[32:35]
	s_setprio 0
	s_add_i32 s79, s77, s68
	v_lshl_add_u64 v[220:221], s[62:63], 0, v[130:131]
	s_mov_b32 m0, s79
	ds_read_b128 v[188:191], v150 offset:16384
	ds_read_b128 v[192:195], v150 offset:17408
	ds_read_b128 v[196:199], v150 offset:18432
	ds_read_b128 v[200:203], v150 offset:19456
	ds_read_b128 v[204:207], v150 offset:20480
	ds_read_b128 v[208:211], v150 offset:21504
	ds_read_b128 v[212:215], v150 offset:22528
	ds_read_b128 v[216:219], v150 offset:23552
	global_load_lds_dwordx4 v[220:221], off
	s_add_i32 m0, s79, 0x2000
	s_add_u32 s88, s62, 0x40000
	v_lshl_add_u64 v[222:223], s[62:63], 0, v[134:135]
	s_addc_u32 s89, s63, 0
	s_add_i32 s79, s82, s68
	global_load_lds_dwordx4 v[222:223], off
	v_lshl_add_u64 v[224:225], s[88:89], 0, v[130:131]
	s_mov_b32 m0, s79
	v_lshl_add_u64 v[226:227], s[64:65], 0, v[132:133]
	global_load_lds_dwordx4 v[224:225], off
	v_lshl_add_u64 v[224:225], s[88:89], 0, v[134:135]
	s_add_i32 m0, s79, 0x2000
	s_nop 0
	global_load_lds_dwordx4 v[224:225], off
	v_lshl_add_u64 v[224:225], s[64:65], 0, v[128:129]
	s_mov_b32 m0, s69
	s_nop 0
	global_load_lds_dwordx4 v[224:225], off
	s_mov_b32 m0, s70
	s_nop 0
	global_load_lds_dwordx4 v[226:227], off
	s_waitcnt vmcnt(8)
	s_waitcnt lgkmcnt(0)
	s_barrier
	s_waitcnt lgkmcnt(0)
	v_mfma_f32_16x16x32_bf16 v[92:95], v[152:155], v[188:191], 0
	v_mfma_f32_16x16x32_bf16 v[92:95], v[156:159], v[192:195], v[92:95]
	v_mfma_f32_16x16x32_bf16 v[88:91], v[160:163], v[188:191], 0
	v_mfma_f32_16x16x32_bf16 v[88:91], v[164:167], v[192:195], v[88:91]
	v_mfma_f32_16x16x32_bf16 v[84:87], v[152:155], v[196:199], 0
	v_mfma_f32_16x16x32_bf16 v[84:87], v[156:159], v[200:203], v[84:87]
	v_mfma_f32_16x16x32_bf16 v[80:83], v[160:163], v[196:199], 0
	v_mfma_f32_16x16x32_bf16 v[80:83], v[164:167], v[200:203], v[80:83]
	s_setprio 1
	v_mfma_f32_16x16x32_bf16 v[76:79], v[152:155], v[204:207], 0
	v_mfma_f32_16x16x32_bf16 v[76:79], v[156:159], v[208:211], v[76:79]
	v_mfma_f32_16x16x32_bf16 v[72:75], v[160:163], v[204:207], 0
	v_mfma_f32_16x16x32_bf16 v[72:75], v[164:167], v[208:211], v[72:75]
	v_mfma_f32_16x16x32_bf16 v[60:63], v[152:155], v[212:215], 0
	v_mfma_f32_16x16x32_bf16 v[60:63], v[156:159], v[216:219], v[60:63]
	v_mfma_f32_16x16x32_bf16 v[56:59], v[160:163], v[212:215], 0
	v_mfma_f32_16x16x32_bf16 v[56:59], v[164:167], v[216:219], v[56:59]
	v_mfma_f32_16x16x32_bf16 v[28:31], v[168:171], v[188:191], 0
	v_mfma_f32_16x16x32_bf16 v[28:31], v[172:175], v[192:195], v[28:31]
	v_mfma_f32_16x16x32_bf16 v[24:27], v[176:179], v[188:191], 0
	v_mfma_f32_16x16x32_bf16 v[24:27], v[184:187], v[192:195], v[24:27]
	v_mfma_f32_16x16x32_bf16 v[20:23], v[168:171], v[196:199], 0
	v_mfma_f32_16x16x32_bf16 v[20:23], v[172:175], v[200:203], v[20:23]
	v_mfma_f32_16x16x32_bf16 v[16:19], v[176:179], v[196:199], 0
	v_mfma_f32_16x16x32_bf16 v[16:19], v[184:187], v[200:203], v[16:19]
	s_barrier
	v_mfma_f32_16x16x32_bf16 v[12:15], v[168:171], v[204:207], 0
	v_mfma_f32_16x16x32_bf16 v[12:15], v[172:175], v[208:211], v[12:15]
	v_mfma_f32_16x16x32_bf16 v[8:11], v[176:179], v[204:207], 0
	v_mfma_f32_16x16x32_bf16 v[8:11], v[184:187], v[208:211], v[8:11]
	v_mfma_f32_16x16x32_bf16 v[4:7], v[168:171], v[212:215], 0
	v_mfma_f32_16x16x32_bf16 v[4:7], v[172:175], v[216:219], v[4:7]
	v_mfma_f32_16x16x32_bf16 v[0:3], v[176:179], v[212:215], 0
	v_mfma_f32_16x16x32_bf16 v[0:3], v[184:187], v[216:219], v[0:3]
	s_setprio 0
	s_branch .Lmid_gemm9
.LBB0_1162:
	ds_read_b128 v[152:155], v148
	ds_read_b128 v[156:159], v148 offset:1024
	ds_read_b128 v[160:163], v148 offset:2048
	ds_read_b128 v[164:167], v148 offset:3072
	ds_read_b128 v[168:171], v149
	ds_read_b128 v[172:175], v149 offset:1024
	ds_read_b128 v[176:179], v149 offset:2048
	ds_read_b128 v[184:187], v149 offset:3072
	s_add_u32 s62, s60, 0xfffc0080
	s_addc_u32 s63, s61, -1
	s_cmp_eq_u32 s87, 12
	s_cselect_b32 s65, s53, s63
	s_cselect_b32 s64, s83, s62
	s_cselect_b32 s63, s49, s86
	s_cselect_b32 s62, s84, s85
	v_lshl_add_u64 v[220:221], s[60:61], 0, v[138:139]
	s_add_i32 m0, s69, 0xc000
	ds_read_b128 v[188:191], v150
	ds_read_b128 v[192:195], v150 offset:1024
	ds_read_b128 v[196:199], v150 offset:2048
	ds_read_b128 v[200:203], v150 offset:3072
	ds_read_b128 v[204:207], v150 offset:4096
	ds_read_b128 v[208:211], v150 offset:5120
	ds_read_b128 v[212:215], v150 offset:6144
	ds_read_b128 v[216:219], v150 offset:7168
	global_load_lds_dwordx4 v[220:221], off
	v_lshl_add_u64 v[220:221], s[60:61], 0, v[140:141]
	s_add_i32 m0, s69, 0xe000
	s_nop 0
	global_load_lds_dwordx4 v[220:221], off
	s_waitcnt vmcnt(8)
	s_waitcnt lgkmcnt(0)
	s_barrier
	s_waitcnt lgkmcnt(0)
	v_mfma_f32_16x16x32_bf16 v[124:127], v[152:155], v[188:191], v[124:127]
	v_mfma_f32_16x16x32_bf16 v[124:127], v[156:159], v[192:195], v[124:127]
	v_mfma_f32_16x16x32_bf16 v[120:123], v[160:163], v[188:191], v[120:123]
	v_mfma_f32_16x16x32_bf16 v[120:123], v[164:167], v[192:195], v[120:123]
	v_mfma_f32_16x16x32_bf16 v[116:119], v[152:155], v[196:199], v[116:119]
	v_mfma_f32_16x16x32_bf16 v[116:119], v[156:159], v[200:203], v[116:119]
	v_mfma_f32_16x16x32_bf16 v[112:115], v[160:163], v[196:199], v[112:115]
	v_mfma_f32_16x16x32_bf16 v[112:115], v[164:167], v[200:203], v[112:115]
	s_setprio 1
	v_mfma_f32_16x16x32_bf16 v[108:111], v[152:155], v[204:207], v[108:111]
	v_mfma_f32_16x16x32_bf16 v[108:111], v[156:159], v[208:211], v[108:111]
	v_mfma_f32_16x16x32_bf16 v[104:107], v[160:163], v[204:207], v[104:107]
	v_mfma_f32_16x16x32_bf16 v[104:107], v[164:167], v[208:211], v[104:107]
	v_mfma_f32_16x16x32_bf16 v[100:103], v[152:155], v[212:215], v[100:103]
	v_mfma_f32_16x16x32_bf16 v[100:103], v[156:159], v[216:219], v[100:103]
	v_mfma_f32_16x16x32_bf16 v[96:99], v[160:163], v[212:215], v[96:99]
	v_mfma_f32_16x16x32_bf16 v[96:99], v[164:167], v[216:219], v[96:99]
	v_mfma_f32_16x16x32_bf16 v[68:71], v[168:171], v[188:191], v[68:71]
	v_mfma_f32_16x16x32_bf16 v[68:71], v[172:175], v[192:195], v[68:71]
	v_mfma_f32_16x16x32_bf16 v[64:67], v[176:179], v[188:191], v[64:67]
	v_mfma_f32_16x16x32_bf16 v[64:67], v[184:187], v[192:195], v[64:67]
	v_mfma_f32_16x16x32_bf16 v[52:55], v[168:171], v[196:199], v[52:55]
	v_mfma_f32_16x16x32_bf16 v[52:55], v[172:175], v[200:203], v[52:55]
	v_mfma_f32_16x16x32_bf16 v[48:51], v[176:179], v[196:199], v[48:51]
	v_mfma_f32_16x16x32_bf16 v[48:51], v[184:187], v[200:203], v[48:51]
	s_barrier
	v_mfma_f32_16x16x32_bf16 v[44:47], v[168:171], v[204:207], v[44:47]
	v_mfma_f32_16x16x32_bf16 v[44:47], v[172:175], v[208:211], v[44:47]
	v_mfma_f32_16x16x32_bf16 v[40:43], v[176:179], v[204:207], v[40:43]
	v_mfma_f32_16x16x32_bf16 v[40:43], v[184:187], v[208:211], v[40:43]
	v_mfma_f32_16x16x32_bf16 v[36:39], v[168:171], v[212:215], v[36:39]
	v_mfma_f32_16x16x32_bf16 v[36:39], v[172:175], v[216:219], v[36:39]
	v_mfma_f32_16x16x32_bf16 v[32:35], v[176:179], v[212:215], v[32:35]
	v_mfma_f32_16x16x32_bf16 v[32:35], v[184:187], v[216:219], v[32:35]
	s_setprio 0
	s_add_i32 s79, s77, s68
	v_lshl_add_u64 v[220:221], s[62:63], 0, v[130:131]
	s_mov_b32 m0, s79
	ds_read_b128 v[188:191], v150 offset:16384
	ds_read_b128 v[192:195], v150 offset:17408
	ds_read_b128 v[196:199], v150 offset:18432
	ds_read_b128 v[200:203], v150 offset:19456
	ds_read_b128 v[204:207], v150 offset:20480
	ds_read_b128 v[208:211], v150 offset:21504
	ds_read_b128 v[212:215], v150 offset:22528
	ds_read_b128 v[216:219], v150 offset:23552
	global_load_lds_dwordx4 v[220:221], off
	s_add_i32 m0, s79, 0x2000
	s_add_u32 s88, s62, 0x40000
	v_lshl_add_u64 v[222:223], s[62:63], 0, v[134:135]
	s_addc_u32 s89, s63, 0
	s_add_i32 s79, s82, s68
	global_load_lds_dwordx4 v[222:223], off
	v_lshl_add_u64 v[224:225], s[88:89], 0, v[130:131]
	s_mov_b32 m0, s79
	v_lshl_add_u64 v[226:227], s[64:65], 0, v[132:133]
	global_load_lds_dwordx4 v[224:225], off
	v_lshl_add_u64 v[224:225], s[88:89], 0, v[134:135]
	s_add_i32 m0, s79, 0x2000
	s_nop 0
	global_load_lds_dwordx4 v[224:225], off
	v_lshl_add_u64 v[224:225], s[64:65], 0, v[128:129]
	s_mov_b32 m0, s69
	s_nop 0
	global_load_lds_dwordx4 v[224:225], off
	s_mov_b32 m0, s70
	s_nop 0
	global_load_lds_dwordx4 v[226:227], off
	s_waitcnt vmcnt(8)
	s_waitcnt lgkmcnt(0)
	s_barrier
	s_waitcnt lgkmcnt(0)
	v_mfma_f32_16x16x32_bf16 v[92:95], v[152:155], v[188:191], v[92:95]
	v_mfma_f32_16x16x32_bf16 v[92:95], v[156:159], v[192:195], v[92:95]
	v_mfma_f32_16x16x32_bf16 v[88:91], v[160:163], v[188:191], v[88:91]
	v_mfma_f32_16x16x32_bf16 v[88:91], v[164:167], v[192:195], v[88:91]
	v_mfma_f32_16x16x32_bf16 v[84:87], v[152:155], v[196:199], v[84:87]
	v_mfma_f32_16x16x32_bf16 v[84:87], v[156:159], v[200:203], v[84:87]
	v_mfma_f32_16x16x32_bf16 v[80:83], v[160:163], v[196:199], v[80:83]
	v_mfma_f32_16x16x32_bf16 v[80:83], v[164:167], v[200:203], v[80:83]
	s_setprio 1
	v_mfma_f32_16x16x32_bf16 v[76:79], v[152:155], v[204:207], v[76:79]
	v_mfma_f32_16x16x32_bf16 v[76:79], v[156:159], v[208:211], v[76:79]
	v_mfma_f32_16x16x32_bf16 v[72:75], v[160:163], v[204:207], v[72:75]
	v_mfma_f32_16x16x32_bf16 v[72:75], v[164:167], v[208:211], v[72:75]
	v_mfma_f32_16x16x32_bf16 v[60:63], v[152:155], v[212:215], v[60:63]
	v_mfma_f32_16x16x32_bf16 v[60:63], v[156:159], v[216:219], v[60:63]
	v_mfma_f32_16x16x32_bf16 v[56:59], v[160:163], v[212:215], v[56:59]
	v_mfma_f32_16x16x32_bf16 v[56:59], v[164:167], v[216:219], v[56:59]
	v_mfma_f32_16x16x32_bf16 v[28:31], v[168:171], v[188:191], v[28:31]
	v_mfma_f32_16x16x32_bf16 v[28:31], v[172:175], v[192:195], v[28:31]
	v_mfma_f32_16x16x32_bf16 v[24:27], v[176:179], v[188:191], v[24:27]
	v_mfma_f32_16x16x32_bf16 v[24:27], v[184:187], v[192:195], v[24:27]
	v_mfma_f32_16x16x32_bf16 v[20:23], v[168:171], v[196:199], v[20:23]
	v_mfma_f32_16x16x32_bf16 v[20:23], v[172:175], v[200:203], v[20:23]
	v_mfma_f32_16x16x32_bf16 v[16:19], v[176:179], v[196:199], v[16:19]
	v_mfma_f32_16x16x32_bf16 v[16:19], v[184:187], v[200:203], v[16:19]
	s_barrier
	v_mfma_f32_16x16x32_bf16 v[12:15], v[168:171], v[204:207], v[12:15]
	v_mfma_f32_16x16x32_bf16 v[12:15], v[172:175], v[208:211], v[12:15]
	v_mfma_f32_16x16x32_bf16 v[8:11], v[176:179], v[204:207], v[8:11]
	v_mfma_f32_16x16x32_bf16 v[8:11], v[184:187], v[208:211], v[8:11]
	v_mfma_f32_16x16x32_bf16 v[4:7], v[168:171], v[212:215], v[4:7]
	v_mfma_f32_16x16x32_bf16 v[4:7], v[172:175], v[216:219], v[4:7]
	v_mfma_f32_16x16x32_bf16 v[0:3], v[176:179], v[212:215], v[0:3]
	v_mfma_f32_16x16x32_bf16 v[0:3], v[184:187], v[216:219], v[0:3]
	s_setprio 0
.Lmid_gemm9:
	s_add_i32 s79, 0, 0x18000
	s_add_i32 s88, 0, 0x1c000
	v_add_u32_e32 v164, s79, v147
	v_add_u32_e32 v181, s88, v147
	ds_read_b128 v[152:155], v164
	ds_read_b128 v[156:159], v164 offset:1024
	ds_read_b128 v[160:163], v164 offset:2048
	ds_read_b128 v[164:167], v164 offset:3072
	ds_read_b128 v[168:171], v181
	ds_read_b128 v[172:175], v181 offset:1024
	ds_read_b128 v[176:179], v181 offset:2048
	ds_read_b128 v[184:187], v181 offset:3072
	s_add_u32 s64, s64, 0x40000
	s_addc_u32 s65, s65, 0
	s_mov_b32 m0, s71
	v_lshl_add_u64 v[228:229], s[64:65], 0, v[128:129]
	ds_read_b128 v[188:191], v150 offset:32768
	ds_read_b128 v[192:195], v150 offset:33792
	ds_read_b128 v[196:199], v150 offset:34816
	ds_read_b128 v[200:203], v150 offset:35840
	ds_read_b128 v[204:207], v150 offset:36864
	ds_read_b128 v[208:211], v150 offset:37888
	ds_read_b128 v[212:215], v150 offset:38912
	ds_read_b128 v[216:219], v150 offset:39936
	global_load_lds_dwordx4 v[228:229], off
	v_lshl_add_u64 v[228:229], s[64:65], 0, v[132:133]
	s_mov_b32 m0, s72
	s_nop 0
	global_load_lds_dwordx4 v[228:229], off
	s_waitcnt vmcnt(8)
	s_waitcnt lgkmcnt(0)
	s_barrier
	s_waitcnt lgkmcnt(0)
	v_mfma_f32_16x16x32_bf16 v[124:127], v[152:155], v[188:191], v[124:127]
	v_mfma_f32_16x16x32_bf16 v[124:127], v[156:159], v[192:195], v[124:127]
	v_mfma_f32_16x16x32_bf16 v[120:123], v[160:163], v[188:191], v[120:123]
	v_mfma_f32_16x16x32_bf16 v[120:123], v[164:167], v[192:195], v[120:123]
	v_mfma_f32_16x16x32_bf16 v[116:119], v[152:155], v[196:199], v[116:119]
	v_mfma_f32_16x16x32_bf16 v[116:119], v[156:159], v[200:203], v[116:119]
	v_mfma_f32_16x16x32_bf16 v[112:115], v[160:163], v[196:199], v[112:115]
	v_mfma_f32_16x16x32_bf16 v[112:115], v[164:167], v[200:203], v[112:115]
	s_setprio 1
	v_mfma_f32_16x16x32_bf16 v[108:111], v[152:155], v[204:207], v[108:111]
	v_mfma_f32_16x16x32_bf16 v[108:111], v[156:159], v[208:211], v[108:111]
	v_mfma_f32_16x16x32_bf16 v[104:107], v[160:163], v[204:207], v[104:107]
	v_mfma_f32_16x16x32_bf16 v[104:107], v[164:167], v[208:211], v[104:107]
	v_mfma_f32_16x16x32_bf16 v[100:103], v[152:155], v[212:215], v[100:103]
	v_mfma_f32_16x16x32_bf16 v[100:103], v[156:159], v[216:219], v[100:103]
	v_mfma_f32_16x16x32_bf16 v[96:99], v[160:163], v[212:215], v[96:99]
	v_mfma_f32_16x16x32_bf16 v[96:99], v[164:167], v[216:219], v[96:99]
	v_mfma_f32_16x16x32_bf16 v[68:71], v[168:171], v[188:191], v[68:71]
	v_mfma_f32_16x16x32_bf16 v[68:71], v[172:175], v[192:195], v[68:71]
	v_mfma_f32_16x16x32_bf16 v[64:67], v[176:179], v[188:191], v[64:67]
	v_mfma_f32_16x16x32_bf16 v[64:67], v[184:187], v[192:195], v[64:67]
	v_mfma_f32_16x16x32_bf16 v[52:55], v[168:171], v[196:199], v[52:55]
	v_mfma_f32_16x16x32_bf16 v[52:55], v[172:175], v[200:203], v[52:55]
	v_mfma_f32_16x16x32_bf16 v[48:51], v[176:179], v[196:199], v[48:51]
	v_mfma_f32_16x16x32_bf16 v[48:51], v[184:187], v[200:203], v[48:51]
	s_barrier
	v_mfma_f32_16x16x32_bf16 v[44:47], v[168:171], v[204:207], v[44:47]
	v_mfma_f32_16x16x32_bf16 v[44:47], v[172:175], v[208:211], v[44:47]
	v_mfma_f32_16x16x32_bf16 v[40:43], v[176:179], v[204:207], v[40:43]
	v_mfma_f32_16x16x32_bf16 v[40:43], v[184:187], v[208:211], v[40:43]
	v_mfma_f32_16x16x32_bf16 v[36:39], v[168:171], v[212:215], v[36:39]
	v_mfma_f32_16x16x32_bf16 v[36:39], v[172:175], v[216:219], v[36:39]
	v_mfma_f32_16x16x32_bf16 v[32:35], v[176:179], v[212:215], v[32:35]
	v_mfma_f32_16x16x32_bf16 v[32:35], v[184:187], v[216:219], v[32:35]
	s_setprio 0
	s_add_i32 s64, s79, s68
	v_lshl_add_u64 v[220:221], v[220:221], 0, s[12:13]
	s_mov_b32 m0, s64
	ds_read_b128 v[188:191], v150 offset:49152
	ds_read_b128 v[192:195], v150 offset:50176
	ds_read_b128 v[196:199], v150 offset:51200
	ds_read_b128 v[200:203], v150 offset:52224
	ds_read_b128 v[204:207], v150 offset:53248
	ds_read_b128 v[208:211], v150 offset:54272
	ds_read_b128 v[212:215], v150 offset:55296
	ds_read_b128 v[216:219], v150 offset:56320
	global_load_lds_dwordx4 v[220:221], off
	s_add_i32 m0, s64, 0x2000
	s_add_u32 s62, s62, 0x40080
	v_lshl_add_u64 v[220:221], v[222:223], 0, s[12:13]
	s_addc_u32 s63, s63, 0
	s_add_i32 s64, s88, s68
	global_load_lds_dwordx4 v[220:221], off
	v_lshl_add_u64 v[220:221], s[62:63], 0, v[130:131]
	s_mov_b32 m0, s64
	s_nop 0
	global_load_lds_dwordx4 v[220:221], off
	v_lshl_add_u64 v[220:221], s[62:63], 0, v[134:135]
	s_add_i32 m0, s64, 0x2000
	s_nop 0
	global_load_lds_dwordx4 v[220:221], off
	v_lshl_add_u64 v[220:221], v[224:225], 0, s[12:13]
	s_mov_b32 m0, s75
	s_nop 0
	global_load_lds_dwordx4 v[220:221], off
	v_lshl_add_u64 v[220:221], v[226:227], 0, s[12:13]
	s_mov_b32 m0, s76
	s_nop 0
	global_load_lds_dwordx4 v[220:221], off
	s_waitcnt vmcnt(8)
	s_waitcnt lgkmcnt(0)
	s_barrier
	s_waitcnt lgkmcnt(0)
	v_mfma_f32_16x16x32_bf16 v[92:95], v[152:155], v[188:191], v[92:95]
	v_mfma_f32_16x16x32_bf16 v[92:95], v[156:159], v[192:195], v[92:95]
	v_mfma_f32_16x16x32_bf16 v[88:91], v[160:163], v[188:191], v[88:91]
	v_mfma_f32_16x16x32_bf16 v[88:91], v[164:167], v[192:195], v[88:91]
	v_mfma_f32_16x16x32_bf16 v[84:87], v[152:155], v[196:199], v[84:87]
	v_mfma_f32_16x16x32_bf16 v[84:87], v[156:159], v[200:203], v[84:87]
	v_mfma_f32_16x16x32_bf16 v[80:83], v[160:163], v[196:199], v[80:83]
	v_mfma_f32_16x16x32_bf16 v[80:83], v[164:167], v[200:203], v[80:83]
	s_setprio 1
	v_mfma_f32_16x16x32_bf16 v[76:79], v[152:155], v[204:207], v[76:79]
	v_mfma_f32_16x16x32_bf16 v[76:79], v[156:159], v[208:211], v[76:79]
	v_mfma_f32_16x16x32_bf16 v[72:75], v[160:163], v[204:207], v[72:75]
	v_mfma_f32_16x16x32_bf16 v[72:75], v[164:167], v[208:211], v[72:75]
	v_mfma_f32_16x16x32_bf16 v[60:63], v[152:155], v[212:215], v[60:63]
	v_mfma_f32_16x16x32_bf16 v[60:63], v[156:159], v[216:219], v[60:63]
	v_mfma_f32_16x16x32_bf16 v[56:59], v[160:163], v[212:215], v[56:59]
	v_mfma_f32_16x16x32_bf16 v[56:59], v[164:167], v[216:219], v[56:59]
	v_mfma_f32_16x16x32_bf16 v[28:31], v[168:171], v[188:191], v[28:31]
	v_mfma_f32_16x16x32_bf16 v[28:31], v[172:175], v[192:195], v[28:31]
	v_mfma_f32_16x16x32_bf16 v[24:27], v[176:179], v[188:191], v[24:27]
	v_mfma_f32_16x16x32_bf16 v[24:27], v[184:187], v[192:195], v[24:27]
	v_mfma_f32_16x16x32_bf16 v[20:23], v[168:171], v[196:199], v[20:23]
	v_mfma_f32_16x16x32_bf16 v[20:23], v[172:175], v[200:203], v[20:23]
	v_mfma_f32_16x16x32_bf16 v[16:19], v[176:179], v[196:199], v[16:19]
	v_mfma_f32_16x16x32_bf16 v[16:19], v[184:187], v[200:203], v[16:19]
	s_barrier
	v_mfma_f32_16x16x32_bf16 v[12:15], v[168:171], v[204:207], v[12:15]
	v_mfma_f32_16x16x32_bf16 v[12:15], v[172:175], v[208:211], v[12:15]
	v_mfma_f32_16x16x32_bf16 v[8:11], v[176:179], v[204:207], v[8:11]
	v_mfma_f32_16x16x32_bf16 v[8:11], v[184:187], v[208:211], v[8:11]
	v_mfma_f32_16x16x32_bf16 v[4:7], v[168:171], v[212:215], v[4:7]
	v_mfma_f32_16x16x32_bf16 v[4:7], v[172:175], v[216:219], v[4:7]
	v_mfma_f32_16x16x32_bf16 v[0:3], v[176:179], v[212:215], v[0:3]
	v_mfma_f32_16x16x32_bf16 v[0:3], v[184:187], v[216:219], v[0:3]
	s_setprio 0
	s_add_i32 s87, s87, 2
	s_add_u32 s60, s60, 0x100
	s_addc_u32 s61, s61, 0
	s_add_u32 s85, s85, 0x100
	s_addc_u32 s86, s86, 0
	s_cmp_gt_u32 s87, 13
	s_cbranch_scc0 .LBB0_1162
	s_and_b64 vcc, exec, s[16:17]
	s_cbranch_vccz .LBB0_1165
	s_barrier

.LBB0_1310:
	s_ashr_i32 s49, s48, 31
	s_lshl_b64 s[50:51], s[48:49], 19
	s_add_u32 s50, s38, s50
	s_addc_u32 s51, s39, s51
	s_and_b64 s[52:53], s[10:11], exec
	s_cselect_b32 s49, s51, s57
	s_cselect_b32 s82, s50, s56
	s_ashr_i32 s47, s46, 31
	s_lshl_b64 s[52:53], s[46:47], 19
	s_add_u32 s52, s62, s52
	s_addc_u32 s53, s63, s53
	s_and_b64 s[60:61], s[10:11], exec
	s_cselect_b32 s47, s53, s59
	s_cselect_b32 s83, s52, s58
	s_add_u32 s56, s56, 0x40080
	s_addc_u32 s57, s57, 0
	s_add_u32 s84, s58, 0x100
	s_addc_u32 s85, s59, 0
	s_mov_b32 s86, -2
	ds_read_b128 v[152:155], v149
	ds_read_b128 v[156:159], v149 offset:1024
	ds_read_b128 v[160:163], v149 offset:2048
	ds_read_b128 v[164:167], v149 offset:3072
	ds_read_b128 v[168:171], v150
	ds_read_b128 v[172:175], v150 offset:1024
	ds_read_b128 v[176:179], v150 offset:2048
	ds_read_b128 v[184:187], v150 offset:3072
	s_add_u32 s58, s56, 0xfffc0080
	s_addc_u32 s59, s57, -1
	s_cmp_eq_u32 s86, 12
	s_cselect_b32 s61, s49, s59
	s_cselect_b32 s60, s82, s58
	s_cselect_b32 s59, s47, s85
	s_cselect_b32 s58, s83, s84
	v_lshl_add_u64 v[144:145], s[56:57], 0, v[136:137]
	s_add_i32 m0, s55, 0xc000
	ds_read_b128 v[188:191], v151
	ds_read_b128 v[192:195], v151 offset:1024
	ds_read_b128 v[196:199], v151 offset:2048
	ds_read_b128 v[200:203], v151 offset:3072
	ds_read_b128 v[204:207], v151 offset:4096
	ds_read_b128 v[208:211], v151 offset:5120
	ds_read_b128 v[212:215], v151 offset:6144
	ds_read_b128 v[216:219], v151 offset:7168
	global_load_lds_dwordx4 v[144:145], off
	v_lshl_add_u64 v[144:145], s[56:57], 0, v[138:139]
	s_add_i32 m0, s55, 0xe000
	s_nop 0
	global_load_lds_dwordx4 v[144:145], off
	s_waitcnt vmcnt(8)
	s_waitcnt lgkmcnt(0)
	s_barrier
	s_waitcnt lgkmcnt(0)
	v_mfma_f32_16x16x32_bf16 v[124:127], v[152:155], v[188:191], 0
	v_mfma_f32_16x16x32_bf16 v[124:127], v[156:159], v[192:195], v[124:127]
	v_mfma_f32_16x16x32_bf16 v[120:123], v[160:163], v[188:191], 0
	v_mfma_f32_16x16x32_bf16 v[120:123], v[164:167], v[192:195], v[120:123]
	v_mfma_f32_16x16x32_bf16 v[116:119], v[152:155], v[196:199], 0
	v_mfma_f32_16x16x32_bf16 v[116:119], v[156:159], v[200:203], v[116:119]
	v_mfma_f32_16x16x32_bf16 v[108:111], v[160:163], v[196:199], 0
	v_mfma_f32_16x16x32_bf16 v[108:111], v[164:167], v[200:203], v[108:111]
	s_setprio 1
	v_mfma_f32_16x16x32_bf16 v[100:103], v[152:155], v[204:207], 0
	v_mfma_f32_16x16x32_bf16 v[100:103], v[156:159], v[208:211], v[100:103]
	v_mfma_f32_16x16x32_bf16 v[92:95], v[160:163], v[204:207], 0
	v_mfma_f32_16x16x32_bf16 v[92:95], v[164:167], v[208:211], v[92:95]
	v_mfma_f32_16x16x32_bf16 v[84:87], v[152:155], v[212:215], 0
	v_mfma_f32_16x16x32_bf16 v[84:87], v[156:159], v[216:219], v[84:87]
	v_mfma_f32_16x16x32_bf16 v[76:79], v[160:163], v[212:215], 0
	v_mfma_f32_16x16x32_bf16 v[76:79], v[164:167], v[216:219], v[76:79]
	v_mfma_f32_16x16x32_bf16 v[112:115], v[168:171], v[188:191], 0
	v_mfma_f32_16x16x32_bf16 v[112:115], v[172:175], v[192:195], v[112:115]
	v_mfma_f32_16x16x32_bf16 v[104:107], v[176:179], v[188:191], 0
	v_mfma_f32_16x16x32_bf16 v[104:107], v[184:187], v[192:195], v[104:107]
	v_mfma_f32_16x16x32_bf16 v[96:99], v[168:171], v[196:199], 0
	v_mfma_f32_16x16x32_bf16 v[96:99], v[172:175], v[200:203], v[96:99]
	v_mfma_f32_16x16x32_bf16 v[88:91], v[176:179], v[196:199], 0
	v_mfma_f32_16x16x32_bf16 v[88:91], v[184:187], v[200:203], v[88:91]
	s_barrier
	v_mfma_f32_16x16x32_bf16 v[80:83], v[168:171], v[204:207], 0
	v_mfma_f32_16x16x32_bf16 v[80:83], v[172:175], v[208:211], v[80:83]
	v_mfma_f32_16x16x32_bf16 v[72:75], v[176:179], v[204:207], 0
	v_mfma_f32_16x16x32_bf16 v[72:75], v[184:187], v[208:211], v[72:75]
	v_mfma_f32_16x16x32_bf16 v[68:71], v[168:171], v[212:215], 0
	v_mfma_f32_16x16x32_bf16 v[68:71], v[172:175], v[216:219], v[68:71]
	v_mfma_f32_16x16x32_bf16 v[64:67], v[176:179], v[212:215], 0
	v_mfma_f32_16x16x32_bf16 v[64:67], v[184:187], v[216:219], v[64:67]
	s_setprio 0
	s_add_i32 s79, s71, s64
	v_lshl_add_u64 v[144:145], s[58:59], 0, v[130:131]
	s_mov_b32 m0, s79
	ds_read_b128 v[188:191], v151 offset:16384
	ds_read_b128 v[192:195], v151 offset:17408
	ds_read_b128 v[196:199], v151 offset:18432
	ds_read_b128 v[200:203], v151 offset:19456
	ds_read_b128 v[204:207], v151 offset:20480
	ds_read_b128 v[208:211], v151 offset:21504
	ds_read_b128 v[212:215], v151 offset:22528
	ds_read_b128 v[216:219], v151 offset:23552
	global_load_lds_dwordx4 v[144:145], off
	s_add_i32 m0, s79, 0x2000
	s_add_u32 s88, s58, 0x40000
	v_lshl_add_u64 v[220:221], s[58:59], 0, v[134:135]
	s_addc_u32 s89, s59, 0
	s_add_i32 s79, s72, s64
	global_load_lds_dwordx4 v[220:221], off
	v_lshl_add_u64 v[222:223], s[88:89], 0, v[130:131]
	s_mov_b32 m0, s79
	v_lshl_add_u64 v[224:225], s[60:61], 0, v[132:133]
	global_load_lds_dwordx4 v[222:223], off
	v_lshl_add_u64 v[222:223], s[88:89], 0, v[134:135]
	s_add_i32 m0, s79, 0x2000
	s_nop 0
	global_load_lds_dwordx4 v[222:223], off
	v_lshl_add_u64 v[222:223], s[60:61], 0, v[128:129]
	s_mov_b32 m0, s55
	s_nop 0
	global_load_lds_dwordx4 v[222:223], off
	s_mov_b32 m0, s65
	s_nop 0
	global_load_lds_dwordx4 v[224:225], off
	s_waitcnt vmcnt(8)
	s_waitcnt lgkmcnt(0)
	s_barrier
	s_waitcnt lgkmcnt(0)
	v_mfma_f32_16x16x32_bf16 v[60:63], v[152:155], v[188:191], 0
	v_mfma_f32_16x16x32_bf16 v[60:63], v[156:159], v[192:195], v[60:63]
	v_mfma_f32_16x16x32_bf16 v[56:59], v[160:163], v[188:191], 0
	v_mfma_f32_16x16x32_bf16 v[56:59], v[164:167], v[192:195], v[56:59]
	v_mfma_f32_16x16x32_bf16 v[52:55], v[152:155], v[196:199], 0
	v_mfma_f32_16x16x32_bf16 v[52:55], v[156:159], v[200:203], v[52:55]
	v_mfma_f32_16x16x32_bf16 v[44:47], v[160:163], v[196:199], 0
	v_mfma_f32_16x16x32_bf16 v[44:47], v[164:167], v[200:203], v[44:47]
	s_setprio 1
	v_mfma_f32_16x16x32_bf16 v[36:39], v[152:155], v[204:207], 0
	v_mfma_f32_16x16x32_bf16 v[36:39], v[156:159], v[208:211], v[36:39]
	v_mfma_f32_16x16x32_bf16 v[28:31], v[160:163], v[204:207], 0
	v_mfma_f32_16x16x32_bf16 v[28:31], v[164:167], v[208:211], v[28:31]
	v_mfma_f32_16x16x32_bf16 v[20:23], v[152:155], v[212:215], 0
	v_mfma_f32_16x16x32_bf16 v[20:23], v[156:159], v[216:219], v[20:23]
	v_mfma_f32_16x16x32_bf16 v[12:15], v[160:163], v[212:215], 0
	v_mfma_f32_16x16x32_bf16 v[12:15], v[164:167], v[216:219], v[12:15]
	v_mfma_f32_16x16x32_bf16 v[48:51], v[168:171], v[188:191], 0
	v_mfma_f32_16x16x32_bf16 v[48:51], v[172:175], v[192:195], v[48:51]
	v_mfma_f32_16x16x32_bf16 v[40:43], v[176:179], v[188:191], 0
	v_mfma_f32_16x16x32_bf16 v[40:43], v[184:187], v[192:195], v[40:43]
	v_mfma_f32_16x16x32_bf16 v[32:35], v[168:171], v[196:199], 0
	v_mfma_f32_16x16x32_bf16 v[32:35], v[172:175], v[200:203], v[32:35]
	v_mfma_f32_16x16x32_bf16 v[24:27], v[176:179], v[196:199], 0
	v_mfma_f32_16x16x32_bf16 v[24:27], v[184:187], v[200:203], v[24:27]
	s_barrier
	v_mfma_f32_16x16x32_bf16 v[16:19], v[168:171], v[204:207], 0
	v_mfma_f32_16x16x32_bf16 v[16:19], v[172:175], v[208:211], v[16:19]
	v_mfma_f32_16x16x32_bf16 v[8:11], v[176:179], v[204:207], 0
	v_mfma_f32_16x16x32_bf16 v[8:11], v[184:187], v[208:211], v[8:11]
	v_mfma_f32_16x16x32_bf16 v[4:7], v[168:171], v[212:215], 0
	v_mfma_f32_16x16x32_bf16 v[4:7], v[172:175], v[216:219], v[4:7]
	v_mfma_f32_16x16x32_bf16 v[0:3], v[176:179], v[212:215], 0
	v_mfma_f32_16x16x32_bf16 v[0:3], v[184:187], v[216:219], v[0:3]
	s_setprio 0
	s_branch .Lmid_gemm10
.LBB0_1311:
	ds_read_b128 v[152:155], v149
	ds_read_b128 v[156:159], v149 offset:1024
	ds_read_b128 v[160:163], v149 offset:2048
	ds_read_b128 v[164:167], v149 offset:3072
	ds_read_b128 v[168:171], v150
	ds_read_b128 v[172:175], v150 offset:1024
	ds_read_b128 v[176:179], v150 offset:2048
	ds_read_b128 v[184:187], v150 offset:3072
	s_add_u32 s58, s56, 0xfffc0080
	s_addc_u32 s59, s57, -1
	s_cmp_eq_u32 s86, 12
	s_cselect_b32 s61, s49, s59
	s_cselect_b32 s60, s82, s58
	s_cselect_b32 s59, s47, s85
	s_cselect_b32 s58, s83, s84
	v_lshl_add_u64 v[144:145], s[56:57], 0, v[136:137]
	s_add_i32 m0, s55, 0xc000
	ds_read_b128 v[188:191], v151
	ds_read_b128 v[192:195], v151 offset:1024
	ds_read_b128 v[196:199], v151 offset:2048
	ds_read_b128 v[200:203], v151 offset:3072
	ds_read_b128 v[204:207], v151 offset:4096
	ds_read_b128 v[208:211], v151 offset:5120
	ds_read_b128 v[212:215], v151 offset:6144
	ds_read_b128 v[216:219], v151 offset:7168
	global_load_lds_dwordx4 v[144:145], off
	v_lshl_add_u64 v[144:145], s[56:57], 0, v[138:139]
	s_add_i32 m0, s55, 0xe000
	s_nop 0
	global_load_lds_dwordx4 v[144:145], off
	s_waitcnt vmcnt(8)
	s_waitcnt lgkmcnt(0)
	s_barrier
	s_waitcnt lgkmcnt(0)
	v_mfma_f32_16x16x32_bf16 v[124:127], v[152:155], v[188:191], v[124:127]
	v_mfma_f32_16x16x32_bf16 v[124:127], v[156:159], v[192:195], v[124:127]
	v_mfma_f32_16x16x32_bf16 v[120:123], v[160:163], v[188:191], v[120:123]
	v_mfma_f32_16x16x32_bf16 v[120:123], v[164:167], v[192:195], v[120:123]
	v_mfma_f32_16x16x32_bf16 v[116:119], v[152:155], v[196:199], v[116:119]
	v_mfma_f32_16x16x32_bf16 v[116:119], v[156:159], v[200:203], v[116:119]
	v_mfma_f32_16x16x32_bf16 v[108:111], v[160:163], v[196:199], v[108:111]
	v_mfma_f32_16x16x32_bf16 v[108:111], v[164:167], v[200:203], v[108:111]
	s_setprio 1
	v_mfma_f32_16x16x32_bf16 v[100:103], v[152:155], v[204:207], v[100:103]
	v_mfma_f32_16x16x32_bf16 v[100:103], v[156:159], v[208:211], v[100:103]
	v_mfma_f32_16x16x32_bf16 v[92:95], v[160:163], v[204:207], v[92:95]
	v_mfma_f32_16x16x32_bf16 v[92:95], v[164:167], v[208:211], v[92:95]
	v_mfma_f32_16x16x32_bf16 v[84:87], v[152:155], v[212:215], v[84:87]
	v_mfma_f32_16x16x32_bf16 v[84:87], v[156:159], v[216:219], v[84:87]
	v_mfma_f32_16x16x32_bf16 v[76:79], v[160:163], v[212:215], v[76:79]
	v_mfma_f32_16x16x32_bf16 v[76:79], v[164:167], v[216:219], v[76:79]
	v_mfma_f32_16x16x32_bf16 v[112:115], v[168:171], v[188:191], v[112:115]
	v_mfma_f32_16x16x32_bf16 v[112:115], v[172:175], v[192:195], v[112:115]
	v_mfma_f32_16x16x32_bf16 v[104:107], v[176:179], v[188:191], v[104:107]
	v_mfma_f32_16x16x32_bf16 v[104:107], v[184:187], v[192:195], v[104:107]
	v_mfma_f32_16x16x32_bf16 v[96:99], v[168:171], v[196:199], v[96:99]
	v_mfma_f32_16x16x32_bf16 v[96:99], v[172:175], v[200:203], v[96:99]
	v_mfma_f32_16x16x32_bf16 v[88:91], v[176:179], v[196:199], v[88:91]
	v_mfma_f32_16x16x32_bf16 v[88:91], v[184:187], v[200:203], v[88:91]
	s_barrier
	v_mfma_f32_16x16x32_bf16 v[80:83], v[168:171], v[204:207], v[80:83]
	v_mfma_f32_16x16x32_bf16 v[80:83], v[172:175], v[208:211], v[80:83]
	v_mfma_f32_16x16x32_bf16 v[72:75], v[176:179], v[204:207], v[72:75]
	v_mfma_f32_16x16x32_bf16 v[72:75], v[184:187], v[208:211], v[72:75]
	v_mfma_f32_16x16x32_bf16 v[68:71], v[168:171], v[212:215], v[68:71]
	v_mfma_f32_16x16x32_bf16 v[68:71], v[172:175], v[216:219], v[68:71]
	v_mfma_f32_16x16x32_bf16 v[64:67], v[176:179], v[212:215], v[64:67]
	v_mfma_f32_16x16x32_bf16 v[64:67], v[184:187], v[216:219], v[64:67]
	s_setprio 0
	s_add_i32 s79, s71, s64
	v_lshl_add_u64 v[144:145], s[58:59], 0, v[130:131]
	s_mov_b32 m0, s79
	ds_read_b128 v[188:191], v151 offset:16384
	ds_read_b128 v[192:195], v151 offset:17408
	ds_read_b128 v[196:199], v151 offset:18432
	ds_read_b128 v[200:203], v151 offset:19456
	ds_read_b128 v[204:207], v151 offset:20480
	ds_read_b128 v[208:211], v151 offset:21504
	ds_read_b128 v[212:215], v151 offset:22528
	ds_read_b128 v[216:219], v151 offset:23552
	global_load_lds_dwordx4 v[144:145], off
	s_add_i32 m0, s79, 0x2000
	s_add_u32 s88, s58, 0x40000
	v_lshl_add_u64 v[220:221], s[58:59], 0, v[134:135]
	s_addc_u32 s89, s59, 0
	s_add_i32 s79, s72, s64
	global_load_lds_dwordx4 v[220:221], off
	v_lshl_add_u64 v[222:223], s[88:89], 0, v[130:131]
	s_mov_b32 m0, s79
	v_lshl_add_u64 v[224:225], s[60:61], 0, v[132:133]
	global_load_lds_dwordx4 v[222:223], off
	v_lshl_add_u64 v[222:223], s[88:89], 0, v[134:135]
	s_add_i32 m0, s79, 0x2000
	s_nop 0
	global_load_lds_dwordx4 v[222:223], off
	v_lshl_add_u64 v[222:223], s[60:61], 0, v[128:129]
	s_mov_b32 m0, s55
	s_nop 0
	global_load_lds_dwordx4 v[222:223], off
	s_mov_b32 m0, s65
	s_nop 0
	global_load_lds_dwordx4 v[224:225], off
	s_waitcnt vmcnt(8)
	s_waitcnt lgkmcnt(0)
	s_barrier
	s_waitcnt lgkmcnt(0)
	v_mfma_f32_16x16x32_bf16 v[60:63], v[152:155], v[188:191], v[60:63]
	v_mfma_f32_16x16x32_bf16 v[60:63], v[156:159], v[192:195], v[60:63]
	v_mfma_f32_16x16x32_bf16 v[56:59], v[160:163], v[188:191], v[56:59]
	v_mfma_f32_16x16x32_bf16 v[56:59], v[164:167], v[192:195], v[56:59]
	v_mfma_f32_16x16x32_bf16 v[52:55], v[152:155], v[196:199], v[52:55]
	v_mfma_f32_16x16x32_bf16 v[52:55], v[156:159], v[200:203], v[52:55]
	v_mfma_f32_16x16x32_bf16 v[44:47], v[160:163], v[196:199], v[44:47]
	v_mfma_f32_16x16x32_bf16 v[44:47], v[164:167], v[200:203], v[44:47]
	s_setprio 1
	v_mfma_f32_16x16x32_bf16 v[36:39], v[152:155], v[204:207], v[36:39]
	v_mfma_f32_16x16x32_bf16 v[36:39], v[156:159], v[208:211], v[36:39]
	v_mfma_f32_16x16x32_bf16 v[28:31], v[160:163], v[204:207], v[28:31]
	v_mfma_f32_16x16x32_bf16 v[28:31], v[164:167], v[208:211], v[28:31]
	v_mfma_f32_16x16x32_bf16 v[20:23], v[152:155], v[212:215], v[20:23]
	v_mfma_f32_16x16x32_bf16 v[20:23], v[156:159], v[216:219], v[20:23]
	v_mfma_f32_16x16x32_bf16 v[12:15], v[160:163], v[212:215], v[12:15]
	v_mfma_f32_16x16x32_bf16 v[12:15], v[164:167], v[216:219], v[12:15]
	v_mfma_f32_16x16x32_bf16 v[48:51], v[168:171], v[188:191], v[48:51]
	v_mfma_f32_16x16x32_bf16 v[48:51], v[172:175], v[192:195], v[48:51]
	v_mfma_f32_16x16x32_bf16 v[40:43], v[176:179], v[188:191], v[40:43]
	v_mfma_f32_16x16x32_bf16 v[40:43], v[184:187], v[192:195], v[40:43]
	v_mfma_f32_16x16x32_bf16 v[32:35], v[168:171], v[196:199], v[32:35]
	v_mfma_f32_16x16x32_bf16 v[32:35], v[172:175], v[200:203], v[32:35]
	v_mfma_f32_16x16x32_bf16 v[24:27], v[176:179], v[196:199], v[24:27]
	v_mfma_f32_16x16x32_bf16 v[24:27], v[184:187], v[200:203], v[24:27]
	s_barrier
	v_mfma_f32_16x16x32_bf16 v[16:19], v[168:171], v[204:207], v[16:19]
	v_mfma_f32_16x16x32_bf16 v[16:19], v[172:175], v[208:211], v[16:19]
	v_mfma_f32_16x16x32_bf16 v[8:11], v[176:179], v[204:207], v[8:11]
	v_mfma_f32_16x16x32_bf16 v[8:11], v[184:187], v[208:211], v[8:11]
	v_mfma_f32_16x16x32_bf16 v[4:7], v[168:171], v[212:215], v[4:7]
	v_mfma_f32_16x16x32_bf16 v[4:7], v[172:175], v[216:219], v[4:7]
	v_mfma_f32_16x16x32_bf16 v[0:3], v[176:179], v[212:215], v[0:3]
	v_mfma_f32_16x16x32_bf16 v[0:3], v[184:187], v[216:219], v[0:3]
	s_setprio 0
.Lmid_gemm10:
	s_add_i32 s79, 0, 0x18000
	s_add_i32 s87, 0, 0x1c000
	v_add_u32_e32 v164, s79, v147
	v_add_u32_e32 v181, s87, v147
	ds_read_b128 v[152:155], v164
	ds_read_b128 v[156:159], v164 offset:1024
	ds_read_b128 v[160:163], v164 offset:2048
	ds_read_b128 v[164:167], v164 offset:3072
	ds_read_b128 v[168:171], v181
	ds_read_b128 v[172:175], v181 offset:1024
	ds_read_b128 v[176:179], v181 offset:2048
	ds_read_b128 v[184:187], v181 offset:3072
	s_add_u32 s60, s60, 0x40000
	s_addc_u32 s61, s61, 0
	s_mov_b32 m0, s66
	v_lshl_add_u64 v[226:227], s[60:61], 0, v[128:129]
	ds_read_b128 v[188:191], v151 offset:32768
	ds_read_b128 v[192:195], v151 offset:33792
	ds_read_b128 v[196:199], v151 offset:34816
	ds_read_b128 v[200:203], v151 offset:35840
	ds_read_b128 v[204:207], v151 offset:36864
	ds_read_b128 v[208:211], v151 offset:37888
	ds_read_b128 v[212:215], v151 offset:38912
	ds_read_b128 v[216:219], v151 offset:39936
	global_load_lds_dwordx4 v[226:227], off
	v_lshl_add_u64 v[226:227], s[60:61], 0, v[132:133]
	s_mov_b32 m0, s67
	s_nop 0
	global_load_lds_dwordx4 v[226:227], off
	s_waitcnt vmcnt(8)
	s_waitcnt lgkmcnt(0)
	s_barrier
	s_waitcnt lgkmcnt(0)
	v_mfma_f32_16x16x32_bf16 v[124:127], v[152:155], v[188:191], v[124:127]
	v_mfma_f32_16x16x32_bf16 v[124:127], v[156:159], v[192:195], v[124:127]
	v_mfma_f32_16x16x32_bf16 v[120:123], v[160:163], v[188:191], v[120:123]
	v_mfma_f32_16x16x32_bf16 v[120:123], v[164:167], v[192:195], v[120:123]
	v_mfma_f32_16x16x32_bf16 v[116:119], v[152:155], v[196:199], v[116:119]
	v_mfma_f32_16x16x32_bf16 v[116:119], v[156:159], v[200:203], v[116:119]
	v_mfma_f32_16x16x32_bf16 v[108:111], v[160:163], v[196:199], v[108:111]
	v_mfma_f32_16x16x32_bf16 v[108:111], v[164:167], v[200:203], v[108:111]
	s_setprio 1
	v_mfma_f32_16x16x32_bf16 v[100:103], v[152:155], v[204:207], v[100:103]
	v_mfma_f32_16x16x32_bf16 v[100:103], v[156:159], v[208:211], v[100:103]
	v_mfma_f32_16x16x32_bf16 v[92:95], v[160:163], v[204:207], v[92:95]
	v_mfma_f32_16x16x32_bf16 v[92:95], v[164:167], v[208:211], v[92:95]
	v_mfma_f32_16x16x32_bf16 v[84:87], v[152:155], v[212:215], v[84:87]
	v_mfma_f32_16x16x32_bf16 v[84:87], v[156:159], v[216:219], v[84:87]
	v_mfma_f32_16x16x32_bf16 v[76:79], v[160:163], v[212:215], v[76:79]
	v_mfma_f32_16x16x32_bf16 v[76:79], v[164:167], v[216:219], v[76:79]
	v_mfma_f32_16x16x32_bf16 v[112:115], v[168:171], v[188:191], v[112:115]
	v_mfma_f32_16x16x32_bf16 v[112:115], v[172:175], v[192:195], v[112:115]
	v_mfma_f32_16x16x32_bf16 v[104:107], v[176:179], v[188:191], v[104:107]
	v_mfma_f32_16x16x32_bf16 v[104:107], v[184:187], v[192:195], v[104:107]
	v_mfma_f32_16x16x32_bf16 v[96:99], v[168:171], v[196:199], v[96:99]
	v_mfma_f32_16x16x32_bf16 v[96:99], v[172:175], v[200:203], v[96:99]
	v_mfma_f32_16x16x32_bf16 v[88:91], v[176:179], v[196:199], v[88:91]
	v_mfma_f32_16x16x32_bf16 v[88:91], v[184:187], v[200:203], v[88:91]
	s_barrier
	v_mfma_f32_16x16x32_bf16 v[80:83], v[168:171], v[204:207], v[80:83]
	v_mfma_f32_16x16x32_bf16 v[80:83], v[172:175], v[208:211], v[80:83]
	v_mfma_f32_16x16x32_bf16 v[72:75], v[176:179], v[204:207], v[72:75]
	v_mfma_f32_16x16x32_bf16 v[72:75], v[184:187], v[208:211], v[72:75]
	v_mfma_f32_16x16x32_bf16 v[68:71], v[168:171], v[212:215], v[68:71]
	v_mfma_f32_16x16x32_bf16 v[68:71], v[172:175], v[216:219], v[68:71]
	v_mfma_f32_16x16x32_bf16 v[64:67], v[176:179], v[212:215], v[64:67]
	v_mfma_f32_16x16x32_bf16 v[64:67], v[184:187], v[216:219], v[64:67]
	s_setprio 0
	s_add_i32 s60, s79, s64
	v_lshl_add_u64 v[144:145], v[144:145], 0, s[16:17]
	s_mov_b32 m0, s60
	ds_read_b128 v[188:191], v151 offset:49152
	ds_read_b128 v[192:195], v151 offset:50176
	ds_read_b128 v[196:199], v151 offset:51200
	ds_read_b128 v[200:203], v151 offset:52224
	ds_read_b128 v[204:207], v151 offset:53248
	ds_read_b128 v[208:211], v151 offset:54272
	ds_read_b128 v[212:215], v151 offset:55296
	ds_read_b128 v[216:219], v151 offset:56320
	global_load_lds_dwordx4 v[144:145], off
	s_add_i32 m0, s60, 0x2000
	s_add_u32 s58, s58, 0x40080
	v_lshl_add_u64 v[144:145], v[220:221], 0, s[16:17]
	s_addc_u32 s59, s59, 0
	s_add_i32 s60, s87, s64
	global_load_lds_dwordx4 v[144:145], off
	v_lshl_add_u64 v[144:145], s[58:59], 0, v[130:131]
	s_mov_b32 m0, s60
	s_nop 0
	global_load_lds_dwordx4 v[144:145], off
	v_lshl_add_u64 v[144:145], s[58:59], 0, v[134:135]
	s_add_i32 m0, s60, 0x2000
	s_nop 0
	global_load_lds_dwordx4 v[144:145], off
	v_lshl_add_u64 v[144:145], v[222:223], 0, s[16:17]
	s_mov_b32 m0, s69
	s_nop 0
	global_load_lds_dwordx4 v[144:145], off
	v_lshl_add_u64 v[144:145], v[224:225], 0, s[16:17]
	s_mov_b32 m0, s70
	s_nop 0
	global_load_lds_dwordx4 v[144:145], off
	s_waitcnt vmcnt(8)
	s_waitcnt lgkmcnt(0)
	s_barrier
	s_waitcnt lgkmcnt(0)
	v_mfma_f32_16x16x32_bf16 v[60:63], v[152:155], v[188:191], v[60:63]
	v_mfma_f32_16x16x32_bf16 v[60:63], v[156:159], v[192:195], v[60:63]
	v_mfma_f32_16x16x32_bf16 v[56:59], v[160:163], v[188:191], v[56:59]
	v_mfma_f32_16x16x32_bf16 v[56:59], v[164:167], v[192:195], v[56:59]
	v_mfma_f32_16x16x32_bf16 v[52:55], v[152:155], v[196:199], v[52:55]
	v_mfma_f32_16x16x32_bf16 v[52:55], v[156:159], v[200:203], v[52:55]
	v_mfma_f32_16x16x32_bf16 v[44:47], v[160:163], v[196:199], v[44:47]
	v_mfma_f32_16x16x32_bf16 v[44:47], v[164:167], v[200:203], v[44:47]
	s_setprio 1
	v_mfma_f32_16x16x32_bf16 v[36:39], v[152:155], v[204:207], v[36:39]
	v_mfma_f32_16x16x32_bf16 v[36:39], v[156:159], v[208:211], v[36:39]
	v_mfma_f32_16x16x32_bf16 v[28:31], v[160:163], v[204:207], v[28:31]
	v_mfma_f32_16x16x32_bf16 v[28:31], v[164:167], v[208:211], v[28:31]
	v_mfma_f32_16x16x32_bf16 v[20:23], v[152:155], v[212:215], v[20:23]
	v_mfma_f32_16x16x32_bf16 v[20:23], v[156:159], v[216:219], v[20:23]
	v_mfma_f32_16x16x32_bf16 v[12:15], v[160:163], v[212:215], v[12:15]
	v_mfma_f32_16x16x32_bf16 v[12:15], v[164:167], v[216:219], v[12:15]
	v_mfma_f32_16x16x32_bf16 v[48:51], v[168:171], v[188:191], v[48:51]
	v_mfma_f32_16x16x32_bf16 v[48:51], v[172:175], v[192:195], v[48:51]
	v_mfma_f32_16x16x32_bf16 v[40:43], v[176:179], v[188:191], v[40:43]
	v_mfma_f32_16x16x32_bf16 v[40:43], v[184:187], v[192:195], v[40:43]
	v_mfma_f32_16x16x32_bf16 v[32:35], v[168:171], v[196:199], v[32:35]
	v_mfma_f32_16x16x32_bf16 v[32:35], v[172:175], v[200:203], v[32:35]
	v_mfma_f32_16x16x32_bf16 v[24:27], v[176:179], v[196:199], v[24:27]
	v_mfma_f32_16x16x32_bf16 v[24:27], v[184:187], v[200:203], v[24:27]
	s_barrier
	v_mfma_f32_16x16x32_bf16 v[16:19], v[168:171], v[204:207], v[16:19]
	v_mfma_f32_16x16x32_bf16 v[16:19], v[172:175], v[208:211], v[16:19]
	v_mfma_f32_16x16x32_bf16 v[8:11], v[176:179], v[204:207], v[8:11]
	v_mfma_f32_16x16x32_bf16 v[8:11], v[184:187], v[208:211], v[8:11]
	v_mfma_f32_16x16x32_bf16 v[4:7], v[168:171], v[212:215], v[4:7]
	v_mfma_f32_16x16x32_bf16 v[4:7], v[172:175], v[216:219], v[4:7]
	v_mfma_f32_16x16x32_bf16 v[0:3], v[176:179], v[212:215], v[0:3]
	v_mfma_f32_16x16x32_bf16 v[0:3], v[184:187], v[216:219], v[0:3]
	s_setprio 0
	s_add_i32 s86, s86, 2
	s_add_u32 s56, s56, 0x100
	s_addc_u32 s57, s57, 0
	s_add_u32 s84, s84, 0x100
	s_addc_u32 s85, s85, 0
	s_cmp_gt_u32 s86, 13
	s_cbranch_scc0 .LBB0_1311
	s_and_b64 vcc, exec, s[18:19]
	s_cbranch_vccz .LBB0_1314
	s_barrier

.LBB0_1433:
	s_ashr_i32 s19, s18, 31
	s_lshl_b64 s[30:31], s[18:19], 19
	s_add_u32 s30, s80, s30
	s_addc_u32 s31, s81, s31
	s_and_b64 s[36:37], s[8:9], exec
	s_cselect_b32 s19, s31, s47
	s_cselect_b32 s66, s30, s46
	s_ashr_i32 s17, s16, 31
	s_lshl_b64 s[36:37], s[16:17], 19
	s_add_u32 s36, s52, s36
	s_addc_u32 s37, s53, s37
	s_and_b64 s[50:51], s[8:9], exec
	s_cselect_b32 s17, s37, s49
	s_cselect_b32 s67, s36, s48
	s_add_u32 s46, s46, 0x40080
	s_addc_u32 s47, s47, 0
	s_add_u32 s68, s48, 0x100
	s_addc_u32 s69, s49, 0
	s_mov_b32 s70, -2
	ds_read_b128 v[140:143], v147
	ds_read_b128 v[150:153], v147 offset:1024
	ds_read_b128 v[154:157], v147 offset:2048
	ds_read_b128 v[158:161], v147 offset:3072
	ds_read_b128 v[162:165], v148
	ds_read_b128 v[166:169], v148 offset:1024
	ds_read_b128 v[170:173], v148 offset:2048
	ds_read_b128 v[174:177], v148 offset:3072
	s_add_u32 s48, s46, 0xfffc0080
	s_addc_u32 s49, s47, -1
	s_cmp_eq_u32 s70, 12
	s_cselect_b32 s51, s19, s49
	s_cselect_b32 s50, s66, s48
	s_cselect_b32 s49, s17, s69
	s_cselect_b32 s48, s67, s68
	v_lshl_add_u64 v[178:179], s[46:47], 0, v[132:133]
	s_add_i32 m0, s45, 0xc000
	ds_read_b128 v[184:187], v149
	ds_read_b128 v[188:191], v149 offset:1024
	ds_read_b128 v[192:195], v149 offset:2048
	ds_read_b128 v[196:199], v149 offset:3072
	ds_read_b128 v[200:203], v149 offset:4096
	ds_read_b128 v[204:207], v149 offset:5120
	ds_read_b128 v[208:211], v149 offset:6144
	ds_read_b128 v[212:215], v149 offset:7168
	global_load_lds_dwordx4 v[178:179], off
	v_lshl_add_u64 v[178:179], s[46:47], 0, v[134:135]
	s_add_i32 m0, s45, 0xe000
	s_nop 0
	global_load_lds_dwordx4 v[178:179], off
	s_waitcnt vmcnt(8)
	s_waitcnt lgkmcnt(0)
	s_barrier
	s_waitcnt lgkmcnt(0)
	v_mfma_f32_16x16x32_bf16 v[124:127], v[140:143], v[184:187], 0
	v_mfma_f32_16x16x32_bf16 v[124:127], v[150:153], v[188:191], v[124:127]
	v_mfma_f32_16x16x32_bf16 v[120:123], v[154:157], v[184:187], 0
	v_mfma_f32_16x16x32_bf16 v[120:123], v[158:161], v[188:191], v[120:123]
	v_mfma_f32_16x16x32_bf16 v[108:111], v[140:143], v[192:195], 0
	v_mfma_f32_16x16x32_bf16 v[108:111], v[150:153], v[196:199], v[108:111]
	v_mfma_f32_16x16x32_bf16 v[104:107], v[154:157], v[192:195], 0
	v_mfma_f32_16x16x32_bf16 v[104:107], v[158:161], v[196:199], v[104:107]
	s_setprio 1
	v_mfma_f32_16x16x32_bf16 v[92:95], v[140:143], v[200:203], 0
	v_mfma_f32_16x16x32_bf16 v[92:95], v[150:153], v[204:207], v[92:95]
	v_mfma_f32_16x16x32_bf16 v[88:91], v[154:157], v[200:203], 0
	v_mfma_f32_16x16x32_bf16 v[88:91], v[158:161], v[204:207], v[88:91]
	v_mfma_f32_16x16x32_bf16 v[76:79], v[140:143], v[208:211], 0
	v_mfma_f32_16x16x32_bf16 v[76:79], v[150:153], v[212:215], v[76:79]
	v_mfma_f32_16x16x32_bf16 v[72:75], v[154:157], v[208:211], 0
	v_mfma_f32_16x16x32_bf16 v[72:75], v[158:161], v[212:215], v[72:75]
	v_mfma_f32_16x16x32_bf16 v[116:119], v[162:165], v[184:187], 0
	v_mfma_f32_16x16x32_bf16 v[116:119], v[166:169], v[188:191], v[116:119]
	v_mfma_f32_16x16x32_bf16 v[112:115], v[170:173], v[184:187], 0
	v_mfma_f32_16x16x32_bf16 v[112:115], v[174:177], v[188:191], v[112:115]
	v_mfma_f32_16x16x32_bf16 v[100:103], v[162:165], v[192:195], 0
	v_mfma_f32_16x16x32_bf16 v[100:103], v[166:169], v[196:199], v[100:103]
	v_mfma_f32_16x16x32_bf16 v[96:99], v[170:173], v[192:195], 0
	v_mfma_f32_16x16x32_bf16 v[96:99], v[174:177], v[196:199], v[96:99]
	s_barrier
	v_mfma_f32_16x16x32_bf16 v[84:87], v[162:165], v[200:203], 0
	v_mfma_f32_16x16x32_bf16 v[84:87], v[166:169], v[204:207], v[84:87]
	v_mfma_f32_16x16x32_bf16 v[80:83], v[170:173], v[200:203], 0
	v_mfma_f32_16x16x32_bf16 v[80:83], v[174:177], v[204:207], v[80:83]
	v_mfma_f32_16x16x32_bf16 v[68:71], v[162:165], v[208:211], 0
	v_mfma_f32_16x16x32_bf16 v[68:71], v[166:169], v[212:215], v[68:71]
	v_mfma_f32_16x16x32_bf16 v[64:67], v[170:173], v[208:211], 0
	v_mfma_f32_16x16x32_bf16 v[64:67], v[174:177], v[212:215], v[64:67]
	s_setprio 0
	s_add_i32 s71, s62, s54
	v_lshl_add_u64 v[178:179], s[48:49], 0, v[130:131]
	s_mov_b32 m0, s71
	ds_read_b128 v[184:187], v149 offset:16384
	ds_read_b128 v[188:191], v149 offset:17408
	ds_read_b128 v[192:195], v149 offset:18432
	ds_read_b128 v[196:199], v149 offset:19456
	ds_read_b128 v[200:203], v149 offset:20480
	ds_read_b128 v[204:207], v149 offset:21504
	ds_read_b128 v[208:211], v149 offset:22528
	ds_read_b128 v[212:215], v149 offset:23552
	global_load_lds_dwordx4 v[178:179], off
	s_add_i32 m0, s71, 0x2000
	s_add_u32 s72, s48, 0x40000
	v_lshl_add_u64 v[216:217], s[48:49], 0, v[128:129]
	s_addc_u32 s73, s49, 0
	s_add_i32 s71, s63, s54
	global_load_lds_dwordx4 v[216:217], off
	v_lshl_add_u64 v[218:219], s[72:73], 0, v[130:131]
	s_mov_b32 m0, s71
	v_lshl_add_u64 v[220:221], s[50:51], 0, v[128:129]
	global_load_lds_dwordx4 v[218:219], off
	v_lshl_add_u64 v[218:219], s[72:73], 0, v[128:129]
	s_add_i32 m0, s71, 0x2000
	s_nop 0
	global_load_lds_dwordx4 v[218:219], off
	v_lshl_add_u64 v[218:219], s[50:51], 0, v[130:131]
	s_mov_b32 m0, s45
	s_nop 0
	global_load_lds_dwordx4 v[218:219], off
	s_mov_b32 m0, s56
	s_nop 0
	global_load_lds_dwordx4 v[220:221], off
	s_waitcnt vmcnt(8)
	s_waitcnt lgkmcnt(0)
	s_barrier
	s_waitcnt lgkmcnt(0)
	v_mfma_f32_16x16x32_bf16 v[60:63], v[140:143], v[184:187], 0
	v_mfma_f32_16x16x32_bf16 v[60:63], v[150:153], v[188:191], v[60:63]
	v_mfma_f32_16x16x32_bf16 v[56:59], v[154:157], v[184:187], 0
	v_mfma_f32_16x16x32_bf16 v[56:59], v[158:161], v[188:191], v[56:59]
	v_mfma_f32_16x16x32_bf16 v[44:47], v[140:143], v[192:195], 0
	v_mfma_f32_16x16x32_bf16 v[44:47], v[150:153], v[196:199], v[44:47]
	v_mfma_f32_16x16x32_bf16 v[40:43], v[154:157], v[192:195], 0
	v_mfma_f32_16x16x32_bf16 v[40:43], v[158:161], v[196:199], v[40:43]
	s_setprio 1
	v_mfma_f32_16x16x32_bf16 v[28:31], v[140:143], v[200:203], 0
	v_mfma_f32_16x16x32_bf16 v[28:31], v[150:153], v[204:207], v[28:31]
	v_mfma_f32_16x16x32_bf16 v[24:27], v[154:157], v[200:203], 0
	v_mfma_f32_16x16x32_bf16 v[24:27], v[158:161], v[204:207], v[24:27]
	v_mfma_f32_16x16x32_bf16 v[12:15], v[140:143], v[208:211], 0
	v_mfma_f32_16x16x32_bf16 v[12:15], v[150:153], v[212:215], v[12:15]
	v_mfma_f32_16x16x32_bf16 v[8:11], v[154:157], v[208:211], 0
	v_mfma_f32_16x16x32_bf16 v[8:11], v[158:161], v[212:215], v[8:11]
	v_mfma_f32_16x16x32_bf16 v[52:55], v[162:165], v[184:187], 0
	v_mfma_f32_16x16x32_bf16 v[52:55], v[166:169], v[188:191], v[52:55]
	v_mfma_f32_16x16x32_bf16 v[48:51], v[170:173], v[184:187], 0
	v_mfma_f32_16x16x32_bf16 v[48:51], v[174:177], v[188:191], v[48:51]
	v_mfma_f32_16x16x32_bf16 v[36:39], v[162:165], v[192:195], 0
	v_mfma_f32_16x16x32_bf16 v[36:39], v[166:169], v[196:199], v[36:39]
	v_mfma_f32_16x16x32_bf16 v[32:35], v[170:173], v[192:195], 0
	v_mfma_f32_16x16x32_bf16 v[32:35], v[174:177], v[196:199], v[32:35]
	s_barrier
	v_mfma_f32_16x16x32_bf16 v[20:23], v[162:165], v[200:203], 0
	v_mfma_f32_16x16x32_bf16 v[20:23], v[166:169], v[204:207], v[20:23]
	v_mfma_f32_16x16x32_bf16 v[16:19], v[170:173], v[200:203], 0
	v_mfma_f32_16x16x32_bf16 v[16:19], v[174:177], v[204:207], v[16:19]
	v_mfma_f32_16x16x32_bf16 v[4:7], v[162:165], v[208:211], 0
	v_mfma_f32_16x16x32_bf16 v[4:7], v[166:169], v[212:215], v[4:7]
	v_mfma_f32_16x16x32_bf16 v[0:3], v[170:173], v[208:211], 0
	v_mfma_f32_16x16x32_bf16 v[0:3], v[174:177], v[212:215], v[0:3]
	s_setprio 0
	s_branch .Lmid_gemm11
.LBB0_1434:
	ds_read_b128 v[140:143], v147
	ds_read_b128 v[150:153], v147 offset:1024
	ds_read_b128 v[154:157], v147 offset:2048
	ds_read_b128 v[158:161], v147 offset:3072
	ds_read_b128 v[162:165], v148
	ds_read_b128 v[166:169], v148 offset:1024
	ds_read_b128 v[170:173], v148 offset:2048
	ds_read_b128 v[174:177], v148 offset:3072
	s_add_u32 s48, s46, 0xfffc0080
	s_addc_u32 s49, s47, -1
	s_cmp_eq_u32 s70, 12
	s_cselect_b32 s51, s19, s49
	s_cselect_b32 s50, s66, s48
	s_cselect_b32 s49, s17, s69
	s_cselect_b32 s48, s67, s68
	v_lshl_add_u64 v[178:179], s[46:47], 0, v[132:133]
	s_add_i32 m0, s45, 0xc000
	ds_read_b128 v[184:187], v149
	ds_read_b128 v[188:191], v149 offset:1024
	ds_read_b128 v[192:195], v149 offset:2048
	ds_read_b128 v[196:199], v149 offset:3072
	ds_read_b128 v[200:203], v149 offset:4096
	ds_read_b128 v[204:207], v149 offset:5120
	ds_read_b128 v[208:211], v149 offset:6144
	ds_read_b128 v[212:215], v149 offset:7168
	global_load_lds_dwordx4 v[178:179], off
	v_lshl_add_u64 v[178:179], s[46:47], 0, v[134:135]
	s_add_i32 m0, s45, 0xe000
	s_nop 0
	global_load_lds_dwordx4 v[178:179], off
	s_waitcnt vmcnt(8)
	s_waitcnt lgkmcnt(0)
	s_barrier
	s_waitcnt lgkmcnt(0)
	v_mfma_f32_16x16x32_bf16 v[124:127], v[140:143], v[184:187], v[124:127]
	v_mfma_f32_16x16x32_bf16 v[124:127], v[150:153], v[188:191], v[124:127]
	v_mfma_f32_16x16x32_bf16 v[120:123], v[154:157], v[184:187], v[120:123]
	v_mfma_f32_16x16x32_bf16 v[120:123], v[158:161], v[188:191], v[120:123]
	v_mfma_f32_16x16x32_bf16 v[108:111], v[140:143], v[192:195], v[108:111]
	v_mfma_f32_16x16x32_bf16 v[108:111], v[150:153], v[196:199], v[108:111]
	v_mfma_f32_16x16x32_bf16 v[104:107], v[154:157], v[192:195], v[104:107]
	v_mfma_f32_16x16x32_bf16 v[104:107], v[158:161], v[196:199], v[104:107]
	s_setprio 1
	v_mfma_f32_16x16x32_bf16 v[92:95], v[140:143], v[200:203], v[92:95]
	v_mfma_f32_16x16x32_bf16 v[92:95], v[150:153], v[204:207], v[92:95]
	v_mfma_f32_16x16x32_bf16 v[88:91], v[154:157], v[200:203], v[88:91]
	v_mfma_f32_16x16x32_bf16 v[88:91], v[158:161], v[204:207], v[88:91]
	v_mfma_f32_16x16x32_bf16 v[76:79], v[140:143], v[208:211], v[76:79]
	v_mfma_f32_16x16x32_bf16 v[76:79], v[150:153], v[212:215], v[76:79]
	v_mfma_f32_16x16x32_bf16 v[72:75], v[154:157], v[208:211], v[72:75]
	v_mfma_f32_16x16x32_bf16 v[72:75], v[158:161], v[212:215], v[72:75]
	v_mfma_f32_16x16x32_bf16 v[116:119], v[162:165], v[184:187], v[116:119]
	v_mfma_f32_16x16x32_bf16 v[116:119], v[166:169], v[188:191], v[116:119]
	v_mfma_f32_16x16x32_bf16 v[112:115], v[170:173], v[184:187], v[112:115]
	v_mfma_f32_16x16x32_bf16 v[112:115], v[174:177], v[188:191], v[112:115]
	v_mfma_f32_16x16x32_bf16 v[100:103], v[162:165], v[192:195], v[100:103]
	v_mfma_f32_16x16x32_bf16 v[100:103], v[166:169], v[196:199], v[100:103]
	v_mfma_f32_16x16x32_bf16 v[96:99], v[170:173], v[192:195], v[96:99]
	v_mfma_f32_16x16x32_bf16 v[96:99], v[174:177], v[196:199], v[96:99]
	s_barrier
	v_mfma_f32_16x16x32_bf16 v[84:87], v[162:165], v[200:203], v[84:87]
	v_mfma_f32_16x16x32_bf16 v[84:87], v[166:169], v[204:207], v[84:87]
	v_mfma_f32_16x16x32_bf16 v[80:83], v[170:173], v[200:203], v[80:83]
	v_mfma_f32_16x16x32_bf16 v[80:83], v[174:177], v[204:207], v[80:83]
	v_mfma_f32_16x16x32_bf16 v[68:71], v[162:165], v[208:211], v[68:71]
	v_mfma_f32_16x16x32_bf16 v[68:71], v[166:169], v[212:215], v[68:71]
	v_mfma_f32_16x16x32_bf16 v[64:67], v[170:173], v[208:211], v[64:67]
	v_mfma_f32_16x16x32_bf16 v[64:67], v[174:177], v[212:215], v[64:67]
	s_setprio 0
	s_add_i32 s71, s62, s54
	v_lshl_add_u64 v[178:179], s[48:49], 0, v[130:131]
	s_mov_b32 m0, s71
	ds_read_b128 v[184:187], v149 offset:16384
	ds_read_b128 v[188:191], v149 offset:17408
	ds_read_b128 v[192:195], v149 offset:18432
	ds_read_b128 v[196:199], v149 offset:19456
	ds_read_b128 v[200:203], v149 offset:20480
	ds_read_b128 v[204:207], v149 offset:21504
	ds_read_b128 v[208:211], v149 offset:22528
	ds_read_b128 v[212:215], v149 offset:23552
	global_load_lds_dwordx4 v[178:179], off
	s_add_i32 m0, s71, 0x2000
	s_add_u32 s72, s48, 0x40000
	v_lshl_add_u64 v[216:217], s[48:49], 0, v[128:129]
	s_addc_u32 s73, s49, 0
	s_add_i32 s71, s63, s54
	global_load_lds_dwordx4 v[216:217], off
	v_lshl_add_u64 v[218:219], s[72:73], 0, v[130:131]
	s_mov_b32 m0, s71
	v_lshl_add_u64 v[220:221], s[50:51], 0, v[128:129]
	global_load_lds_dwordx4 v[218:219], off
	v_lshl_add_u64 v[218:219], s[72:73], 0, v[128:129]
	s_add_i32 m0, s71, 0x2000
	s_nop 0
	global_load_lds_dwordx4 v[218:219], off
	v_lshl_add_u64 v[218:219], s[50:51], 0, v[130:131]
	s_mov_b32 m0, s45
	s_nop 0
	global_load_lds_dwordx4 v[218:219], off
	s_mov_b32 m0, s56
	s_nop 0
	global_load_lds_dwordx4 v[220:221], off
	s_waitcnt vmcnt(8)
	s_waitcnt lgkmcnt(0)
	s_barrier
	s_waitcnt lgkmcnt(0)
	v_mfma_f32_16x16x32_bf16 v[60:63], v[140:143], v[184:187], v[60:63]
	v_mfma_f32_16x16x32_bf16 v[60:63], v[150:153], v[188:191], v[60:63]
	v_mfma_f32_16x16x32_bf16 v[56:59], v[154:157], v[184:187], v[56:59]
	v_mfma_f32_16x16x32_bf16 v[56:59], v[158:161], v[188:191], v[56:59]
	v_mfma_f32_16x16x32_bf16 v[44:47], v[140:143], v[192:195], v[44:47]
	v_mfma_f32_16x16x32_bf16 v[44:47], v[150:153], v[196:199], v[44:47]
	v_mfma_f32_16x16x32_bf16 v[40:43], v[154:157], v[192:195], v[40:43]
	v_mfma_f32_16x16x32_bf16 v[40:43], v[158:161], v[196:199], v[40:43]
	s_setprio 1
	v_mfma_f32_16x16x32_bf16 v[28:31], v[140:143], v[200:203], v[28:31]
	v_mfma_f32_16x16x32_bf16 v[28:31], v[150:153], v[204:207], v[28:31]
	v_mfma_f32_16x16x32_bf16 v[24:27], v[154:157], v[200:203], v[24:27]
	v_mfma_f32_16x16x32_bf16 v[24:27], v[158:161], v[204:207], v[24:27]
	v_mfma_f32_16x16x32_bf16 v[12:15], v[140:143], v[208:211], v[12:15]
	v_mfma_f32_16x16x32_bf16 v[12:15], v[150:153], v[212:215], v[12:15]
	v_mfma_f32_16x16x32_bf16 v[8:11], v[154:157], v[208:211], v[8:11]
	v_mfma_f32_16x16x32_bf16 v[8:11], v[158:161], v[212:215], v[8:11]
	v_mfma_f32_16x16x32_bf16 v[52:55], v[162:165], v[184:187], v[52:55]
	v_mfma_f32_16x16x32_bf16 v[52:55], v[166:169], v[188:191], v[52:55]
	v_mfma_f32_16x16x32_bf16 v[48:51], v[170:173], v[184:187], v[48:51]
	v_mfma_f32_16x16x32_bf16 v[48:51], v[174:177], v[188:191], v[48:51]
	v_mfma_f32_16x16x32_bf16 v[36:39], v[162:165], v[192:195], v[36:39]
	v_mfma_f32_16x16x32_bf16 v[36:39], v[166:169], v[196:199], v[36:39]
	v_mfma_f32_16x16x32_bf16 v[32:35], v[170:173], v[192:195], v[32:35]
	v_mfma_f32_16x16x32_bf16 v[32:35], v[174:177], v[196:199], v[32:35]
	s_barrier
	v_mfma_f32_16x16x32_bf16 v[20:23], v[162:165], v[200:203], v[20:23]
	v_mfma_f32_16x16x32_bf16 v[20:23], v[166:169], v[204:207], v[20:23]
	v_mfma_f32_16x16x32_bf16 v[16:19], v[170:173], v[200:203], v[16:19]
	v_mfma_f32_16x16x32_bf16 v[16:19], v[174:177], v[204:207], v[16:19]
	v_mfma_f32_16x16x32_bf16 v[4:7], v[162:165], v[208:211], v[4:7]
	v_mfma_f32_16x16x32_bf16 v[4:7], v[166:169], v[212:215], v[4:7]
	v_mfma_f32_16x16x32_bf16 v[0:3], v[170:173], v[208:211], v[0:3]
	v_mfma_f32_16x16x32_bf16 v[0:3], v[174:177], v[212:215], v[0:3]
	s_setprio 0
.Lmid_gemm11:
	s_add_i32 s71, 0, 0x18000
	s_add_i32 s72, 0, 0x1c000
	v_add_u32_e32 v158, s71, v145
	v_add_u32_e32 v174, s72, v145
	ds_read_b128 v[140:143], v158
	ds_read_b128 v[150:153], v158 offset:1024
	ds_read_b128 v[154:157], v158 offset:2048
	ds_read_b128 v[158:161], v158 offset:3072
	ds_read_b128 v[162:165], v174
	ds_read_b128 v[166:169], v174 offset:1024
	ds_read_b128 v[170:173], v174 offset:2048
	ds_read_b128 v[174:177], v174 offset:3072
	s_add_u32 s50, s50, 0x40000
	s_addc_u32 s51, s51, 0
	s_mov_b32 m0, s57
	v_lshl_add_u64 v[222:223], s[50:51], 0, v[130:131]
	ds_read_b128 v[184:187], v149 offset:32768
	ds_read_b128 v[188:191], v149 offset:33792
	ds_read_b128 v[192:195], v149 offset:34816
	ds_read_b128 v[196:199], v149 offset:35840
	ds_read_b128 v[200:203], v149 offset:36864
	ds_read_b128 v[204:207], v149 offset:37888
	ds_read_b128 v[208:211], v149 offset:38912
	ds_read_b128 v[212:215], v149 offset:39936
	global_load_lds_dwordx4 v[222:223], off
	v_lshl_add_u64 v[222:223], s[50:51], 0, v[128:129]
	s_mov_b32 m0, s58
	s_nop 0
	global_load_lds_dwordx4 v[222:223], off
	s_waitcnt vmcnt(8)
	s_waitcnt lgkmcnt(0)
	s_barrier
	s_waitcnt lgkmcnt(0)
	v_mfma_f32_16x16x32_bf16 v[124:127], v[140:143], v[184:187], v[124:127]
	v_mfma_f32_16x16x32_bf16 v[124:127], v[150:153], v[188:191], v[124:127]
	v_mfma_f32_16x16x32_bf16 v[120:123], v[154:157], v[184:187], v[120:123]
	v_mfma_f32_16x16x32_bf16 v[120:123], v[158:161], v[188:191], v[120:123]
	v_mfma_f32_16x16x32_bf16 v[108:111], v[140:143], v[192:195], v[108:111]
	v_mfma_f32_16x16x32_bf16 v[108:111], v[150:153], v[196:199], v[108:111]
	v_mfma_f32_16x16x32_bf16 v[104:107], v[154:157], v[192:195], v[104:107]
	v_mfma_f32_16x16x32_bf16 v[104:107], v[158:161], v[196:199], v[104:107]
	s_setprio 1
	v_mfma_f32_16x16x32_bf16 v[92:95], v[140:143], v[200:203], v[92:95]
	v_mfma_f32_16x16x32_bf16 v[92:95], v[150:153], v[204:207], v[92:95]
	v_mfma_f32_16x16x32_bf16 v[88:91], v[154:157], v[200:203], v[88:91]
	v_mfma_f32_16x16x32_bf16 v[88:91], v[158:161], v[204:207], v[88:91]
	v_mfma_f32_16x16x32_bf16 v[76:79], v[140:143], v[208:211], v[76:79]
	v_mfma_f32_16x16x32_bf16 v[76:79], v[150:153], v[212:215], v[76:79]
	v_mfma_f32_16x16x32_bf16 v[72:75], v[154:157], v[208:211], v[72:75]
	v_mfma_f32_16x16x32_bf16 v[72:75], v[158:161], v[212:215], v[72:75]
	v_mfma_f32_16x16x32_bf16 v[116:119], v[162:165], v[184:187], v[116:119]
	v_mfma_f32_16x16x32_bf16 v[116:119], v[166:169], v[188:191], v[116:119]
	v_mfma_f32_16x16x32_bf16 v[112:115], v[170:173], v[184:187], v[112:115]
	v_mfma_f32_16x16x32_bf16 v[112:115], v[174:177], v[188:191], v[112:115]
	v_mfma_f32_16x16x32_bf16 v[100:103], v[162:165], v[192:195], v[100:103]
	v_mfma_f32_16x16x32_bf16 v[100:103], v[166:169], v[196:199], v[100:103]
	v_mfma_f32_16x16x32_bf16 v[96:99], v[170:173], v[192:195], v[96:99]
	v_mfma_f32_16x16x32_bf16 v[96:99], v[174:177], v[196:199], v[96:99]
	s_barrier
	v_mfma_f32_16x16x32_bf16 v[84:87], v[162:165], v[200:203], v[84:87]
	v_mfma_f32_16x16x32_bf16 v[84:87], v[166:169], v[204:207], v[84:87]
	v_mfma_f32_16x16x32_bf16 v[80:83], v[170:173], v[200:203], v[80:83]
	v_mfma_f32_16x16x32_bf16 v[80:83], v[174:177], v[204:207], v[80:83]
	v_mfma_f32_16x16x32_bf16 v[68:71], v[162:165], v[208:211], v[68:71]
	v_mfma_f32_16x16x32_bf16 v[68:71], v[166:169], v[212:215], v[68:71]
	v_mfma_f32_16x16x32_bf16 v[64:67], v[170:173], v[208:211], v[64:67]
	v_mfma_f32_16x16x32_bf16 v[64:67], v[174:177], v[212:215], v[64:67]
	s_setprio 0
	s_add_i32 s50, s71, s54
	v_lshl_add_u64 v[178:179], v[178:179], 0, s[10:11]
	s_mov_b32 m0, s50
	ds_read_b128 v[184:187], v149 offset:49152
	ds_read_b128 v[188:191], v149 offset:50176
	ds_read_b128 v[192:195], v149 offset:51200
	ds_read_b128 v[196:199], v149 offset:52224
	ds_read_b128 v[200:203], v149 offset:53248
	ds_read_b128 v[204:207], v149 offset:54272
	ds_read_b128 v[208:211], v149 offset:55296
	ds_read_b128 v[212:215], v149 offset:56320
	global_load_lds_dwordx4 v[178:179], off
	s_add_i32 m0, s50, 0x2000
	s_add_u32 s48, s48, 0x40080
	v_lshl_add_u64 v[178:179], v[216:217], 0, s[10:11]
	s_addc_u32 s49, s49, 0
	s_add_i32 s50, s72, s54
	global_load_lds_dwordx4 v[178:179], off
	v_lshl_add_u64 v[178:179], s[48:49], 0, v[130:131]
	s_mov_b32 m0, s50
	s_nop 0
	global_load_lds_dwordx4 v[178:179], off
	v_lshl_add_u64 v[178:179], s[48:49], 0, v[128:129]
	s_add_i32 m0, s50, 0x2000
	s_nop 0
	global_load_lds_dwordx4 v[178:179], off
	v_lshl_add_u64 v[178:179], v[218:219], 0, s[10:11]
	s_mov_b32 m0, s60
	s_nop 0
	global_load_lds_dwordx4 v[178:179], off
	v_lshl_add_u64 v[178:179], v[220:221], 0, s[10:11]
	s_mov_b32 m0, s61
	s_nop 0
	global_load_lds_dwordx4 v[178:179], off
	s_waitcnt vmcnt(8)
	s_waitcnt lgkmcnt(0)
	s_barrier
	s_waitcnt lgkmcnt(0)
	v_mfma_f32_16x16x32_bf16 v[60:63], v[140:143], v[184:187], v[60:63]
	v_mfma_f32_16x16x32_bf16 v[60:63], v[150:153], v[188:191], v[60:63]
	v_mfma_f32_16x16x32_bf16 v[56:59], v[154:157], v[184:187], v[56:59]
	v_mfma_f32_16x16x32_bf16 v[56:59], v[158:161], v[188:191], v[56:59]
	v_mfma_f32_16x16x32_bf16 v[44:47], v[140:143], v[192:195], v[44:47]
	v_mfma_f32_16x16x32_bf16 v[44:47], v[150:153], v[196:199], v[44:47]
	v_mfma_f32_16x16x32_bf16 v[40:43], v[154:157], v[192:195], v[40:43]
	v_mfma_f32_16x16x32_bf16 v[40:43], v[158:161], v[196:199], v[40:43]
	s_setprio 1
	v_mfma_f32_16x16x32_bf16 v[28:31], v[140:143], v[200:203], v[28:31]
	v_mfma_f32_16x16x32_bf16 v[28:31], v[150:153], v[204:207], v[28:31]
	v_mfma_f32_16x16x32_bf16 v[24:27], v[154:157], v[200:203], v[24:27]
	v_mfma_f32_16x16x32_bf16 v[24:27], v[158:161], v[204:207], v[24:27]
	v_mfma_f32_16x16x32_bf16 v[12:15], v[140:143], v[208:211], v[12:15]
	v_mfma_f32_16x16x32_bf16 v[12:15], v[150:153], v[212:215], v[12:15]
	v_mfma_f32_16x16x32_bf16 v[8:11], v[154:157], v[208:211], v[8:11]
	v_mfma_f32_16x16x32_bf16 v[8:11], v[158:161], v[212:215], v[8:11]
	v_mfma_f32_16x16x32_bf16 v[52:55], v[162:165], v[184:187], v[52:55]
	v_mfma_f32_16x16x32_bf16 v[52:55], v[166:169], v[188:191], v[52:55]
	v_mfma_f32_16x16x32_bf16 v[48:51], v[170:173], v[184:187], v[48:51]
	v_mfma_f32_16x16x32_bf16 v[48:51], v[174:177], v[188:191], v[48:51]
	v_mfma_f32_16x16x32_bf16 v[36:39], v[162:165], v[192:195], v[36:39]
	v_mfma_f32_16x16x32_bf16 v[36:39], v[166:169], v[196:199], v[36:39]
	v_mfma_f32_16x16x32_bf16 v[32:35], v[170:173], v[192:195], v[32:35]
	v_mfma_f32_16x16x32_bf16 v[32:35], v[174:177], v[196:199], v[32:35]
	s_barrier
	v_mfma_f32_16x16x32_bf16 v[20:23], v[162:165], v[200:203], v[20:23]
	v_mfma_f32_16x16x32_bf16 v[20:23], v[166:169], v[204:207], v[20:23]
	v_mfma_f32_16x16x32_bf16 v[16:19], v[170:173], v[200:203], v[16:19]
	v_mfma_f32_16x16x32_bf16 v[16:19], v[174:177], v[204:207], v[16:19]
	v_mfma_f32_16x16x32_bf16 v[4:7], v[162:165], v[208:211], v[4:7]
	v_mfma_f32_16x16x32_bf16 v[4:7], v[166:169], v[212:215], v[4:7]
	v_mfma_f32_16x16x32_bf16 v[0:3], v[170:173], v[208:211], v[0:3]
	v_mfma_f32_16x16x32_bf16 v[0:3], v[174:177], v[212:215], v[0:3]
	s_setprio 0
	s_add_i32 s70, s70, 2
	s_add_u32 s46, s46, 0x100
	s_addc_u32 s47, s47, 0
	s_add_u32 s68, s68, 0x100
	s_addc_u32 s69, s69, 0
	s_cmp_gt_u32 s70, 13
	s_cbranch_scc0 .LBB0_1434
	s_and_b64 vcc, exec, s[12:13]
	s_cbranch_vccz .LBB0_1437
	s_barrier

.LBB0_1513:
	s_add_u32 s74, s48, 0x100
	s_addc_u32 s75, s49, 0
	s_mov_b32 s76, -2
	ds_read_b128 v[152:155], v149
	ds_read_b128 v[156:159], v149 offset:1024
	ds_read_b128 v[160:163], v149 offset:2048
	ds_read_b128 v[164:167], v149 offset:3072
	ds_read_b128 v[168:171], v150
	ds_read_b128 v[172:175], v150 offset:1024
	ds_read_b128 v[176:179], v150 offset:2048
	ds_read_b128 v[184:187], v150 offset:3072
	s_add_u32 s48, s46, 0x100
	s_addc_u32 s49, s47, 0
	s_cmp_eq_u32 s76, 40
	s_cselect_b32 s53, s9, s49
	s_cselect_b32 s52, s8, s48
	s_cselect_b32 s51, s45, s75
	s_cselect_b32 s50, s44, s74
	v_lshl_add_u64 v[144:145], s[46:47], 0, v[136:137]
	s_add_i32 m0, s57, 0xc000
	ds_read_b128 v[188:191], v151
	ds_read_b128 v[192:195], v151 offset:1024
	ds_read_b128 v[196:199], v151 offset:2048
	ds_read_b128 v[200:203], v151 offset:3072
	ds_read_b128 v[204:207], v151 offset:4096
	ds_read_b128 v[208:211], v151 offset:5120
	ds_read_b128 v[212:215], v151 offset:6144
	ds_read_b128 v[216:219], v151 offset:7168
	global_load_lds_dwordx4 v[144:145], off
	v_lshl_add_u64 v[144:145], s[46:47], 0, v[138:139]
	s_add_i32 m0, s57, 0xe000
	s_nop 0
	global_load_lds_dwordx4 v[144:145], off
	s_waitcnt vmcnt(8)
	s_waitcnt lgkmcnt(0)
	s_barrier
	s_waitcnt lgkmcnt(0)
	v_mfma_f32_16x16x32_bf16 v[124:127], v[152:155], v[188:191], 0
	v_mfma_f32_16x16x32_bf16 v[124:127], v[156:159], v[192:195], v[124:127]
	v_mfma_f32_16x16x32_bf16 v[120:123], v[160:163], v[188:191], 0
	v_mfma_f32_16x16x32_bf16 v[120:123], v[164:167], v[192:195], v[120:123]
	v_mfma_f32_16x16x32_bf16 v[116:119], v[152:155], v[196:199], 0
	v_mfma_f32_16x16x32_bf16 v[116:119], v[156:159], v[200:203], v[116:119]
	v_mfma_f32_16x16x32_bf16 v[108:111], v[160:163], v[196:199], 0
	v_mfma_f32_16x16x32_bf16 v[108:111], v[164:167], v[200:203], v[108:111]
	s_setprio 1
	v_mfma_f32_16x16x32_bf16 v[100:103], v[152:155], v[204:207], 0
	v_mfma_f32_16x16x32_bf16 v[100:103], v[156:159], v[208:211], v[100:103]
	v_mfma_f32_16x16x32_bf16 v[92:95], v[160:163], v[204:207], 0
	v_mfma_f32_16x16x32_bf16 v[92:95], v[164:167], v[208:211], v[92:95]
	v_mfma_f32_16x16x32_bf16 v[84:87], v[152:155], v[212:215], 0
	v_mfma_f32_16x16x32_bf16 v[84:87], v[156:159], v[216:219], v[84:87]
	v_mfma_f32_16x16x32_bf16 v[76:79], v[160:163], v[212:215], 0
	v_mfma_f32_16x16x32_bf16 v[76:79], v[164:167], v[216:219], v[76:79]
	v_mfma_f32_16x16x32_bf16 v[112:115], v[168:171], v[188:191], 0
	v_mfma_f32_16x16x32_bf16 v[112:115], v[172:175], v[192:195], v[112:115]
	v_mfma_f32_16x16x32_bf16 v[104:107], v[176:179], v[188:191], 0
	v_mfma_f32_16x16x32_bf16 v[104:107], v[184:187], v[192:195], v[104:107]
	v_mfma_f32_16x16x32_bf16 v[96:99], v[168:171], v[196:199], 0
	v_mfma_f32_16x16x32_bf16 v[96:99], v[172:175], v[200:203], v[96:99]
	v_mfma_f32_16x16x32_bf16 v[88:91], v[176:179], v[196:199], 0
	v_mfma_f32_16x16x32_bf16 v[88:91], v[184:187], v[200:203], v[88:91]
	s_barrier
	v_mfma_f32_16x16x32_bf16 v[80:83], v[168:171], v[204:207], 0
	v_mfma_f32_16x16x32_bf16 v[80:83], v[172:175], v[208:211], v[80:83]
	v_mfma_f32_16x16x32_bf16 v[72:75], v[176:179], v[204:207], 0
	v_mfma_f32_16x16x32_bf16 v[72:75], v[184:187], v[208:211], v[72:75]
	v_mfma_f32_16x16x32_bf16 v[68:71], v[168:171], v[212:215], 0
	v_mfma_f32_16x16x32_bf16 v[68:71], v[172:175], v[216:219], v[68:71]
	v_mfma_f32_16x16x32_bf16 v[64:67], v[176:179], v[212:215], 0
	v_mfma_f32_16x16x32_bf16 v[64:67], v[184:187], v[216:219], v[64:67]
	s_setprio 0
	s_add_i32 s46, s64, s56
	v_lshl_add_u64 v[144:145], s[50:51], 0, v[130:131]
	s_mov_b32 m0, s46
	ds_read_b128 v[188:191], v151 offset:16384
	ds_read_b128 v[192:195], v151 offset:17408
	ds_read_b128 v[196:199], v151 offset:18432
	ds_read_b128 v[200:203], v151 offset:19456
	ds_read_b128 v[204:207], v151 offset:20480
	ds_read_b128 v[208:211], v151 offset:21504
	ds_read_b128 v[212:215], v151 offset:22528
	ds_read_b128 v[216:219], v151 offset:23552
	global_load_lds_dwordx4 v[144:145], off
	s_add_i32 m0, s46, 0x2000
	s_add_u32 s46, s50, 0xb0000
	v_lshl_add_u64 v[220:221], s[50:51], 0, v[134:135]
	s_addc_u32 s47, s51, 0
	s_add_i32 s77, s65, s56
	global_load_lds_dwordx4 v[220:221], off
	v_lshl_add_u64 v[222:223], s[46:47], 0, v[130:131]
	s_mov_b32 m0, s77
	v_lshl_add_u64 v[224:225], s[52:53], 0, v[132:133]
	global_load_lds_dwordx4 v[222:223], off
	v_lshl_add_u64 v[222:223], s[46:47], 0, v[134:135]
	s_add_i32 m0, s77, 0x2000
	s_nop 0
	global_load_lds_dwordx4 v[222:223], off
	v_lshl_add_u64 v[222:223], s[52:53], 0, v[128:129]
	s_mov_b32 m0, s57
	s_nop 0
	global_load_lds_dwordx4 v[222:223], off
	s_mov_b32 m0, s58
	s_nop 0
	global_load_lds_dwordx4 v[224:225], off
	s_waitcnt vmcnt(8)
	s_waitcnt lgkmcnt(0)
	s_barrier
	s_waitcnt lgkmcnt(0)
	v_mfma_f32_16x16x32_bf16 v[60:63], v[152:155], v[188:191], 0
	v_mfma_f32_16x16x32_bf16 v[60:63], v[156:159], v[192:195], v[60:63]
	v_mfma_f32_16x16x32_bf16 v[56:59], v[160:163], v[188:191], 0
	v_mfma_f32_16x16x32_bf16 v[56:59], v[164:167], v[192:195], v[56:59]
	v_mfma_f32_16x16x32_bf16 v[52:55], v[152:155], v[196:199], 0
	v_mfma_f32_16x16x32_bf16 v[52:55], v[156:159], v[200:203], v[52:55]
	v_mfma_f32_16x16x32_bf16 v[44:47], v[160:163], v[196:199], 0
	v_mfma_f32_16x16x32_bf16 v[44:47], v[164:167], v[200:203], v[44:47]
	s_setprio 1
	v_mfma_f32_16x16x32_bf16 v[36:39], v[152:155], v[204:207], 0
	v_mfma_f32_16x16x32_bf16 v[36:39], v[156:159], v[208:211], v[36:39]
	v_mfma_f32_16x16x32_bf16 v[28:31], v[160:163], v[204:207], 0
	v_mfma_f32_16x16x32_bf16 v[28:31], v[164:167], v[208:211], v[28:31]
	v_mfma_f32_16x16x32_bf16 v[20:23], v[152:155], v[212:215], 0
	v_mfma_f32_16x16x32_bf16 v[20:23], v[156:159], v[216:219], v[20:23]
	v_mfma_f32_16x16x32_bf16 v[12:15], v[160:163], v[212:215], 0
	v_mfma_f32_16x16x32_bf16 v[12:15], v[164:167], v[216:219], v[12:15]
	v_mfma_f32_16x16x32_bf16 v[48:51], v[168:171], v[188:191], 0
	v_mfma_f32_16x16x32_bf16 v[48:51], v[172:175], v[192:195], v[48:51]
	v_mfma_f32_16x16x32_bf16 v[40:43], v[176:179], v[188:191], 0
	v_mfma_f32_16x16x32_bf16 v[40:43], v[184:187], v[192:195], v[40:43]
	v_mfma_f32_16x16x32_bf16 v[32:35], v[168:171], v[196:199], 0
	v_mfma_f32_16x16x32_bf16 v[32:35], v[172:175], v[200:203], v[32:35]
	v_mfma_f32_16x16x32_bf16 v[24:27], v[176:179], v[196:199], 0
	v_mfma_f32_16x16x32_bf16 v[24:27], v[184:187], v[200:203], v[24:27]
	s_barrier
	v_mfma_f32_16x16x32_bf16 v[16:19], v[168:171], v[204:207], 0
	v_mfma_f32_16x16x32_bf16 v[16:19], v[172:175], v[208:211], v[16:19]
	v_mfma_f32_16x16x32_bf16 v[8:11], v[176:179], v[204:207], 0
	v_mfma_f32_16x16x32_bf16 v[8:11], v[184:187], v[208:211], v[8:11]
	v_mfma_f32_16x16x32_bf16 v[4:7], v[168:171], v[212:215], 0
	v_mfma_f32_16x16x32_bf16 v[4:7], v[172:175], v[216:219], v[4:7]
	v_mfma_f32_16x16x32_bf16 v[0:3], v[176:179], v[212:215], 0
	v_mfma_f32_16x16x32_bf16 v[0:3], v[184:187], v[216:219], v[0:3]
	s_setprio 0
	s_branch .Lmid_gemm12
.LBB0_1514:
	ds_read_b128 v[152:155], v149
	ds_read_b128 v[156:159], v149 offset:1024
	ds_read_b128 v[160:163], v149 offset:2048
	ds_read_b128 v[164:167], v149 offset:3072
	ds_read_b128 v[168:171], v150
	ds_read_b128 v[172:175], v150 offset:1024
	ds_read_b128 v[176:179], v150 offset:2048
	ds_read_b128 v[184:187], v150 offset:3072
	s_add_u32 s48, s46, 0x100
	s_addc_u32 s49, s47, 0
	s_cmp_eq_u32 s76, 40
	s_cselect_b32 s53, s9, s49
	s_cselect_b32 s52, s8, s48
	s_cselect_b32 s51, s45, s75
	s_cselect_b32 s50, s44, s74
	v_lshl_add_u64 v[144:145], s[46:47], 0, v[136:137]
	s_add_i32 m0, s57, 0xc000
	ds_read_b128 v[188:191], v151
	ds_read_b128 v[192:195], v151 offset:1024
	ds_read_b128 v[196:199], v151 offset:2048
	ds_read_b128 v[200:203], v151 offset:3072
	ds_read_b128 v[204:207], v151 offset:4096
	ds_read_b128 v[208:211], v151 offset:5120
	ds_read_b128 v[212:215], v151 offset:6144
	ds_read_b128 v[216:219], v151 offset:7168
	global_load_lds_dwordx4 v[144:145], off
	v_lshl_add_u64 v[144:145], s[46:47], 0, v[138:139]
	s_add_i32 m0, s57, 0xe000
	s_nop 0
	global_load_lds_dwordx4 v[144:145], off
	s_waitcnt vmcnt(8)
	s_waitcnt lgkmcnt(0)
	s_barrier
	s_waitcnt lgkmcnt(0)
	v_mfma_f32_16x16x32_bf16 v[124:127], v[152:155], v[188:191], v[124:127]
	v_mfma_f32_16x16x32_bf16 v[124:127], v[156:159], v[192:195], v[124:127]
	v_mfma_f32_16x16x32_bf16 v[120:123], v[160:163], v[188:191], v[120:123]
	v_mfma_f32_16x16x32_bf16 v[120:123], v[164:167], v[192:195], v[120:123]
	v_mfma_f32_16x16x32_bf16 v[116:119], v[152:155], v[196:199], v[116:119]
	v_mfma_f32_16x16x32_bf16 v[116:119], v[156:159], v[200:203], v[116:119]
	v_mfma_f32_16x16x32_bf16 v[108:111], v[160:163], v[196:199], v[108:111]
	v_mfma_f32_16x16x32_bf16 v[108:111], v[164:167], v[200:203], v[108:111]
	s_setprio 1
	v_mfma_f32_16x16x32_bf16 v[100:103], v[152:155], v[204:207], v[100:103]
	v_mfma_f32_16x16x32_bf16 v[100:103], v[156:159], v[208:211], v[100:103]
	v_mfma_f32_16x16x32_bf16 v[92:95], v[160:163], v[204:207], v[92:95]
	v_mfma_f32_16x16x32_bf16 v[92:95], v[164:167], v[208:211], v[92:95]
	v_mfma_f32_16x16x32_bf16 v[84:87], v[152:155], v[212:215], v[84:87]
	v_mfma_f32_16x16x32_bf16 v[84:87], v[156:159], v[216:219], v[84:87]
	v_mfma_f32_16x16x32_bf16 v[76:79], v[160:163], v[212:215], v[76:79]
	v_mfma_f32_16x16x32_bf16 v[76:79], v[164:167], v[216:219], v[76:79]
	v_mfma_f32_16x16x32_bf16 v[112:115], v[168:171], v[188:191], v[112:115]
	v_mfma_f32_16x16x32_bf16 v[112:115], v[172:175], v[192:195], v[112:115]
	v_mfma_f32_16x16x32_bf16 v[104:107], v[176:179], v[188:191], v[104:107]
	v_mfma_f32_16x16x32_bf16 v[104:107], v[184:187], v[192:195], v[104:107]
	v_mfma_f32_16x16x32_bf16 v[96:99], v[168:171], v[196:199], v[96:99]
	v_mfma_f32_16x16x32_bf16 v[96:99], v[172:175], v[200:203], v[96:99]
	v_mfma_f32_16x16x32_bf16 v[88:91], v[176:179], v[196:199], v[88:91]
	v_mfma_f32_16x16x32_bf16 v[88:91], v[184:187], v[200:203], v[88:91]
	s_barrier
	v_mfma_f32_16x16x32_bf16 v[80:83], v[168:171], v[204:207], v[80:83]
	v_mfma_f32_16x16x32_bf16 v[80:83], v[172:175], v[208:211], v[80:83]
	v_mfma_f32_16x16x32_bf16 v[72:75], v[176:179], v[204:207], v[72:75]
	v_mfma_f32_16x16x32_bf16 v[72:75], v[184:187], v[208:211], v[72:75]
	v_mfma_f32_16x16x32_bf16 v[68:71], v[168:171], v[212:215], v[68:71]
	v_mfma_f32_16x16x32_bf16 v[68:71], v[172:175], v[216:219], v[68:71]
	v_mfma_f32_16x16x32_bf16 v[64:67], v[176:179], v[212:215], v[64:67]
	v_mfma_f32_16x16x32_bf16 v[64:67], v[184:187], v[216:219], v[64:67]
	s_setprio 0
	s_add_i32 s46, s64, s56
	v_lshl_add_u64 v[144:145], s[50:51], 0, v[130:131]
	s_mov_b32 m0, s46
	ds_read_b128 v[188:191], v151 offset:16384
	ds_read_b128 v[192:195], v151 offset:17408
	ds_read_b128 v[196:199], v151 offset:18432
	ds_read_b128 v[200:203], v151 offset:19456
	ds_read_b128 v[204:207], v151 offset:20480
	ds_read_b128 v[208:211], v151 offset:21504
	ds_read_b128 v[212:215], v151 offset:22528
	ds_read_b128 v[216:219], v151 offset:23552
	global_load_lds_dwordx4 v[144:145], off
	s_add_i32 m0, s46, 0x2000
	s_add_u32 s46, s50, 0xb0000
	v_lshl_add_u64 v[220:221], s[50:51], 0, v[134:135]
	s_addc_u32 s47, s51, 0
	s_add_i32 s77, s65, s56
	global_load_lds_dwordx4 v[220:221], off
	v_lshl_add_u64 v[222:223], s[46:47], 0, v[130:131]
	s_mov_b32 m0, s77
	v_lshl_add_u64 v[224:225], s[52:53], 0, v[132:133]
	global_load_lds_dwordx4 v[222:223], off
	v_lshl_add_u64 v[222:223], s[46:47], 0, v[134:135]
	s_add_i32 m0, s77, 0x2000
	s_nop 0
	global_load_lds_dwordx4 v[222:223], off
	v_lshl_add_u64 v[222:223], s[52:53], 0, v[128:129]
	s_mov_b32 m0, s57
	s_nop 0
	global_load_lds_dwordx4 v[222:223], off
	s_mov_b32 m0, s58
	s_nop 0
	global_load_lds_dwordx4 v[224:225], off
	s_waitcnt vmcnt(8)
	s_waitcnt lgkmcnt(0)
	s_barrier
	s_waitcnt lgkmcnt(0)
	v_mfma_f32_16x16x32_bf16 v[60:63], v[152:155], v[188:191], v[60:63]
	v_mfma_f32_16x16x32_bf16 v[60:63], v[156:159], v[192:195], v[60:63]
	v_mfma_f32_16x16x32_bf16 v[56:59], v[160:163], v[188:191], v[56:59]
	v_mfma_f32_16x16x32_bf16 v[56:59], v[164:167], v[192:195], v[56:59]
	v_mfma_f32_16x16x32_bf16 v[52:55], v[152:155], v[196:199], v[52:55]
	v_mfma_f32_16x16x32_bf16 v[52:55], v[156:159], v[200:203], v[52:55]
	v_mfma_f32_16x16x32_bf16 v[44:47], v[160:163], v[196:199], v[44:47]
	v_mfma_f32_16x16x32_bf16 v[44:47], v[164:167], v[200:203], v[44:47]
	s_setprio 1
	v_mfma_f32_16x16x32_bf16 v[36:39], v[152:155], v[204:207], v[36:39]
	v_mfma_f32_16x16x32_bf16 v[36:39], v[156:159], v[208:211], v[36:39]
	v_mfma_f32_16x16x32_bf16 v[28:31], v[160:163], v[204:207], v[28:31]
	v_mfma_f32_16x16x32_bf16 v[28:31], v[164:167], v[208:211], v[28:31]
	v_mfma_f32_16x16x32_bf16 v[20:23], v[152:155], v[212:215], v[20:23]
	v_mfma_f32_16x16x32_bf16 v[20:23], v[156:159], v[216:219], v[20:23]
	v_mfma_f32_16x16x32_bf16 v[12:15], v[160:163], v[212:215], v[12:15]
	v_mfma_f32_16x16x32_bf16 v[12:15], v[164:167], v[216:219], v[12:15]
	v_mfma_f32_16x16x32_bf16 v[48:51], v[168:171], v[188:191], v[48:51]
	v_mfma_f32_16x16x32_bf16 v[48:51], v[172:175], v[192:195], v[48:51]
	v_mfma_f32_16x16x32_bf16 v[40:43], v[176:179], v[188:191], v[40:43]
	v_mfma_f32_16x16x32_bf16 v[40:43], v[184:187], v[192:195], v[40:43]
	v_mfma_f32_16x16x32_bf16 v[32:35], v[168:171], v[196:199], v[32:35]
	v_mfma_f32_16x16x32_bf16 v[32:35], v[172:175], v[200:203], v[32:35]
	v_mfma_f32_16x16x32_bf16 v[24:27], v[176:179], v[196:199], v[24:27]
	v_mfma_f32_16x16x32_bf16 v[24:27], v[184:187], v[200:203], v[24:27]
	s_barrier
	v_mfma_f32_16x16x32_bf16 v[16:19], v[168:171], v[204:207], v[16:19]
	v_mfma_f32_16x16x32_bf16 v[16:19], v[172:175], v[208:211], v[16:19]
	v_mfma_f32_16x16x32_bf16 v[8:11], v[176:179], v[204:207], v[8:11]
	v_mfma_f32_16x16x32_bf16 v[8:11], v[184:187], v[208:211], v[8:11]
	v_mfma_f32_16x16x32_bf16 v[4:7], v[168:171], v[212:215], v[4:7]
	v_mfma_f32_16x16x32_bf16 v[4:7], v[172:175], v[216:219], v[4:7]
	v_mfma_f32_16x16x32_bf16 v[0:3], v[176:179], v[212:215], v[0:3]
	v_mfma_f32_16x16x32_bf16 v[0:3], v[184:187], v[216:219], v[0:3]
	s_setprio 0
.Lmid_gemm12:
	s_add_i32 s77, 0, 0x18000
	s_add_i32 s79, 0, 0x1c000
	v_add_u32_e32 v164, s77, v147
	v_add_u32_e32 v181, s79, v147
	ds_read_b128 v[152:155], v164
	ds_read_b128 v[156:159], v164 offset:1024
	ds_read_b128 v[160:163], v164 offset:2048
	ds_read_b128 v[164:167], v164 offset:3072
	ds_read_b128 v[168:171], v181
	ds_read_b128 v[172:175], v181 offset:1024
	ds_read_b128 v[176:179], v181 offset:2048
	ds_read_b128 v[184:187], v181 offset:3072
	s_add_u32 s46, s52, 0xb0000
	s_addc_u32 s47, s53, 0
	s_mov_b32 m0, s59
	v_lshl_add_u64 v[226:227], s[46:47], 0, v[128:129]
	ds_read_b128 v[188:191], v151 offset:32768
	ds_read_b128 v[192:195], v151 offset:33792
	ds_read_b128 v[196:199], v151 offset:34816
	ds_read_b128 v[200:203], v151 offset:35840
	ds_read_b128 v[204:207], v151 offset:36864
	ds_read_b128 v[208:211], v151 offset:37888
	ds_read_b128 v[212:215], v151 offset:38912
	ds_read_b128 v[216:219], v151 offset:39936
	global_load_lds_dwordx4 v[226:227], off
	v_lshl_add_u64 v[226:227], s[46:47], 0, v[132:133]
	s_mov_b32 m0, s60
	s_nop 0
	global_load_lds_dwordx4 v[226:227], off
	s_waitcnt vmcnt(8)
	s_waitcnt lgkmcnt(0)
	s_barrier
	s_waitcnt lgkmcnt(0)
	v_mfma_f32_16x16x32_bf16 v[124:127], v[152:155], v[188:191], v[124:127]
	v_mfma_f32_16x16x32_bf16 v[124:127], v[156:159], v[192:195], v[124:127]
	v_mfma_f32_16x16x32_bf16 v[120:123], v[160:163], v[188:191], v[120:123]
	v_mfma_f32_16x16x32_bf16 v[120:123], v[164:167], v[192:195], v[120:123]
	v_mfma_f32_16x16x32_bf16 v[116:119], v[152:155], v[196:199], v[116:119]
	v_mfma_f32_16x16x32_bf16 v[116:119], v[156:159], v[200:203], v[116:119]
	v_mfma_f32_16x16x32_bf16 v[108:111], v[160:163], v[196:199], v[108:111]
	v_mfma_f32_16x16x32_bf16 v[108:111], v[164:167], v[200:203], v[108:111]
	s_setprio 1
	v_mfma_f32_16x16x32_bf16 v[100:103], v[152:155], v[204:207], v[100:103]
	v_mfma_f32_16x16x32_bf16 v[100:103], v[156:159], v[208:211], v[100:103]
	v_mfma_f32_16x16x32_bf16 v[92:95], v[160:163], v[204:207], v[92:95]
	v_mfma_f32_16x16x32_bf16 v[92:95], v[164:167], v[208:211], v[92:95]
	v_mfma_f32_16x16x32_bf16 v[84:87], v[152:155], v[212:215], v[84:87]
	v_mfma_f32_16x16x32_bf16 v[84:87], v[156:159], v[216:219], v[84:87]
	v_mfma_f32_16x16x32_bf16 v[76:79], v[160:163], v[212:215], v[76:79]
	v_mfma_f32_16x16x32_bf16 v[76:79], v[164:167], v[216:219], v[76:79]
	v_mfma_f32_16x16x32_bf16 v[112:115], v[168:171], v[188:191], v[112:115]
	v_mfma_f32_16x16x32_bf16 v[112:115], v[172:175], v[192:195], v[112:115]
	v_mfma_f32_16x16x32_bf16 v[104:107], v[176:179], v[188:191], v[104:107]
	v_mfma_f32_16x16x32_bf16 v[104:107], v[184:187], v[192:195], v[104:107]
	v_mfma_f32_16x16x32_bf16 v[96:99], v[168:171], v[196:199], v[96:99]
	v_mfma_f32_16x16x32_bf16 v[96:99], v[172:175], v[200:203], v[96:99]
	v_mfma_f32_16x16x32_bf16 v[88:91], v[176:179], v[196:199], v[88:91]
	v_mfma_f32_16x16x32_bf16 v[88:91], v[184:187], v[200:203], v[88:91]
	s_barrier
	v_mfma_f32_16x16x32_bf16 v[80:83], v[168:171], v[204:207], v[80:83]
	v_mfma_f32_16x16x32_bf16 v[80:83], v[172:175], v[208:211], v[80:83]
	v_mfma_f32_16x16x32_bf16 v[72:75], v[176:179], v[204:207], v[72:75]
	v_mfma_f32_16x16x32_bf16 v[72:75], v[184:187], v[208:211], v[72:75]
	v_mfma_f32_16x16x32_bf16 v[68:71], v[168:171], v[212:215], v[68:71]
	v_mfma_f32_16x16x32_bf16 v[68:71], v[172:175], v[216:219], v[68:71]
	v_mfma_f32_16x16x32_bf16 v[64:67], v[176:179], v[212:215], v[64:67]
	v_mfma_f32_16x16x32_bf16 v[64:67], v[184:187], v[216:219], v[64:67]
	s_setprio 0
	s_add_i32 s46, s77, s56
	v_lshl_add_u64 v[144:145], v[144:145], 0, s[10:11]
	s_mov_b32 m0, s46
	ds_read_b128 v[188:191], v151 offset:49152
	ds_read_b128 v[192:195], v151 offset:50176
	ds_read_b128 v[196:199], v151 offset:51200
	ds_read_b128 v[200:203], v151 offset:52224
	ds_read_b128 v[204:207], v151 offset:53248
	ds_read_b128 v[208:211], v151 offset:54272
	ds_read_b128 v[212:215], v151 offset:55296
	ds_read_b128 v[216:219], v151 offset:56320
	global_load_lds_dwordx4 v[144:145], off
	s_add_i32 m0, s46, 0x2000
	s_add_u32 s46, s50, 0xb0080
	v_lshl_add_u64 v[144:145], v[220:221], 0, s[10:11]
	s_addc_u32 s47, s51, 0
	s_add_i32 s50, s79, s56
	global_load_lds_dwordx4 v[144:145], off
	v_lshl_add_u64 v[144:145], s[46:47], 0, v[130:131]
	s_mov_b32 m0, s50
	s_nop 0
	global_load_lds_dwordx4 v[144:145], off
	v_lshl_add_u64 v[144:145], s[46:47], 0, v[134:135]
	s_add_i32 m0, s50, 0x2000
	s_nop 0
	global_load_lds_dwordx4 v[144:145], off
	v_lshl_add_u64 v[144:145], v[222:223], 0, s[10:11]
	s_mov_b32 m0, s62
	s_nop 0
	global_load_lds_dwordx4 v[144:145], off
	v_lshl_add_u64 v[144:145], v[224:225], 0, s[10:11]
	s_mov_b32 m0, s63
	s_nop 0
	global_load_lds_dwordx4 v[144:145], off
	s_waitcnt vmcnt(8)
	s_waitcnt lgkmcnt(0)
	s_barrier
	s_waitcnt lgkmcnt(0)
	v_mfma_f32_16x16x32_bf16 v[60:63], v[152:155], v[188:191], v[60:63]
	v_mfma_f32_16x16x32_bf16 v[60:63], v[156:159], v[192:195], v[60:63]
	v_mfma_f32_16x16x32_bf16 v[56:59], v[160:163], v[188:191], v[56:59]
	v_mfma_f32_16x16x32_bf16 v[56:59], v[164:167], v[192:195], v[56:59]
	v_mfma_f32_16x16x32_bf16 v[52:55], v[152:155], v[196:199], v[52:55]
	v_mfma_f32_16x16x32_bf16 v[52:55], v[156:159], v[200:203], v[52:55]
	v_mfma_f32_16x16x32_bf16 v[44:47], v[160:163], v[196:199], v[44:47]
	v_mfma_f32_16x16x32_bf16 v[44:47], v[164:167], v[200:203], v[44:47]
	s_setprio 1
	v_mfma_f32_16x16x32_bf16 v[36:39], v[152:155], v[204:207], v[36:39]
	v_mfma_f32_16x16x32_bf16 v[36:39], v[156:159], v[208:211], v[36:39]
	v_mfma_f32_16x16x32_bf16 v[28:31], v[160:163], v[204:207], v[28:31]
	v_mfma_f32_16x16x32_bf16 v[28:31], v[164:167], v[208:211], v[28:31]
	v_mfma_f32_16x16x32_bf16 v[20:23], v[152:155], v[212:215], v[20:23]
	v_mfma_f32_16x16x32_bf16 v[20:23], v[156:159], v[216:219], v[20:23]
	v_mfma_f32_16x16x32_bf16 v[12:15], v[160:163], v[212:215], v[12:15]
	v_mfma_f32_16x16x32_bf16 v[12:15], v[164:167], v[216:219], v[12:15]
	v_mfma_f32_16x16x32_bf16 v[48:51], v[168:171], v[188:191], v[48:51]
	v_mfma_f32_16x16x32_bf16 v[48:51], v[172:175], v[192:195], v[48:51]
	v_mfma_f32_16x16x32_bf16 v[40:43], v[176:179], v[188:191], v[40:43]
	v_mfma_f32_16x16x32_bf16 v[40:43], v[184:187], v[192:195], v[40:43]
	v_mfma_f32_16x16x32_bf16 v[32:35], v[168:171], v[196:199], v[32:35]
	v_mfma_f32_16x16x32_bf16 v[32:35], v[172:175], v[200:203], v[32:35]
	v_mfma_f32_16x16x32_bf16 v[24:27], v[176:179], v[196:199], v[24:27]
	v_mfma_f32_16x16x32_bf16 v[24:27], v[184:187], v[200:203], v[24:27]
	s_barrier
	v_mfma_f32_16x16x32_bf16 v[16:19], v[168:171], v[204:207], v[16:19]
	v_mfma_f32_16x16x32_bf16 v[16:19], v[172:175], v[208:211], v[16:19]
	v_mfma_f32_16x16x32_bf16 v[8:11], v[176:179], v[204:207], v[8:11]
	v_mfma_f32_16x16x32_bf16 v[8:11], v[184:187], v[208:211], v[8:11]
	v_mfma_f32_16x16x32_bf16 v[4:7], v[168:171], v[212:215], v[4:7]
	v_mfma_f32_16x16x32_bf16 v[4:7], v[172:175], v[216:219], v[4:7]
	v_mfma_f32_16x16x32_bf16 v[0:3], v[176:179], v[212:215], v[0:3]
	v_mfma_f32_16x16x32_bf16 v[0:3], v[184:187], v[216:219], v[0:3]
	s_setprio 0
	s_add_i32 s76, s76, 2
	s_add_u32 s74, s74, 0x100
	s_addc_u32 s75, s75, 0
	s_cmp_gt_u32 s76, 41
	s_mov_b64 s[46:47], s[48:49]
	s_cbranch_scc0 .LBB0_1514
	s_and_b64 vcc, exec, s[12:13]
	s_cbranch_vccz .LBB0_1517
	s_barrier
